# yfin load hoist (40 loads per token issued together) on top of v016
# speedup vs baseline: 1.0618x; 1.0400x over previous
.LBB0_145:
	s_or_b64 exec, exec, s[8:9]
	s_movk_i32 s9, 0x410
	v_lshrrev_b32_e32 v130, 2, v140
	v_lshlrev_b32_e32 v131, 1, v140
	v_and_b32_e32 v0, 15, v140
	v_and_b32_e32 v130, 0xfffffcc, v130
	v_and_b32_e32 v131, 0x180, v131
	v_add_u32_e32 v131, 0, v131
	v_lshlrev_b32_e32 v0, 2, v0
	v_mul_lo_u32 v130, v130, s9
	v_add3_u32 v130, v131, v0, v130
	s_waitcnt vmcnt(0)
	s_barrier
	ds_write2_b32 v130, v114, v126 offset1:16
	v_add_u32_e32 v114, 0x400, v130
	ds_write2_b32 v114, v115, v127 offset0:4 offset1:20
	v_add_u32_e32 v115, 0x800, v130
	ds_write2_b32 v115, v116, v128 offset0:8 offset1:24
	v_add_u32_e32 v116, 0xc00, v130
	ds_write2_b32 v116, v117, v129 offset0:12 offset1:28
	v_add_u32_e32 v117, 0x4000, v130
	ds_write2_b32 v117, v82, v94 offset0:64 offset1:80
	v_add_u32_e32 v82, 0x4400, v130
	ds_write2_b32 v82, v83, v95 offset0:68 offset1:84
	v_add_u32_e32 v83, 0x4800, v130
	ds_write2_b32 v83, v84, v96 offset0:72 offset1:88
	v_add_u32_e32 v84, 0x4c00, v130
	ds_write2_b32 v84, v85, v97 offset0:76 offset1:92
	v_add_u32_e32 v85, 0x8000, v130
	ds_write2_b32 v85, v74, v78 offset0:128 offset1:144
	v_add_u32_e32 v74, 0x8400, v130
	ds_write2_b32 v74, v75, v79 offset0:132 offset1:148
	v_add_u32_e32 v75, 0x8800, v130
	ds_write2_b32 v75, v76, v80 offset0:136 offset1:152
	v_add_u32_e32 v76, 0x8c00, v130
	v_add_u32_e32 v80, 0xc000, v130
	ds_write2_b32 v76, v77, v81 offset0:140 offset1:156
	ds_write2_b32 v80, v66, v70 offset0:192 offset1:208
	v_add_u32_e32 v77, 0xc400, v130
	v_add_u32_e32 v78, 0xc800, v130
	v_add_u32_e32 v79, 0xcc00, v130
	v_add_u32_e32 v81, 0x9000, v130
	v_lshlrev_b32_e32 v66, 2, v140
	ds_write2_b32 v77, v67, v71 offset0:196 offset1:212
	ds_write2_b32 v78, v68, v72 offset0:200 offset1:216
	ds_write2_b32 v79, v69, v73 offset0:204 offset1:220
	ds_write2_b32 v130, v98, v118 offset0:128 offset1:144
	ds_write2_b32 v114, v99, v119 offset0:132 offset1:148
	ds_write2_b32 v115, v100, v120 offset0:136 offset1:152
	ds_write2_b32 v116, v101, v121 offset0:140 offset1:156
	ds_write2_b32 v117, v102, v122 offset0:192 offset1:208
	ds_write2_b32 v82, v103, v123 offset0:196 offset1:212
	ds_write2_b32 v83, v104, v124 offset0:200 offset1:216
	ds_write2_b32 v84, v105, v125 offset0:204 offset1:220
	ds_write2_b32 v74, v90, v110 offset1:16
	ds_write2_b32 v75, v91, v111 offset0:4 offset1:20
	ds_write2_b32 v76, v92, v112 offset0:8 offset1:24
	ds_write2_b32 v81, v93, v113 offset0:12 offset1:28
	ds_write2_b32 v77, v86, v106 offset0:64 offset1:80
	ds_write2_b32 v78, v87, v107 offset0:68 offset1:84
	ds_write2_b32 v79, v88, v108 offset0:72 offset1:88
	v_lshlrev_b32_e32 v0, 3, v140
	v_and_b32_e32 v66, 12, v66
	s_movk_i32 s8, 0xe0
	v_ashrrev_i32_e32 v87, 5, v140
	v_and_or_b32 v0, v0, s8, v66
	v_add_u32_e32 v68, s39, v87
	v_or_b32_e32 v66, s36, v0
	v_ashrrev_i32_e32 v69, 31, v68
	v_ashrrev_i32_e32 v67, 31, v66
	v_lshlrev_b64 v[70:71], 10, v[68:69]
	v_lshl_add_u64 v[98:99], v[70:71], 0, v[66:67]
	v_add_u32_e32 v86, 0xd000, v130
	v_lshl_add_u64 v[110:111], v[98:99], 2, s[26:27]
	ds_write2_b32 v86, v89, v109 offset0:76 offset1:92
	s_waitcnt lgkmcnt(0)
	s_barrier
	v_lshlrev_b32_e32 v141, 2, v98
	global_load_dwordx4 v[132:135], v141, s[26:27]
	global_load_dwordx4 v[136:139], v141, s[26:27] offset:64
	v_add_u32_e32 v141, 0x10000, v141
	global_load_dwordx4 v[142:145], v141, s[26:27]
	global_load_dwordx4 v[146:149], v141, s[26:27] offset:64
	v_add_u32_e32 v141, 0x10000, v141
	global_load_dwordx4 v[150:153], v141, s[26:27]
	global_load_dwordx4 v[154:157], v141, s[26:27] offset:64
	v_add_u32_e32 v141, 0x10000, v141
	global_load_dwordx4 v[158:161], v141, s[26:27]
	global_load_dwordx4 v[162:165], v141, s[26:27] offset:64
	v_add_u32_e32 v141, 0x10000, v141
	global_load_dwordx4 v[166:169], v141, s[26:27]
	global_load_dwordx4 v[170:173], v141, s[26:27] offset:64
	v_add_u32_e32 v141, 0x10000, v141
	global_load_dwordx4 v[174:177], v141, s[26:27]
	global_load_dwordx4 v[178:181], v141, s[26:27] offset:64
	v_add_u32_e32 v141, 0x10000, v141
	global_load_dwordx4 v[182:185], v141, s[26:27]
	global_load_dwordx4 v[186:189], v141, s[26:27] offset:64
	v_add_u32_e32 v141, 0x10000, v141
	global_load_dwordx4 v[190:193], v141, s[26:27]
	global_load_dwordx4 v[194:197], v141, s[26:27] offset:64
	v_lshl_add_u32 v101, v0, 2, 0
	v_mul_lo_u32 v72, v87, s9
	v_add_u32_e32 v88, v101, v72
	ds_read_b128 v[102:105], v88
	ds_read_b128 v[106:109], v88 offset:64
	v_and_b32_e32 v70, 64, v218
	v_xor_b32_e32 v0, 1, v218
	v_add_u32_e32 v100, 64, v70
	v_cmp_lt_i32_e32 vcc, v0, v100
	v_xor_b32_e32 v70, 2, v218
	v_xor_b32_e32 v71, 4, v218
	v_cndmask_b32_e32 v0, v218, v0, vcc
	v_lshlrev_b32_e32 v0, 2, v0
	v_cmp_lt_i32_e32 vcc, v70, v100
	v_xor_b32_e32 v112, 8, v218
	v_and_b32_e32 v89, 31, v140
	v_cndmask_b32_e32 v70, v218, v70, vcc
	v_lshlrev_b32_e32 v70, 2, v70
	v_cmp_lt_i32_e32 vcc, v71, v100
	s_ashr_i32 s57, s56, 31
	s_lshl_b64 s[8:9], s[56:57], 2
	v_cndmask_b32_e32 v71, v218, v71, vcc
	v_cmp_lt_i32_e32 vcc, v112, v100
	v_lshlrev_b32_e32 v71, 2, v71
	s_add_u32 s8, s46, s8
	s_movk_i32 s14, 0x410
	s_addc_u32 s9, s47, s9
	s_waitcnt lgkmcnt(1)
	s_waitcnt vmcnt(15)
	v_pk_fma_f32 v[90:91], v[102:103], 0.5, v[132:133] op_sel_hi:[1,0,1]
	s_waitcnt vmcnt(15)
	v_pk_fma_f32 v[92:93], v[104:105], 0.5, v[134:135] op_sel_hi:[1,0,1]
	v_pk_mul_f32 v[72:73], v[90:91], v[90:91]
	v_pk_mul_f32 v[102:103], v[92:93], v[92:93]
	v_add_f32_e32 v72, v72, v73
	s_waitcnt lgkmcnt(0)
	s_waitcnt vmcnt(14)
	v_pk_fma_f32 v[94:95], v[106:107], 0.5, v[136:137] op_sel_hi:[1,0,1]
	v_add_f32_e32 v72, v102, v72
	v_pk_mul_f32 v[104:105], v[94:95], v[94:95]
	v_add_f32_e32 v72, v103, v72
	s_waitcnt vmcnt(14)
	v_pk_fma_f32 v[96:97], v[108:109], 0.5, v[138:139] op_sel_hi:[1,0,1]
	v_add_f32_e32 v72, v104, v72
	v_pk_mul_f32 v[106:107], v[96:97], v[96:97]
	v_add_f32_e32 v72, v105, v72
	v_add_f32_e32 v72, v106, v72
	v_add_f32_e32 v72, v107, v72
	ds_bpermute_b32 v102, v0, v72
	v_xor_b32_e32 v103, 16, v218
	v_cndmask_b32_e32 v73, v218, v112, vcc
	v_cmp_lt_i32_e32 vcc, v103, v100
	v_lshlrev_b32_e32 v73, 2, v73
	s_waitcnt lgkmcnt(0)
	v_add_f32_e32 v102, v72, v102
	ds_bpermute_b32 v104, v70, v102
	v_cndmask_b32_e32 v72, v218, v103, vcc
	v_cmp_eq_u32_e32 vcc, 0, v89
	v_lshlrev_b32_e32 v72, 2, v72
	global_store_dwordx4 v[110:111], v[90:93], off
	s_waitcnt lgkmcnt(0)
	v_add_f32_e32 v89, v102, v104
	ds_bpermute_b32 v100, v71, v89
	v_cvt_pk_bf16_f32 v102, v90, v91
	global_store_dwordx4 v[110:111], v[94:97], off offset:64
	v_cvt_pk_bf16_f32 v103, v92, v93
	v_lshl_add_u64 v[92:93], v[98:99], 1, s[44:45]
	s_waitcnt lgkmcnt(0)
	v_add_f32_e32 v89, v89, v100
	ds_bpermute_b32 v100, v73, v89
	v_cvt_pk_bf16_f32 v94, v94, v95
	v_cvt_pk_bf16_f32 v95, v96, v97
	global_store_dwordx2 v[92:93], v[102:103], off
	global_store_dwordx2 v[92:93], v[94:95], off offset:32
	s_waitcnt lgkmcnt(0)
	v_add_f32_e32 v89, v89, v100
	ds_bpermute_b32 v90, v72, v89
	s_and_saveexec_b64 s[10:11], vcc
	v_readlane_b32 s62, v253, 50
	s_cbranch_execz .LBB0_147
	s_waitcnt lgkmcnt(0)
	v_add_f32_e32 v89, v89, v90
	v_lshl_add_u64 v[68:69], v[68:69], 4, s[8:9]
	global_store_dword v[68:69], v89, off
.LBB0_147:
	s_or_b64 exec, exec, s[10:11]
	v_add_u32_e32 v68, 0x200, v140
	s_waitcnt lgkmcnt(0)
	v_ashrrev_i32_e32 v90, 5, v68
	v_mul_lo_u32 v68, v90, s14
	v_add_u32_e32 v89, v101, v68
	v_add_u32_e32 v68, s39, v90
	v_ashrrev_i32_e32 v69, 31, v68
	v_lshlrev_b64 v[92:93], 10, v[68:69]
	v_lshl_add_u64 v[106:107], v[92:93], 0, v[66:67]
	v_lshl_add_u64 v[108:109], v[106:107], 2, s[26:27]
	ds_read_b128 v[92:95], v89
	s_waitcnt lgkmcnt(0)
	s_waitcnt vmcnt(18)
	v_pk_fma_f32 v[92:93], v[92:93], 0.5, v[142:143] op_sel_hi:[1,0,1]
	s_waitcnt vmcnt(18)
	v_pk_fma_f32 v[94:95], v[94:95], 0.5, v[144:145] op_sel_hi:[1,0,1]
	ds_read_b128 v[96:99], v89 offset:64
	global_store_dwordx4 v[108:109], v[92:95], off
	s_waitcnt lgkmcnt(0)
	s_waitcnt vmcnt(18)
	v_pk_fma_f32 v[96:97], v[96:97], 0.5, v[146:147] op_sel_hi:[1,0,1]
	v_cvt_pk_bf16_f32 v102, v92, v93
	v_pk_mul_f32 v[92:93], v[92:93], v[92:93]
	v_cvt_pk_bf16_f32 v103, v94, v95
	v_pk_mul_f32 v[94:95], v[94:95], v[94:95]
	v_add_f32_e32 v91, v92, v93
	s_waitcnt vmcnt(18)
	v_pk_fma_f32 v[98:99], v[98:99], 0.5, v[148:149] op_sel_hi:[1,0,1]
	v_lshl_add_u64 v[104:105], v[106:107], 1, s[44:45]
	v_add_f32_e32 v91, v94, v91
	global_store_dwordx4 v[108:109], v[96:99], off offset:64
	global_store_dwordx2 v[104:105], v[102:103], off
	v_cvt_pk_bf16_f32 v102, v96, v97
	v_pk_mul_f32 v[96:97], v[96:97], v[96:97]
	v_add_f32_e32 v91, v95, v91
	v_add_f32_e32 v91, v96, v91
	v_cvt_pk_bf16_f32 v103, v98, v99
	v_pk_mul_f32 v[98:99], v[98:99], v[98:99]
	v_add_f32_e32 v91, v97, v91
	v_add_f32_e32 v91, v98, v91
	v_add_f32_e32 v91, v99, v91
	ds_bpermute_b32 v92, v0, v91
	global_store_dwordx2 v[104:105], v[102:103], off offset:32
	s_waitcnt lgkmcnt(0)
	v_add_f32_e32 v91, v91, v92
	ds_bpermute_b32 v92, v70, v91
	s_waitcnt lgkmcnt(0)
	v_add_f32_e32 v91, v91, v92
	ds_bpermute_b32 v92, v71, v91
	s_waitcnt lgkmcnt(0)
	v_add_f32_e32 v91, v91, v92
	ds_bpermute_b32 v92, v73, v91
	s_waitcnt lgkmcnt(0)
	v_add_f32_e32 v91, v91, v92
	ds_bpermute_b32 v92, v72, v91
	s_and_saveexec_b64 s[10:11], vcc
	s_cbranch_execz .LBB0_149
	s_waitcnt lgkmcnt(0)
	v_add_f32_e32 v91, v91, v92
	v_lshl_add_u64 v[68:69], v[68:69], 4, s[8:9]
	global_store_dword v[68:69], v91, off
.LBB0_149:
	s_or_b64 exec, exec, s[10:11]
	v_add_u32_e32 v68, 0x400, v140
	s_waitcnt lgkmcnt(0)
	v_ashrrev_i32_e32 v92, 5, v68
	v_mul_lo_u32 v68, v92, s14
	v_add_u32_e32 v91, v101, v68
	v_add_u32_e32 v68, s39, v92
	v_ashrrev_i32_e32 v69, 31, v68
	v_lshlrev_b64 v[94:95], 10, v[68:69]
	v_lshl_add_u64 v[98:99], v[94:95], 0, v[66:67]
	v_lshl_add_u64 v[110:111], v[98:99], 2, s[26:27]
	ds_read_b128 v[94:97], v91
	v_lshl_add_u64 v[98:99], v[98:99], 1, s[44:45]
	s_waitcnt lgkmcnt(0)
	s_waitcnt vmcnt(21)
	v_pk_fma_f32 v[94:95], v[94:95], 0.5, v[150:151] op_sel_hi:[1,0,1]
	s_waitcnt vmcnt(21)
	v_pk_fma_f32 v[96:97], v[96:97], 0.5, v[152:153] op_sel_hi:[1,0,1]
	ds_read_b128 v[102:105], v91 offset:64
	global_store_dwordx4 v[110:111], v[94:97], off
	s_waitcnt lgkmcnt(0)
	s_waitcnt vmcnt(21)
	v_pk_fma_f32 v[102:103], v[102:103], 0.5, v[154:155] op_sel_hi:[1,0,1]
	v_cvt_pk_bf16_f32 v106, v94, v95
	v_pk_mul_f32 v[94:95], v[94:95], v[94:95]
	s_waitcnt vmcnt(21)
	v_pk_fma_f32 v[104:105], v[104:105], 0.5, v[156:157] op_sel_hi:[1,0,1]
	v_cvt_pk_bf16_f32 v107, v96, v97
	v_pk_mul_f32 v[96:97], v[96:97], v[96:97]
	v_add_f32_e32 v93, v94, v95
	global_store_dwordx4 v[110:111], v[102:105], off offset:64
	global_store_dwordx2 v[98:99], v[106:107], off
	v_cvt_pk_bf16_f32 v106, v102, v103
	v_cvt_pk_bf16_f32 v107, v104, v105
	v_add_f32_e32 v93, v96, v93
	global_store_dwordx2 v[98:99], v[106:107], off offset:32
	v_pk_mul_f32 v[98:99], v[102:103], v[102:103]
	v_add_f32_e32 v93, v97, v93
	v_add_f32_e32 v93, v98, v93
	v_pk_mul_f32 v[102:103], v[104:105], v[104:105]
	v_add_f32_e32 v93, v99, v93
	v_add_f32_e32 v93, v102, v93
	v_add_f32_e32 v93, v103, v93
	ds_bpermute_b32 v94, v0, v93
	s_waitcnt lgkmcnt(0)
	v_add_f32_e32 v93, v93, v94
	ds_bpermute_b32 v94, v70, v93
	s_waitcnt lgkmcnt(0)
	v_add_f32_e32 v93, v93, v94
	ds_bpermute_b32 v94, v71, v93
	s_waitcnt lgkmcnt(0)
	v_add_f32_e32 v93, v93, v94
	ds_bpermute_b32 v94, v73, v93
	s_waitcnt lgkmcnt(0)
	v_add_f32_e32 v93, v93, v94
	ds_bpermute_b32 v94, v72, v93
	s_and_saveexec_b64 s[10:11], vcc
	s_cbranch_execz .LBB0_151
	s_waitcnt lgkmcnt(0)
	v_add_f32_e32 v93, v93, v94
	v_lshl_add_u64 v[68:69], v[68:69], 4, s[8:9]
	global_store_dword v[68:69], v93, off
.LBB0_151:
	s_or_b64 exec, exec, s[10:11]
	v_add_u32_e32 v68, 0x600, v140
	s_waitcnt lgkmcnt(0)
	v_ashrrev_i32_e32 v94, 5, v68
	v_mul_lo_u32 v68, v94, s14
	v_add_u32_e32 v93, v101, v68
	v_add_u32_e32 v68, s39, v94
	v_ashrrev_i32_e32 v69, 31, v68
	v_lshlrev_b64 v[96:97], 10, v[68:69]
	v_lshl_add_u64 v[110:111], v[96:97], 0, v[66:67]
	v_lshl_add_u64 v[112:113], v[110:111], 2, s[26:27]
	ds_read_b128 v[96:99], v93
	s_waitcnt lgkmcnt(0)
	s_waitcnt vmcnt(24)
	v_pk_fma_f32 v[96:97], v[96:97], 0.5, v[158:159] op_sel_hi:[1,0,1]
	s_waitcnt vmcnt(24)
	v_pk_fma_f32 v[98:99], v[98:99], 0.5, v[160:161] op_sel_hi:[1,0,1]
	ds_read_b128 v[102:105], v93 offset:64
	global_store_dwordx4 v[112:113], v[96:99], off
	s_waitcnt lgkmcnt(0)
	s_waitcnt vmcnt(24)
	v_pk_fma_f32 v[102:103], v[102:103], 0.5, v[162:163] op_sel_hi:[1,0,1]
	v_cvt_pk_bf16_f32 v106, v96, v97
	v_pk_mul_f32 v[96:97], v[96:97], v[96:97]
	v_cvt_pk_bf16_f32 v107, v98, v99
	v_pk_mul_f32 v[98:99], v[98:99], v[98:99]
	v_add_f32_e32 v95, v96, v97
	s_waitcnt vmcnt(24)
	v_pk_fma_f32 v[104:105], v[104:105], 0.5, v[164:165] op_sel_hi:[1,0,1]
	v_lshl_add_u64 v[108:109], v[110:111], 1, s[44:45]
	v_add_f32_e32 v95, v98, v95
	global_store_dwordx4 v[112:113], v[102:105], off offset:64
	global_store_dwordx2 v[108:109], v[106:107], off
	v_cvt_pk_bf16_f32 v106, v102, v103
	v_pk_mul_f32 v[102:103], v[102:103], v[102:103]
	v_add_f32_e32 v95, v99, v95
	v_add_f32_e32 v95, v102, v95
	v_cvt_pk_bf16_f32 v107, v104, v105
	v_pk_mul_f32 v[104:105], v[104:105], v[104:105]
	v_add_f32_e32 v95, v103, v95
	v_add_f32_e32 v95, v104, v95
	v_add_f32_e32 v95, v105, v95
	ds_bpermute_b32 v96, v0, v95
	global_store_dwordx2 v[108:109], v[106:107], off offset:32
	s_waitcnt lgkmcnt(0)
	v_add_f32_e32 v95, v95, v96
	ds_bpermute_b32 v96, v70, v95
	s_waitcnt lgkmcnt(0)
	v_add_f32_e32 v95, v95, v96
	ds_bpermute_b32 v96, v71, v95
	s_waitcnt lgkmcnt(0)
	v_add_f32_e32 v95, v95, v96
	ds_bpermute_b32 v96, v73, v95
	s_waitcnt lgkmcnt(0)
	v_add_f32_e32 v95, v95, v96
	ds_bpermute_b32 v96, v72, v95
	s_and_saveexec_b64 s[10:11], vcc
	s_cbranch_execz .LBB0_153
	s_waitcnt lgkmcnt(0)
	v_add_f32_e32 v95, v95, v96
	v_lshl_add_u64 v[68:69], v[68:69], 4, s[8:9]
	global_store_dword v[68:69], v95, off
.LBB0_153:
	s_or_b64 exec, exec, s[10:11]
	v_add_u32_e32 v68, 0x800, v140
	s_waitcnt lgkmcnt(0)
	v_ashrrev_i32_e32 v96, 5, v68
	v_mul_lo_u32 v68, v96, s14
	v_add_u32_e32 v95, v101, v68
	v_add_u32_e32 v68, s39, v96
	v_ashrrev_i32_e32 v69, 31, v68
	v_lshlrev_b64 v[98:99], 10, v[68:69]
	v_lshl_add_u64 v[98:99], v[98:99], 0, v[66:67]
	v_lshl_add_u64 v[118:119], v[98:99], 2, s[26:27]
	ds_read_b128 v[102:105], v95
	v_lshl_add_u64 v[98:99], v[98:99], 1, s[44:45]
	s_waitcnt lgkmcnt(0)
	s_waitcnt vmcnt(27)
	v_pk_fma_f32 v[102:103], v[102:103], 0.5, v[166:167] op_sel_hi:[1,0,1]
	s_waitcnt vmcnt(27)
	v_pk_fma_f32 v[104:105], v[104:105], 0.5, v[168:169] op_sel_hi:[1,0,1]
	ds_read_b128 v[106:109], v95 offset:64
	global_store_dwordx4 v[118:119], v[102:105], off
	s_waitcnt lgkmcnt(0)
	s_waitcnt vmcnt(27)
	v_pk_fma_f32 v[106:107], v[106:107], 0.5, v[170:171] op_sel_hi:[1,0,1]
	s_waitcnt vmcnt(27)
	v_pk_fma_f32 v[108:109], v[108:109], 0.5, v[172:173] op_sel_hi:[1,0,1]
	v_cvt_pk_bf16_f32 v110, v102, v103
	v_cvt_pk_bf16_f32 v111, v104, v105
	global_store_dwordx4 v[118:119], v[106:109], off offset:64
	global_store_dwordx2 v[98:99], v[110:111], off
	v_cvt_pk_bf16_f32 v110, v106, v107
	v_cvt_pk_bf16_f32 v111, v108, v109
	global_store_dwordx2 v[98:99], v[110:111], off offset:32
	v_pk_mul_f32 v[98:99], v[102:103], v[102:103]
	v_pk_mul_f32 v[102:103], v[104:105], v[104:105]
	v_add_f32_e32 v97, v98, v99
	v_add_f32_e32 v97, v102, v97
	v_pk_mul_f32 v[104:105], v[106:107], v[106:107]
	v_add_f32_e32 v97, v103, v97
	v_add_f32_e32 v97, v104, v97
	v_pk_mul_f32 v[106:107], v[108:109], v[108:109]
	v_add_f32_e32 v97, v105, v97
	v_add_f32_e32 v97, v106, v97
	v_add_f32_e32 v97, v107, v97
	ds_bpermute_b32 v98, v0, v97
	s_waitcnt lgkmcnt(0)
	v_add_f32_e32 v97, v97, v98
	ds_bpermute_b32 v98, v70, v97
	s_waitcnt lgkmcnt(0)
	v_add_f32_e32 v97, v97, v98
	ds_bpermute_b32 v98, v71, v97
	s_waitcnt lgkmcnt(0)
	v_add_f32_e32 v97, v97, v98
	ds_bpermute_b32 v98, v73, v97
	s_waitcnt lgkmcnt(0)
	v_add_f32_e32 v97, v97, v98
	ds_bpermute_b32 v98, v72, v97
	s_and_saveexec_b64 s[10:11], vcc
	s_cbranch_execz .LBB0_155
	s_waitcnt lgkmcnt(0)
	v_add_f32_e32 v97, v97, v98
	v_lshl_add_u64 v[68:69], v[68:69], 4, s[8:9]
	global_store_dword v[68:69], v97, off
.LBB0_155:
	s_or_b64 exec, exec, s[10:11]
	v_add_u32_e32 v68, 0xa00, v140
	s_waitcnt lgkmcnt(0)
	v_ashrrev_i32_e32 v98, 5, v68
	v_mul_lo_u32 v68, v98, s14
	v_add_u32_e32 v97, v101, v68
	v_add_u32_e32 v68, s39, v98
	v_ashrrev_i32_e32 v69, 31, v68
	v_lshlrev_b64 v[102:103], 10, v[68:69]
	v_lshl_add_u64 v[118:119], v[102:103], 0, v[66:67]
	v_lshl_add_u64 v[120:121], v[118:119], 2, s[26:27]
	ds_read_b128 v[102:105], v97
	s_waitcnt lgkmcnt(0)
	s_waitcnt vmcnt(30)
	v_pk_fma_f32 v[102:103], v[102:103], 0.5, v[174:175] op_sel_hi:[1,0,1]
	s_waitcnt vmcnt(30)
	v_pk_fma_f32 v[104:105], v[104:105], 0.5, v[176:177] op_sel_hi:[1,0,1]
	ds_read_b128 v[106:109], v97 offset:64
	global_store_dwordx4 v[120:121], v[102:105], off
	s_waitcnt lgkmcnt(0)
	s_waitcnt vmcnt(30)
	v_pk_fma_f32 v[106:107], v[106:107], 0.5, v[178:179] op_sel_hi:[1,0,1]
	v_cvt_pk_bf16_f32 v110, v102, v103
	v_pk_mul_f32 v[102:103], v[102:103], v[102:103]
	v_cvt_pk_bf16_f32 v111, v104, v105
	v_pk_mul_f32 v[104:105], v[104:105], v[104:105]
	v_add_f32_e32 v99, v102, v103
	s_waitcnt vmcnt(30)
	v_pk_fma_f32 v[108:109], v[108:109], 0.5, v[180:181] op_sel_hi:[1,0,1]
	v_lshl_add_u64 v[112:113], v[118:119], 1, s[44:45]
	v_add_f32_e32 v99, v104, v99
	global_store_dwordx4 v[120:121], v[106:109], off offset:64
	global_store_dwordx2 v[112:113], v[110:111], off
	v_cvt_pk_bf16_f32 v110, v106, v107
	v_pk_mul_f32 v[106:107], v[106:107], v[106:107]
	v_add_f32_e32 v99, v105, v99
	v_add_f32_e32 v99, v106, v99
	v_cvt_pk_bf16_f32 v111, v108, v109
	v_pk_mul_f32 v[108:109], v[108:109], v[108:109]
	v_add_f32_e32 v99, v107, v99
	v_add_f32_e32 v99, v108, v99
	v_add_f32_e32 v99, v109, v99
	ds_bpermute_b32 v100, v0, v99
	global_store_dwordx2 v[112:113], v[110:111], off offset:32
	s_waitcnt lgkmcnt(0)
	v_add_f32_e32 v99, v99, v100
	ds_bpermute_b32 v100, v70, v99
	s_waitcnt lgkmcnt(0)
	v_add_f32_e32 v99, v99, v100
	ds_bpermute_b32 v100, v71, v99
	s_waitcnt lgkmcnt(0)
	v_add_f32_e32 v99, v99, v100
	ds_bpermute_b32 v100, v73, v99
	s_waitcnt lgkmcnt(0)
	v_add_f32_e32 v99, v99, v100
	ds_bpermute_b32 v100, v72, v99
	s_and_saveexec_b64 s[10:11], vcc
	s_cbranch_execz .LBB0_157
	s_waitcnt lgkmcnt(0)
	v_add_f32_e32 v99, v99, v100
	v_lshl_add_u64 v[68:69], v[68:69], 4, s[8:9]
	global_store_dword v[68:69], v99, off
.LBB0_157:
	s_or_b64 exec, exec, s[10:11]
	v_add_u32_e32 v68, 0xc00, v140
	s_waitcnt lgkmcnt(0)
	v_ashrrev_i32_e32 v100, 5, v68
	v_mul_lo_u32 v68, v100, s14
	v_add_u32_e32 v99, v101, v68
	v_add_u32_e32 v68, s39, v100
	v_ashrrev_i32_e32 v69, 31, v68
	v_lshlrev_b64 v[102:103], 10, v[68:69]
	v_lshl_add_u64 v[118:119], v[102:103], 0, v[66:67]
	v_lshl_add_u64 v[120:121], v[118:119], 2, s[26:27]
	ds_read_b128 v[102:105], v99
	s_waitcnt lgkmcnt(0)
	s_waitcnt vmcnt(33)
	v_pk_fma_f32 v[102:103], v[102:103], 0.5, v[182:183] op_sel_hi:[1,0,1]
	s_waitcnt vmcnt(33)
	v_pk_fma_f32 v[104:105], v[104:105], 0.5, v[184:185] op_sel_hi:[1,0,1]
	ds_read_b128 v[106:109], v99 offset:64
	global_store_dwordx4 v[120:121], v[102:105], off
	s_waitcnt lgkmcnt(0)
	s_waitcnt vmcnt(33)
	v_pk_fma_f32 v[106:107], v[106:107], 0.5, v[186:187] op_sel_hi:[1,0,1]
	v_cvt_pk_bf16_f32 v110, v102, v103
	v_pk_mul_f32 v[102:103], v[102:103], v[102:103]
	v_cvt_pk_bf16_f32 v111, v104, v105
	v_pk_mul_f32 v[104:105], v[104:105], v[104:105]
	v_add_f32_e32 v102, v102, v103
	s_waitcnt vmcnt(33)
	v_pk_fma_f32 v[108:109], v[108:109], 0.5, v[188:189] op_sel_hi:[1,0,1]
	v_lshl_add_u64 v[112:113], v[118:119], 1, s[44:45]
	v_add_f32_e32 v102, v104, v102
	global_store_dwordx4 v[120:121], v[106:109], off offset:64
	global_store_dwordx2 v[112:113], v[110:111], off
	v_cvt_pk_bf16_f32 v110, v106, v107
	v_pk_mul_f32 v[106:107], v[106:107], v[106:107]
	v_add_f32_e32 v102, v105, v102
	v_add_f32_e32 v102, v106, v102
	v_cvt_pk_bf16_f32 v111, v108, v109
	v_pk_mul_f32 v[108:109], v[108:109], v[108:109]
	v_add_f32_e32 v102, v107, v102
	v_add_f32_e32 v102, v108, v102
	v_add_f32_e32 v102, v109, v102
	ds_bpermute_b32 v103, v0, v102
	global_store_dwordx2 v[112:113], v[110:111], off offset:32
	s_waitcnt lgkmcnt(0)
	v_add_f32_e32 v102, v102, v103
	ds_bpermute_b32 v103, v70, v102
	s_waitcnt lgkmcnt(0)
	v_add_f32_e32 v102, v102, v103
	ds_bpermute_b32 v103, v71, v102
	s_waitcnt lgkmcnt(0)
	v_add_f32_e32 v102, v102, v103
	ds_bpermute_b32 v103, v73, v102
	s_waitcnt lgkmcnt(0)
	v_add_f32_e32 v102, v102, v103
	ds_bpermute_b32 v103, v72, v102
	s_and_saveexec_b64 s[10:11], vcc
	s_cbranch_execz .LBB0_159
	s_waitcnt lgkmcnt(0)
	v_add_f32_e32 v102, v102, v103
	v_lshl_add_u64 v[68:69], v[68:69], 4, s[8:9]
	global_store_dword v[68:69], v102, off
.LBB0_159:
	s_or_b64 exec, exec, s[10:11]
	v_add_u32_e32 v68, 0xe00, v140
	v_ashrrev_i32_e32 v102, 5, v68
	v_mul_lo_u32 v68, v102, s14
	v_add_u32_e32 v101, v101, v68
	v_add_u32_e32 v68, s39, v102
	v_ashrrev_i32_e32 v69, 31, v68
	v_lshlrev_b64 v[104:105], 10, v[68:69]
	v_lshl_add_u64 v[112:113], v[104:105], 0, v[66:67]
	v_lshl_add_u64 v[122:123], v[112:113], 2, s[26:27]
	ds_read_b128 v[104:107], v101
	v_lshl_add_u64 v[112:113], v[112:113], 1, s[44:45]
	s_waitcnt lgkmcnt(0)
	s_waitcnt vmcnt(36)
	v_pk_fma_f32 v[104:105], v[104:105], 0.5, v[190:191] op_sel_hi:[1,0,1]
	s_waitcnt vmcnt(36)
	v_pk_fma_f32 v[106:107], v[106:107], 0.5, v[192:193] op_sel_hi:[1,0,1]
	ds_read_b128 v[108:111], v101 offset:64
	global_store_dwordx4 v[122:123], v[104:107], off
	s_waitcnt lgkmcnt(0)
	s_waitcnt vmcnt(36)
	v_pk_fma_f32 v[108:109], v[108:109], 0.5, v[194:195] op_sel_hi:[1,0,1]
	v_cvt_pk_bf16_f32 v118, v104, v105
	v_pk_mul_f32 v[104:105], v[104:105], v[104:105]
	v_cvt_pk_bf16_f32 v119, v106, v107
	v_pk_mul_f32 v[106:107], v[106:107], v[106:107]
	v_add_f32_e32 v103, v104, v105
	s_waitcnt vmcnt(36)
	v_pk_fma_f32 v[110:111], v[110:111], 0.5, v[196:197] op_sel_hi:[1,0,1]
	v_add_f32_e32 v103, v106, v103
	global_store_dwordx4 v[122:123], v[108:111], off offset:64
	global_store_dwordx2 v[112:113], v[118:119], off
	v_cvt_pk_bf16_f32 v118, v108, v109
	v_pk_mul_f32 v[108:109], v[108:109], v[108:109]
	v_add_f32_e32 v103, v107, v103
	v_add_f32_e32 v103, v108, v103
	v_cvt_pk_bf16_f32 v119, v110, v111
	v_pk_mul_f32 v[110:111], v[110:111], v[110:111]
	v_add_f32_e32 v103, v109, v103
	v_add_f32_e32 v103, v110, v103
	v_add_f32_e32 v103, v111, v103
	ds_bpermute_b32 v104, v0, v103
	global_store_dwordx2 v[112:113], v[118:119], off offset:32
	s_waitcnt lgkmcnt(0)
	v_add_f32_e32 v103, v103, v104
	ds_bpermute_b32 v104, v70, v103
	s_waitcnt lgkmcnt(0)
	v_add_f32_e32 v103, v103, v104
	ds_bpermute_b32 v104, v71, v103
	s_waitcnt lgkmcnt(0)
	v_add_f32_e32 v103, v103, v104
	ds_bpermute_b32 v104, v73, v103
	s_waitcnt lgkmcnt(0)
	v_add_f32_e32 v103, v103, v104
	ds_bpermute_b32 v104, v72, v103
	s_and_saveexec_b64 s[10:11], vcc
	s_cbranch_execz .LBB0_161
	s_waitcnt lgkmcnt(0)
	v_add_f32_e32 v103, v103, v104
	v_lshl_add_u64 v[68:69], v[68:69], 4, s[8:9]
	global_store_dword v[68:69], v103, off
.LBB0_161:
	s_or_b64 exec, exec, s[10:11]
	s_waitcnt lgkmcnt(0)
	s_barrier
	ds_write2_b32 v130, v2, v18 offset1:16
	ds_write2_b32 v114, v3, v19 offset0:4 offset1:20
	ds_write2_b32 v115, v4, v20 offset0:8 offset1:24
	ds_write2_b32 v116, v5, v21 offset0:12 offset1:28
	ds_write2_b32 v117, v6, v22 offset0:64 offset1:80
	ds_write2_b32 v82, v7, v23 offset0:68 offset1:84
	ds_write2_b32 v83, v8, v24 offset0:72 offset1:88
	ds_write2_b32 v84, v9, v25 offset0:76 offset1:92
	ds_write2_b32 v85, v10, v26 offset0:128 offset1:144
	ds_write2_b32 v74, v11, v27 offset0:132 offset1:148
	ds_write2_b32 v75, v12, v28 offset0:136 offset1:152
	ds_write2_b32 v76, v13, v29 offset0:140 offset1:156
	ds_write2_b32 v80, v14, v30 offset0:192 offset1:208
	ds_write2_b32 v77, v15, v31 offset0:196 offset1:212
	ds_write2_b32 v78, v16, v32 offset0:200 offset1:216
	ds_write2_b32 v79, v17, v33 offset0:204 offset1:220
	ds_write2_b32 v130, v34, v50 offset0:128 offset1:144
	ds_write2_b32 v114, v35, v51 offset0:132 offset1:148
	ds_write2_b32 v115, v36, v52 offset0:136 offset1:152
	ds_write2_b32 v116, v37, v53 offset0:140 offset1:156
	ds_write2_b32 v117, v38, v54 offset0:192 offset1:208
	ds_write2_b32 v82, v39, v55 offset0:196 offset1:212
	ds_write2_b32 v83, v40, v56 offset0:200 offset1:216
	ds_write2_b32 v84, v41, v57 offset0:204 offset1:220
	ds_write2_b32 v74, v42, v58 offset1:16
	ds_write2_b32 v75, v43, v59 offset0:4 offset1:20
	ds_write2_b32 v76, v44, v60 offset0:8 offset1:24
	ds_write2_b32 v81, v45, v61 offset0:12 offset1:28
	ds_write2_b32 v77, v46, v62 offset0:64 offset1:80
	ds_write2_b32 v78, v47, v63 offset0:68 offset1:84
	ds_write2_b32 v79, v48, v64 offset0:72 offset1:88
	ds_write2_b32 v86, v49, v65 offset0:76 offset1:92
	v_add_u32_e32 v2, s38, v87
	v_ashrrev_i32_e32 v3, 31, v2
	v_lshlrev_b64 v[4:5], 10, v[2:3]
	v_lshl_add_u64 v[20:21], v[4:5], 0, v[66:67]
	v_lshl_add_u64 v[22:23], v[20:21], 2, s[26:27]
	s_waitcnt lgkmcnt(0)
	s_barrier
	v_lshlrev_b32_e32 v141, 2, v20
	global_load_dwordx4 v[132:135], v141, s[26:27]
	global_load_dwordx4 v[136:139], v141, s[26:27] offset:64
	v_add_u32_e32 v141, 0x10000, v141
	global_load_dwordx4 v[142:145], v141, s[26:27]
	global_load_dwordx4 v[146:149], v141, s[26:27] offset:64
	v_add_u32_e32 v141, 0x10000, v141
	global_load_dwordx4 v[150:153], v141, s[26:27]
	global_load_dwordx4 v[154:157], v141, s[26:27] offset:64
	v_add_u32_e32 v141, 0x10000, v141
	global_load_dwordx4 v[158:161], v141, s[26:27]
	global_load_dwordx4 v[162:165], v141, s[26:27] offset:64
	v_add_u32_e32 v141, 0x10000, v141
	global_load_dwordx4 v[166:169], v141, s[26:27]
	global_load_dwordx4 v[170:173], v141, s[26:27] offset:64
	v_add_u32_e32 v141, 0x10000, v141
	global_load_dwordx4 v[174:177], v141, s[26:27]
	global_load_dwordx4 v[178:181], v141, s[26:27] offset:64
	v_add_u32_e32 v141, 0x10000, v141
	global_load_dwordx4 v[182:185], v141, s[26:27]
	global_load_dwordx4 v[186:189], v141, s[26:27] offset:64
	v_add_u32_e32 v141, 0x10000, v141
	global_load_dwordx4 v[190:193], v141, s[26:27]
	global_load_dwordx4 v[194:197], v141, s[26:27] offset:64
	ds_read_b128 v[12:15], v88
	ds_read_b128 v[16:19], v88 offset:64
	s_waitcnt lgkmcnt(1)
	s_waitcnt vmcnt(15)
	v_pk_fma_f32 v[4:5], v[12:13], 0.5, v[132:133] op_sel_hi:[1,0,1]
	s_waitcnt vmcnt(15)
	v_pk_fma_f32 v[6:7], v[14:15], 0.5, v[134:135] op_sel_hi:[1,0,1]
	v_pk_mul_f32 v[12:13], v[4:5], v[4:5]
	v_pk_mul_f32 v[14:15], v[6:7], v[6:7]
	v_add_f32_e32 v12, v12, v13
	s_waitcnt lgkmcnt(0)
	s_waitcnt vmcnt(14)
	v_pk_fma_f32 v[8:9], v[16:17], 0.5, v[136:137] op_sel_hi:[1,0,1]
	v_add_f32_e32 v12, v14, v12
	v_pk_mul_f32 v[16:17], v[8:9], v[8:9]
	v_add_f32_e32 v12, v15, v12
	s_waitcnt vmcnt(14)
	v_pk_fma_f32 v[10:11], v[18:19], 0.5, v[138:139] op_sel_hi:[1,0,1]
	v_add_f32_e32 v12, v16, v12
	v_pk_mul_f32 v[18:19], v[10:11], v[10:11]
	v_add_f32_e32 v12, v17, v12
	v_add_f32_e32 v12, v18, v12
	v_add_f32_e32 v12, v19, v12
	ds_bpermute_b32 v13, v0, v12
	global_store_dwordx4 v[22:23], v[4:7], off
	global_store_dwordx4 v[22:23], v[8:11], off offset:64
	s_waitcnt lgkmcnt(0)
	v_add_f32_e32 v12, v12, v13
	ds_bpermute_b32 v13, v70, v12
	v_cvt_pk_bf16_f32 v8, v8, v9
	v_cvt_pk_bf16_f32 v9, v10, v11
	s_waitcnt lgkmcnt(0)
	v_add_f32_e32 v12, v12, v13
	ds_bpermute_b32 v13, v71, v12
	s_waitcnt lgkmcnt(0)
	v_add_f32_e32 v14, v12, v13
	ds_bpermute_b32 v15, v73, v14
	v_cvt_pk_bf16_f32 v12, v4, v5
	v_cvt_pk_bf16_f32 v13, v6, v7
	v_lshl_add_u64 v[6:7], v[20:21], 1, s[44:45]
	global_store_dwordx2 v[6:7], v[12:13], off
	s_waitcnt lgkmcnt(0)
	v_add_f32_e32 v4, v14, v15
	ds_bpermute_b32 v5, v72, v4
	global_store_dwordx2 v[6:7], v[8:9], off offset:32
	s_and_saveexec_b64 s[10:11], vcc
	s_cbranch_execz .LBB0_163
	s_waitcnt lgkmcnt(0)
	v_add_f32_e32 v4, v4, v5
	v_lshl_add_u64 v[2:3], v[2:3], 4, s[8:9]
	global_store_dword v[2:3], v4, off
.LBB0_163:
	s_or_b64 exec, exec, s[10:11]
	v_add_u32_e32 v2, s38, v90
	v_ashrrev_i32_e32 v3, 31, v2
	s_waitcnt lgkmcnt(0)
	v_lshlrev_b64 v[4:5], 10, v[2:3]
	v_lshl_add_u64 v[16:17], v[4:5], 0, v[66:67]
	v_lshl_add_u64 v[18:19], v[16:17], 2, s[26:27]
	ds_read_b128 v[4:7], v89
	s_waitcnt lgkmcnt(0)
	s_waitcnt vmcnt(18)
	v_pk_fma_f32 v[4:5], v[4:5], 0.5, v[142:143] op_sel_hi:[1,0,1]
	s_waitcnt vmcnt(18)
	v_pk_fma_f32 v[6:7], v[6:7], 0.5, v[144:145] op_sel_hi:[1,0,1]
	ds_read_b128 v[8:11], v89 offset:64
	global_store_dwordx4 v[18:19], v[4:7], off
	s_waitcnt lgkmcnt(0)
	s_waitcnt vmcnt(18)
	v_pk_fma_f32 v[8:9], v[8:9], 0.5, v[146:147] op_sel_hi:[1,0,1]
	v_cvt_pk_bf16_f32 v12, v4, v5
	v_pk_mul_f32 v[4:5], v[4:5], v[4:5]
	v_cvt_pk_bf16_f32 v13, v6, v7
	v_pk_mul_f32 v[6:7], v[6:7], v[6:7]
	v_add_f32_e32 v4, v4, v5
	s_waitcnt vmcnt(18)
	v_pk_fma_f32 v[10:11], v[10:11], 0.5, v[148:149] op_sel_hi:[1,0,1]
	v_lshl_add_u64 v[14:15], v[16:17], 1, s[44:45]
	v_add_f32_e32 v4, v6, v4
	global_store_dwordx4 v[18:19], v[8:11], off offset:64
	global_store_dwordx2 v[14:15], v[12:13], off
	v_cvt_pk_bf16_f32 v12, v8, v9
	v_pk_mul_f32 v[8:9], v[8:9], v[8:9]
	v_add_f32_e32 v4, v7, v4
	v_add_f32_e32 v4, v8, v4
	v_cvt_pk_bf16_f32 v13, v10, v11
	v_pk_mul_f32 v[10:11], v[10:11], v[10:11]
	v_add_f32_e32 v4, v9, v4
	v_add_f32_e32 v4, v10, v4
	v_add_f32_e32 v4, v11, v4
	ds_bpermute_b32 v5, v0, v4
	global_store_dwordx2 v[14:15], v[12:13], off offset:32
	s_waitcnt lgkmcnt(0)
	v_add_f32_e32 v4, v4, v5
	ds_bpermute_b32 v5, v70, v4
	s_waitcnt lgkmcnt(0)
	v_add_f32_e32 v4, v4, v5
	ds_bpermute_b32 v5, v71, v4
	s_waitcnt lgkmcnt(0)
	v_add_f32_e32 v4, v4, v5
	ds_bpermute_b32 v5, v73, v4
	s_waitcnt lgkmcnt(0)
	v_add_f32_e32 v4, v4, v5
	ds_bpermute_b32 v5, v72, v4
	s_and_saveexec_b64 s[10:11], vcc
	s_cbranch_execz .LBB0_165
	s_waitcnt lgkmcnt(0)
	v_add_f32_e32 v4, v4, v5
	v_lshl_add_u64 v[2:3], v[2:3], 4, s[8:9]
	global_store_dword v[2:3], v4, off
.LBB0_165:
	s_or_b64 exec, exec, s[10:11]
	v_add_u32_e32 v2, s38, v92
	v_ashrrev_i32_e32 v3, 31, v2
	s_waitcnt lgkmcnt(0)
	v_lshlrev_b64 v[4:5], 10, v[2:3]
	v_lshl_add_u64 v[16:17], v[4:5], 0, v[66:67]
	v_lshl_add_u64 v[18:19], v[16:17], 2, s[26:27]
	ds_read_b128 v[4:7], v91
	s_waitcnt lgkmcnt(0)
	s_waitcnt vmcnt(21)
	v_pk_fma_f32 v[4:5], v[4:5], 0.5, v[150:151] op_sel_hi:[1,0,1]
	s_waitcnt vmcnt(21)
	v_pk_fma_f32 v[6:7], v[6:7], 0.5, v[152:153] op_sel_hi:[1,0,1]
	ds_read_b128 v[8:11], v91 offset:64
	global_store_dwordx4 v[18:19], v[4:7], off
	s_waitcnt lgkmcnt(0)
	s_waitcnt vmcnt(21)
	v_pk_fma_f32 v[8:9], v[8:9], 0.5, v[154:155] op_sel_hi:[1,0,1]
	v_cvt_pk_bf16_f32 v12, v4, v5
	v_pk_mul_f32 v[4:5], v[4:5], v[4:5]
	v_cvt_pk_bf16_f32 v13, v6, v7
	v_pk_mul_f32 v[6:7], v[6:7], v[6:7]
	v_add_f32_e32 v4, v4, v5
	s_waitcnt vmcnt(21)
	v_pk_fma_f32 v[10:11], v[10:11], 0.5, v[156:157] op_sel_hi:[1,0,1]
	v_lshl_add_u64 v[14:15], v[16:17], 1, s[44:45]
	v_add_f32_e32 v4, v6, v4
	global_store_dwordx4 v[18:19], v[8:11], off offset:64
	global_store_dwordx2 v[14:15], v[12:13], off
	v_cvt_pk_bf16_f32 v12, v8, v9
	v_pk_mul_f32 v[8:9], v[8:9], v[8:9]
	v_add_f32_e32 v4, v7, v4
	v_add_f32_e32 v4, v8, v4
	v_cvt_pk_bf16_f32 v13, v10, v11
	v_pk_mul_f32 v[10:11], v[10:11], v[10:11]
	v_add_f32_e32 v4, v9, v4
	v_add_f32_e32 v4, v10, v4
	v_add_f32_e32 v4, v11, v4
	ds_bpermute_b32 v5, v0, v4
	global_store_dwordx2 v[14:15], v[12:13], off offset:32
	s_waitcnt lgkmcnt(0)
	v_add_f32_e32 v4, v4, v5
	ds_bpermute_b32 v5, v70, v4
	s_waitcnt lgkmcnt(0)
	v_add_f32_e32 v4, v4, v5
	ds_bpermute_b32 v5, v71, v4
	s_waitcnt lgkmcnt(0)
	v_add_f32_e32 v4, v4, v5
	ds_bpermute_b32 v5, v73, v4
	s_waitcnt lgkmcnt(0)
	v_add_f32_e32 v4, v4, v5
	ds_bpermute_b32 v5, v72, v4
	s_and_saveexec_b64 s[10:11], vcc
	s_cbranch_execz .LBB0_167
	s_waitcnt lgkmcnt(0)
	v_add_f32_e32 v4, v4, v5
	v_lshl_add_u64 v[2:3], v[2:3], 4, s[8:9]
	global_store_dword v[2:3], v4, off
.LBB0_167:
	s_or_b64 exec, exec, s[10:11]
	v_add_u32_e32 v2, s38, v94
	v_ashrrev_i32_e32 v3, 31, v2
	s_waitcnt lgkmcnt(0)
	v_lshlrev_b64 v[4:5], 10, v[2:3]
	v_lshl_add_u64 v[16:17], v[4:5], 0, v[66:67]
	v_lshl_add_u64 v[18:19], v[16:17], 2, s[26:27]
	ds_read_b128 v[4:7], v93
	s_waitcnt lgkmcnt(0)
	s_waitcnt vmcnt(24)
	v_pk_fma_f32 v[4:5], v[4:5], 0.5, v[158:159] op_sel_hi:[1,0,1]
	s_waitcnt vmcnt(24)
	v_pk_fma_f32 v[6:7], v[6:7], 0.5, v[160:161] op_sel_hi:[1,0,1]
	ds_read_b128 v[8:11], v93 offset:64
	global_store_dwordx4 v[18:19], v[4:7], off
	s_waitcnt lgkmcnt(0)
	s_waitcnt vmcnt(24)
	v_pk_fma_f32 v[8:9], v[8:9], 0.5, v[162:163] op_sel_hi:[1,0,1]
	v_cvt_pk_bf16_f32 v12, v4, v5
	v_pk_mul_f32 v[4:5], v[4:5], v[4:5]
	v_cvt_pk_bf16_f32 v13, v6, v7
	v_pk_mul_f32 v[6:7], v[6:7], v[6:7]
	v_add_f32_e32 v4, v4, v5
	s_waitcnt vmcnt(24)
	v_pk_fma_f32 v[10:11], v[10:11], 0.5, v[164:165] op_sel_hi:[1,0,1]
	v_lshl_add_u64 v[14:15], v[16:17], 1, s[44:45]
	v_add_f32_e32 v4, v6, v4
	global_store_dwordx4 v[18:19], v[8:11], off offset:64
	global_store_dwordx2 v[14:15], v[12:13], off
	v_cvt_pk_bf16_f32 v12, v8, v9
	v_pk_mul_f32 v[8:9], v[8:9], v[8:9]
	v_add_f32_e32 v4, v7, v4
	v_add_f32_e32 v4, v8, v4
	v_cvt_pk_bf16_f32 v13, v10, v11
	v_pk_mul_f32 v[10:11], v[10:11], v[10:11]
	v_add_f32_e32 v4, v9, v4
	v_add_f32_e32 v4, v10, v4
	v_add_f32_e32 v4, v11, v4
	ds_bpermute_b32 v5, v0, v4
	global_store_dwordx2 v[14:15], v[12:13], off offset:32
	s_waitcnt lgkmcnt(0)
	v_add_f32_e32 v4, v4, v5
	ds_bpermute_b32 v5, v70, v4
	s_waitcnt lgkmcnt(0)
	v_add_f32_e32 v4, v4, v5
	ds_bpermute_b32 v5, v71, v4
	s_waitcnt lgkmcnt(0)
	v_add_f32_e32 v4, v4, v5
	ds_bpermute_b32 v5, v73, v4
	s_waitcnt lgkmcnt(0)
	v_add_f32_e32 v4, v4, v5
	ds_bpermute_b32 v5, v72, v4
	s_and_saveexec_b64 s[10:11], vcc
	s_cbranch_execz .LBB0_169
	s_waitcnt lgkmcnt(0)
	v_add_f32_e32 v4, v4, v5
	v_lshl_add_u64 v[2:3], v[2:3], 4, s[8:9]
	global_store_dword v[2:3], v4, off
.LBB0_169:
	s_or_b64 exec, exec, s[10:11]
	v_add_u32_e32 v2, s38, v96
	v_ashrrev_i32_e32 v3, 31, v2
	s_waitcnt lgkmcnt(0)
	v_lshlrev_b64 v[4:5], 10, v[2:3]
	v_lshl_add_u64 v[16:17], v[4:5], 0, v[66:67]
	v_lshl_add_u64 v[18:19], v[16:17], 2, s[26:27]
	ds_read_b128 v[4:7], v95
	s_waitcnt lgkmcnt(0)
	s_waitcnt vmcnt(27)
	v_pk_fma_f32 v[4:5], v[4:5], 0.5, v[166:167] op_sel_hi:[1,0,1]
	s_waitcnt vmcnt(27)
	v_pk_fma_f32 v[6:7], v[6:7], 0.5, v[168:169] op_sel_hi:[1,0,1]
	ds_read_b128 v[8:11], v95 offset:64
	global_store_dwordx4 v[18:19], v[4:7], off
	s_waitcnt lgkmcnt(0)
	s_waitcnt vmcnt(27)
	v_pk_fma_f32 v[8:9], v[8:9], 0.5, v[170:171] op_sel_hi:[1,0,1]
	v_cvt_pk_bf16_f32 v12, v4, v5
	v_pk_mul_f32 v[4:5], v[4:5], v[4:5]
	v_cvt_pk_bf16_f32 v13, v6, v7
	v_pk_mul_f32 v[6:7], v[6:7], v[6:7]
	v_add_f32_e32 v4, v4, v5
	s_waitcnt vmcnt(27)
	v_pk_fma_f32 v[10:11], v[10:11], 0.5, v[172:173] op_sel_hi:[1,0,1]
	v_lshl_add_u64 v[14:15], v[16:17], 1, s[44:45]
	v_add_f32_e32 v4, v6, v4
	global_store_dwordx4 v[18:19], v[8:11], off offset:64
	global_store_dwordx2 v[14:15], v[12:13], off
	v_cvt_pk_bf16_f32 v12, v8, v9
	v_pk_mul_f32 v[8:9], v[8:9], v[8:9]
	v_add_f32_e32 v4, v7, v4
	v_add_f32_e32 v4, v8, v4
	v_cvt_pk_bf16_f32 v13, v10, v11
	v_pk_mul_f32 v[10:11], v[10:11], v[10:11]
	v_add_f32_e32 v4, v9, v4
	v_add_f32_e32 v4, v10, v4
	v_add_f32_e32 v4, v11, v4
	ds_bpermute_b32 v5, v0, v4
	global_store_dwordx2 v[14:15], v[12:13], off offset:32
	s_waitcnt lgkmcnt(0)
	v_add_f32_e32 v4, v4, v5
	ds_bpermute_b32 v5, v70, v4
	s_waitcnt lgkmcnt(0)
	v_add_f32_e32 v4, v4, v5
	ds_bpermute_b32 v5, v71, v4
	s_waitcnt lgkmcnt(0)
	v_add_f32_e32 v4, v4, v5
	ds_bpermute_b32 v5, v73, v4
	s_waitcnt lgkmcnt(0)
	v_add_f32_e32 v4, v4, v5
	ds_bpermute_b32 v5, v72, v4
	s_and_saveexec_b64 s[10:11], vcc
	s_cbranch_execz .LBB0_171
	s_waitcnt lgkmcnt(0)
	v_add_f32_e32 v4, v4, v5
	v_lshl_add_u64 v[2:3], v[2:3], 4, s[8:9]
	global_store_dword v[2:3], v4, off
.LBB0_171:
	s_or_b64 exec, exec, s[10:11]
	v_add_u32_e32 v2, s38, v98
	v_ashrrev_i32_e32 v3, 31, v2
	s_waitcnt lgkmcnt(0)
	v_lshlrev_b64 v[4:5], 10, v[2:3]
	v_lshl_add_u64 v[16:17], v[4:5], 0, v[66:67]
	v_lshl_add_u64 v[18:19], v[16:17], 2, s[26:27]
	ds_read_b128 v[4:7], v97
	s_waitcnt lgkmcnt(0)
	s_waitcnt vmcnt(30)
	v_pk_fma_f32 v[4:5], v[4:5], 0.5, v[174:175] op_sel_hi:[1,0,1]
	s_waitcnt vmcnt(30)
	v_pk_fma_f32 v[6:7], v[6:7], 0.5, v[176:177] op_sel_hi:[1,0,1]
	ds_read_b128 v[8:11], v97 offset:64
	global_store_dwordx4 v[18:19], v[4:7], off
	s_waitcnt lgkmcnt(0)
	s_waitcnt vmcnt(30)
	v_pk_fma_f32 v[8:9], v[8:9], 0.5, v[178:179] op_sel_hi:[1,0,1]
	v_cvt_pk_bf16_f32 v12, v4, v5
	v_pk_mul_f32 v[4:5], v[4:5], v[4:5]
	v_cvt_pk_bf16_f32 v13, v6, v7
	v_pk_mul_f32 v[6:7], v[6:7], v[6:7]
	v_add_f32_e32 v4, v4, v5
	s_waitcnt vmcnt(30)
	v_pk_fma_f32 v[10:11], v[10:11], 0.5, v[180:181] op_sel_hi:[1,0,1]
	v_lshl_add_u64 v[14:15], v[16:17], 1, s[44:45]
	v_add_f32_e32 v4, v6, v4
	global_store_dwordx4 v[18:19], v[8:11], off offset:64
	global_store_dwordx2 v[14:15], v[12:13], off
	v_cvt_pk_bf16_f32 v12, v8, v9
	v_pk_mul_f32 v[8:9], v[8:9], v[8:9]
	v_add_f32_e32 v4, v7, v4
	v_add_f32_e32 v4, v8, v4
	v_cvt_pk_bf16_f32 v13, v10, v11
	v_pk_mul_f32 v[10:11], v[10:11], v[10:11]
	v_add_f32_e32 v4, v9, v4
	v_add_f32_e32 v4, v10, v4
	v_add_f32_e32 v4, v11, v4
	ds_bpermute_b32 v5, v0, v4
	global_store_dwordx2 v[14:15], v[12:13], off offset:32
	s_waitcnt lgkmcnt(0)
	v_add_f32_e32 v4, v4, v5
	ds_bpermute_b32 v5, v70, v4
	s_waitcnt lgkmcnt(0)
	v_add_f32_e32 v4, v4, v5
	ds_bpermute_b32 v5, v71, v4
	s_waitcnt lgkmcnt(0)
	v_add_f32_e32 v4, v4, v5
	ds_bpermute_b32 v5, v73, v4
	s_waitcnt lgkmcnt(0)
	v_add_f32_e32 v4, v4, v5
	ds_bpermute_b32 v5, v72, v4
	s_and_saveexec_b64 s[10:11], vcc
	s_cbranch_execz .LBB0_173
	s_waitcnt lgkmcnt(0)
	v_add_f32_e32 v4, v4, v5
	v_lshl_add_u64 v[2:3], v[2:3], 4, s[8:9]
	global_store_dword v[2:3], v4, off
.LBB0_173:
	s_or_b64 exec, exec, s[10:11]
	v_add_u32_e32 v2, s38, v100
	v_ashrrev_i32_e32 v3, 31, v2
	s_waitcnt lgkmcnt(0)
	v_lshlrev_b64 v[4:5], 10, v[2:3]
	v_lshl_add_u64 v[16:17], v[4:5], 0, v[66:67]
	v_lshl_add_u64 v[18:19], v[16:17], 2, s[26:27]
	ds_read_b128 v[4:7], v99
	s_waitcnt lgkmcnt(0)
	s_waitcnt vmcnt(33)
	v_pk_fma_f32 v[4:5], v[4:5], 0.5, v[182:183] op_sel_hi:[1,0,1]
	s_waitcnt vmcnt(33)
	v_pk_fma_f32 v[6:7], v[6:7], 0.5, v[184:185] op_sel_hi:[1,0,1]
	ds_read_b128 v[8:11], v99 offset:64
	global_store_dwordx4 v[18:19], v[4:7], off
	s_waitcnt lgkmcnt(0)
	s_waitcnt vmcnt(33)
	v_pk_fma_f32 v[8:9], v[8:9], 0.5, v[186:187] op_sel_hi:[1,0,1]
	v_cvt_pk_bf16_f32 v12, v4, v5
	v_pk_mul_f32 v[4:5], v[4:5], v[4:5]
	v_cvt_pk_bf16_f32 v13, v6, v7
	v_pk_mul_f32 v[6:7], v[6:7], v[6:7]
	v_add_f32_e32 v4, v4, v5
	s_waitcnt vmcnt(33)
	v_pk_fma_f32 v[10:11], v[10:11], 0.5, v[188:189] op_sel_hi:[1,0,1]
	v_lshl_add_u64 v[14:15], v[16:17], 1, s[44:45]
	v_add_f32_e32 v4, v6, v4
	global_store_dwordx4 v[18:19], v[8:11], off offset:64
	global_store_dwordx2 v[14:15], v[12:13], off
	v_cvt_pk_bf16_f32 v12, v8, v9
	v_pk_mul_f32 v[8:9], v[8:9], v[8:9]
	v_add_f32_e32 v4, v7, v4
	v_add_f32_e32 v4, v8, v4
	v_cvt_pk_bf16_f32 v13, v10, v11
	v_pk_mul_f32 v[10:11], v[10:11], v[10:11]
	v_add_f32_e32 v4, v9, v4
	v_add_f32_e32 v4, v10, v4
	v_add_f32_e32 v4, v11, v4
	ds_bpermute_b32 v5, v0, v4
	global_store_dwordx2 v[14:15], v[12:13], off offset:32
	s_waitcnt lgkmcnt(0)
	v_add_f32_e32 v4, v4, v5
	ds_bpermute_b32 v5, v70, v4
	s_waitcnt lgkmcnt(0)
	v_add_f32_e32 v4, v4, v5
	ds_bpermute_b32 v5, v71, v4
	s_waitcnt lgkmcnt(0)
	v_add_f32_e32 v4, v4, v5
	ds_bpermute_b32 v5, v73, v4
	s_waitcnt lgkmcnt(0)
	v_add_f32_e32 v4, v4, v5
	ds_bpermute_b32 v5, v72, v4
	s_and_saveexec_b64 s[10:11], vcc
	s_cbranch_execz .LBB0_175
	s_waitcnt lgkmcnt(0)
	v_add_f32_e32 v4, v4, v5
	v_lshl_add_u64 v[2:3], v[2:3], 4, s[8:9]
	global_store_dword v[2:3], v4, off
.LBB0_175:
	s_or_b64 exec, exec, s[10:11]
	v_add_u32_e32 v2, s38, v102
	v_ashrrev_i32_e32 v3, 31, v2
	s_waitcnt lgkmcnt(0)
	v_lshlrev_b64 v[4:5], 10, v[2:3]
	v_lshl_add_u64 v[16:17], v[4:5], 0, v[66:67]
	v_lshl_add_u64 v[18:19], v[16:17], 2, s[26:27]
	ds_read_b128 v[4:7], v101
	s_waitcnt lgkmcnt(0)
	s_waitcnt vmcnt(36)
	v_pk_fma_f32 v[4:5], v[4:5], 0.5, v[190:191] op_sel_hi:[1,0,1]
	s_waitcnt vmcnt(36)
	v_pk_fma_f32 v[6:7], v[6:7], 0.5, v[192:193] op_sel_hi:[1,0,1]
	ds_read_b128 v[8:11], v101 offset:64
	global_store_dwordx4 v[18:19], v[4:7], off
	s_waitcnt lgkmcnt(0)
	s_waitcnt vmcnt(36)
	v_pk_fma_f32 v[8:9], v[8:9], 0.5, v[194:195] op_sel_hi:[1,0,1]
	v_cvt_pk_bf16_f32 v12, v4, v5
	v_pk_mul_f32 v[4:5], v[4:5], v[4:5]
	v_cvt_pk_bf16_f32 v13, v6, v7
	v_pk_mul_f32 v[6:7], v[6:7], v[6:7]
	v_add_f32_e32 v4, v4, v5
	s_waitcnt vmcnt(36)
	v_pk_fma_f32 v[10:11], v[10:11], 0.5, v[196:197] op_sel_hi:[1,0,1]
	v_lshl_add_u64 v[14:15], v[16:17], 1, s[44:45]
	v_add_f32_e32 v4, v6, v4
	global_store_dwordx4 v[18:19], v[8:11], off offset:64
	global_store_dwordx2 v[14:15], v[12:13], off
	v_cvt_pk_bf16_f32 v12, v8, v9
	v_pk_mul_f32 v[8:9], v[8:9], v[8:9]
	v_add_f32_e32 v4, v7, v4
	v_add_f32_e32 v4, v8, v4
	v_cvt_pk_bf16_f32 v13, v10, v11
	v_pk_mul_f32 v[10:11], v[10:11], v[10:11]
	v_add_f32_e32 v4, v9, v4
	v_add_f32_e32 v4, v10, v4
	v_add_f32_e32 v4, v11, v4
	ds_bpermute_b32 v0, v0, v4
	global_store_dwordx2 v[14:15], v[12:13], off offset:32
	s_waitcnt lgkmcnt(0)
	v_add_f32_e32 v0, v4, v0
	ds_bpermute_b32 v4, v70, v0
	s_waitcnt lgkmcnt(0)
	v_add_f32_e32 v0, v0, v4
	ds_bpermute_b32 v4, v71, v0
	s_waitcnt lgkmcnt(0)
	v_add_f32_e32 v0, v0, v4
	ds_bpermute_b32 v4, v73, v0
	s_waitcnt lgkmcnt(0)
	v_add_f32_e32 v0, v0, v4
	ds_bpermute_b32 v4, v72, v0
	s_and_saveexec_b64 s[10:11], vcc
	s_cbranch_execz .LBB0_177
	s_waitcnt lgkmcnt(0)
	v_add_f32_e32 v0, v0, v4
	v_lshl_add_u64 v[2:3], v[2:3], 4, s[8:9]
	global_store_dword v[2:3], v0, off

.LBB0_260:
	s_or_b64 exec, exec, s[12:13]
	s_movk_i32 s9, 0x410
	v_lshrrev_b32_e32 v130, 2, v142
	v_lshlrev_b32_e32 v131, 1, v142
	v_and_b32_e32 v0, 15, v142
	v_and_b32_e32 v130, 0xfffffcc, v130
	v_and_b32_e32 v131, 0x180, v131
	v_add_u32_e32 v131, 0, v131
	v_lshlrev_b32_e32 v0, 2, v0
	v_mul_lo_u32 v130, v130, s9
	v_add3_u32 v130, v131, v0, v130
	s_waitcnt vmcnt(0)
	s_barrier
	ds_write2_b32 v130, v114, v126 offset1:16
	v_add_u32_e32 v114, 0x400, v130
	ds_write2_b32 v114, v115, v127 offset0:4 offset1:20
	v_add_u32_e32 v115, 0x800, v130
	ds_write2_b32 v115, v116, v128 offset0:8 offset1:24
	v_add_u32_e32 v116, 0xc00, v130
	ds_write2_b32 v116, v117, v129 offset0:12 offset1:28
	v_add_u32_e32 v117, 0x4000, v130
	ds_write2_b32 v117, v82, v94 offset0:64 offset1:80
	v_add_u32_e32 v82, 0x4400, v130
	ds_write2_b32 v82, v83, v95 offset0:68 offset1:84
	v_add_u32_e32 v83, 0x4800, v130
	ds_write2_b32 v83, v84, v96 offset0:72 offset1:88
	v_add_u32_e32 v84, 0x4c00, v130
	ds_write2_b32 v84, v85, v97 offset0:76 offset1:92
	v_add_u32_e32 v85, 0x8000, v130
	ds_write2_b32 v85, v74, v78 offset0:128 offset1:144
	v_add_u32_e32 v74, 0x8400, v130
	ds_write2_b32 v74, v75, v79 offset0:132 offset1:148
	v_add_u32_e32 v75, 0x8800, v130
	ds_write2_b32 v75, v76, v80 offset0:136 offset1:152
	v_add_u32_e32 v76, 0x8c00, v130
	v_add_u32_e32 v80, 0xc000, v130
	ds_write2_b32 v76, v77, v81 offset0:140 offset1:156
	ds_write2_b32 v80, v66, v70 offset0:192 offset1:208
	v_add_u32_e32 v77, 0xc400, v130
	v_add_u32_e32 v78, 0xc800, v130
	v_add_u32_e32 v79, 0xcc00, v130
	v_add_u32_e32 v81, 0x9000, v130
	v_lshlrev_b32_e32 v66, 2, v142
	ds_write2_b32 v77, v67, v71 offset0:196 offset1:212
	ds_write2_b32 v78, v68, v72 offset0:200 offset1:216
	ds_write2_b32 v79, v69, v73 offset0:204 offset1:220
	ds_write2_b32 v130, v98, v118 offset0:128 offset1:144
	ds_write2_b32 v114, v99, v119 offset0:132 offset1:148
	ds_write2_b32 v115, v100, v120 offset0:136 offset1:152
	ds_write2_b32 v116, v101, v121 offset0:140 offset1:156
	ds_write2_b32 v117, v102, v122 offset0:192 offset1:208
	ds_write2_b32 v82, v103, v123 offset0:196 offset1:212
	ds_write2_b32 v83, v104, v124 offset0:200 offset1:216
	ds_write2_b32 v84, v105, v125 offset0:204 offset1:220
	ds_write2_b32 v74, v90, v110 offset1:16
	ds_write2_b32 v75, v91, v111 offset0:4 offset1:20
	ds_write2_b32 v76, v92, v112 offset0:8 offset1:24
	ds_write2_b32 v81, v93, v113 offset0:12 offset1:28
	ds_write2_b32 v77, v86, v106 offset0:64 offset1:80
	ds_write2_b32 v78, v87, v107 offset0:68 offset1:84
	ds_write2_b32 v79, v88, v108 offset0:72 offset1:88
	v_lshlrev_b32_e32 v0, 3, v142
	v_and_b32_e32 v66, 12, v66
	s_movk_i32 s7, 0xe0
	v_ashrrev_i32_e32 v87, 5, v142
	v_and_or_b32 v0, v0, s7, v66
	v_add_u32_e32 v68, s8, v87
	v_or_b32_e32 v66, s10, v0
	v_ashrrev_i32_e32 v69, 31, v68
	v_ashrrev_i32_e32 v67, 31, v66
	v_lshlrev_b64 v[70:71], 10, v[68:69]
	v_lshl_add_u64 v[98:99], v[70:71], 0, v[66:67]
	v_add_u32_e32 v86, 0xd000, v130
	v_lshl_add_u64 v[110:111], v[98:99], 2, s[26:27]
	ds_write2_b32 v86, v89, v109 offset0:76 offset1:92
	s_waitcnt lgkmcnt(0)
	s_barrier
	v_lshlrev_b32_e32 v140, 2, v98
	global_load_dwordx4 v[132:135], v140, s[26:27]
	global_load_dwordx4 v[136:139], v140, s[26:27] offset:64
	v_add_u32_e32 v140, 0x10000, v140
	global_load_dwordx4 v[144:147], v140, s[26:27]
	global_load_dwordx4 v[148:151], v140, s[26:27] offset:64
	v_add_u32_e32 v140, 0x10000, v140
	global_load_dwordx4 v[152:155], v140, s[26:27]
	global_load_dwordx4 v[156:159], v140, s[26:27] offset:64
	v_add_u32_e32 v140, 0x10000, v140
	global_load_dwordx4 v[160:163], v140, s[26:27]
	global_load_dwordx4 v[164:167], v140, s[26:27] offset:64
	v_add_u32_e32 v140, 0x10000, v140
	global_load_dwordx4 v[168:171], v140, s[26:27]
	global_load_dwordx4 v[172:175], v140, s[26:27] offset:64
	v_add_u32_e32 v140, 0x10000, v140
	global_load_dwordx4 v[176:179], v140, s[26:27]
	global_load_dwordx4 v[180:183], v140, s[26:27] offset:64
	v_add_u32_e32 v140, 0x10000, v140
	global_load_dwordx4 v[184:187], v140, s[26:27]
	global_load_dwordx4 v[188:191], v140, s[26:27] offset:64
	v_add_u32_e32 v140, 0x10000, v140
	global_load_dwordx4 v[192:195], v140, s[26:27]
	global_load_dwordx4 v[196:199], v140, s[26:27] offset:64
	v_lshl_add_u32 v101, v0, 2, 0
	v_mul_lo_u32 v72, v87, s9
	v_add_u32_e32 v88, v101, v72
	ds_read_b128 v[102:105], v88
	ds_read_b128 v[106:109], v88 offset:64
	v_and_b32_e32 v70, 64, v218
	v_xor_b32_e32 v0, 1, v218
	v_add_u32_e32 v100, 64, v70
	v_cmp_lt_i32_e32 vcc, v0, v100
	v_xor_b32_e32 v70, 2, v218
	v_xor_b32_e32 v71, 4, v218
	v_cndmask_b32_e32 v0, v218, v0, vcc
	v_lshlrev_b32_e32 v0, 2, v0
	v_cmp_lt_i32_e32 vcc, v70, v100
	v_xor_b32_e32 v112, 8, v218
	v_and_b32_e32 v89, 31, v142
	v_cndmask_b32_e32 v70, v218, v70, vcc
	v_lshlrev_b32_e32 v70, 2, v70
	v_cmp_lt_i32_e32 vcc, v71, v100
	s_ashr_i32 s57, s56, 31
	s_lshl_b64 s[10:11], s[56:57], 2
	v_cndmask_b32_e32 v71, v218, v71, vcc
	v_cmp_lt_i32_e32 vcc, v112, v100
	v_lshlrev_b32_e32 v71, 2, v71
	s_add_u32 s10, s46, s10
	s_movk_i32 s7, 0x410
	s_addc_u32 s11, s47, s11
	s_waitcnt lgkmcnt(1)
	s_waitcnt vmcnt(15)
	v_pk_add_f32 v[90:91], v[102:103], v[132:133]
	s_waitcnt vmcnt(15)
	v_pk_add_f32 v[92:93], v[104:105], v[134:135]
	v_pk_mul_f32 v[72:73], v[90:91], v[90:91]
	v_pk_mul_f32 v[102:103], v[92:93], v[92:93]
	v_add_f32_e32 v72, v72, v73
	s_waitcnt lgkmcnt(0)
	s_waitcnt vmcnt(14)
	v_pk_add_f32 v[94:95], v[106:107], v[136:137]
	v_add_f32_e32 v72, v102, v72
	v_pk_mul_f32 v[104:105], v[94:95], v[94:95]
	v_add_f32_e32 v72, v103, v72
	s_waitcnt vmcnt(14)
	v_pk_add_f32 v[96:97], v[108:109], v[138:139]
	v_add_f32_e32 v72, v104, v72
	v_pk_mul_f32 v[106:107], v[96:97], v[96:97]
	v_add_f32_e32 v72, v105, v72
	v_add_f32_e32 v72, v106, v72
	v_add_f32_e32 v72, v107, v72
	ds_bpermute_b32 v102, v0, v72
	v_xor_b32_e32 v103, 16, v218
	v_cndmask_b32_e32 v73, v218, v112, vcc
	v_cmp_lt_i32_e32 vcc, v103, v100
	v_lshlrev_b32_e32 v73, 2, v73
	s_waitcnt lgkmcnt(0)
	v_add_f32_e32 v102, v72, v102
	ds_bpermute_b32 v104, v70, v102
	v_cndmask_b32_e32 v72, v218, v103, vcc
	v_cmp_eq_u32_e32 vcc, 0, v89
	v_lshlrev_b32_e32 v72, 2, v72
	global_store_dwordx4 v[110:111], v[90:93], off
	s_waitcnt lgkmcnt(0)
	v_add_f32_e32 v89, v102, v104
	ds_bpermute_b32 v100, v71, v89
	v_cvt_pk_bf16_f32 v102, v90, v91
	global_store_dwordx4 v[110:111], v[94:97], off offset:64
	v_cvt_pk_bf16_f32 v103, v92, v93
	v_lshl_add_u64 v[92:93], v[98:99], 1, s[44:45]
	s_waitcnt lgkmcnt(0)
	v_add_f32_e32 v89, v89, v100
	ds_bpermute_b32 v100, v73, v89
	v_cvt_pk_bf16_f32 v94, v94, v95
	v_cvt_pk_bf16_f32 v95, v96, v97
	global_store_dwordx2 v[92:93], v[102:103], off
	global_store_dwordx2 v[92:93], v[94:95], off offset:32
	s_waitcnt lgkmcnt(0)
	v_add_f32_e32 v89, v89, v100
	ds_bpermute_b32 v90, v72, v89
	s_and_saveexec_b64 s[12:13], vcc
	s_cbranch_execz .LBB0_262
	s_waitcnt lgkmcnt(0)
	v_add_f32_e32 v89, v89, v90
	v_lshl_add_u64 v[68:69], v[68:69], 4, s[10:11]
	global_store_dword v[68:69], v89, off
.LBB0_262:
	s_or_b64 exec, exec, s[12:13]
	v_add_u32_e32 v68, 0x200, v142
	s_waitcnt lgkmcnt(0)
	v_ashrrev_i32_e32 v90, 5, v68
	v_mul_lo_u32 v68, v90, s7
	v_add_u32_e32 v89, v101, v68
	v_add_u32_e32 v68, s8, v90
	v_ashrrev_i32_e32 v69, 31, v68
	v_lshlrev_b64 v[92:93], 10, v[68:69]
	v_lshl_add_u64 v[106:107], v[92:93], 0, v[66:67]
	v_lshl_add_u64 v[108:109], v[106:107], 2, s[26:27]
	ds_read_b128 v[92:95], v89
	s_waitcnt lgkmcnt(0)
	s_waitcnt vmcnt(18)
	v_pk_add_f32 v[92:93], v[92:93], v[144:145]
	s_waitcnt vmcnt(18)
	v_pk_add_f32 v[94:95], v[94:95], v[146:147]
	ds_read_b128 v[96:99], v89 offset:64
	global_store_dwordx4 v[108:109], v[92:95], off
	s_waitcnt lgkmcnt(0)
	s_waitcnt vmcnt(18)
	v_pk_add_f32 v[96:97], v[96:97], v[148:149]
	v_cvt_pk_bf16_f32 v102, v92, v93
	v_pk_mul_f32 v[92:93], v[92:93], v[92:93]
	v_cvt_pk_bf16_f32 v103, v94, v95
	v_pk_mul_f32 v[94:95], v[94:95], v[94:95]
	v_add_f32_e32 v91, v92, v93
	s_waitcnt vmcnt(18)
	v_pk_add_f32 v[98:99], v[98:99], v[150:151]
	v_lshl_add_u64 v[104:105], v[106:107], 1, s[44:45]
	v_add_f32_e32 v91, v94, v91
	global_store_dwordx4 v[108:109], v[96:99], off offset:64
	global_store_dwordx2 v[104:105], v[102:103], off
	v_cvt_pk_bf16_f32 v102, v96, v97
	v_pk_mul_f32 v[96:97], v[96:97], v[96:97]
	v_add_f32_e32 v91, v95, v91
	v_add_f32_e32 v91, v96, v91
	v_cvt_pk_bf16_f32 v103, v98, v99
	v_pk_mul_f32 v[98:99], v[98:99], v[98:99]
	v_add_f32_e32 v91, v97, v91
	v_add_f32_e32 v91, v98, v91
	v_add_f32_e32 v91, v99, v91
	ds_bpermute_b32 v92, v0, v91
	global_store_dwordx2 v[104:105], v[102:103], off offset:32
	s_waitcnt lgkmcnt(0)
	v_add_f32_e32 v91, v91, v92
	ds_bpermute_b32 v92, v70, v91
	s_waitcnt lgkmcnt(0)
	v_add_f32_e32 v91, v91, v92
	ds_bpermute_b32 v92, v71, v91
	s_waitcnt lgkmcnt(0)
	v_add_f32_e32 v91, v91, v92
	ds_bpermute_b32 v92, v73, v91
	s_waitcnt lgkmcnt(0)
	v_add_f32_e32 v91, v91, v92
	ds_bpermute_b32 v92, v72, v91
	s_and_saveexec_b64 s[12:13], vcc
	s_cbranch_execz .LBB0_264
	s_waitcnt lgkmcnt(0)
	v_add_f32_e32 v91, v91, v92
	v_lshl_add_u64 v[68:69], v[68:69], 4, s[10:11]
	global_store_dword v[68:69], v91, off
.LBB0_264:
	s_or_b64 exec, exec, s[12:13]
	v_add_u32_e32 v68, 0x400, v142
	s_waitcnt lgkmcnt(0)
	v_ashrrev_i32_e32 v92, 5, v68
	v_mul_lo_u32 v68, v92, s7
	v_add_u32_e32 v91, v101, v68
	v_add_u32_e32 v68, s8, v92
	v_ashrrev_i32_e32 v69, 31, v68
	v_lshlrev_b64 v[94:95], 10, v[68:69]
	v_lshl_add_u64 v[98:99], v[94:95], 0, v[66:67]
	v_lshl_add_u64 v[110:111], v[98:99], 2, s[26:27]
	ds_read_b128 v[94:97], v91
	v_lshl_add_u64 v[98:99], v[98:99], 1, s[44:45]
	s_waitcnt lgkmcnt(0)
	s_waitcnt vmcnt(21)
	v_pk_add_f32 v[94:95], v[94:95], v[152:153]
	s_waitcnt vmcnt(21)
	v_pk_add_f32 v[96:97], v[96:97], v[154:155]
	ds_read_b128 v[102:105], v91 offset:64
	global_store_dwordx4 v[110:111], v[94:97], off
	s_waitcnt lgkmcnt(0)
	s_waitcnt vmcnt(21)
	v_pk_add_f32 v[102:103], v[102:103], v[156:157]
	v_cvt_pk_bf16_f32 v106, v94, v95
	v_pk_mul_f32 v[94:95], v[94:95], v[94:95]
	s_waitcnt vmcnt(21)
	v_pk_add_f32 v[104:105], v[104:105], v[158:159]
	v_cvt_pk_bf16_f32 v107, v96, v97
	v_pk_mul_f32 v[96:97], v[96:97], v[96:97]
	v_add_f32_e32 v93, v94, v95
	global_store_dwordx4 v[110:111], v[102:105], off offset:64
	global_store_dwordx2 v[98:99], v[106:107], off
	v_cvt_pk_bf16_f32 v106, v102, v103
	v_cvt_pk_bf16_f32 v107, v104, v105
	v_add_f32_e32 v93, v96, v93
	global_store_dwordx2 v[98:99], v[106:107], off offset:32
	v_pk_mul_f32 v[98:99], v[102:103], v[102:103]
	v_add_f32_e32 v93, v97, v93
	v_add_f32_e32 v93, v98, v93
	v_pk_mul_f32 v[102:103], v[104:105], v[104:105]
	v_add_f32_e32 v93, v99, v93
	v_add_f32_e32 v93, v102, v93
	v_add_f32_e32 v93, v103, v93
	ds_bpermute_b32 v94, v0, v93
	s_waitcnt lgkmcnt(0)
	v_add_f32_e32 v93, v93, v94
	ds_bpermute_b32 v94, v70, v93
	s_waitcnt lgkmcnt(0)
	v_add_f32_e32 v93, v93, v94
	ds_bpermute_b32 v94, v71, v93
	s_waitcnt lgkmcnt(0)
	v_add_f32_e32 v93, v93, v94
	ds_bpermute_b32 v94, v73, v93
	s_waitcnt lgkmcnt(0)
	v_add_f32_e32 v93, v93, v94
	ds_bpermute_b32 v94, v72, v93
	s_and_saveexec_b64 s[12:13], vcc
	s_cbranch_execz .LBB0_266
	s_waitcnt lgkmcnt(0)
	v_add_f32_e32 v93, v93, v94
	v_lshl_add_u64 v[68:69], v[68:69], 4, s[10:11]
	global_store_dword v[68:69], v93, off
.LBB0_266:
	s_or_b64 exec, exec, s[12:13]
	v_add_u32_e32 v68, 0x600, v142
	s_waitcnt lgkmcnt(0)
	v_ashrrev_i32_e32 v94, 5, v68
	v_mul_lo_u32 v68, v94, s7
	v_add_u32_e32 v93, v101, v68
	v_add_u32_e32 v68, s8, v94
	v_ashrrev_i32_e32 v69, 31, v68
	v_lshlrev_b64 v[96:97], 10, v[68:69]
	v_lshl_add_u64 v[110:111], v[96:97], 0, v[66:67]
	v_lshl_add_u64 v[112:113], v[110:111], 2, s[26:27]
	ds_read_b128 v[96:99], v93
	s_waitcnt lgkmcnt(0)
	s_waitcnt vmcnt(24)
	v_pk_add_f32 v[96:97], v[96:97], v[160:161]
	s_waitcnt vmcnt(24)
	v_pk_add_f32 v[98:99], v[98:99], v[162:163]
	ds_read_b128 v[102:105], v93 offset:64
	global_store_dwordx4 v[112:113], v[96:99], off
	s_waitcnt lgkmcnt(0)
	s_waitcnt vmcnt(24)
	v_pk_add_f32 v[102:103], v[102:103], v[164:165]
	v_cvt_pk_bf16_f32 v106, v96, v97
	v_pk_mul_f32 v[96:97], v[96:97], v[96:97]
	v_cvt_pk_bf16_f32 v107, v98, v99
	v_pk_mul_f32 v[98:99], v[98:99], v[98:99]
	v_add_f32_e32 v95, v96, v97
	s_waitcnt vmcnt(24)
	v_pk_add_f32 v[104:105], v[104:105], v[166:167]
	v_lshl_add_u64 v[108:109], v[110:111], 1, s[44:45]
	v_add_f32_e32 v95, v98, v95
	global_store_dwordx4 v[112:113], v[102:105], off offset:64
	global_store_dwordx2 v[108:109], v[106:107], off
	v_cvt_pk_bf16_f32 v106, v102, v103
	v_pk_mul_f32 v[102:103], v[102:103], v[102:103]
	v_add_f32_e32 v95, v99, v95
	v_add_f32_e32 v95, v102, v95
	v_cvt_pk_bf16_f32 v107, v104, v105
	v_pk_mul_f32 v[104:105], v[104:105], v[104:105]
	v_add_f32_e32 v95, v103, v95
	v_add_f32_e32 v95, v104, v95
	v_add_f32_e32 v95, v105, v95
	ds_bpermute_b32 v96, v0, v95
	global_store_dwordx2 v[108:109], v[106:107], off offset:32
	s_waitcnt lgkmcnt(0)
	v_add_f32_e32 v95, v95, v96
	ds_bpermute_b32 v96, v70, v95
	s_waitcnt lgkmcnt(0)
	v_add_f32_e32 v95, v95, v96
	ds_bpermute_b32 v96, v71, v95
	s_waitcnt lgkmcnt(0)
	v_add_f32_e32 v95, v95, v96
	ds_bpermute_b32 v96, v73, v95
	s_waitcnt lgkmcnt(0)
	v_add_f32_e32 v95, v95, v96
	ds_bpermute_b32 v96, v72, v95
	s_and_saveexec_b64 s[12:13], vcc
	s_cbranch_execz .LBB0_268
	s_waitcnt lgkmcnt(0)
	v_add_f32_e32 v95, v95, v96
	v_lshl_add_u64 v[68:69], v[68:69], 4, s[10:11]
	global_store_dword v[68:69], v95, off
.LBB0_268:
	s_or_b64 exec, exec, s[12:13]
	v_add_u32_e32 v68, 0x800, v142
	s_waitcnt lgkmcnt(0)
	v_ashrrev_i32_e32 v96, 5, v68
	v_mul_lo_u32 v68, v96, s7
	v_add_u32_e32 v95, v101, v68
	v_add_u32_e32 v68, s8, v96
	v_ashrrev_i32_e32 v69, 31, v68
	v_lshlrev_b64 v[98:99], 10, v[68:69]
	v_lshl_add_u64 v[98:99], v[98:99], 0, v[66:67]
	v_lshl_add_u64 v[118:119], v[98:99], 2, s[26:27]
	ds_read_b128 v[102:105], v95
	v_lshl_add_u64 v[98:99], v[98:99], 1, s[44:45]
	s_waitcnt lgkmcnt(0)
	s_waitcnt vmcnt(27)
	v_pk_add_f32 v[102:103], v[102:103], v[168:169]
	s_waitcnt vmcnt(27)
	v_pk_add_f32 v[104:105], v[104:105], v[170:171]
	ds_read_b128 v[106:109], v95 offset:64
	global_store_dwordx4 v[118:119], v[102:105], off
	s_waitcnt lgkmcnt(0)
	s_waitcnt vmcnt(27)
	v_pk_add_f32 v[106:107], v[106:107], v[172:173]
	s_waitcnt vmcnt(27)
	v_pk_add_f32 v[108:109], v[108:109], v[174:175]
	v_cvt_pk_bf16_f32 v110, v102, v103
	v_cvt_pk_bf16_f32 v111, v104, v105
	global_store_dwordx4 v[118:119], v[106:109], off offset:64
	global_store_dwordx2 v[98:99], v[110:111], off
	v_cvt_pk_bf16_f32 v110, v106, v107
	v_cvt_pk_bf16_f32 v111, v108, v109
	global_store_dwordx2 v[98:99], v[110:111], off offset:32
	v_pk_mul_f32 v[98:99], v[102:103], v[102:103]
	v_pk_mul_f32 v[102:103], v[104:105], v[104:105]
	v_add_f32_e32 v97, v98, v99
	v_add_f32_e32 v97, v102, v97
	v_pk_mul_f32 v[104:105], v[106:107], v[106:107]
	v_add_f32_e32 v97, v103, v97
	v_add_f32_e32 v97, v104, v97
	v_pk_mul_f32 v[106:107], v[108:109], v[108:109]
	v_add_f32_e32 v97, v105, v97
	v_add_f32_e32 v97, v106, v97
	v_add_f32_e32 v97, v107, v97
	ds_bpermute_b32 v98, v0, v97
	s_waitcnt lgkmcnt(0)
	v_add_f32_e32 v97, v97, v98
	ds_bpermute_b32 v98, v70, v97
	s_waitcnt lgkmcnt(0)
	v_add_f32_e32 v97, v97, v98
	ds_bpermute_b32 v98, v71, v97
	s_waitcnt lgkmcnt(0)
	v_add_f32_e32 v97, v97, v98
	ds_bpermute_b32 v98, v73, v97
	s_waitcnt lgkmcnt(0)
	v_add_f32_e32 v97, v97, v98
	ds_bpermute_b32 v98, v72, v97
	s_and_saveexec_b64 s[12:13], vcc
	s_cbranch_execz .LBB0_270
	s_waitcnt lgkmcnt(0)
	v_add_f32_e32 v97, v97, v98
	v_lshl_add_u64 v[68:69], v[68:69], 4, s[10:11]
	global_store_dword v[68:69], v97, off
.LBB0_270:
	s_or_b64 exec, exec, s[12:13]
	v_add_u32_e32 v68, 0xa00, v142
	s_waitcnt lgkmcnt(0)
	v_ashrrev_i32_e32 v98, 5, v68
	v_mul_lo_u32 v68, v98, s7
	v_add_u32_e32 v97, v101, v68
	v_add_u32_e32 v68, s8, v98
	v_ashrrev_i32_e32 v69, 31, v68
	v_lshlrev_b64 v[102:103], 10, v[68:69]
	v_lshl_add_u64 v[118:119], v[102:103], 0, v[66:67]
	v_lshl_add_u64 v[120:121], v[118:119], 2, s[26:27]
	ds_read_b128 v[102:105], v97
	s_waitcnt lgkmcnt(0)
	s_waitcnt vmcnt(30)
	v_pk_add_f32 v[102:103], v[102:103], v[176:177]
	s_waitcnt vmcnt(30)
	v_pk_add_f32 v[104:105], v[104:105], v[178:179]
	ds_read_b128 v[106:109], v97 offset:64
	global_store_dwordx4 v[120:121], v[102:105], off
	s_waitcnt lgkmcnt(0)
	s_waitcnt vmcnt(30)
	v_pk_add_f32 v[106:107], v[106:107], v[180:181]
	v_cvt_pk_bf16_f32 v110, v102, v103
	v_pk_mul_f32 v[102:103], v[102:103], v[102:103]
	v_cvt_pk_bf16_f32 v111, v104, v105
	v_pk_mul_f32 v[104:105], v[104:105], v[104:105]
	v_add_f32_e32 v99, v102, v103
	s_waitcnt vmcnt(30)
	v_pk_add_f32 v[108:109], v[108:109], v[182:183]
	v_lshl_add_u64 v[112:113], v[118:119], 1, s[44:45]
	v_add_f32_e32 v99, v104, v99
	global_store_dwordx4 v[120:121], v[106:109], off offset:64
	global_store_dwordx2 v[112:113], v[110:111], off
	v_cvt_pk_bf16_f32 v110, v106, v107
	v_pk_mul_f32 v[106:107], v[106:107], v[106:107]
	v_add_f32_e32 v99, v105, v99
	v_add_f32_e32 v99, v106, v99
	v_cvt_pk_bf16_f32 v111, v108, v109
	v_pk_mul_f32 v[108:109], v[108:109], v[108:109]
	v_add_f32_e32 v99, v107, v99
	v_add_f32_e32 v99, v108, v99
	v_add_f32_e32 v99, v109, v99
	ds_bpermute_b32 v100, v0, v99
	global_store_dwordx2 v[112:113], v[110:111], off offset:32
	s_waitcnt lgkmcnt(0)
	v_add_f32_e32 v99, v99, v100
	ds_bpermute_b32 v100, v70, v99
	s_waitcnt lgkmcnt(0)
	v_add_f32_e32 v99, v99, v100
	ds_bpermute_b32 v100, v71, v99
	s_waitcnt lgkmcnt(0)
	v_add_f32_e32 v99, v99, v100
	ds_bpermute_b32 v100, v73, v99
	s_waitcnt lgkmcnt(0)
	v_add_f32_e32 v99, v99, v100
	ds_bpermute_b32 v100, v72, v99
	s_and_saveexec_b64 s[12:13], vcc
	s_cbranch_execz .LBB0_272
	s_waitcnt lgkmcnt(0)
	v_add_f32_e32 v99, v99, v100
	v_lshl_add_u64 v[68:69], v[68:69], 4, s[10:11]
	global_store_dword v[68:69], v99, off
.LBB0_272:
	s_or_b64 exec, exec, s[12:13]
	v_add_u32_e32 v68, 0xc00, v142
	s_waitcnt lgkmcnt(0)
	v_ashrrev_i32_e32 v100, 5, v68
	v_mul_lo_u32 v68, v100, s7
	v_add_u32_e32 v99, v101, v68
	v_add_u32_e32 v68, s8, v100
	v_ashrrev_i32_e32 v69, 31, v68
	v_lshlrev_b64 v[102:103], 10, v[68:69]
	v_lshl_add_u64 v[118:119], v[102:103], 0, v[66:67]
	v_lshl_add_u64 v[120:121], v[118:119], 2, s[26:27]
	ds_read_b128 v[102:105], v99
	s_waitcnt lgkmcnt(0)
	s_waitcnt vmcnt(33)
	v_pk_add_f32 v[102:103], v[102:103], v[184:185]
	s_waitcnt vmcnt(33)
	v_pk_add_f32 v[104:105], v[104:105], v[186:187]
	ds_read_b128 v[106:109], v99 offset:64
	global_store_dwordx4 v[120:121], v[102:105], off
	s_waitcnt lgkmcnt(0)
	s_waitcnt vmcnt(33)
	v_pk_add_f32 v[106:107], v[106:107], v[188:189]
	v_cvt_pk_bf16_f32 v110, v102, v103
	v_pk_mul_f32 v[102:103], v[102:103], v[102:103]
	v_cvt_pk_bf16_f32 v111, v104, v105
	v_pk_mul_f32 v[104:105], v[104:105], v[104:105]
	v_add_f32_e32 v102, v102, v103
	s_waitcnt vmcnt(33)
	v_pk_add_f32 v[108:109], v[108:109], v[190:191]
	v_lshl_add_u64 v[112:113], v[118:119], 1, s[44:45]
	v_add_f32_e32 v102, v104, v102
	global_store_dwordx4 v[120:121], v[106:109], off offset:64
	global_store_dwordx2 v[112:113], v[110:111], off
	v_cvt_pk_bf16_f32 v110, v106, v107
	v_pk_mul_f32 v[106:107], v[106:107], v[106:107]
	v_add_f32_e32 v102, v105, v102
	v_add_f32_e32 v102, v106, v102
	v_cvt_pk_bf16_f32 v111, v108, v109
	v_pk_mul_f32 v[108:109], v[108:109], v[108:109]
	v_add_f32_e32 v102, v107, v102
	v_add_f32_e32 v102, v108, v102
	v_add_f32_e32 v102, v109, v102
	ds_bpermute_b32 v103, v0, v102
	global_store_dwordx2 v[112:113], v[110:111], off offset:32
	s_waitcnt lgkmcnt(0)
	v_add_f32_e32 v102, v102, v103
	ds_bpermute_b32 v103, v70, v102
	s_waitcnt lgkmcnt(0)
	v_add_f32_e32 v102, v102, v103
	ds_bpermute_b32 v103, v71, v102
	s_waitcnt lgkmcnt(0)
	v_add_f32_e32 v102, v102, v103
	ds_bpermute_b32 v103, v73, v102
	s_waitcnt lgkmcnt(0)
	v_add_f32_e32 v102, v102, v103
	ds_bpermute_b32 v103, v72, v102
	s_and_saveexec_b64 s[12:13], vcc
	s_cbranch_execz .LBB0_274
	s_waitcnt lgkmcnt(0)
	v_add_f32_e32 v102, v102, v103
	v_lshl_add_u64 v[68:69], v[68:69], 4, s[10:11]
	global_store_dword v[68:69], v102, off
.LBB0_274:
	s_or_b64 exec, exec, s[12:13]
	v_add_u32_e32 v68, 0xe00, v142
	v_ashrrev_i32_e32 v102, 5, v68
	v_mul_lo_u32 v68, v102, s7
	v_add_u32_e32 v101, v101, v68
	v_add_u32_e32 v68, s8, v102
	v_ashrrev_i32_e32 v69, 31, v68
	v_lshlrev_b64 v[104:105], 10, v[68:69]
	v_lshl_add_u64 v[112:113], v[104:105], 0, v[66:67]
	v_lshl_add_u64 v[122:123], v[112:113], 2, s[26:27]
	ds_read_b128 v[104:107], v101
	v_lshl_add_u64 v[112:113], v[112:113], 1, s[44:45]
	s_waitcnt lgkmcnt(0)
	s_waitcnt vmcnt(36)
	v_pk_add_f32 v[104:105], v[104:105], v[192:193]
	s_waitcnt vmcnt(36)
	v_pk_add_f32 v[106:107], v[106:107], v[194:195]
	ds_read_b128 v[108:111], v101 offset:64
	global_store_dwordx4 v[122:123], v[104:107], off
	s_waitcnt lgkmcnt(0)
	s_waitcnt vmcnt(36)
	v_pk_add_f32 v[108:109], v[108:109], v[196:197]
	v_cvt_pk_bf16_f32 v118, v104, v105
	v_pk_mul_f32 v[104:105], v[104:105], v[104:105]
	v_cvt_pk_bf16_f32 v119, v106, v107
	v_pk_mul_f32 v[106:107], v[106:107], v[106:107]
	v_add_f32_e32 v103, v104, v105
	s_waitcnt vmcnt(36)
	v_pk_add_f32 v[110:111], v[110:111], v[198:199]
	v_add_f32_e32 v103, v106, v103
	global_store_dwordx4 v[122:123], v[108:111], off offset:64
	global_store_dwordx2 v[112:113], v[118:119], off
	v_cvt_pk_bf16_f32 v118, v108, v109
	v_pk_mul_f32 v[108:109], v[108:109], v[108:109]
	v_add_f32_e32 v103, v107, v103
	v_add_f32_e32 v103, v108, v103
	v_cvt_pk_bf16_f32 v119, v110, v111
	v_pk_mul_f32 v[110:111], v[110:111], v[110:111]
	v_add_f32_e32 v103, v109, v103
	v_add_f32_e32 v103, v110, v103
	v_add_f32_e32 v103, v111, v103
	ds_bpermute_b32 v104, v0, v103
	global_store_dwordx2 v[112:113], v[118:119], off offset:32
	s_waitcnt lgkmcnt(0)
	v_add_f32_e32 v103, v103, v104
	ds_bpermute_b32 v104, v70, v103
	s_waitcnt lgkmcnt(0)
	v_add_f32_e32 v103, v103, v104
	ds_bpermute_b32 v104, v71, v103
	s_waitcnt lgkmcnt(0)
	v_add_f32_e32 v103, v103, v104
	ds_bpermute_b32 v104, v73, v103
	s_waitcnt lgkmcnt(0)
	v_add_f32_e32 v103, v103, v104
	ds_bpermute_b32 v104, v72, v103
	s_and_saveexec_b64 s[8:9], vcc
	s_cbranch_execz .LBB0_276
	s_waitcnt lgkmcnt(0)
	v_add_f32_e32 v103, v103, v104
	v_lshl_add_u64 v[68:69], v[68:69], 4, s[10:11]
	global_store_dword v[68:69], v103, off
.LBB0_276:
	s_or_b64 exec, exec, s[8:9]
	s_waitcnt lgkmcnt(0)
	s_barrier
	ds_write2_b32 v130, v2, v18 offset1:16
	ds_write2_b32 v114, v3, v19 offset0:4 offset1:20
	ds_write2_b32 v115, v4, v20 offset0:8 offset1:24
	ds_write2_b32 v116, v5, v21 offset0:12 offset1:28
	ds_write2_b32 v117, v6, v22 offset0:64 offset1:80
	ds_write2_b32 v82, v7, v23 offset0:68 offset1:84
	ds_write2_b32 v83, v8, v24 offset0:72 offset1:88
	ds_write2_b32 v84, v9, v25 offset0:76 offset1:92
	ds_write2_b32 v85, v10, v26 offset0:128 offset1:144
	ds_write2_b32 v74, v11, v27 offset0:132 offset1:148
	ds_write2_b32 v75, v12, v28 offset0:136 offset1:152
	ds_write2_b32 v76, v13, v29 offset0:140 offset1:156
	ds_write2_b32 v80, v14, v30 offset0:192 offset1:208
	ds_write2_b32 v77, v15, v31 offset0:196 offset1:212
	ds_write2_b32 v78, v16, v32 offset0:200 offset1:216
	ds_write2_b32 v79, v17, v33 offset0:204 offset1:220
	ds_write2_b32 v130, v34, v50 offset0:128 offset1:144
	ds_write2_b32 v114, v35, v51 offset0:132 offset1:148
	ds_write2_b32 v115, v36, v52 offset0:136 offset1:152
	ds_write2_b32 v116, v37, v53 offset0:140 offset1:156
	ds_write2_b32 v117, v38, v54 offset0:192 offset1:208
	ds_write2_b32 v82, v39, v55 offset0:196 offset1:212
	ds_write2_b32 v83, v40, v56 offset0:200 offset1:216
	ds_write2_b32 v84, v41, v57 offset0:204 offset1:220
	ds_write2_b32 v74, v42, v58 offset1:16
	ds_write2_b32 v75, v43, v59 offset0:4 offset1:20
	ds_write2_b32 v76, v44, v60 offset0:8 offset1:24
	ds_write2_b32 v81, v45, v61 offset0:12 offset1:28
	ds_write2_b32 v77, v46, v62 offset0:64 offset1:80
	ds_write2_b32 v78, v47, v63 offset0:68 offset1:84
	ds_write2_b32 v79, v48, v64 offset0:72 offset1:88
	ds_write2_b32 v86, v49, v65 offset0:76 offset1:92
	v_add_u32_e32 v2, s6, v87
	v_ashrrev_i32_e32 v3, 31, v2
	v_lshlrev_b64 v[4:5], 10, v[2:3]
	v_lshl_add_u64 v[20:21], v[4:5], 0, v[66:67]
	v_lshl_add_u64 v[22:23], v[20:21], 2, s[26:27]
	s_waitcnt lgkmcnt(0)
	s_barrier
	v_lshlrev_b32_e32 v140, 2, v20
	global_load_dwordx4 v[132:135], v140, s[26:27]
	global_load_dwordx4 v[136:139], v140, s[26:27] offset:64
	v_add_u32_e32 v140, 0x10000, v140
	global_load_dwordx4 v[144:147], v140, s[26:27]
	global_load_dwordx4 v[148:151], v140, s[26:27] offset:64
	v_add_u32_e32 v140, 0x10000, v140
	global_load_dwordx4 v[152:155], v140, s[26:27]
	global_load_dwordx4 v[156:159], v140, s[26:27] offset:64
	v_add_u32_e32 v140, 0x10000, v140
	global_load_dwordx4 v[160:163], v140, s[26:27]
	global_load_dwordx4 v[164:167], v140, s[26:27] offset:64
	v_add_u32_e32 v140, 0x10000, v140
	global_load_dwordx4 v[168:171], v140, s[26:27]
	global_load_dwordx4 v[172:175], v140, s[26:27] offset:64
	v_add_u32_e32 v140, 0x10000, v140
	global_load_dwordx4 v[176:179], v140, s[26:27]
	global_load_dwordx4 v[180:183], v140, s[26:27] offset:64
	v_add_u32_e32 v140, 0x10000, v140
	global_load_dwordx4 v[184:187], v140, s[26:27]
	global_load_dwordx4 v[188:191], v140, s[26:27] offset:64
	v_add_u32_e32 v140, 0x10000, v140
	global_load_dwordx4 v[192:195], v140, s[26:27]
	global_load_dwordx4 v[196:199], v140, s[26:27] offset:64
	ds_read_b128 v[12:15], v88
	ds_read_b128 v[16:19], v88 offset:64
	s_waitcnt lgkmcnt(1)
	s_waitcnt vmcnt(15)
	v_pk_add_f32 v[4:5], v[12:13], v[132:133]
	s_waitcnt vmcnt(15)
	v_pk_add_f32 v[6:7], v[14:15], v[134:135]
	v_pk_mul_f32 v[12:13], v[4:5], v[4:5]
	v_pk_mul_f32 v[14:15], v[6:7], v[6:7]
	v_add_f32_e32 v12, v12, v13
	s_waitcnt lgkmcnt(0)
	s_waitcnt vmcnt(14)
	v_pk_add_f32 v[8:9], v[16:17], v[136:137]
	v_add_f32_e32 v12, v14, v12
	v_pk_mul_f32 v[16:17], v[8:9], v[8:9]
	v_add_f32_e32 v12, v15, v12
	s_waitcnt vmcnt(14)
	v_pk_add_f32 v[10:11], v[18:19], v[138:139]
	v_add_f32_e32 v12, v16, v12
	v_pk_mul_f32 v[18:19], v[10:11], v[10:11]
	v_add_f32_e32 v12, v17, v12
	v_add_f32_e32 v12, v18, v12
	v_add_f32_e32 v12, v19, v12
	ds_bpermute_b32 v13, v0, v12
	global_store_dwordx4 v[22:23], v[4:7], off
	global_store_dwordx4 v[22:23], v[8:11], off offset:64
	s_waitcnt lgkmcnt(0)
	v_add_f32_e32 v12, v12, v13
	ds_bpermute_b32 v13, v70, v12
	v_cvt_pk_bf16_f32 v8, v8, v9
	v_cvt_pk_bf16_f32 v9, v10, v11
	s_waitcnt lgkmcnt(0)
	v_add_f32_e32 v12, v12, v13
	ds_bpermute_b32 v13, v71, v12
	s_waitcnt lgkmcnt(0)
	v_add_f32_e32 v14, v12, v13
	ds_bpermute_b32 v15, v73, v14
	v_cvt_pk_bf16_f32 v12, v4, v5
	v_cvt_pk_bf16_f32 v13, v6, v7
	v_lshl_add_u64 v[6:7], v[20:21], 1, s[44:45]
	global_store_dwordx2 v[6:7], v[12:13], off
	s_waitcnt lgkmcnt(0)
	v_add_f32_e32 v4, v14, v15
	ds_bpermute_b32 v5, v72, v4
	global_store_dwordx2 v[6:7], v[8:9], off offset:32
	s_and_saveexec_b64 s[8:9], vcc
	s_cbranch_execz .LBB0_278
	s_waitcnt lgkmcnt(0)
	v_add_f32_e32 v4, v4, v5
	v_lshl_add_u64 v[2:3], v[2:3], 4, s[10:11]
	global_store_dword v[2:3], v4, off
.LBB0_278:
	s_or_b64 exec, exec, s[8:9]
	v_add_u32_e32 v2, s6, v90
	v_ashrrev_i32_e32 v3, 31, v2
	s_waitcnt lgkmcnt(0)
	v_lshlrev_b64 v[4:5], 10, v[2:3]
	v_lshl_add_u64 v[16:17], v[4:5], 0, v[66:67]
	v_lshl_add_u64 v[18:19], v[16:17], 2, s[26:27]
	ds_read_b128 v[4:7], v89
	s_waitcnt lgkmcnt(0)
	s_waitcnt vmcnt(18)
	v_pk_add_f32 v[4:5], v[4:5], v[144:145]
	s_waitcnt vmcnt(18)
	v_pk_add_f32 v[6:7], v[6:7], v[146:147]
	ds_read_b128 v[8:11], v89 offset:64
	global_store_dwordx4 v[18:19], v[4:7], off
	s_waitcnt lgkmcnt(0)
	s_waitcnt vmcnt(18)
	v_pk_add_f32 v[8:9], v[8:9], v[148:149]
	v_cvt_pk_bf16_f32 v12, v4, v5
	v_pk_mul_f32 v[4:5], v[4:5], v[4:5]
	v_cvt_pk_bf16_f32 v13, v6, v7
	v_pk_mul_f32 v[6:7], v[6:7], v[6:7]
	v_add_f32_e32 v4, v4, v5
	s_waitcnt vmcnt(18)
	v_pk_add_f32 v[10:11], v[10:11], v[150:151]
	v_lshl_add_u64 v[14:15], v[16:17], 1, s[44:45]
	v_add_f32_e32 v4, v6, v4
	global_store_dwordx4 v[18:19], v[8:11], off offset:64
	global_store_dwordx2 v[14:15], v[12:13], off
	v_cvt_pk_bf16_f32 v12, v8, v9
	v_pk_mul_f32 v[8:9], v[8:9], v[8:9]
	v_add_f32_e32 v4, v7, v4
	v_add_f32_e32 v4, v8, v4
	v_cvt_pk_bf16_f32 v13, v10, v11
	v_pk_mul_f32 v[10:11], v[10:11], v[10:11]
	v_add_f32_e32 v4, v9, v4
	v_add_f32_e32 v4, v10, v4
	v_add_f32_e32 v4, v11, v4
	ds_bpermute_b32 v5, v0, v4
	global_store_dwordx2 v[14:15], v[12:13], off offset:32
	s_waitcnt lgkmcnt(0)
	v_add_f32_e32 v4, v4, v5
	ds_bpermute_b32 v5, v70, v4
	s_waitcnt lgkmcnt(0)
	v_add_f32_e32 v4, v4, v5
	ds_bpermute_b32 v5, v71, v4
	s_waitcnt lgkmcnt(0)
	v_add_f32_e32 v4, v4, v5
	ds_bpermute_b32 v5, v73, v4
	s_waitcnt lgkmcnt(0)
	v_add_f32_e32 v4, v4, v5
	ds_bpermute_b32 v5, v72, v4
	s_and_saveexec_b64 s[8:9], vcc
	s_cbranch_execz .LBB0_280
	s_waitcnt lgkmcnt(0)
	v_add_f32_e32 v4, v4, v5
	v_lshl_add_u64 v[2:3], v[2:3], 4, s[10:11]
	global_store_dword v[2:3], v4, off
.LBB0_280:
	s_or_b64 exec, exec, s[8:9]
	v_add_u32_e32 v2, s6, v92
	v_ashrrev_i32_e32 v3, 31, v2
	s_waitcnt lgkmcnt(0)
	v_lshlrev_b64 v[4:5], 10, v[2:3]
	v_lshl_add_u64 v[16:17], v[4:5], 0, v[66:67]
	v_lshl_add_u64 v[18:19], v[16:17], 2, s[26:27]
	ds_read_b128 v[4:7], v91
	s_waitcnt lgkmcnt(0)
	s_waitcnt vmcnt(21)
	v_pk_add_f32 v[4:5], v[4:5], v[152:153]
	s_waitcnt vmcnt(21)
	v_pk_add_f32 v[6:7], v[6:7], v[154:155]
	ds_read_b128 v[8:11], v91 offset:64
	global_store_dwordx4 v[18:19], v[4:7], off
	s_waitcnt lgkmcnt(0)
	s_waitcnt vmcnt(21)
	v_pk_add_f32 v[8:9], v[8:9], v[156:157]
	v_cvt_pk_bf16_f32 v12, v4, v5
	v_pk_mul_f32 v[4:5], v[4:5], v[4:5]
	v_cvt_pk_bf16_f32 v13, v6, v7
	v_pk_mul_f32 v[6:7], v[6:7], v[6:7]
	v_add_f32_e32 v4, v4, v5
	s_waitcnt vmcnt(21)
	v_pk_add_f32 v[10:11], v[10:11], v[158:159]
	v_lshl_add_u64 v[14:15], v[16:17], 1, s[44:45]
	v_add_f32_e32 v4, v6, v4
	global_store_dwordx4 v[18:19], v[8:11], off offset:64
	global_store_dwordx2 v[14:15], v[12:13], off
	v_cvt_pk_bf16_f32 v12, v8, v9
	v_pk_mul_f32 v[8:9], v[8:9], v[8:9]
	v_add_f32_e32 v4, v7, v4
	v_add_f32_e32 v4, v8, v4
	v_cvt_pk_bf16_f32 v13, v10, v11
	v_pk_mul_f32 v[10:11], v[10:11], v[10:11]
	v_add_f32_e32 v4, v9, v4
	v_add_f32_e32 v4, v10, v4
	v_add_f32_e32 v4, v11, v4
	ds_bpermute_b32 v5, v0, v4
	global_store_dwordx2 v[14:15], v[12:13], off offset:32
	s_waitcnt lgkmcnt(0)
	v_add_f32_e32 v4, v4, v5
	ds_bpermute_b32 v5, v70, v4
	s_waitcnt lgkmcnt(0)
	v_add_f32_e32 v4, v4, v5
	ds_bpermute_b32 v5, v71, v4
	s_waitcnt lgkmcnt(0)
	v_add_f32_e32 v4, v4, v5
	ds_bpermute_b32 v5, v73, v4
	s_waitcnt lgkmcnt(0)
	v_add_f32_e32 v4, v4, v5
	ds_bpermute_b32 v5, v72, v4
	s_and_saveexec_b64 s[8:9], vcc
	s_cbranch_execz .LBB0_282
	s_waitcnt lgkmcnt(0)
	v_add_f32_e32 v4, v4, v5
	v_lshl_add_u64 v[2:3], v[2:3], 4, s[10:11]
	global_store_dword v[2:3], v4, off
.LBB0_282:
	s_or_b64 exec, exec, s[8:9]
	v_add_u32_e32 v2, s6, v94
	v_ashrrev_i32_e32 v3, 31, v2
	s_waitcnt lgkmcnt(0)
	v_lshlrev_b64 v[4:5], 10, v[2:3]
	v_lshl_add_u64 v[16:17], v[4:5], 0, v[66:67]
	v_lshl_add_u64 v[18:19], v[16:17], 2, s[26:27]
	ds_read_b128 v[4:7], v93
	s_waitcnt lgkmcnt(0)
	s_waitcnt vmcnt(24)
	v_pk_add_f32 v[4:5], v[4:5], v[160:161]
	s_waitcnt vmcnt(24)
	v_pk_add_f32 v[6:7], v[6:7], v[162:163]
	ds_read_b128 v[8:11], v93 offset:64
	global_store_dwordx4 v[18:19], v[4:7], off
	s_waitcnt lgkmcnt(0)
	s_waitcnt vmcnt(24)
	v_pk_add_f32 v[8:9], v[8:9], v[164:165]
	v_cvt_pk_bf16_f32 v12, v4, v5
	v_pk_mul_f32 v[4:5], v[4:5], v[4:5]
	v_cvt_pk_bf16_f32 v13, v6, v7
	v_pk_mul_f32 v[6:7], v[6:7], v[6:7]
	v_add_f32_e32 v4, v4, v5
	s_waitcnt vmcnt(24)
	v_pk_add_f32 v[10:11], v[10:11], v[166:167]
	v_lshl_add_u64 v[14:15], v[16:17], 1, s[44:45]
	v_add_f32_e32 v4, v6, v4
	global_store_dwordx4 v[18:19], v[8:11], off offset:64
	global_store_dwordx2 v[14:15], v[12:13], off
	v_cvt_pk_bf16_f32 v12, v8, v9
	v_pk_mul_f32 v[8:9], v[8:9], v[8:9]
	v_add_f32_e32 v4, v7, v4
	v_add_f32_e32 v4, v8, v4
	v_cvt_pk_bf16_f32 v13, v10, v11
	v_pk_mul_f32 v[10:11], v[10:11], v[10:11]
	v_add_f32_e32 v4, v9, v4
	v_add_f32_e32 v4, v10, v4
	v_add_f32_e32 v4, v11, v4
	ds_bpermute_b32 v5, v0, v4
	global_store_dwordx2 v[14:15], v[12:13], off offset:32
	s_waitcnt lgkmcnt(0)
	v_add_f32_e32 v4, v4, v5
	ds_bpermute_b32 v5, v70, v4
	s_waitcnt lgkmcnt(0)
	v_add_f32_e32 v4, v4, v5
	ds_bpermute_b32 v5, v71, v4
	s_waitcnt lgkmcnt(0)
	v_add_f32_e32 v4, v4, v5
	ds_bpermute_b32 v5, v73, v4
	s_waitcnt lgkmcnt(0)
	v_add_f32_e32 v4, v4, v5
	ds_bpermute_b32 v5, v72, v4
	s_and_saveexec_b64 s[8:9], vcc
	s_cbranch_execz .LBB0_284
	s_waitcnt lgkmcnt(0)
	v_add_f32_e32 v4, v4, v5
	v_lshl_add_u64 v[2:3], v[2:3], 4, s[10:11]
	global_store_dword v[2:3], v4, off
.LBB0_284:
	s_or_b64 exec, exec, s[8:9]
	v_add_u32_e32 v2, s6, v96
	v_ashrrev_i32_e32 v3, 31, v2
	s_waitcnt lgkmcnt(0)
	v_lshlrev_b64 v[4:5], 10, v[2:3]
	v_lshl_add_u64 v[16:17], v[4:5], 0, v[66:67]
	v_lshl_add_u64 v[18:19], v[16:17], 2, s[26:27]
	ds_read_b128 v[4:7], v95
	s_waitcnt lgkmcnt(0)
	s_waitcnt vmcnt(27)
	v_pk_add_f32 v[4:5], v[4:5], v[168:169]
	s_waitcnt vmcnt(27)
	v_pk_add_f32 v[6:7], v[6:7], v[170:171]
	ds_read_b128 v[8:11], v95 offset:64
	global_store_dwordx4 v[18:19], v[4:7], off
	s_waitcnt lgkmcnt(0)
	s_waitcnt vmcnt(27)
	v_pk_add_f32 v[8:9], v[8:9], v[172:173]
	v_cvt_pk_bf16_f32 v12, v4, v5
	v_pk_mul_f32 v[4:5], v[4:5], v[4:5]
	v_cvt_pk_bf16_f32 v13, v6, v7
	v_pk_mul_f32 v[6:7], v[6:7], v[6:7]
	v_add_f32_e32 v4, v4, v5
	s_waitcnt vmcnt(27)
	v_pk_add_f32 v[10:11], v[10:11], v[174:175]
	v_lshl_add_u64 v[14:15], v[16:17], 1, s[44:45]
	v_add_f32_e32 v4, v6, v4
	global_store_dwordx4 v[18:19], v[8:11], off offset:64
	global_store_dwordx2 v[14:15], v[12:13], off
	v_cvt_pk_bf16_f32 v12, v8, v9
	v_pk_mul_f32 v[8:9], v[8:9], v[8:9]
	v_add_f32_e32 v4, v7, v4
	v_add_f32_e32 v4, v8, v4
	v_cvt_pk_bf16_f32 v13, v10, v11
	v_pk_mul_f32 v[10:11], v[10:11], v[10:11]
	v_add_f32_e32 v4, v9, v4
	v_add_f32_e32 v4, v10, v4
	v_add_f32_e32 v4, v11, v4
	ds_bpermute_b32 v5, v0, v4
	global_store_dwordx2 v[14:15], v[12:13], off offset:32
	s_waitcnt lgkmcnt(0)
	v_add_f32_e32 v4, v4, v5
	ds_bpermute_b32 v5, v70, v4
	s_waitcnt lgkmcnt(0)
	v_add_f32_e32 v4, v4, v5
	ds_bpermute_b32 v5, v71, v4
	s_waitcnt lgkmcnt(0)
	v_add_f32_e32 v4, v4, v5
	ds_bpermute_b32 v5, v73, v4
	s_waitcnt lgkmcnt(0)
	v_add_f32_e32 v4, v4, v5
	ds_bpermute_b32 v5, v72, v4
	s_and_saveexec_b64 s[8:9], vcc
	s_cbranch_execz .LBB0_286
	s_waitcnt lgkmcnt(0)
	v_add_f32_e32 v4, v4, v5
	v_lshl_add_u64 v[2:3], v[2:3], 4, s[10:11]
	global_store_dword v[2:3], v4, off
.LBB0_286:
	s_or_b64 exec, exec, s[8:9]
	v_add_u32_e32 v2, s6, v98
	v_ashrrev_i32_e32 v3, 31, v2
	s_waitcnt lgkmcnt(0)
	v_lshlrev_b64 v[4:5], 10, v[2:3]
	v_lshl_add_u64 v[16:17], v[4:5], 0, v[66:67]
	v_lshl_add_u64 v[18:19], v[16:17], 2, s[26:27]
	ds_read_b128 v[4:7], v97
	s_waitcnt lgkmcnt(0)
	s_waitcnt vmcnt(30)
	v_pk_add_f32 v[4:5], v[4:5], v[176:177]
	s_waitcnt vmcnt(30)
	v_pk_add_f32 v[6:7], v[6:7], v[178:179]
	ds_read_b128 v[8:11], v97 offset:64
	global_store_dwordx4 v[18:19], v[4:7], off
	s_waitcnt lgkmcnt(0)
	s_waitcnt vmcnt(30)
	v_pk_add_f32 v[8:9], v[8:9], v[180:181]
	v_cvt_pk_bf16_f32 v12, v4, v5
	v_pk_mul_f32 v[4:5], v[4:5], v[4:5]
	v_cvt_pk_bf16_f32 v13, v6, v7
	v_pk_mul_f32 v[6:7], v[6:7], v[6:7]
	v_add_f32_e32 v4, v4, v5
	s_waitcnt vmcnt(30)
	v_pk_add_f32 v[10:11], v[10:11], v[182:183]
	v_lshl_add_u64 v[14:15], v[16:17], 1, s[44:45]
	v_add_f32_e32 v4, v6, v4
	global_store_dwordx4 v[18:19], v[8:11], off offset:64
	global_store_dwordx2 v[14:15], v[12:13], off
	v_cvt_pk_bf16_f32 v12, v8, v9
	v_pk_mul_f32 v[8:9], v[8:9], v[8:9]
	v_add_f32_e32 v4, v7, v4
	v_add_f32_e32 v4, v8, v4
	v_cvt_pk_bf16_f32 v13, v10, v11
	v_pk_mul_f32 v[10:11], v[10:11], v[10:11]
	v_add_f32_e32 v4, v9, v4
	v_add_f32_e32 v4, v10, v4
	v_add_f32_e32 v4, v11, v4
	ds_bpermute_b32 v5, v0, v4
	global_store_dwordx2 v[14:15], v[12:13], off offset:32
	s_waitcnt lgkmcnt(0)
	v_add_f32_e32 v4, v4, v5
	ds_bpermute_b32 v5, v70, v4
	s_waitcnt lgkmcnt(0)
	v_add_f32_e32 v4, v4, v5
	ds_bpermute_b32 v5, v71, v4
	s_waitcnt lgkmcnt(0)
	v_add_f32_e32 v4, v4, v5
	ds_bpermute_b32 v5, v73, v4
	s_waitcnt lgkmcnt(0)
	v_add_f32_e32 v4, v4, v5
	ds_bpermute_b32 v5, v72, v4
	s_and_saveexec_b64 s[8:9], vcc
	s_cbranch_execz .LBB0_288
	s_waitcnt lgkmcnt(0)
	v_add_f32_e32 v4, v4, v5
	v_lshl_add_u64 v[2:3], v[2:3], 4, s[10:11]
	global_store_dword v[2:3], v4, off
.LBB0_288:
	s_or_b64 exec, exec, s[8:9]
	v_add_u32_e32 v2, s6, v100
	v_ashrrev_i32_e32 v3, 31, v2
	s_waitcnt lgkmcnt(0)
	v_lshlrev_b64 v[4:5], 10, v[2:3]
	v_lshl_add_u64 v[16:17], v[4:5], 0, v[66:67]
	v_lshl_add_u64 v[18:19], v[16:17], 2, s[26:27]
	ds_read_b128 v[4:7], v99
	s_waitcnt lgkmcnt(0)
	s_waitcnt vmcnt(33)
	v_pk_add_f32 v[4:5], v[4:5], v[184:185]
	s_waitcnt vmcnt(33)
	v_pk_add_f32 v[6:7], v[6:7], v[186:187]
	ds_read_b128 v[8:11], v99 offset:64
	global_store_dwordx4 v[18:19], v[4:7], off
	s_waitcnt lgkmcnt(0)
	s_waitcnt vmcnt(33)
	v_pk_add_f32 v[8:9], v[8:9], v[188:189]
	v_cvt_pk_bf16_f32 v12, v4, v5
	v_pk_mul_f32 v[4:5], v[4:5], v[4:5]
	v_cvt_pk_bf16_f32 v13, v6, v7
	v_pk_mul_f32 v[6:7], v[6:7], v[6:7]
	v_add_f32_e32 v4, v4, v5
	s_waitcnt vmcnt(33)
	v_pk_add_f32 v[10:11], v[10:11], v[190:191]
	v_lshl_add_u64 v[14:15], v[16:17], 1, s[44:45]
	v_add_f32_e32 v4, v6, v4
	global_store_dwordx4 v[18:19], v[8:11], off offset:64
	global_store_dwordx2 v[14:15], v[12:13], off
	v_cvt_pk_bf16_f32 v12, v8, v9
	v_pk_mul_f32 v[8:9], v[8:9], v[8:9]
	v_add_f32_e32 v4, v7, v4
	v_add_f32_e32 v4, v8, v4
	v_cvt_pk_bf16_f32 v13, v10, v11
	v_pk_mul_f32 v[10:11], v[10:11], v[10:11]
	v_add_f32_e32 v4, v9, v4
	v_add_f32_e32 v4, v10, v4
	v_add_f32_e32 v4, v11, v4
	ds_bpermute_b32 v5, v0, v4
	global_store_dwordx2 v[14:15], v[12:13], off offset:32
	s_waitcnt lgkmcnt(0)
	v_add_f32_e32 v4, v4, v5
	ds_bpermute_b32 v5, v70, v4
	s_waitcnt lgkmcnt(0)
	v_add_f32_e32 v4, v4, v5
	ds_bpermute_b32 v5, v71, v4
	s_waitcnt lgkmcnt(0)
	v_add_f32_e32 v4, v4, v5
	ds_bpermute_b32 v5, v73, v4
	s_waitcnt lgkmcnt(0)
	v_add_f32_e32 v4, v4, v5
	ds_bpermute_b32 v5, v72, v4
	s_and_saveexec_b64 s[8:9], vcc
	s_cbranch_execz .LBB0_290
	s_waitcnt lgkmcnt(0)
	v_add_f32_e32 v4, v4, v5
	v_lshl_add_u64 v[2:3], v[2:3], 4, s[10:11]
	global_store_dword v[2:3], v4, off
.LBB0_290:
	s_or_b64 exec, exec, s[8:9]
	v_add_u32_e32 v2, s6, v102
	v_ashrrev_i32_e32 v3, 31, v2
	s_waitcnt lgkmcnt(0)
	v_lshlrev_b64 v[4:5], 10, v[2:3]
	v_lshl_add_u64 v[16:17], v[4:5], 0, v[66:67]
	v_lshl_add_u64 v[18:19], v[16:17], 2, s[26:27]
	ds_read_b128 v[4:7], v101
	s_waitcnt lgkmcnt(0)
	s_waitcnt vmcnt(36)
	v_pk_add_f32 v[4:5], v[4:5], v[192:193]
	s_waitcnt vmcnt(36)
	v_pk_add_f32 v[6:7], v[6:7], v[194:195]
	ds_read_b128 v[8:11], v101 offset:64
	global_store_dwordx4 v[18:19], v[4:7], off
	s_waitcnt lgkmcnt(0)
	s_waitcnt vmcnt(36)
	v_pk_add_f32 v[8:9], v[8:9], v[196:197]
	v_cvt_pk_bf16_f32 v12, v4, v5
	v_pk_mul_f32 v[4:5], v[4:5], v[4:5]
	v_cvt_pk_bf16_f32 v13, v6, v7
	v_pk_mul_f32 v[6:7], v[6:7], v[6:7]
	v_add_f32_e32 v4, v4, v5
	s_waitcnt vmcnt(36)
	v_pk_add_f32 v[10:11], v[10:11], v[198:199]
	v_lshl_add_u64 v[14:15], v[16:17], 1, s[44:45]
	v_add_f32_e32 v4, v6, v4
	global_store_dwordx4 v[18:19], v[8:11], off offset:64
	global_store_dwordx2 v[14:15], v[12:13], off
	v_cvt_pk_bf16_f32 v12, v8, v9
	v_pk_mul_f32 v[8:9], v[8:9], v[8:9]
	v_add_f32_e32 v4, v7, v4
	v_add_f32_e32 v4, v8, v4
	v_cvt_pk_bf16_f32 v13, v10, v11
	v_pk_mul_f32 v[10:11], v[10:11], v[10:11]
	v_add_f32_e32 v4, v9, v4
	v_add_f32_e32 v4, v10, v4
	v_add_f32_e32 v4, v11, v4
	ds_bpermute_b32 v0, v0, v4
	global_store_dwordx2 v[14:15], v[12:13], off offset:32
	s_waitcnt lgkmcnt(0)
	v_add_f32_e32 v0, v4, v0
	ds_bpermute_b32 v4, v70, v0
	s_waitcnt lgkmcnt(0)
	v_add_f32_e32 v0, v0, v4
	ds_bpermute_b32 v4, v71, v0
	s_waitcnt lgkmcnt(0)
	v_add_f32_e32 v0, v0, v4
	ds_bpermute_b32 v4, v73, v0
	s_waitcnt lgkmcnt(0)
	v_add_f32_e32 v0, v0, v4
	ds_bpermute_b32 v4, v72, v0
	s_and_saveexec_b64 s[6:7], vcc
	s_cbranch_execz .LBB0_292
	s_waitcnt lgkmcnt(0)
	v_add_f32_e32 v0, v0, v4
	v_lshl_add_u64 v[2:3], v[2:3], 4, s[10:11]
	global_store_dword v[2:3], v0, off

.LBB0_417:
	s_or_b64 exec, exec, s[6:7]
	s_movk_i32 s7, 0x410
	v_lshrrev_b32_e32 v130, 2, v142
	v_lshlrev_b32_e32 v131, 1, v142
	v_and_b32_e32 v0, 15, v142
	v_and_b32_e32 v130, 0xfffffcc, v130
	v_and_b32_e32 v131, 0x180, v131
	v_add_u32_e32 v131, 0, v131
	v_lshlrev_b32_e32 v0, 2, v0
	v_mul_lo_u32 v130, v130, s7
	v_add3_u32 v130, v131, v0, v130
	s_waitcnt vmcnt(0)
	s_barrier
	ds_write2_b32 v130, v114, v126 offset1:16
	v_add_u32_e32 v114, 0x400, v130
	ds_write2_b32 v114, v115, v127 offset0:4 offset1:20
	v_add_u32_e32 v115, 0x800, v130
	ds_write2_b32 v115, v116, v128 offset0:8 offset1:24
	v_add_u32_e32 v116, 0xc00, v130
	ds_write2_b32 v116, v117, v129 offset0:12 offset1:28
	v_add_u32_e32 v117, 0x4000, v130
	ds_write2_b32 v117, v82, v94 offset0:64 offset1:80
	v_add_u32_e32 v82, 0x4400, v130
	ds_write2_b32 v82, v83, v95 offset0:68 offset1:84
	v_add_u32_e32 v83, 0x4800, v130
	ds_write2_b32 v83, v84, v96 offset0:72 offset1:88
	v_add_u32_e32 v84, 0x4c00, v130
	ds_write2_b32 v84, v85, v97 offset0:76 offset1:92
	v_add_u32_e32 v85, 0x8000, v130
	ds_write2_b32 v85, v74, v78 offset0:128 offset1:144
	v_add_u32_e32 v74, 0x8400, v130
	ds_write2_b32 v74, v75, v79 offset0:132 offset1:148
	v_add_u32_e32 v75, 0x8800, v130
	ds_write2_b32 v75, v76, v80 offset0:136 offset1:152
	v_add_u32_e32 v76, 0x8c00, v130
	v_add_u32_e32 v80, 0xc000, v130
	ds_write2_b32 v76, v77, v81 offset0:140 offset1:156
	ds_write2_b32 v80, v66, v70 offset0:192 offset1:208
	v_add_u32_e32 v77, 0xc400, v130
	v_add_u32_e32 v78, 0xc800, v130
	v_add_u32_e32 v79, 0xcc00, v130
	v_add_u32_e32 v81, 0x9000, v130
	v_lshlrev_b32_e32 v66, 2, v142
	ds_write2_b32 v77, v67, v71 offset0:196 offset1:212
	ds_write2_b32 v78, v68, v72 offset0:200 offset1:216
	ds_write2_b32 v79, v69, v73 offset0:204 offset1:220
	ds_write2_b32 v130, v98, v118 offset0:128 offset1:144
	ds_write2_b32 v114, v99, v119 offset0:132 offset1:148
	ds_write2_b32 v115, v100, v120 offset0:136 offset1:152
	ds_write2_b32 v116, v101, v121 offset0:140 offset1:156
	ds_write2_b32 v117, v102, v122 offset0:192 offset1:208
	ds_write2_b32 v82, v103, v123 offset0:196 offset1:212
	ds_write2_b32 v83, v104, v124 offset0:200 offset1:216
	ds_write2_b32 v84, v105, v125 offset0:204 offset1:220
	ds_write2_b32 v74, v90, v110 offset1:16
	ds_write2_b32 v75, v91, v111 offset0:4 offset1:20
	ds_write2_b32 v76, v92, v112 offset0:8 offset1:24
	ds_write2_b32 v81, v93, v113 offset0:12 offset1:28
	ds_write2_b32 v77, v86, v106 offset0:64 offset1:80
	ds_write2_b32 v78, v87, v107 offset0:68 offset1:84
	ds_write2_b32 v79, v88, v108 offset0:72 offset1:88
	v_lshlrev_b32_e32 v0, 3, v142
	v_and_b32_e32 v66, 12, v66
	s_movk_i32 s6, 0xe0
	v_ashrrev_i32_e32 v87, 5, v142
	v_and_or_b32 v0, v0, s6, v66
	v_add_u32_e32 v68, s15, v87
	v_or_b32_e32 v66, s36, v0
	v_ashrrev_i32_e32 v69, 31, v68
	v_ashrrev_i32_e32 v67, 31, v66
	v_lshlrev_b64 v[70:71], 10, v[68:69]
	v_lshl_add_u64 v[98:99], v[70:71], 0, v[66:67]
	v_add_u32_e32 v86, 0xd000, v130
	v_lshl_add_u64 v[110:111], v[98:99], 2, s[26:27]
	ds_write2_b32 v86, v89, v109 offset0:76 offset1:92
	s_waitcnt lgkmcnt(0)
	s_barrier
	v_lshlrev_b32_e32 v140, 2, v98
	global_load_dwordx4 v[132:135], v140, s[26:27]
	global_load_dwordx4 v[136:139], v140, s[26:27] offset:64
	v_add_u32_e32 v140, 0x10000, v140
	global_load_dwordx4 v[144:147], v140, s[26:27]
	global_load_dwordx4 v[148:151], v140, s[26:27] offset:64
	v_add_u32_e32 v140, 0x10000, v140
	global_load_dwordx4 v[152:155], v140, s[26:27]
	global_load_dwordx4 v[156:159], v140, s[26:27] offset:64
	v_add_u32_e32 v140, 0x10000, v140
	global_load_dwordx4 v[160:163], v140, s[26:27]
	global_load_dwordx4 v[164:167], v140, s[26:27] offset:64
	v_add_u32_e32 v140, 0x10000, v140
	global_load_dwordx4 v[168:171], v140, s[26:27]
	global_load_dwordx4 v[172:175], v140, s[26:27] offset:64
	v_add_u32_e32 v140, 0x10000, v140
	global_load_dwordx4 v[176:179], v140, s[26:27]
	global_load_dwordx4 v[180:183], v140, s[26:27] offset:64
	v_add_u32_e32 v140, 0x10000, v140
	global_load_dwordx4 v[184:187], v140, s[26:27]
	global_load_dwordx4 v[188:191], v140, s[26:27] offset:64
	v_add_u32_e32 v140, 0x10000, v140
	global_load_dwordx4 v[192:195], v140, s[26:27]
	global_load_dwordx4 v[196:199], v140, s[26:27] offset:64
	v_lshl_add_u32 v101, v0, 2, 0
	v_mul_lo_u32 v72, v87, s7
	v_add_u32_e32 v88, v101, v72
	ds_read_b128 v[102:105], v88
	ds_read_b128 v[106:109], v88 offset:64
	v_and_b32_e32 v70, 64, v218
	v_xor_b32_e32 v0, 1, v218
	v_add_u32_e32 v100, 64, v70
	v_cmp_lt_i32_e32 vcc, v0, v100
	v_xor_b32_e32 v70, 2, v218
	v_xor_b32_e32 v71, 4, v218
	v_cndmask_b32_e32 v0, v218, v0, vcc
	v_lshlrev_b32_e32 v0, 2, v0
	v_cmp_lt_i32_e32 vcc, v70, v100
	v_xor_b32_e32 v112, 8, v218
	v_and_b32_e32 v89, 31, v142
	v_cndmask_b32_e32 v70, v218, v70, vcc
	v_lshlrev_b32_e32 v70, 2, v70
	v_cmp_lt_i32_e32 vcc, v71, v100
	s_ashr_i32 s57, s56, 31
	s_lshl_b64 s[6:7], s[56:57], 2
	v_cndmask_b32_e32 v71, v218, v71, vcc
	v_cmp_lt_i32_e32 vcc, v112, v100
	v_lshlrev_b32_e32 v71, 2, v71
	s_add_u32 s6, s46, s6
	s_movk_i32 s12, 0x410
	s_addc_u32 s7, s47, s7
	s_waitcnt lgkmcnt(1)
	s_waitcnt vmcnt(15)
	v_pk_add_f32 v[90:91], v[102:103], v[132:133]
	s_waitcnt vmcnt(15)
	v_pk_add_f32 v[92:93], v[104:105], v[134:135]
	v_pk_mul_f32 v[72:73], v[90:91], v[90:91]
	v_pk_mul_f32 v[102:103], v[92:93], v[92:93]
	v_add_f32_e32 v72, v72, v73
	s_waitcnt lgkmcnt(0)
	s_waitcnt vmcnt(14)
	v_pk_add_f32 v[94:95], v[106:107], v[136:137]
	v_add_f32_e32 v72, v102, v72
	v_pk_mul_f32 v[104:105], v[94:95], v[94:95]
	v_add_f32_e32 v72, v103, v72
	s_waitcnt vmcnt(14)
	v_pk_add_f32 v[96:97], v[108:109], v[138:139]
	v_add_f32_e32 v72, v104, v72
	v_pk_mul_f32 v[106:107], v[96:97], v[96:97]
	v_add_f32_e32 v72, v105, v72
	v_add_f32_e32 v72, v106, v72
	v_add_f32_e32 v72, v107, v72
	ds_bpermute_b32 v102, v0, v72
	v_xor_b32_e32 v103, 16, v218
	v_cndmask_b32_e32 v73, v218, v112, vcc
	v_cmp_lt_i32_e32 vcc, v103, v100
	v_lshlrev_b32_e32 v73, 2, v73
	s_waitcnt lgkmcnt(0)
	v_add_f32_e32 v102, v72, v102
	ds_bpermute_b32 v104, v70, v102
	v_cndmask_b32_e32 v72, v218, v103, vcc
	v_cmp_eq_u32_e32 vcc, 0, v89
	v_lshlrev_b32_e32 v72, 2, v72
	global_store_dwordx4 v[110:111], v[90:93], off
	s_waitcnt lgkmcnt(0)
	v_add_f32_e32 v89, v102, v104
	ds_bpermute_b32 v100, v71, v89
	v_cvt_pk_bf16_f32 v102, v90, v91
	global_store_dwordx4 v[110:111], v[94:97], off offset:64
	v_cvt_pk_bf16_f32 v103, v92, v93
	v_lshl_add_u64 v[92:93], v[98:99], 1, s[44:45]
	s_waitcnt lgkmcnt(0)
	v_add_f32_e32 v89, v89, v100
	ds_bpermute_b32 v100, v73, v89
	v_cvt_pk_bf16_f32 v94, v94, v95
	v_cvt_pk_bf16_f32 v95, v96, v97
	global_store_dwordx2 v[92:93], v[102:103], off
	global_store_dwordx2 v[92:93], v[94:95], off offset:32
	s_waitcnt lgkmcnt(0)
	v_add_f32_e32 v89, v89, v100
	ds_bpermute_b32 v90, v72, v89
	s_and_saveexec_b64 s[8:9], vcc
	s_cbranch_execz .LBB0_419
	s_waitcnt lgkmcnt(0)
	v_add_f32_e32 v89, v89, v90
	v_lshl_add_u64 v[68:69], v[68:69], 4, s[6:7]
	global_store_dword v[68:69], v89, off
.LBB0_419:
	s_or_b64 exec, exec, s[8:9]
	v_add_u32_e32 v68, 0x200, v142
	s_waitcnt lgkmcnt(0)
	v_ashrrev_i32_e32 v90, 5, v68
	v_mul_lo_u32 v68, v90, s12
	v_add_u32_e32 v89, v101, v68
	v_add_u32_e32 v68, s15, v90
	v_ashrrev_i32_e32 v69, 31, v68
	v_lshlrev_b64 v[92:93], 10, v[68:69]
	v_lshl_add_u64 v[106:107], v[92:93], 0, v[66:67]
	v_lshl_add_u64 v[108:109], v[106:107], 2, s[26:27]
	ds_read_b128 v[92:95], v89
	s_waitcnt lgkmcnt(0)
	s_waitcnt vmcnt(18)
	v_pk_add_f32 v[92:93], v[92:93], v[144:145]
	s_waitcnt vmcnt(18)
	v_pk_add_f32 v[94:95], v[94:95], v[146:147]
	ds_read_b128 v[96:99], v89 offset:64
	global_store_dwordx4 v[108:109], v[92:95], off
	s_waitcnt lgkmcnt(0)
	s_waitcnt vmcnt(18)
	v_pk_add_f32 v[96:97], v[96:97], v[148:149]
	v_cvt_pk_bf16_f32 v102, v92, v93
	v_pk_mul_f32 v[92:93], v[92:93], v[92:93]
	v_cvt_pk_bf16_f32 v103, v94, v95
	v_pk_mul_f32 v[94:95], v[94:95], v[94:95]
	v_add_f32_e32 v91, v92, v93
	s_waitcnt vmcnt(18)
	v_pk_add_f32 v[98:99], v[98:99], v[150:151]
	v_lshl_add_u64 v[104:105], v[106:107], 1, s[44:45]
	v_add_f32_e32 v91, v94, v91
	global_store_dwordx4 v[108:109], v[96:99], off offset:64
	global_store_dwordx2 v[104:105], v[102:103], off
	v_cvt_pk_bf16_f32 v102, v96, v97
	v_pk_mul_f32 v[96:97], v[96:97], v[96:97]
	v_add_f32_e32 v91, v95, v91
	v_add_f32_e32 v91, v96, v91
	v_cvt_pk_bf16_f32 v103, v98, v99
	v_pk_mul_f32 v[98:99], v[98:99], v[98:99]
	v_add_f32_e32 v91, v97, v91
	v_add_f32_e32 v91, v98, v91
	v_add_f32_e32 v91, v99, v91
	ds_bpermute_b32 v92, v0, v91
	global_store_dwordx2 v[104:105], v[102:103], off offset:32
	s_waitcnt lgkmcnt(0)
	v_add_f32_e32 v91, v91, v92
	ds_bpermute_b32 v92, v70, v91
	s_waitcnt lgkmcnt(0)
	v_add_f32_e32 v91, v91, v92
	ds_bpermute_b32 v92, v71, v91
	s_waitcnt lgkmcnt(0)
	v_add_f32_e32 v91, v91, v92
	ds_bpermute_b32 v92, v73, v91
	s_waitcnt lgkmcnt(0)
	v_add_f32_e32 v91, v91, v92
	ds_bpermute_b32 v92, v72, v91
	s_and_saveexec_b64 s[8:9], vcc
	s_cbranch_execz .LBB0_421
	s_waitcnt lgkmcnt(0)
	v_add_f32_e32 v91, v91, v92
	v_lshl_add_u64 v[68:69], v[68:69], 4, s[6:7]
	global_store_dword v[68:69], v91, off
.LBB0_421:
	s_or_b64 exec, exec, s[8:9]
	v_add_u32_e32 v68, 0x400, v142
	s_waitcnt lgkmcnt(0)
	v_ashrrev_i32_e32 v92, 5, v68
	v_mul_lo_u32 v68, v92, s12
	v_add_u32_e32 v91, v101, v68
	v_add_u32_e32 v68, s15, v92
	v_ashrrev_i32_e32 v69, 31, v68
	v_lshlrev_b64 v[94:95], 10, v[68:69]
	v_lshl_add_u64 v[98:99], v[94:95], 0, v[66:67]
	v_lshl_add_u64 v[110:111], v[98:99], 2, s[26:27]
	ds_read_b128 v[94:97], v91
	v_lshl_add_u64 v[98:99], v[98:99], 1, s[44:45]
	s_waitcnt lgkmcnt(0)
	s_waitcnt vmcnt(21)
	v_pk_add_f32 v[94:95], v[94:95], v[152:153]
	s_waitcnt vmcnt(21)
	v_pk_add_f32 v[96:97], v[96:97], v[154:155]
	ds_read_b128 v[102:105], v91 offset:64
	global_store_dwordx4 v[110:111], v[94:97], off
	s_waitcnt lgkmcnt(0)
	s_waitcnt vmcnt(21)
	v_pk_add_f32 v[102:103], v[102:103], v[156:157]
	v_cvt_pk_bf16_f32 v106, v94, v95
	v_pk_mul_f32 v[94:95], v[94:95], v[94:95]
	s_waitcnt vmcnt(21)
	v_pk_add_f32 v[104:105], v[104:105], v[158:159]
	v_cvt_pk_bf16_f32 v107, v96, v97
	v_pk_mul_f32 v[96:97], v[96:97], v[96:97]
	v_add_f32_e32 v93, v94, v95
	global_store_dwordx4 v[110:111], v[102:105], off offset:64
	global_store_dwordx2 v[98:99], v[106:107], off
	v_cvt_pk_bf16_f32 v106, v102, v103
	v_cvt_pk_bf16_f32 v107, v104, v105
	v_add_f32_e32 v93, v96, v93
	global_store_dwordx2 v[98:99], v[106:107], off offset:32
	v_pk_mul_f32 v[98:99], v[102:103], v[102:103]
	v_add_f32_e32 v93, v97, v93
	v_add_f32_e32 v93, v98, v93
	v_pk_mul_f32 v[102:103], v[104:105], v[104:105]
	v_add_f32_e32 v93, v99, v93
	v_add_f32_e32 v93, v102, v93
	v_add_f32_e32 v93, v103, v93
	ds_bpermute_b32 v94, v0, v93
	s_waitcnt lgkmcnt(0)
	v_add_f32_e32 v93, v93, v94
	ds_bpermute_b32 v94, v70, v93
	s_waitcnt lgkmcnt(0)
	v_add_f32_e32 v93, v93, v94
	ds_bpermute_b32 v94, v71, v93
	s_waitcnt lgkmcnt(0)
	v_add_f32_e32 v93, v93, v94
	ds_bpermute_b32 v94, v73, v93
	s_waitcnt lgkmcnt(0)
	v_add_f32_e32 v93, v93, v94
	ds_bpermute_b32 v94, v72, v93
	s_and_saveexec_b64 s[8:9], vcc
	s_cbranch_execz .LBB0_423
	s_waitcnt lgkmcnt(0)
	v_add_f32_e32 v93, v93, v94
	v_lshl_add_u64 v[68:69], v[68:69], 4, s[6:7]
	global_store_dword v[68:69], v93, off
.LBB0_423:
	s_or_b64 exec, exec, s[8:9]
	v_add_u32_e32 v68, 0x600, v142
	s_waitcnt lgkmcnt(0)
	v_ashrrev_i32_e32 v94, 5, v68
	v_mul_lo_u32 v68, v94, s12
	v_add_u32_e32 v93, v101, v68
	v_add_u32_e32 v68, s15, v94
	v_ashrrev_i32_e32 v69, 31, v68
	v_lshlrev_b64 v[96:97], 10, v[68:69]
	v_lshl_add_u64 v[110:111], v[96:97], 0, v[66:67]
	v_lshl_add_u64 v[112:113], v[110:111], 2, s[26:27]
	ds_read_b128 v[96:99], v93
	s_waitcnt lgkmcnt(0)
	s_waitcnt vmcnt(24)
	v_pk_add_f32 v[96:97], v[96:97], v[160:161]
	s_waitcnt vmcnt(24)
	v_pk_add_f32 v[98:99], v[98:99], v[162:163]
	ds_read_b128 v[102:105], v93 offset:64
	global_store_dwordx4 v[112:113], v[96:99], off
	s_waitcnt lgkmcnt(0)
	s_waitcnt vmcnt(24)
	v_pk_add_f32 v[102:103], v[102:103], v[164:165]
	v_cvt_pk_bf16_f32 v106, v96, v97
	v_pk_mul_f32 v[96:97], v[96:97], v[96:97]
	v_cvt_pk_bf16_f32 v107, v98, v99
	v_pk_mul_f32 v[98:99], v[98:99], v[98:99]
	v_add_f32_e32 v95, v96, v97
	s_waitcnt vmcnt(24)
	v_pk_add_f32 v[104:105], v[104:105], v[166:167]
	v_lshl_add_u64 v[108:109], v[110:111], 1, s[44:45]
	v_add_f32_e32 v95, v98, v95
	global_store_dwordx4 v[112:113], v[102:105], off offset:64
	global_store_dwordx2 v[108:109], v[106:107], off
	v_cvt_pk_bf16_f32 v106, v102, v103
	v_pk_mul_f32 v[102:103], v[102:103], v[102:103]
	v_add_f32_e32 v95, v99, v95
	v_add_f32_e32 v95, v102, v95
	v_cvt_pk_bf16_f32 v107, v104, v105
	v_pk_mul_f32 v[104:105], v[104:105], v[104:105]
	v_add_f32_e32 v95, v103, v95
	v_add_f32_e32 v95, v104, v95
	v_add_f32_e32 v95, v105, v95
	ds_bpermute_b32 v96, v0, v95
	global_store_dwordx2 v[108:109], v[106:107], off offset:32
	s_waitcnt lgkmcnt(0)
	v_add_f32_e32 v95, v95, v96
	ds_bpermute_b32 v96, v70, v95
	s_waitcnt lgkmcnt(0)
	v_add_f32_e32 v95, v95, v96
	ds_bpermute_b32 v96, v71, v95
	s_waitcnt lgkmcnt(0)
	v_add_f32_e32 v95, v95, v96
	ds_bpermute_b32 v96, v73, v95
	s_waitcnt lgkmcnt(0)
	v_add_f32_e32 v95, v95, v96
	ds_bpermute_b32 v96, v72, v95
	s_and_saveexec_b64 s[8:9], vcc
	s_cbranch_execz .LBB0_425
	s_waitcnt lgkmcnt(0)
	v_add_f32_e32 v95, v95, v96
	v_lshl_add_u64 v[68:69], v[68:69], 4, s[6:7]
	global_store_dword v[68:69], v95, off
.LBB0_425:
	s_or_b64 exec, exec, s[8:9]
	v_add_u32_e32 v68, 0x800, v142
	s_waitcnt lgkmcnt(0)
	v_ashrrev_i32_e32 v96, 5, v68
	v_mul_lo_u32 v68, v96, s12
	v_add_u32_e32 v95, v101, v68
	v_add_u32_e32 v68, s15, v96
	v_ashrrev_i32_e32 v69, 31, v68
	v_lshlrev_b64 v[98:99], 10, v[68:69]
	v_lshl_add_u64 v[98:99], v[98:99], 0, v[66:67]
	v_lshl_add_u64 v[118:119], v[98:99], 2, s[26:27]
	ds_read_b128 v[102:105], v95
	v_lshl_add_u64 v[98:99], v[98:99], 1, s[44:45]
	s_waitcnt lgkmcnt(0)
	s_waitcnt vmcnt(27)
	v_pk_add_f32 v[102:103], v[102:103], v[168:169]
	s_waitcnt vmcnt(27)
	v_pk_add_f32 v[104:105], v[104:105], v[170:171]
	ds_read_b128 v[106:109], v95 offset:64
	global_store_dwordx4 v[118:119], v[102:105], off
	s_waitcnt lgkmcnt(0)
	s_waitcnt vmcnt(27)
	v_pk_add_f32 v[106:107], v[106:107], v[172:173]
	s_waitcnt vmcnt(27)
	v_pk_add_f32 v[108:109], v[108:109], v[174:175]
	v_cvt_pk_bf16_f32 v110, v102, v103
	v_cvt_pk_bf16_f32 v111, v104, v105
	global_store_dwordx4 v[118:119], v[106:109], off offset:64
	global_store_dwordx2 v[98:99], v[110:111], off
	v_cvt_pk_bf16_f32 v110, v106, v107
	v_cvt_pk_bf16_f32 v111, v108, v109
	global_store_dwordx2 v[98:99], v[110:111], off offset:32
	v_pk_mul_f32 v[98:99], v[102:103], v[102:103]
	v_pk_mul_f32 v[102:103], v[104:105], v[104:105]
	v_add_f32_e32 v97, v98, v99
	v_add_f32_e32 v97, v102, v97
	v_pk_mul_f32 v[104:105], v[106:107], v[106:107]
	v_add_f32_e32 v97, v103, v97
	v_add_f32_e32 v97, v104, v97
	v_pk_mul_f32 v[106:107], v[108:109], v[108:109]
	v_add_f32_e32 v97, v105, v97
	v_add_f32_e32 v97, v106, v97
	v_add_f32_e32 v97, v107, v97
	ds_bpermute_b32 v98, v0, v97
	s_waitcnt lgkmcnt(0)
	v_add_f32_e32 v97, v97, v98
	ds_bpermute_b32 v98, v70, v97
	s_waitcnt lgkmcnt(0)
	v_add_f32_e32 v97, v97, v98
	ds_bpermute_b32 v98, v71, v97
	s_waitcnt lgkmcnt(0)
	v_add_f32_e32 v97, v97, v98
	ds_bpermute_b32 v98, v73, v97
	s_waitcnt lgkmcnt(0)
	v_add_f32_e32 v97, v97, v98
	ds_bpermute_b32 v98, v72, v97
	s_and_saveexec_b64 s[8:9], vcc
	s_cbranch_execz .LBB0_427
	s_waitcnt lgkmcnt(0)
	v_add_f32_e32 v97, v97, v98
	v_lshl_add_u64 v[68:69], v[68:69], 4, s[6:7]
	global_store_dword v[68:69], v97, off
.LBB0_427:
	s_or_b64 exec, exec, s[8:9]
	v_add_u32_e32 v68, 0xa00, v142
	s_waitcnt lgkmcnt(0)
	v_ashrrev_i32_e32 v98, 5, v68
	v_mul_lo_u32 v68, v98, s12
	v_add_u32_e32 v97, v101, v68
	v_add_u32_e32 v68, s15, v98
	v_ashrrev_i32_e32 v69, 31, v68
	v_lshlrev_b64 v[102:103], 10, v[68:69]
	v_lshl_add_u64 v[118:119], v[102:103], 0, v[66:67]
	v_lshl_add_u64 v[120:121], v[118:119], 2, s[26:27]
	ds_read_b128 v[102:105], v97
	s_waitcnt lgkmcnt(0)
	s_waitcnt vmcnt(30)
	v_pk_add_f32 v[102:103], v[102:103], v[176:177]
	s_waitcnt vmcnt(30)
	v_pk_add_f32 v[104:105], v[104:105], v[178:179]
	ds_read_b128 v[106:109], v97 offset:64
	global_store_dwordx4 v[120:121], v[102:105], off
	s_waitcnt lgkmcnt(0)
	s_waitcnt vmcnt(30)
	v_pk_add_f32 v[106:107], v[106:107], v[180:181]
	v_cvt_pk_bf16_f32 v110, v102, v103
	v_pk_mul_f32 v[102:103], v[102:103], v[102:103]
	v_cvt_pk_bf16_f32 v111, v104, v105
	v_pk_mul_f32 v[104:105], v[104:105], v[104:105]
	v_add_f32_e32 v99, v102, v103
	s_waitcnt vmcnt(30)
	v_pk_add_f32 v[108:109], v[108:109], v[182:183]
	v_lshl_add_u64 v[112:113], v[118:119], 1, s[44:45]
	v_add_f32_e32 v99, v104, v99
	global_store_dwordx4 v[120:121], v[106:109], off offset:64
	global_store_dwordx2 v[112:113], v[110:111], off
	v_cvt_pk_bf16_f32 v110, v106, v107
	v_pk_mul_f32 v[106:107], v[106:107], v[106:107]
	v_add_f32_e32 v99, v105, v99
	v_add_f32_e32 v99, v106, v99
	v_cvt_pk_bf16_f32 v111, v108, v109
	v_pk_mul_f32 v[108:109], v[108:109], v[108:109]
	v_add_f32_e32 v99, v107, v99
	v_add_f32_e32 v99, v108, v99
	v_add_f32_e32 v99, v109, v99
	ds_bpermute_b32 v100, v0, v99
	global_store_dwordx2 v[112:113], v[110:111], off offset:32
	s_waitcnt lgkmcnt(0)
	v_add_f32_e32 v99, v99, v100
	ds_bpermute_b32 v100, v70, v99
	s_waitcnt lgkmcnt(0)
	v_add_f32_e32 v99, v99, v100
	ds_bpermute_b32 v100, v71, v99
	s_waitcnt lgkmcnt(0)
	v_add_f32_e32 v99, v99, v100
	ds_bpermute_b32 v100, v73, v99
	s_waitcnt lgkmcnt(0)
	v_add_f32_e32 v99, v99, v100
	ds_bpermute_b32 v100, v72, v99
	s_and_saveexec_b64 s[8:9], vcc
	s_cbranch_execz .LBB0_429
	s_waitcnt lgkmcnt(0)
	v_add_f32_e32 v99, v99, v100
	v_lshl_add_u64 v[68:69], v[68:69], 4, s[6:7]
	global_store_dword v[68:69], v99, off
.LBB0_429:
	s_or_b64 exec, exec, s[8:9]
	v_add_u32_e32 v68, 0xc00, v142
	s_waitcnt lgkmcnt(0)
	v_ashrrev_i32_e32 v100, 5, v68
	v_mul_lo_u32 v68, v100, s12
	v_add_u32_e32 v99, v101, v68
	v_add_u32_e32 v68, s15, v100
	v_ashrrev_i32_e32 v69, 31, v68
	v_lshlrev_b64 v[102:103], 10, v[68:69]
	v_lshl_add_u64 v[118:119], v[102:103], 0, v[66:67]
	v_lshl_add_u64 v[120:121], v[118:119], 2, s[26:27]
	ds_read_b128 v[102:105], v99
	s_waitcnt lgkmcnt(0)
	s_waitcnt vmcnt(33)
	v_pk_add_f32 v[102:103], v[102:103], v[184:185]
	s_waitcnt vmcnt(33)
	v_pk_add_f32 v[104:105], v[104:105], v[186:187]
	ds_read_b128 v[106:109], v99 offset:64
	global_store_dwordx4 v[120:121], v[102:105], off
	s_waitcnt lgkmcnt(0)
	s_waitcnt vmcnt(33)
	v_pk_add_f32 v[106:107], v[106:107], v[188:189]
	v_cvt_pk_bf16_f32 v110, v102, v103
	v_pk_mul_f32 v[102:103], v[102:103], v[102:103]
	v_cvt_pk_bf16_f32 v111, v104, v105
	v_pk_mul_f32 v[104:105], v[104:105], v[104:105]
	v_add_f32_e32 v102, v102, v103
	s_waitcnt vmcnt(33)
	v_pk_add_f32 v[108:109], v[108:109], v[190:191]
	v_lshl_add_u64 v[112:113], v[118:119], 1, s[44:45]
	v_add_f32_e32 v102, v104, v102
	global_store_dwordx4 v[120:121], v[106:109], off offset:64
	global_store_dwordx2 v[112:113], v[110:111], off
	v_cvt_pk_bf16_f32 v110, v106, v107
	v_pk_mul_f32 v[106:107], v[106:107], v[106:107]
	v_add_f32_e32 v102, v105, v102
	v_add_f32_e32 v102, v106, v102
	v_cvt_pk_bf16_f32 v111, v108, v109
	v_pk_mul_f32 v[108:109], v[108:109], v[108:109]
	v_add_f32_e32 v102, v107, v102
	v_add_f32_e32 v102, v108, v102
	v_add_f32_e32 v102, v109, v102
	ds_bpermute_b32 v103, v0, v102
	global_store_dwordx2 v[112:113], v[110:111], off offset:32
	s_waitcnt lgkmcnt(0)
	v_add_f32_e32 v102, v102, v103
	ds_bpermute_b32 v103, v70, v102
	s_waitcnt lgkmcnt(0)
	v_add_f32_e32 v102, v102, v103
	ds_bpermute_b32 v103, v71, v102
	s_waitcnt lgkmcnt(0)
	v_add_f32_e32 v102, v102, v103
	ds_bpermute_b32 v103, v73, v102
	s_waitcnt lgkmcnt(0)
	v_add_f32_e32 v102, v102, v103
	ds_bpermute_b32 v103, v72, v102
	s_and_saveexec_b64 s[8:9], vcc
	s_cbranch_execz .LBB0_431
	s_waitcnt lgkmcnt(0)
	v_add_f32_e32 v102, v102, v103
	v_lshl_add_u64 v[68:69], v[68:69], 4, s[6:7]
	global_store_dword v[68:69], v102, off
.LBB0_431:
	s_or_b64 exec, exec, s[8:9]
	v_add_u32_e32 v68, 0xe00, v142
	v_ashrrev_i32_e32 v102, 5, v68
	v_mul_lo_u32 v68, v102, s12
	v_add_u32_e32 v101, v101, v68
	v_add_u32_e32 v68, s15, v102
	v_ashrrev_i32_e32 v69, 31, v68
	v_lshlrev_b64 v[104:105], 10, v[68:69]
	v_lshl_add_u64 v[112:113], v[104:105], 0, v[66:67]
	v_lshl_add_u64 v[122:123], v[112:113], 2, s[26:27]
	ds_read_b128 v[104:107], v101
	v_lshl_add_u64 v[112:113], v[112:113], 1, s[44:45]
	s_waitcnt lgkmcnt(0)
	s_waitcnt vmcnt(36)
	v_pk_add_f32 v[104:105], v[104:105], v[192:193]
	s_waitcnt vmcnt(36)
	v_pk_add_f32 v[106:107], v[106:107], v[194:195]
	ds_read_b128 v[108:111], v101 offset:64
	global_store_dwordx4 v[122:123], v[104:107], off
	s_waitcnt lgkmcnt(0)
	s_waitcnt vmcnt(36)
	v_pk_add_f32 v[108:109], v[108:109], v[196:197]
	v_cvt_pk_bf16_f32 v118, v104, v105
	v_pk_mul_f32 v[104:105], v[104:105], v[104:105]
	v_cvt_pk_bf16_f32 v119, v106, v107
	v_pk_mul_f32 v[106:107], v[106:107], v[106:107]
	v_add_f32_e32 v103, v104, v105
	s_waitcnt vmcnt(36)
	v_pk_add_f32 v[110:111], v[110:111], v[198:199]
	v_add_f32_e32 v103, v106, v103
	global_store_dwordx4 v[122:123], v[108:111], off offset:64
	global_store_dwordx2 v[112:113], v[118:119], off
	v_cvt_pk_bf16_f32 v118, v108, v109
	v_pk_mul_f32 v[108:109], v[108:109], v[108:109]
	v_add_f32_e32 v103, v107, v103
	v_add_f32_e32 v103, v108, v103
	v_cvt_pk_bf16_f32 v119, v110, v111
	v_pk_mul_f32 v[110:111], v[110:111], v[110:111]
	v_add_f32_e32 v103, v109, v103
	v_add_f32_e32 v103, v110, v103
	v_add_f32_e32 v103, v111, v103
	ds_bpermute_b32 v104, v0, v103
	global_store_dwordx2 v[112:113], v[118:119], off offset:32
	s_waitcnt lgkmcnt(0)
	v_add_f32_e32 v103, v103, v104
	ds_bpermute_b32 v104, v70, v103
	s_waitcnt lgkmcnt(0)
	v_add_f32_e32 v103, v103, v104
	ds_bpermute_b32 v104, v71, v103
	s_waitcnt lgkmcnt(0)
	v_add_f32_e32 v103, v103, v104
	ds_bpermute_b32 v104, v73, v103
	s_waitcnt lgkmcnt(0)
	v_add_f32_e32 v103, v103, v104
	ds_bpermute_b32 v104, v72, v103
	s_and_saveexec_b64 s[8:9], vcc
	s_cbranch_execz .LBB0_433
	s_waitcnt lgkmcnt(0)
	v_add_f32_e32 v103, v103, v104
	v_lshl_add_u64 v[68:69], v[68:69], 4, s[6:7]
	global_store_dword v[68:69], v103, off
.LBB0_433:
	s_or_b64 exec, exec, s[8:9]
	s_waitcnt lgkmcnt(0)
	s_barrier
	ds_write2_b32 v130, v2, v18 offset1:16
	ds_write2_b32 v114, v3, v19 offset0:4 offset1:20
	ds_write2_b32 v115, v4, v20 offset0:8 offset1:24
	ds_write2_b32 v116, v5, v21 offset0:12 offset1:28
	ds_write2_b32 v117, v6, v22 offset0:64 offset1:80
	ds_write2_b32 v82, v7, v23 offset0:68 offset1:84
	ds_write2_b32 v83, v8, v24 offset0:72 offset1:88
	ds_write2_b32 v84, v9, v25 offset0:76 offset1:92
	ds_write2_b32 v85, v10, v26 offset0:128 offset1:144
	ds_write2_b32 v74, v11, v27 offset0:132 offset1:148
	ds_write2_b32 v75, v12, v28 offset0:136 offset1:152
	ds_write2_b32 v76, v13, v29 offset0:140 offset1:156
	ds_write2_b32 v80, v14, v30 offset0:192 offset1:208
	ds_write2_b32 v77, v15, v31 offset0:196 offset1:212
	ds_write2_b32 v78, v16, v32 offset0:200 offset1:216
	ds_write2_b32 v79, v17, v33 offset0:204 offset1:220
	ds_write2_b32 v130, v34, v50 offset0:128 offset1:144
	ds_write2_b32 v114, v35, v51 offset0:132 offset1:148
	ds_write2_b32 v115, v36, v52 offset0:136 offset1:152
	ds_write2_b32 v116, v37, v53 offset0:140 offset1:156
	ds_write2_b32 v117, v38, v54 offset0:192 offset1:208
	ds_write2_b32 v82, v39, v55 offset0:196 offset1:212
	ds_write2_b32 v83, v40, v56 offset0:200 offset1:216
	ds_write2_b32 v84, v41, v57 offset0:204 offset1:220
	ds_write2_b32 v74, v42, v58 offset1:16
	ds_write2_b32 v75, v43, v59 offset0:4 offset1:20
	ds_write2_b32 v76, v44, v60 offset0:8 offset1:24
	ds_write2_b32 v81, v45, v61 offset0:12 offset1:28
	ds_write2_b32 v77, v46, v62 offset0:64 offset1:80
	ds_write2_b32 v78, v47, v63 offset0:68 offset1:84
	ds_write2_b32 v79, v48, v64 offset0:72 offset1:88
	ds_write2_b32 v86, v49, v65 offset0:76 offset1:92
	v_add_u32_e32 v2, s14, v87
	v_ashrrev_i32_e32 v3, 31, v2
	v_lshlrev_b64 v[4:5], 10, v[2:3]
	v_lshl_add_u64 v[20:21], v[4:5], 0, v[66:67]
	v_lshl_add_u64 v[22:23], v[20:21], 2, s[26:27]
	s_waitcnt lgkmcnt(0)
	s_barrier
	v_lshlrev_b32_e32 v140, 2, v20
	global_load_dwordx4 v[132:135], v140, s[26:27]
	global_load_dwordx4 v[136:139], v140, s[26:27] offset:64
	v_add_u32_e32 v140, 0x10000, v140
	global_load_dwordx4 v[144:147], v140, s[26:27]
	global_load_dwordx4 v[148:151], v140, s[26:27] offset:64
	v_add_u32_e32 v140, 0x10000, v140
	global_load_dwordx4 v[152:155], v140, s[26:27]
	global_load_dwordx4 v[156:159], v140, s[26:27] offset:64
	v_add_u32_e32 v140, 0x10000, v140
	global_load_dwordx4 v[160:163], v140, s[26:27]
	global_load_dwordx4 v[164:167], v140, s[26:27] offset:64
	v_add_u32_e32 v140, 0x10000, v140
	global_load_dwordx4 v[168:171], v140, s[26:27]
	global_load_dwordx4 v[172:175], v140, s[26:27] offset:64
	v_add_u32_e32 v140, 0x10000, v140
	global_load_dwordx4 v[176:179], v140, s[26:27]
	global_load_dwordx4 v[180:183], v140, s[26:27] offset:64
	v_add_u32_e32 v140, 0x10000, v140
	global_load_dwordx4 v[184:187], v140, s[26:27]
	global_load_dwordx4 v[188:191], v140, s[26:27] offset:64
	v_add_u32_e32 v140, 0x10000, v140
	global_load_dwordx4 v[192:195], v140, s[26:27]
	global_load_dwordx4 v[196:199], v140, s[26:27] offset:64
	ds_read_b128 v[12:15], v88
	ds_read_b128 v[16:19], v88 offset:64
	s_waitcnt lgkmcnt(1)
	s_waitcnt vmcnt(15)
	v_pk_add_f32 v[4:5], v[12:13], v[132:133]
	s_waitcnt vmcnt(15)
	v_pk_add_f32 v[6:7], v[14:15], v[134:135]
	v_pk_mul_f32 v[12:13], v[4:5], v[4:5]
	v_pk_mul_f32 v[14:15], v[6:7], v[6:7]
	v_add_f32_e32 v12, v12, v13
	s_waitcnt lgkmcnt(0)
	s_waitcnt vmcnt(14)
	v_pk_add_f32 v[8:9], v[16:17], v[136:137]
	v_add_f32_e32 v12, v14, v12
	v_pk_mul_f32 v[16:17], v[8:9], v[8:9]
	v_add_f32_e32 v12, v15, v12
	s_waitcnt vmcnt(14)
	v_pk_add_f32 v[10:11], v[18:19], v[138:139]
	v_add_f32_e32 v12, v16, v12
	v_pk_mul_f32 v[18:19], v[10:11], v[10:11]
	v_add_f32_e32 v12, v17, v12
	v_add_f32_e32 v12, v18, v12
	v_add_f32_e32 v12, v19, v12
	ds_bpermute_b32 v13, v0, v12
	global_store_dwordx4 v[22:23], v[4:7], off
	global_store_dwordx4 v[22:23], v[8:11], off offset:64
	s_waitcnt lgkmcnt(0)
	v_add_f32_e32 v12, v12, v13
	ds_bpermute_b32 v13, v70, v12
	v_cvt_pk_bf16_f32 v8, v8, v9
	v_cvt_pk_bf16_f32 v9, v10, v11
	s_waitcnt lgkmcnt(0)
	v_add_f32_e32 v12, v12, v13
	ds_bpermute_b32 v13, v71, v12
	s_waitcnt lgkmcnt(0)
	v_add_f32_e32 v14, v12, v13
	ds_bpermute_b32 v15, v73, v14
	v_cvt_pk_bf16_f32 v12, v4, v5
	v_cvt_pk_bf16_f32 v13, v6, v7
	v_lshl_add_u64 v[6:7], v[20:21], 1, s[44:45]
	global_store_dwordx2 v[6:7], v[12:13], off
	s_waitcnt lgkmcnt(0)
	v_add_f32_e32 v4, v14, v15
	ds_bpermute_b32 v5, v72, v4
	global_store_dwordx2 v[6:7], v[8:9], off offset:32
	s_and_saveexec_b64 s[8:9], vcc
	s_cbranch_execz .LBB0_435
	s_waitcnt lgkmcnt(0)
	v_add_f32_e32 v4, v4, v5
	v_lshl_add_u64 v[2:3], v[2:3], 4, s[6:7]
	global_store_dword v[2:3], v4, off
.LBB0_435:
	s_or_b64 exec, exec, s[8:9]
	v_add_u32_e32 v2, s14, v90
	v_ashrrev_i32_e32 v3, 31, v2
	s_waitcnt lgkmcnt(0)
	v_lshlrev_b64 v[4:5], 10, v[2:3]
	v_lshl_add_u64 v[16:17], v[4:5], 0, v[66:67]
	v_lshl_add_u64 v[18:19], v[16:17], 2, s[26:27]
	ds_read_b128 v[4:7], v89
	s_waitcnt lgkmcnt(0)
	s_waitcnt vmcnt(18)
	v_pk_add_f32 v[4:5], v[4:5], v[144:145]
	s_waitcnt vmcnt(18)
	v_pk_add_f32 v[6:7], v[6:7], v[146:147]
	ds_read_b128 v[8:11], v89 offset:64
	global_store_dwordx4 v[18:19], v[4:7], off
	s_waitcnt lgkmcnt(0)
	s_waitcnt vmcnt(18)
	v_pk_add_f32 v[8:9], v[8:9], v[148:149]
	v_cvt_pk_bf16_f32 v12, v4, v5
	v_pk_mul_f32 v[4:5], v[4:5], v[4:5]
	v_cvt_pk_bf16_f32 v13, v6, v7
	v_pk_mul_f32 v[6:7], v[6:7], v[6:7]
	v_add_f32_e32 v4, v4, v5
	s_waitcnt vmcnt(18)
	v_pk_add_f32 v[10:11], v[10:11], v[150:151]
	v_lshl_add_u64 v[14:15], v[16:17], 1, s[44:45]
	v_add_f32_e32 v4, v6, v4
	global_store_dwordx4 v[18:19], v[8:11], off offset:64
	global_store_dwordx2 v[14:15], v[12:13], off
	v_cvt_pk_bf16_f32 v12, v8, v9
	v_pk_mul_f32 v[8:9], v[8:9], v[8:9]
	v_add_f32_e32 v4, v7, v4
	v_add_f32_e32 v4, v8, v4
	v_cvt_pk_bf16_f32 v13, v10, v11
	v_pk_mul_f32 v[10:11], v[10:11], v[10:11]
	v_add_f32_e32 v4, v9, v4
	v_add_f32_e32 v4, v10, v4
	v_add_f32_e32 v4, v11, v4
	ds_bpermute_b32 v5, v0, v4
	global_store_dwordx2 v[14:15], v[12:13], off offset:32
	s_waitcnt lgkmcnt(0)
	v_add_f32_e32 v4, v4, v5
	ds_bpermute_b32 v5, v70, v4
	s_waitcnt lgkmcnt(0)
	v_add_f32_e32 v4, v4, v5
	ds_bpermute_b32 v5, v71, v4
	s_waitcnt lgkmcnt(0)
	v_add_f32_e32 v4, v4, v5
	ds_bpermute_b32 v5, v73, v4
	s_waitcnt lgkmcnt(0)
	v_add_f32_e32 v4, v4, v5
	ds_bpermute_b32 v5, v72, v4
	s_and_saveexec_b64 s[8:9], vcc
	s_cbranch_execz .LBB0_437
	s_waitcnt lgkmcnt(0)
	v_add_f32_e32 v4, v4, v5
	v_lshl_add_u64 v[2:3], v[2:3], 4, s[6:7]
	global_store_dword v[2:3], v4, off
.LBB0_437:
	s_or_b64 exec, exec, s[8:9]
	v_add_u32_e32 v2, s14, v92
	v_ashrrev_i32_e32 v3, 31, v2
	s_waitcnt lgkmcnt(0)
	v_lshlrev_b64 v[4:5], 10, v[2:3]
	v_lshl_add_u64 v[16:17], v[4:5], 0, v[66:67]
	v_lshl_add_u64 v[18:19], v[16:17], 2, s[26:27]
	ds_read_b128 v[4:7], v91
	s_waitcnt lgkmcnt(0)
	s_waitcnt vmcnt(21)
	v_pk_add_f32 v[4:5], v[4:5], v[152:153]
	s_waitcnt vmcnt(21)
	v_pk_add_f32 v[6:7], v[6:7], v[154:155]
	ds_read_b128 v[8:11], v91 offset:64
	global_store_dwordx4 v[18:19], v[4:7], off
	s_waitcnt lgkmcnt(0)
	s_waitcnt vmcnt(21)
	v_pk_add_f32 v[8:9], v[8:9], v[156:157]
	v_cvt_pk_bf16_f32 v12, v4, v5
	v_pk_mul_f32 v[4:5], v[4:5], v[4:5]
	v_cvt_pk_bf16_f32 v13, v6, v7
	v_pk_mul_f32 v[6:7], v[6:7], v[6:7]
	v_add_f32_e32 v4, v4, v5
	s_waitcnt vmcnt(21)
	v_pk_add_f32 v[10:11], v[10:11], v[158:159]
	v_lshl_add_u64 v[14:15], v[16:17], 1, s[44:45]
	v_add_f32_e32 v4, v6, v4
	global_store_dwordx4 v[18:19], v[8:11], off offset:64
	global_store_dwordx2 v[14:15], v[12:13], off
	v_cvt_pk_bf16_f32 v12, v8, v9
	v_pk_mul_f32 v[8:9], v[8:9], v[8:9]
	v_add_f32_e32 v4, v7, v4
	v_add_f32_e32 v4, v8, v4
	v_cvt_pk_bf16_f32 v13, v10, v11
	v_pk_mul_f32 v[10:11], v[10:11], v[10:11]
	v_add_f32_e32 v4, v9, v4
	v_add_f32_e32 v4, v10, v4
	v_add_f32_e32 v4, v11, v4
	ds_bpermute_b32 v5, v0, v4
	global_store_dwordx2 v[14:15], v[12:13], off offset:32
	s_waitcnt lgkmcnt(0)
	v_add_f32_e32 v4, v4, v5
	ds_bpermute_b32 v5, v70, v4
	s_waitcnt lgkmcnt(0)
	v_add_f32_e32 v4, v4, v5
	ds_bpermute_b32 v5, v71, v4
	s_waitcnt lgkmcnt(0)
	v_add_f32_e32 v4, v4, v5
	ds_bpermute_b32 v5, v73, v4
	s_waitcnt lgkmcnt(0)
	v_add_f32_e32 v4, v4, v5
	ds_bpermute_b32 v5, v72, v4
	s_and_saveexec_b64 s[8:9], vcc
	s_cbranch_execz .LBB0_439
	s_waitcnt lgkmcnt(0)
	v_add_f32_e32 v4, v4, v5
	v_lshl_add_u64 v[2:3], v[2:3], 4, s[6:7]
	global_store_dword v[2:3], v4, off
.LBB0_439:
	s_or_b64 exec, exec, s[8:9]
	v_add_u32_e32 v2, s14, v94
	v_ashrrev_i32_e32 v3, 31, v2
	s_waitcnt lgkmcnt(0)
	v_lshlrev_b64 v[4:5], 10, v[2:3]
	v_lshl_add_u64 v[16:17], v[4:5], 0, v[66:67]
	v_lshl_add_u64 v[18:19], v[16:17], 2, s[26:27]
	ds_read_b128 v[4:7], v93
	s_waitcnt lgkmcnt(0)
	s_waitcnt vmcnt(24)
	v_pk_add_f32 v[4:5], v[4:5], v[160:161]
	s_waitcnt vmcnt(24)
	v_pk_add_f32 v[6:7], v[6:7], v[162:163]
	ds_read_b128 v[8:11], v93 offset:64
	global_store_dwordx4 v[18:19], v[4:7], off
	s_waitcnt lgkmcnt(0)
	s_waitcnt vmcnt(24)
	v_pk_add_f32 v[8:9], v[8:9], v[164:165]
	v_cvt_pk_bf16_f32 v12, v4, v5
	v_pk_mul_f32 v[4:5], v[4:5], v[4:5]
	v_cvt_pk_bf16_f32 v13, v6, v7
	v_pk_mul_f32 v[6:7], v[6:7], v[6:7]
	v_add_f32_e32 v4, v4, v5
	s_waitcnt vmcnt(24)
	v_pk_add_f32 v[10:11], v[10:11], v[166:167]
	v_lshl_add_u64 v[14:15], v[16:17], 1, s[44:45]
	v_add_f32_e32 v4, v6, v4
	global_store_dwordx4 v[18:19], v[8:11], off offset:64
	global_store_dwordx2 v[14:15], v[12:13], off
	v_cvt_pk_bf16_f32 v12, v8, v9
	v_pk_mul_f32 v[8:9], v[8:9], v[8:9]
	v_add_f32_e32 v4, v7, v4
	v_add_f32_e32 v4, v8, v4
	v_cvt_pk_bf16_f32 v13, v10, v11
	v_pk_mul_f32 v[10:11], v[10:11], v[10:11]
	v_add_f32_e32 v4, v9, v4
	v_add_f32_e32 v4, v10, v4
	v_add_f32_e32 v4, v11, v4
	ds_bpermute_b32 v5, v0, v4
	global_store_dwordx2 v[14:15], v[12:13], off offset:32
	s_waitcnt lgkmcnt(0)
	v_add_f32_e32 v4, v4, v5
	ds_bpermute_b32 v5, v70, v4
	s_waitcnt lgkmcnt(0)
	v_add_f32_e32 v4, v4, v5
	ds_bpermute_b32 v5, v71, v4
	s_waitcnt lgkmcnt(0)
	v_add_f32_e32 v4, v4, v5
	ds_bpermute_b32 v5, v73, v4
	s_waitcnt lgkmcnt(0)
	v_add_f32_e32 v4, v4, v5
	ds_bpermute_b32 v5, v72, v4
	s_and_saveexec_b64 s[8:9], vcc
	s_cbranch_execz .LBB0_441
	s_waitcnt lgkmcnt(0)
	v_add_f32_e32 v4, v4, v5
	v_lshl_add_u64 v[2:3], v[2:3], 4, s[6:7]
	global_store_dword v[2:3], v4, off
.LBB0_441:
	s_or_b64 exec, exec, s[8:9]
	v_add_u32_e32 v2, s14, v96
	v_ashrrev_i32_e32 v3, 31, v2
	s_waitcnt lgkmcnt(0)
	v_lshlrev_b64 v[4:5], 10, v[2:3]
	v_lshl_add_u64 v[16:17], v[4:5], 0, v[66:67]
	v_lshl_add_u64 v[18:19], v[16:17], 2, s[26:27]
	ds_read_b128 v[4:7], v95
	s_waitcnt lgkmcnt(0)
	s_waitcnt vmcnt(27)
	v_pk_add_f32 v[4:5], v[4:5], v[168:169]
	s_waitcnt vmcnt(27)
	v_pk_add_f32 v[6:7], v[6:7], v[170:171]
	ds_read_b128 v[8:11], v95 offset:64
	global_store_dwordx4 v[18:19], v[4:7], off
	s_waitcnt lgkmcnt(0)
	s_waitcnt vmcnt(27)
	v_pk_add_f32 v[8:9], v[8:9], v[172:173]
	v_cvt_pk_bf16_f32 v12, v4, v5
	v_pk_mul_f32 v[4:5], v[4:5], v[4:5]
	v_cvt_pk_bf16_f32 v13, v6, v7
	v_pk_mul_f32 v[6:7], v[6:7], v[6:7]
	v_add_f32_e32 v4, v4, v5
	s_waitcnt vmcnt(27)
	v_pk_add_f32 v[10:11], v[10:11], v[174:175]
	v_lshl_add_u64 v[14:15], v[16:17], 1, s[44:45]
	v_add_f32_e32 v4, v6, v4
	global_store_dwordx4 v[18:19], v[8:11], off offset:64
	global_store_dwordx2 v[14:15], v[12:13], off
	v_cvt_pk_bf16_f32 v12, v8, v9
	v_pk_mul_f32 v[8:9], v[8:9], v[8:9]
	v_add_f32_e32 v4, v7, v4
	v_add_f32_e32 v4, v8, v4
	v_cvt_pk_bf16_f32 v13, v10, v11
	v_pk_mul_f32 v[10:11], v[10:11], v[10:11]
	v_add_f32_e32 v4, v9, v4
	v_add_f32_e32 v4, v10, v4
	v_add_f32_e32 v4, v11, v4
	ds_bpermute_b32 v5, v0, v4
	global_store_dwordx2 v[14:15], v[12:13], off offset:32
	s_waitcnt lgkmcnt(0)
	v_add_f32_e32 v4, v4, v5
	ds_bpermute_b32 v5, v70, v4
	s_waitcnt lgkmcnt(0)
	v_add_f32_e32 v4, v4, v5
	ds_bpermute_b32 v5, v71, v4
	s_waitcnt lgkmcnt(0)
	v_add_f32_e32 v4, v4, v5
	ds_bpermute_b32 v5, v73, v4
	s_waitcnt lgkmcnt(0)
	v_add_f32_e32 v4, v4, v5
	ds_bpermute_b32 v5, v72, v4
	s_and_saveexec_b64 s[8:9], vcc
	s_cbranch_execz .LBB0_443
	s_waitcnt lgkmcnt(0)
	v_add_f32_e32 v4, v4, v5
	v_lshl_add_u64 v[2:3], v[2:3], 4, s[6:7]
	global_store_dword v[2:3], v4, off
.LBB0_443:
	s_or_b64 exec, exec, s[8:9]
	v_add_u32_e32 v2, s14, v98
	v_ashrrev_i32_e32 v3, 31, v2
	s_waitcnt lgkmcnt(0)
	v_lshlrev_b64 v[4:5], 10, v[2:3]
	v_lshl_add_u64 v[16:17], v[4:5], 0, v[66:67]
	v_lshl_add_u64 v[18:19], v[16:17], 2, s[26:27]
	ds_read_b128 v[4:7], v97
	s_waitcnt lgkmcnt(0)
	s_waitcnt vmcnt(30)
	v_pk_add_f32 v[4:5], v[4:5], v[176:177]
	s_waitcnt vmcnt(30)
	v_pk_add_f32 v[6:7], v[6:7], v[178:179]
	ds_read_b128 v[8:11], v97 offset:64
	global_store_dwordx4 v[18:19], v[4:7], off
	s_waitcnt lgkmcnt(0)
	s_waitcnt vmcnt(30)
	v_pk_add_f32 v[8:9], v[8:9], v[180:181]
	v_cvt_pk_bf16_f32 v12, v4, v5
	v_pk_mul_f32 v[4:5], v[4:5], v[4:5]
	v_cvt_pk_bf16_f32 v13, v6, v7
	v_pk_mul_f32 v[6:7], v[6:7], v[6:7]
	v_add_f32_e32 v4, v4, v5
	s_waitcnt vmcnt(30)
	v_pk_add_f32 v[10:11], v[10:11], v[182:183]
	v_lshl_add_u64 v[14:15], v[16:17], 1, s[44:45]
	v_add_f32_e32 v4, v6, v4
	global_store_dwordx4 v[18:19], v[8:11], off offset:64
	global_store_dwordx2 v[14:15], v[12:13], off
	v_cvt_pk_bf16_f32 v12, v8, v9
	v_pk_mul_f32 v[8:9], v[8:9], v[8:9]
	v_add_f32_e32 v4, v7, v4
	v_add_f32_e32 v4, v8, v4
	v_cvt_pk_bf16_f32 v13, v10, v11
	v_pk_mul_f32 v[10:11], v[10:11], v[10:11]
	v_add_f32_e32 v4, v9, v4
	v_add_f32_e32 v4, v10, v4
	v_add_f32_e32 v4, v11, v4
	ds_bpermute_b32 v5, v0, v4
	global_store_dwordx2 v[14:15], v[12:13], off offset:32
	s_waitcnt lgkmcnt(0)
	v_add_f32_e32 v4, v4, v5
	ds_bpermute_b32 v5, v70, v4
	s_waitcnt lgkmcnt(0)
	v_add_f32_e32 v4, v4, v5
	ds_bpermute_b32 v5, v71, v4
	s_waitcnt lgkmcnt(0)
	v_add_f32_e32 v4, v4, v5
	ds_bpermute_b32 v5, v73, v4
	s_waitcnt lgkmcnt(0)
	v_add_f32_e32 v4, v4, v5
	ds_bpermute_b32 v5, v72, v4
	s_and_saveexec_b64 s[8:9], vcc
	s_cbranch_execz .LBB0_445
	s_waitcnt lgkmcnt(0)
	v_add_f32_e32 v4, v4, v5
	v_lshl_add_u64 v[2:3], v[2:3], 4, s[6:7]
	global_store_dword v[2:3], v4, off
.LBB0_445:
	s_or_b64 exec, exec, s[8:9]
	v_add_u32_e32 v2, s14, v100
	v_ashrrev_i32_e32 v3, 31, v2
	s_waitcnt lgkmcnt(0)
	v_lshlrev_b64 v[4:5], 10, v[2:3]
	v_lshl_add_u64 v[16:17], v[4:5], 0, v[66:67]
	v_lshl_add_u64 v[18:19], v[16:17], 2, s[26:27]
	ds_read_b128 v[4:7], v99
	s_waitcnt lgkmcnt(0)
	s_waitcnt vmcnt(33)
	v_pk_add_f32 v[4:5], v[4:5], v[184:185]
	s_waitcnt vmcnt(33)
	v_pk_add_f32 v[6:7], v[6:7], v[186:187]
	ds_read_b128 v[8:11], v99 offset:64
	global_store_dwordx4 v[18:19], v[4:7], off
	s_waitcnt lgkmcnt(0)
	s_waitcnt vmcnt(33)
	v_pk_add_f32 v[8:9], v[8:9], v[188:189]
	v_cvt_pk_bf16_f32 v12, v4, v5
	v_pk_mul_f32 v[4:5], v[4:5], v[4:5]
	v_cvt_pk_bf16_f32 v13, v6, v7
	v_pk_mul_f32 v[6:7], v[6:7], v[6:7]
	v_add_f32_e32 v4, v4, v5
	s_waitcnt vmcnt(33)
	v_pk_add_f32 v[10:11], v[10:11], v[190:191]
	v_lshl_add_u64 v[14:15], v[16:17], 1, s[44:45]
	v_add_f32_e32 v4, v6, v4
	global_store_dwordx4 v[18:19], v[8:11], off offset:64
	global_store_dwordx2 v[14:15], v[12:13], off
	v_cvt_pk_bf16_f32 v12, v8, v9
	v_pk_mul_f32 v[8:9], v[8:9], v[8:9]
	v_add_f32_e32 v4, v7, v4
	v_add_f32_e32 v4, v8, v4
	v_cvt_pk_bf16_f32 v13, v10, v11
	v_pk_mul_f32 v[10:11], v[10:11], v[10:11]
	v_add_f32_e32 v4, v9, v4
	v_add_f32_e32 v4, v10, v4
	v_add_f32_e32 v4, v11, v4
	ds_bpermute_b32 v5, v0, v4
	global_store_dwordx2 v[14:15], v[12:13], off offset:32
	s_waitcnt lgkmcnt(0)
	v_add_f32_e32 v4, v4, v5
	ds_bpermute_b32 v5, v70, v4
	s_waitcnt lgkmcnt(0)
	v_add_f32_e32 v4, v4, v5
	ds_bpermute_b32 v5, v71, v4
	s_waitcnt lgkmcnt(0)
	v_add_f32_e32 v4, v4, v5
	ds_bpermute_b32 v5, v73, v4
	s_waitcnt lgkmcnt(0)
	v_add_f32_e32 v4, v4, v5
	ds_bpermute_b32 v5, v72, v4
	s_and_saveexec_b64 s[8:9], vcc
	s_cbranch_execz .LBB0_447
	s_waitcnt lgkmcnt(0)
	v_add_f32_e32 v4, v4, v5
	v_lshl_add_u64 v[2:3], v[2:3], 4, s[6:7]
	global_store_dword v[2:3], v4, off
.LBB0_447:
	s_or_b64 exec, exec, s[8:9]
	v_add_u32_e32 v2, s14, v102
	v_ashrrev_i32_e32 v3, 31, v2
	s_waitcnt lgkmcnt(0)
	v_lshlrev_b64 v[4:5], 10, v[2:3]
	v_lshl_add_u64 v[16:17], v[4:5], 0, v[66:67]
	v_lshl_add_u64 v[18:19], v[16:17], 2, s[26:27]
	ds_read_b128 v[4:7], v101
	s_waitcnt lgkmcnt(0)
	s_waitcnt vmcnt(36)
	v_pk_add_f32 v[4:5], v[4:5], v[192:193]
	s_waitcnt vmcnt(36)
	v_pk_add_f32 v[6:7], v[6:7], v[194:195]
	ds_read_b128 v[8:11], v101 offset:64
	global_store_dwordx4 v[18:19], v[4:7], off
	s_waitcnt lgkmcnt(0)
	s_waitcnt vmcnt(36)
	v_pk_add_f32 v[8:9], v[8:9], v[196:197]
	v_cvt_pk_bf16_f32 v12, v4, v5
	v_pk_mul_f32 v[4:5], v[4:5], v[4:5]
	v_cvt_pk_bf16_f32 v13, v6, v7
	v_pk_mul_f32 v[6:7], v[6:7], v[6:7]
	v_add_f32_e32 v4, v4, v5
	s_waitcnt vmcnt(36)
	v_pk_add_f32 v[10:11], v[10:11], v[198:199]
	v_lshl_add_u64 v[14:15], v[16:17], 1, s[44:45]
	v_add_f32_e32 v4, v6, v4
	global_store_dwordx4 v[18:19], v[8:11], off offset:64
	global_store_dwordx2 v[14:15], v[12:13], off
	v_cvt_pk_bf16_f32 v12, v8, v9
	v_pk_mul_f32 v[8:9], v[8:9], v[8:9]
	v_add_f32_e32 v4, v7, v4
	v_add_f32_e32 v4, v8, v4
	v_cvt_pk_bf16_f32 v13, v10, v11
	v_pk_mul_f32 v[10:11], v[10:11], v[10:11]
	v_add_f32_e32 v4, v9, v4
	v_add_f32_e32 v4, v10, v4
	v_add_f32_e32 v4, v11, v4
	ds_bpermute_b32 v0, v0, v4
	global_store_dwordx2 v[14:15], v[12:13], off offset:32
	s_waitcnt lgkmcnt(0)
	v_add_f32_e32 v0, v4, v0
	ds_bpermute_b32 v4, v70, v0
	s_waitcnt lgkmcnt(0)
	v_add_f32_e32 v0, v0, v4
	ds_bpermute_b32 v4, v71, v0
	s_waitcnt lgkmcnt(0)
	v_add_f32_e32 v0, v0, v4
	ds_bpermute_b32 v4, v73, v0
	s_waitcnt lgkmcnt(0)
	v_add_f32_e32 v0, v0, v4
	ds_bpermute_b32 v4, v72, v0
	s_and_saveexec_b64 s[8:9], vcc
	s_cbranch_execz .LBB0_449
	s_waitcnt lgkmcnt(0)
	v_add_f32_e32 v0, v0, v4
	v_lshl_add_u64 v[2:3], v[2:3], 4, s[6:7]
	global_store_dword v[2:3], v0, off

.LBB0_507:
	v_ashrrev_i32_e32 v3, 31, v2
	v_lshlrev_b64 v[10:11], 10, v[2:3]
	v_lshl_or_b32 v10, v4, 1, v10
	global_load_ushort v40, v10, s[8:9]
	global_load_ushort v48, v10, s[10:11]
	global_load_ushort v56, v10, s[12:13]
	global_load_ushort v64, v10, s[14:15]
	global_load_ushort v72, v10, s[16:17]
	global_load_ushort v41, v10, s[8:9] offset:128
	global_load_ushort v49, v10, s[10:11] offset:128
	global_load_ushort v57, v10, s[12:13] offset:128
	global_load_ushort v65, v10, s[14:15] offset:128
	global_load_ushort v73, v10, s[16:17] offset:128
	global_load_ushort v42, v10, s[8:9] offset:256
	global_load_ushort v50, v10, s[10:11] offset:256
	global_load_ushort v58, v10, s[12:13] offset:256
	global_load_ushort v66, v10, s[14:15] offset:256
	global_load_ushort v74, v10, s[16:17] offset:256
	global_load_ushort v43, v10, s[8:9] offset:384
	global_load_ushort v51, v10, s[10:11] offset:384
	global_load_ushort v59, v10, s[12:13] offset:384
	global_load_ushort v67, v10, s[14:15] offset:384
	global_load_ushort v75, v10, s[16:17] offset:384
	global_load_ushort v44, v10, s[8:9] offset:512
	global_load_ushort v52, v10, s[10:11] offset:512
	global_load_ushort v60, v10, s[12:13] offset:512
	global_load_ushort v68, v10, s[14:15] offset:512
	global_load_ushort v76, v10, s[16:17] offset:512
	global_load_ushort v45, v10, s[8:9] offset:640
	global_load_ushort v53, v10, s[10:11] offset:640
	global_load_ushort v61, v10, s[12:13] offset:640
	global_load_ushort v69, v10, s[14:15] offset:640
	global_load_ushort v77, v10, s[16:17] offset:640
	global_load_ushort v46, v10, s[8:9] offset:768
	global_load_ushort v54, v10, s[10:11] offset:768
	global_load_ushort v62, v10, s[12:13] offset:768
	global_load_ushort v70, v10, s[14:15] offset:768
	global_load_ushort v78, v10, s[16:17] offset:768
	global_load_ushort v47, v10, s[8:9] offset:896
	global_load_ushort v55, v10, s[10:11] offset:896
	global_load_ushort v63, v10, s[12:13] offset:896
	global_load_ushort v71, v10, s[14:15] offset:896
	global_load_ushort v79, v10, s[16:17] offset:896
	s_waitcnt vmcnt(0)
	v_lshl_add_u64 v[12:13], s[8:9], 0, v[10:11]
	v_mov_b32_e32 v3, v40
	v_mad_i64_i32 v[8:9], s[20:21], v2, s34, v[6:7]
	v_add_u32_e32 v2, s26, v2
	v_lshlrev_b32_e32 v3, 16, v3
	s_nop 1
	v_add_f32_dpp v12, v3, v3 quad_perm:[1,0,3,2] row_mask:0xf bank_mask:0xf bound_ctrl:1
	s_nop 1
	v_add_f32_dpp v12, v12, v12 quad_perm:[2,3,0,1] row_mask:0xf bank_mask:0xf bound_ctrl:1
	s_nop 1
	v_add_f32_dpp v12, v12, v12 row_half_mirror row_mask:0xf bank_mask:0xf bound_ctrl:1
	s_nop 1
	v_add_f32_dpp v12, v12, v12 row_mirror row_mask:0xf bank_mask:0xf bound_ctrl:1
	s_nop 0
	v_readlane_b32 s22, v12, 16
	v_readlane_b32 s23, v12, 48
	v_readlane_b32 s20, v12, 0
	v_readlane_b32 s21, v12, 32
	v_mov_b32_e32 v12, s22
	v_mov_b32_e32 v13, s23
	v_pk_add_f32 v[12:13], s[20:21], v[12:13]
	s_nop 0
	v_add_f32_e32 v12, v12, v13
	v_fmac_f32_e32 v3, 0xbc800000, v12
	v_mul_f32_e32 v12, v3, v3
	v_mov_b32_e32 v13, v1
	s_nop 1
	v_mov_b32_dpp v13, v12 quad_perm:[1,0,3,2] row_mask:0xf bank_mask:0xf
	v_fmac_f32_e32 v13, v3, v3
	s_nop 1
	v_add_f32_dpp v12, v13, v13 quad_perm:[2,3,0,1] row_mask:0xf bank_mask:0xf bound_ctrl:1
	s_nop 1
	v_add_f32_dpp v12, v12, v12 row_half_mirror row_mask:0xf bank_mask:0xf bound_ctrl:1
	s_nop 1
	v_add_f32_dpp v12, v12, v12 row_mirror row_mask:0xf bank_mask:0xf bound_ctrl:1
	s_nop 0
	v_readlane_b32 s22, v12, 16
	v_readlane_b32 s23, v12, 48
	v_readlane_b32 s20, v12, 0
	v_readlane_b32 s21, v12, 32
	v_mov_b32_e32 v12, s22
	v_mov_b32_e32 v13, s23
	v_pk_add_f32 v[12:13], s[20:21], v[12:13]
	s_nop 0
	v_add_f32_e32 v36, v12, v13
	v_lshl_add_u64 v[12:13], s[10:11], 0, v[10:11]
	v_mov_b32_e32 v12, v48
	v_lshlrev_b32_e32 v37, 16, v12
	v_lshl_add_u64 v[12:13], s[12:13], 0, v[10:11]
	v_mov_b32_e32 v12, v56
	v_lshlrev_b32_e32 v12, 16, v12
	v_mul_f32_e32 v12, v37, v12
	v_mul_f32_e32 v13, v0, v12
	v_mov_b32_e32 v37, v1
	s_nop 1
	v_mov_b32_dpp v37, v13 quad_perm:[1,0,3,2] row_mask:0xf bank_mask:0xf
	v_fmac_f32_e32 v37, v0, v12
	s_nop 1
	v_add_f32_dpp v12, v37, v37 quad_perm:[2,3,0,1] row_mask:0xf bank_mask:0xf bound_ctrl:1
	s_nop 1
	v_add_f32_dpp v12, v12, v12 row_half_mirror row_mask:0xf bank_mask:0xf bound_ctrl:1
	s_nop 1
	v_add_f32_dpp v12, v12, v12 row_mirror row_mask:0xf bank_mask:0xf bound_ctrl:1
	s_nop 0
	v_readlane_b32 s21, v12, 16
	v_readlane_b32 s23, v12, 48
	v_readlane_b32 s20, v12, 0
	v_readlane_b32 s22, v12, 32
	v_mov_b32_e32 v12, s21
	v_mov_b32_e32 v13, s23
	v_add_f32_e32 v12, s20, v12
	v_add_f32_e32 v13, s22, v13
	v_add_f32_e32 v37, v12, v13
	v_fmamk_f32 v12, v36, 0x3c800000, v216
	v_cmp_gt_f32_e32 vcc, s27, v12
	v_mul_f32_e32 v13, 0x4b800000, v12
	s_nop 0
	v_cndmask_b32_e32 v12, v12, v13, vcc
	v_rsq_f32_e32 v12, v12
	s_nop 0
	v_mul_f32_e32 v13, 0x45800000, v12
	v_cndmask_b32_e32 v12, v12, v13, vcc
	v_mul_f32_e32 v3, v3, v12
	v_lshl_add_u64 v[12:13], s[14:15], 0, v[10:11]
	v_mov_b32_e32 v12, v64
	v_fma_f32 v3, v5, v3, v14
	v_lshlrev_b32_e32 v12, 16, v12
	v_fmac_f32_e32 v3, v37, v12
	v_lshl_add_u64 v[12:13], s[16:17], 0, v[10:11]
	v_mov_b32_e32 v12, v72
	v_mov_b32_e32 v13, v11
	v_lshlrev_b32_e32 v12, 16, v12
	v_mul_f32_e32 v3, v3, v12
	v_cvt_pk_bf16_f32 v3, v3, s0
	v_or_b32_e32 v12, 0x80, v10
	global_store_short v[8:9], v3, off
	v_lshl_add_u64 v[36:37], s[8:9], 0, v[12:13]
	v_mov_b32_e32 v3, v41
	v_lshlrev_b32_e32 v3, 16, v3
	s_nop 1
	v_add_f32_dpp v36, v3, v3 quad_perm:[1,0,3,2] row_mask:0xf bank_mask:0xf bound_ctrl:1
	s_nop 1
	v_add_f32_dpp v36, v36, v36 quad_perm:[2,3,0,1] row_mask:0xf bank_mask:0xf bound_ctrl:1
	s_nop 1
	v_add_f32_dpp v36, v36, v36 row_half_mirror row_mask:0xf bank_mask:0xf bound_ctrl:1
	s_nop 1
	v_add_f32_dpp v36, v36, v36 row_mirror row_mask:0xf bank_mask:0xf bound_ctrl:1
	s_nop 0
	v_readlane_b32 s22, v36, 16
	v_readlane_b32 s23, v36, 48
	v_readlane_b32 s20, v36, 0
	v_readlane_b32 s21, v36, 32
	v_mov_b32_e32 v36, s22
	v_mov_b32_e32 v37, s23
	v_pk_add_f32 v[36:37], s[20:21], v[36:37]
	s_nop 0
	v_add_f32_e32 v36, v36, v37
	v_fmac_f32_e32 v3, 0xbc800000, v36
	v_mul_f32_e32 v36, v3, v3
	v_mov_b32_e32 v37, v1
	s_nop 1
	v_mov_b32_dpp v37, v36 quad_perm:[1,0,3,2] row_mask:0xf bank_mask:0xf
	v_fmac_f32_e32 v37, v3, v3
	s_nop 1
	v_add_f32_dpp v36, v37, v37 quad_perm:[2,3,0,1] row_mask:0xf bank_mask:0xf bound_ctrl:1
	s_nop 1
	v_add_f32_dpp v36, v36, v36 row_half_mirror row_mask:0xf bank_mask:0xf bound_ctrl:1
	s_nop 1
	v_add_f32_dpp v36, v36, v36 row_mirror row_mask:0xf bank_mask:0xf bound_ctrl:1
	s_nop 0
	v_readlane_b32 s22, v36, 16
	v_readlane_b32 s23, v36, 48
	v_readlane_b32 s20, v36, 0
	v_readlane_b32 s21, v36, 32
	v_mov_b32_e32 v36, s22
	v_mov_b32_e32 v37, s23
	v_pk_add_f32 v[36:37], s[20:21], v[36:37]
	s_nop 0
	v_add_f32_e32 v38, v36, v37
	v_lshl_add_u64 v[36:37], s[10:11], 0, v[12:13]
	v_mov_b32_e32 v36, v49
	v_lshlrev_b32_e32 v39, 16, v36
	v_lshl_add_u64 v[36:37], s[12:13], 0, v[12:13]
	v_mov_b32_e32 v36, v57
	v_lshlrev_b32_e32 v36, 16, v36
	v_mul_f32_e32 v36, v39, v36
	v_mul_f32_e32 v37, v15, v36
	v_mov_b32_e32 v39, v1
	s_nop 1
	v_mov_b32_dpp v39, v37 quad_perm:[1,0,3,2] row_mask:0xf bank_mask:0xf
	v_fmac_f32_e32 v39, v15, v36
	s_nop 1
	v_add_f32_dpp v36, v39, v39 quad_perm:[2,3,0,1] row_mask:0xf bank_mask:0xf bound_ctrl:1
	s_nop 1
	v_add_f32_dpp v36, v36, v36 row_half_mirror row_mask:0xf bank_mask:0xf bound_ctrl:1
	s_nop 1
	v_add_f32_dpp v36, v36, v36 row_mirror row_mask:0xf bank_mask:0xf bound_ctrl:1
	s_nop 0
	v_readlane_b32 s21, v36, 16
	v_readlane_b32 s23, v36, 48
	v_readlane_b32 s20, v36, 0
	v_readlane_b32 s22, v36, 32
	v_mov_b32_e32 v36, s21
	v_mov_b32_e32 v37, s23
	v_add_f32_e32 v36, s20, v36
	v_add_f32_e32 v37, s22, v37
	v_add_f32_e32 v39, v36, v37
	v_fmamk_f32 v36, v38, 0x3c800000, v216
	v_cmp_gt_f32_e32 vcc, s27, v36
	v_mul_f32_e32 v37, 0x4b800000, v36
	s_nop 0
	v_cndmask_b32_e32 v36, v36, v37, vcc
	v_rsq_f32_e32 v36, v36
	s_nop 0
	v_mul_f32_e32 v37, 0x45800000, v36
	v_cndmask_b32_e32 v36, v36, v37, vcc
	v_mul_f32_e32 v3, v3, v36
	v_lshl_add_u64 v[36:37], s[14:15], 0, v[12:13]
	v_mov_b32_e32 v36, v65
	v_lshl_add_u64 v[12:13], s[16:17], 0, v[12:13]
	v_mov_b32_e32 v12, v73
	v_fma_f32 v3, v16, v3, v17
	v_mov_b32_e32 v13, v11
	v_lshlrev_b32_e32 v36, 16, v36
	v_fmac_f32_e32 v3, v39, v36
	v_lshlrev_b32_e32 v12, 16, v12
	v_mul_f32_e32 v3, v3, v12
	v_cvt_pk_bf16_f32 v3, v3, s0
	v_or_b32_e32 v12, 0x100, v10
	global_store_short v[8:9], v3, off offset:128
	v_lshl_add_u64 v[36:37], s[8:9], 0, v[12:13]
	v_mov_b32_e32 v3, v42
	v_lshlrev_b32_e32 v3, 16, v3
	s_nop 1
	v_add_f32_dpp v36, v3, v3 quad_perm:[1,0,3,2] row_mask:0xf bank_mask:0xf bound_ctrl:1
	s_nop 1
	v_add_f32_dpp v36, v36, v36 quad_perm:[2,3,0,1] row_mask:0xf bank_mask:0xf bound_ctrl:1
	s_nop 1
	v_add_f32_dpp v36, v36, v36 row_half_mirror row_mask:0xf bank_mask:0xf bound_ctrl:1
	s_nop 1
	v_add_f32_dpp v36, v36, v36 row_mirror row_mask:0xf bank_mask:0xf bound_ctrl:1
	s_nop 0
	v_readlane_b32 s22, v36, 16
	v_readlane_b32 s23, v36, 48
	v_readlane_b32 s20, v36, 0
	v_readlane_b32 s21, v36, 32
	v_mov_b32_e32 v36, s22
	v_mov_b32_e32 v37, s23
	v_pk_add_f32 v[36:37], s[20:21], v[36:37]
	s_nop 0
	v_add_f32_e32 v36, v36, v37
	v_fmac_f32_e32 v3, 0xbc800000, v36
	v_mul_f32_e32 v36, v3, v3
	v_mov_b32_e32 v37, v1
	s_nop 1
	v_mov_b32_dpp v37, v36 quad_perm:[1,0,3,2] row_mask:0xf bank_mask:0xf
	v_fmac_f32_e32 v37, v3, v3
	s_nop 1
	v_add_f32_dpp v36, v37, v37 quad_perm:[2,3,0,1] row_mask:0xf bank_mask:0xf bound_ctrl:1
	s_nop 1
	v_add_f32_dpp v36, v36, v36 row_half_mirror row_mask:0xf bank_mask:0xf bound_ctrl:1
	s_nop 1
	v_add_f32_dpp v36, v36, v36 row_mirror row_mask:0xf bank_mask:0xf bound_ctrl:1
	s_nop 0
	v_readlane_b32 s22, v36, 16
	v_readlane_b32 s23, v36, 48
	v_readlane_b32 s20, v36, 0
	v_readlane_b32 s21, v36, 32
	v_mov_b32_e32 v36, s22
	v_mov_b32_e32 v37, s23
	v_pk_add_f32 v[36:37], s[20:21], v[36:37]
	s_nop 0
	v_add_f32_e32 v38, v36, v37
	v_lshl_add_u64 v[36:37], s[10:11], 0, v[12:13]
	v_mov_b32_e32 v36, v50
	v_lshlrev_b32_e32 v39, 16, v36
	v_lshl_add_u64 v[36:37], s[12:13], 0, v[12:13]
	v_mov_b32_e32 v36, v58
	v_lshlrev_b32_e32 v36, 16, v36
	v_mul_f32_e32 v36, v39, v36
	v_mul_f32_e32 v37, v18, v36
	v_mov_b32_e32 v39, v1
	s_nop 1
	v_mov_b32_dpp v39, v37 quad_perm:[1,0,3,2] row_mask:0xf bank_mask:0xf
	v_fmac_f32_e32 v39, v18, v36
	s_nop 1
	v_add_f32_dpp v36, v39, v39 quad_perm:[2,3,0,1] row_mask:0xf bank_mask:0xf bound_ctrl:1
	s_nop 1
	v_add_f32_dpp v36, v36, v36 row_half_mirror row_mask:0xf bank_mask:0xf bound_ctrl:1
	s_nop 1
	v_add_f32_dpp v36, v36, v36 row_mirror row_mask:0xf bank_mask:0xf bound_ctrl:1
	s_nop 0
	v_readlane_b32 s21, v36, 16
	v_readlane_b32 s23, v36, 48
	v_readlane_b32 s20, v36, 0
	v_readlane_b32 s22, v36, 32
	v_mov_b32_e32 v36, s21
	v_mov_b32_e32 v37, s23
	v_add_f32_e32 v36, s20, v36
	v_add_f32_e32 v37, s22, v37
	v_add_f32_e32 v39, v36, v37
	v_fmamk_f32 v36, v38, 0x3c800000, v216
	v_cmp_gt_f32_e32 vcc, s27, v36
	v_mul_f32_e32 v37, 0x4b800000, v36
	s_nop 0
	v_cndmask_b32_e32 v36, v36, v37, vcc
	v_rsq_f32_e32 v36, v36
	s_nop 0
	v_mul_f32_e32 v37, 0x45800000, v36
	v_cndmask_b32_e32 v36, v36, v37, vcc
	v_mul_f32_e32 v3, v3, v36
	v_lshl_add_u64 v[36:37], s[14:15], 0, v[12:13]
	v_mov_b32_e32 v36, v66
	v_lshl_add_u64 v[12:13], s[16:17], 0, v[12:13]
	v_mov_b32_e32 v12, v74
	v_fma_f32 v3, v19, v3, v20
	v_mov_b32_e32 v13, v11
	v_lshlrev_b32_e32 v36, 16, v36
	v_fmac_f32_e32 v3, v39, v36
	v_lshlrev_b32_e32 v12, 16, v12
	v_mul_f32_e32 v3, v3, v12
	v_cvt_pk_bf16_f32 v3, v3, s0
	v_or_b32_e32 v12, 0x180, v10
	global_store_short v[8:9], v3, off offset:256
	v_lshl_add_u64 v[36:37], s[8:9], 0, v[12:13]
	v_mov_b32_e32 v3, v43
	v_lshlrev_b32_e32 v3, 16, v3
	s_nop 1
	v_add_f32_dpp v36, v3, v3 quad_perm:[1,0,3,2] row_mask:0xf bank_mask:0xf bound_ctrl:1
	s_nop 1
	v_add_f32_dpp v36, v36, v36 quad_perm:[2,3,0,1] row_mask:0xf bank_mask:0xf bound_ctrl:1
	s_nop 1
	v_add_f32_dpp v36, v36, v36 row_half_mirror row_mask:0xf bank_mask:0xf bound_ctrl:1
	s_nop 1
	v_add_f32_dpp v36, v36, v36 row_mirror row_mask:0xf bank_mask:0xf bound_ctrl:1
	s_nop 0
	v_readlane_b32 s22, v36, 16
	v_readlane_b32 s23, v36, 48
	v_readlane_b32 s20, v36, 0
	v_readlane_b32 s21, v36, 32
	v_mov_b32_e32 v36, s22
	v_mov_b32_e32 v37, s23
	v_pk_add_f32 v[36:37], s[20:21], v[36:37]
	s_nop 0
	v_add_f32_e32 v36, v36, v37
	v_fmac_f32_e32 v3, 0xbc800000, v36
	v_mul_f32_e32 v36, v3, v3
	v_mov_b32_e32 v37, v1
	s_nop 1
	v_mov_b32_dpp v37, v36 quad_perm:[1,0,3,2] row_mask:0xf bank_mask:0xf
	v_fmac_f32_e32 v37, v3, v3
	s_nop 1
	v_add_f32_dpp v36, v37, v37 quad_perm:[2,3,0,1] row_mask:0xf bank_mask:0xf bound_ctrl:1
	s_nop 1
	v_add_f32_dpp v36, v36, v36 row_half_mirror row_mask:0xf bank_mask:0xf bound_ctrl:1
	s_nop 1
	v_add_f32_dpp v36, v36, v36 row_mirror row_mask:0xf bank_mask:0xf bound_ctrl:1
	s_nop 0
	v_readlane_b32 s22, v36, 16
	v_readlane_b32 s23, v36, 48
	v_readlane_b32 s20, v36, 0
	v_readlane_b32 s21, v36, 32
	v_mov_b32_e32 v36, s22
	v_mov_b32_e32 v37, s23
	v_pk_add_f32 v[36:37], s[20:21], v[36:37]
	s_nop 0
	v_add_f32_e32 v38, v36, v37
	v_lshl_add_u64 v[36:37], s[10:11], 0, v[12:13]
	v_mov_b32_e32 v36, v51
	v_lshlrev_b32_e32 v39, 16, v36
	v_lshl_add_u64 v[36:37], s[12:13], 0, v[12:13]
	v_mov_b32_e32 v36, v59
	v_lshlrev_b32_e32 v36, 16, v36
	v_mul_f32_e32 v36, v39, v36
	v_mul_f32_e32 v37, v21, v36
	v_mov_b32_e32 v39, v1
	s_nop 1
	v_mov_b32_dpp v39, v37 quad_perm:[1,0,3,2] row_mask:0xf bank_mask:0xf
	v_fmac_f32_e32 v39, v21, v36
	s_nop 1
	v_add_f32_dpp v36, v39, v39 quad_perm:[2,3,0,1] row_mask:0xf bank_mask:0xf bound_ctrl:1
	s_nop 1
	v_add_f32_dpp v36, v36, v36 row_half_mirror row_mask:0xf bank_mask:0xf bound_ctrl:1
	s_nop 1
	v_add_f32_dpp v36, v36, v36 row_mirror row_mask:0xf bank_mask:0xf bound_ctrl:1
	s_nop 0
	v_readlane_b32 s21, v36, 16
	v_readlane_b32 s23, v36, 48
	v_readlane_b32 s20, v36, 0
	v_readlane_b32 s22, v36, 32
	v_mov_b32_e32 v36, s21
	v_mov_b32_e32 v37, s23
	v_add_f32_e32 v36, s20, v36
	v_add_f32_e32 v37, s22, v37
	v_add_f32_e32 v39, v36, v37
	v_fmamk_f32 v36, v38, 0x3c800000, v216
	v_cmp_gt_f32_e32 vcc, s27, v36
	v_mul_f32_e32 v37, 0x4b800000, v36
	s_nop 0
	v_cndmask_b32_e32 v36, v36, v37, vcc
	v_rsq_f32_e32 v36, v36
	s_nop 0
	v_mul_f32_e32 v37, 0x45800000, v36
	v_cndmask_b32_e32 v36, v36, v37, vcc
	v_mul_f32_e32 v3, v3, v36
	v_lshl_add_u64 v[36:37], s[14:15], 0, v[12:13]
	v_mov_b32_e32 v36, v67
	v_lshl_add_u64 v[12:13], s[16:17], 0, v[12:13]
	v_mov_b32_e32 v12, v75
	v_fma_f32 v3, v22, v3, v23
	v_mov_b32_e32 v13, v11
	v_lshlrev_b32_e32 v36, 16, v36
	v_fmac_f32_e32 v3, v39, v36
	v_lshlrev_b32_e32 v12, 16, v12
	v_mul_f32_e32 v3, v3, v12
	v_cvt_pk_bf16_f32 v3, v3, s0
	v_or_b32_e32 v12, 0x200, v10
	global_store_short v[8:9], v3, off offset:384
	v_lshl_add_u64 v[36:37], s[8:9], 0, v[12:13]
	v_mov_b32_e32 v3, v44
	v_lshlrev_b32_e32 v3, 16, v3
	s_nop 1
	v_add_f32_dpp v36, v3, v3 quad_perm:[1,0,3,2] row_mask:0xf bank_mask:0xf bound_ctrl:1
	s_nop 1
	v_add_f32_dpp v36, v36, v36 quad_perm:[2,3,0,1] row_mask:0xf bank_mask:0xf bound_ctrl:1
	s_nop 1
	v_add_f32_dpp v36, v36, v36 row_half_mirror row_mask:0xf bank_mask:0xf bound_ctrl:1
	s_nop 1
	v_add_f32_dpp v36, v36, v36 row_mirror row_mask:0xf bank_mask:0xf bound_ctrl:1
	s_nop 0
	v_readlane_b32 s22, v36, 16
	v_readlane_b32 s23, v36, 48
	v_readlane_b32 s20, v36, 0
	v_readlane_b32 s21, v36, 32
	v_mov_b32_e32 v36, s22
	v_mov_b32_e32 v37, s23
	v_pk_add_f32 v[36:37], s[20:21], v[36:37]
	s_nop 0
	v_add_f32_e32 v36, v36, v37
	v_fmac_f32_e32 v3, 0xbc800000, v36
	v_mul_f32_e32 v36, v3, v3
	v_mov_b32_e32 v37, v1
	s_nop 1
	v_mov_b32_dpp v37, v36 quad_perm:[1,0,3,2] row_mask:0xf bank_mask:0xf
	v_fmac_f32_e32 v37, v3, v3
	s_nop 1
	v_add_f32_dpp v36, v37, v37 quad_perm:[2,3,0,1] row_mask:0xf bank_mask:0xf bound_ctrl:1
	s_nop 1
	v_add_f32_dpp v36, v36, v36 row_half_mirror row_mask:0xf bank_mask:0xf bound_ctrl:1
	s_nop 1
	v_add_f32_dpp v36, v36, v36 row_mirror row_mask:0xf bank_mask:0xf bound_ctrl:1
	s_nop 0
	v_readlane_b32 s22, v36, 16
	v_readlane_b32 s23, v36, 48
	v_readlane_b32 s20, v36, 0
	v_readlane_b32 s21, v36, 32
	v_mov_b32_e32 v36, s22
	v_mov_b32_e32 v37, s23
	v_pk_add_f32 v[36:37], s[20:21], v[36:37]
	s_nop 0
	v_add_f32_e32 v38, v36, v37
	v_lshl_add_u64 v[36:37], s[10:11], 0, v[12:13]
	v_mov_b32_e32 v36, v52
	v_lshlrev_b32_e32 v39, 16, v36
	v_lshl_add_u64 v[36:37], s[12:13], 0, v[12:13]
	v_mov_b32_e32 v36, v60
	v_lshlrev_b32_e32 v36, 16, v36
	v_mul_f32_e32 v36, v39, v36
	v_mul_f32_e32 v37, v24, v36
	v_mov_b32_e32 v39, v1
	s_nop 1
	v_mov_b32_dpp v39, v37 quad_perm:[1,0,3,2] row_mask:0xf bank_mask:0xf
	v_fmac_f32_e32 v39, v24, v36
	s_nop 1
	v_add_f32_dpp v36, v39, v39 quad_perm:[2,3,0,1] row_mask:0xf bank_mask:0xf bound_ctrl:1
	s_nop 1
	v_add_f32_dpp v36, v36, v36 row_half_mirror row_mask:0xf bank_mask:0xf bound_ctrl:1
	s_nop 1
	v_add_f32_dpp v36, v36, v36 row_mirror row_mask:0xf bank_mask:0xf bound_ctrl:1
	s_nop 0
	v_readlane_b32 s21, v36, 16
	v_readlane_b32 s23, v36, 48
	v_readlane_b32 s20, v36, 0
	v_readlane_b32 s22, v36, 32
	v_mov_b32_e32 v36, s21
	v_mov_b32_e32 v37, s23
	v_add_f32_e32 v36, s20, v36
	v_add_f32_e32 v37, s22, v37
	v_add_f32_e32 v39, v36, v37
	v_fmamk_f32 v36, v38, 0x3c800000, v216
	v_cmp_gt_f32_e32 vcc, s27, v36
	v_mul_f32_e32 v37, 0x4b800000, v36
	s_nop 0
	v_cndmask_b32_e32 v36, v36, v37, vcc
	v_rsq_f32_e32 v36, v36
	s_nop 0
	v_mul_f32_e32 v37, 0x45800000, v36
	v_cndmask_b32_e32 v36, v36, v37, vcc
	v_mul_f32_e32 v3, v3, v36
	v_lshl_add_u64 v[36:37], s[14:15], 0, v[12:13]
	v_mov_b32_e32 v36, v68
	v_lshl_add_u64 v[12:13], s[16:17], 0, v[12:13]
	v_mov_b32_e32 v12, v76
	v_fma_f32 v3, v25, v3, v26
	v_mov_b32_e32 v13, v11
	v_lshlrev_b32_e32 v36, 16, v36
	v_fmac_f32_e32 v3, v39, v36
	v_lshlrev_b32_e32 v12, 16, v12
	v_mul_f32_e32 v3, v3, v12
	v_cvt_pk_bf16_f32 v3, v3, s0
	v_or_b32_e32 v12, 0x280, v10
	global_store_short v[8:9], v3, off offset:512
	v_lshl_add_u64 v[36:37], s[8:9], 0, v[12:13]
	v_mov_b32_e32 v3, v45
	v_lshlrev_b32_e32 v3, 16, v3
	s_nop 1
	v_add_f32_dpp v36, v3, v3 quad_perm:[1,0,3,2] row_mask:0xf bank_mask:0xf bound_ctrl:1
	s_nop 1
	v_add_f32_dpp v36, v36, v36 quad_perm:[2,3,0,1] row_mask:0xf bank_mask:0xf bound_ctrl:1
	s_nop 1
	v_add_f32_dpp v36, v36, v36 row_half_mirror row_mask:0xf bank_mask:0xf bound_ctrl:1
	s_nop 1
	v_add_f32_dpp v36, v36, v36 row_mirror row_mask:0xf bank_mask:0xf bound_ctrl:1
	s_nop 0
	v_readlane_b32 s22, v36, 16
	v_readlane_b32 s23, v36, 48
	v_readlane_b32 s20, v36, 0
	v_readlane_b32 s21, v36, 32
	v_mov_b32_e32 v36, s22
	v_mov_b32_e32 v37, s23
	v_pk_add_f32 v[36:37], s[20:21], v[36:37]
	s_nop 0
	v_add_f32_e32 v36, v36, v37
	v_fmac_f32_e32 v3, 0xbc800000, v36
	v_mul_f32_e32 v36, v3, v3
	v_mov_b32_e32 v37, v1
	s_nop 1
	v_mov_b32_dpp v37, v36 quad_perm:[1,0,3,2] row_mask:0xf bank_mask:0xf
	v_fmac_f32_e32 v37, v3, v3
	s_nop 1
	v_add_f32_dpp v36, v37, v37 quad_perm:[2,3,0,1] row_mask:0xf bank_mask:0xf bound_ctrl:1
	s_nop 1
	v_add_f32_dpp v36, v36, v36 row_half_mirror row_mask:0xf bank_mask:0xf bound_ctrl:1
	s_nop 1
	v_add_f32_dpp v36, v36, v36 row_mirror row_mask:0xf bank_mask:0xf bound_ctrl:1
	s_nop 0
	v_readlane_b32 s22, v36, 16
	v_readlane_b32 s23, v36, 48
	v_readlane_b32 s20, v36, 0
	v_readlane_b32 s21, v36, 32
	v_mov_b32_e32 v36, s22
	v_mov_b32_e32 v37, s23
	v_pk_add_f32 v[36:37], s[20:21], v[36:37]
	s_nop 0
	v_add_f32_e32 v38, v36, v37
	v_lshl_add_u64 v[36:37], s[10:11], 0, v[12:13]
	v_mov_b32_e32 v36, v53
	v_lshlrev_b32_e32 v39, 16, v36
	v_lshl_add_u64 v[36:37], s[12:13], 0, v[12:13]
	v_mov_b32_e32 v36, v61
	v_lshlrev_b32_e32 v36, 16, v36
	v_mul_f32_e32 v36, v39, v36
	v_mul_f32_e32 v37, v27, v36
	v_mov_b32_e32 v39, v1
	s_nop 1
	v_mov_b32_dpp v39, v37 quad_perm:[1,0,3,2] row_mask:0xf bank_mask:0xf
	v_fmac_f32_e32 v39, v27, v36
	s_nop 1
	v_add_f32_dpp v36, v39, v39 quad_perm:[2,3,0,1] row_mask:0xf bank_mask:0xf bound_ctrl:1
	s_nop 1
	v_add_f32_dpp v36, v36, v36 row_half_mirror row_mask:0xf bank_mask:0xf bound_ctrl:1
	s_nop 1
	v_add_f32_dpp v36, v36, v36 row_mirror row_mask:0xf bank_mask:0xf bound_ctrl:1
	s_nop 0
	v_readlane_b32 s21, v36, 16
	v_readlane_b32 s23, v36, 48
	v_readlane_b32 s20, v36, 0
	v_readlane_b32 s22, v36, 32
	v_mov_b32_e32 v36, s21
	v_mov_b32_e32 v37, s23
	v_add_f32_e32 v36, s20, v36
	v_add_f32_e32 v37, s22, v37
	v_add_f32_e32 v39, v36, v37
	v_fmamk_f32 v36, v38, 0x3c800000, v216
	v_cmp_gt_f32_e32 vcc, s27, v36
	v_mul_f32_e32 v37, 0x4b800000, v36
	s_nop 0
	v_cndmask_b32_e32 v36, v36, v37, vcc
	v_rsq_f32_e32 v36, v36
	s_nop 0
	v_mul_f32_e32 v37, 0x45800000, v36
	v_cndmask_b32_e32 v36, v36, v37, vcc
	v_mul_f32_e32 v3, v3, v36
	v_lshl_add_u64 v[36:37], s[14:15], 0, v[12:13]
	v_mov_b32_e32 v36, v69
	v_lshl_add_u64 v[12:13], s[16:17], 0, v[12:13]
	v_mov_b32_e32 v12, v77
	v_fma_f32 v3, v28, v3, v29
	v_mov_b32_e32 v13, v11
	v_lshlrev_b32_e32 v36, 16, v36
	v_fmac_f32_e32 v3, v39, v36
	v_lshlrev_b32_e32 v12, 16, v12
	v_mul_f32_e32 v3, v3, v12
	v_cvt_pk_bf16_f32 v3, v3, s0
	v_or_b32_e32 v12, 0x300, v10
	global_store_short v[8:9], v3, off offset:640
	v_lshl_add_u64 v[36:37], s[8:9], 0, v[12:13]
	v_mov_b32_e32 v3, v46
	v_or_b32_e32 v10, 0x380, v10
	v_lshlrev_b32_e32 v3, 16, v3
	s_nop 1
	v_add_f32_dpp v36, v3, v3 quad_perm:[1,0,3,2] row_mask:0xf bank_mask:0xf bound_ctrl:1
	s_nop 1
	v_add_f32_dpp v36, v36, v36 quad_perm:[2,3,0,1] row_mask:0xf bank_mask:0xf bound_ctrl:1
	s_nop 1
	v_add_f32_dpp v36, v36, v36 row_half_mirror row_mask:0xf bank_mask:0xf bound_ctrl:1
	s_nop 1
	v_add_f32_dpp v36, v36, v36 row_mirror row_mask:0xf bank_mask:0xf bound_ctrl:1
	s_nop 0
	v_readlane_b32 s22, v36, 16
	v_readlane_b32 s23, v36, 48
	v_readlane_b32 s20, v36, 0
	v_readlane_b32 s21, v36, 32
	v_mov_b32_e32 v36, s22
	v_mov_b32_e32 v37, s23
	v_pk_add_f32 v[36:37], s[20:21], v[36:37]
	s_nop 0
	v_add_f32_e32 v36, v36, v37
	v_fmac_f32_e32 v3, 0xbc800000, v36
	v_mul_f32_e32 v36, v3, v3
	v_mov_b32_e32 v37, v1
	s_nop 1
	v_mov_b32_dpp v37, v36 quad_perm:[1,0,3,2] row_mask:0xf bank_mask:0xf
	v_fmac_f32_e32 v37, v3, v3
	s_nop 1
	v_add_f32_dpp v36, v37, v37 quad_perm:[2,3,0,1] row_mask:0xf bank_mask:0xf bound_ctrl:1
	s_nop 1
	v_add_f32_dpp v36, v36, v36 row_half_mirror row_mask:0xf bank_mask:0xf bound_ctrl:1
	s_nop 1
	v_add_f32_dpp v36, v36, v36 row_mirror row_mask:0xf bank_mask:0xf bound_ctrl:1
	s_nop 0
	v_readlane_b32 s22, v36, 16
	v_readlane_b32 s23, v36, 48
	v_readlane_b32 s20, v36, 0
	v_readlane_b32 s21, v36, 32
	v_mov_b32_e32 v36, s22
	v_mov_b32_e32 v37, s23
	v_pk_add_f32 v[36:37], s[20:21], v[36:37]
	s_nop 0
	v_add_f32_e32 v38, v36, v37
	v_lshl_add_u64 v[36:37], s[10:11], 0, v[12:13]
	v_mov_b32_e32 v36, v54
	v_lshlrev_b32_e32 v39, 16, v36
	v_lshl_add_u64 v[36:37], s[12:13], 0, v[12:13]
	v_mov_b32_e32 v36, v62
	v_lshlrev_b32_e32 v36, 16, v36
	v_mul_f32_e32 v36, v39, v36
	v_mul_f32_e32 v37, v30, v36
	v_mov_b32_e32 v39, v1
	s_nop 1
	v_mov_b32_dpp v39, v37 quad_perm:[1,0,3,2] row_mask:0xf bank_mask:0xf
	v_fmac_f32_e32 v39, v30, v36
	s_nop 1
	v_add_f32_dpp v36, v39, v39 quad_perm:[2,3,0,1] row_mask:0xf bank_mask:0xf bound_ctrl:1
	s_nop 1
	v_add_f32_dpp v36, v36, v36 row_half_mirror row_mask:0xf bank_mask:0xf bound_ctrl:1
	s_nop 1
	v_add_f32_dpp v36, v36, v36 row_mirror row_mask:0xf bank_mask:0xf bound_ctrl:1
	s_nop 0
	v_readlane_b32 s21, v36, 16
	v_readlane_b32 s23, v36, 48
	v_readlane_b32 s20, v36, 0
	v_readlane_b32 s22, v36, 32
	v_mov_b32_e32 v36, s21
	v_mov_b32_e32 v37, s23
	v_add_f32_e32 v36, s20, v36
	v_add_f32_e32 v37, s22, v37
	v_add_f32_e32 v39, v36, v37
	v_fmamk_f32 v36, v38, 0x3c800000, v216
	v_cmp_gt_f32_e32 vcc, s27, v36
	v_mul_f32_e32 v37, 0x4b800000, v36
	s_nop 0
	v_cndmask_b32_e32 v36, v36, v37, vcc
	v_rsq_f32_e32 v36, v36
	s_nop 0
	v_mul_f32_e32 v37, 0x45800000, v36
	v_cndmask_b32_e32 v36, v36, v37, vcc
	v_mul_f32_e32 v3, v3, v36
	v_lshl_add_u64 v[36:37], s[14:15], 0, v[12:13]
	v_mov_b32_e32 v36, v70
	v_lshl_add_u64 v[12:13], s[16:17], 0, v[12:13]
	v_mov_b32_e32 v12, v78
	v_fma_f32 v3, v31, v3, v32
	v_lshlrev_b32_e32 v36, 16, v36
	v_fmac_f32_e32 v3, v39, v36
	v_lshlrev_b32_e32 v12, 16, v12
	v_mul_f32_e32 v3, v3, v12
	v_cvt_pk_bf16_f32 v3, v3, s0
	global_store_short v[8:9], v3, off offset:768
	v_lshl_add_u64 v[12:13], s[8:9], 0, v[10:11]
	v_mov_b32_e32 v3, v47
	v_lshlrev_b32_e32 v3, 16, v3
	s_nop 1
	v_add_f32_dpp v12, v3, v3 quad_perm:[1,0,3,2] row_mask:0xf bank_mask:0xf bound_ctrl:1
	s_nop 1
	v_add_f32_dpp v12, v12, v12 quad_perm:[2,3,0,1] row_mask:0xf bank_mask:0xf bound_ctrl:1
	s_nop 1
	v_add_f32_dpp v12, v12, v12 row_half_mirror row_mask:0xf bank_mask:0xf bound_ctrl:1
	s_nop 1
	v_add_f32_dpp v12, v12, v12 row_mirror row_mask:0xf bank_mask:0xf bound_ctrl:1
	s_nop 0
	v_readlane_b32 s22, v12, 16
	v_readlane_b32 s23, v12, 48
	v_readlane_b32 s20, v12, 0
	v_readlane_b32 s21, v12, 32
	v_mov_b32_e32 v12, s22
	v_mov_b32_e32 v13, s23
	v_pk_add_f32 v[12:13], s[20:21], v[12:13]
	s_nop 0
	v_add_f32_e32 v12, v12, v13
	v_fmac_f32_e32 v3, 0xbc800000, v12
	v_mul_f32_e32 v12, v3, v3
	v_mov_b32_e32 v13, v1
	s_nop 1
	v_mov_b32_dpp v13, v12 quad_perm:[1,0,3,2] row_mask:0xf bank_mask:0xf
	v_fmac_f32_e32 v13, v3, v3
	s_nop 1
	v_add_f32_dpp v12, v13, v13 quad_perm:[2,3,0,1] row_mask:0xf bank_mask:0xf bound_ctrl:1
	s_nop 1
	v_add_f32_dpp v12, v12, v12 row_half_mirror row_mask:0xf bank_mask:0xf bound_ctrl:1
	s_nop 1
	v_add_f32_dpp v12, v12, v12 row_mirror row_mask:0xf bank_mask:0xf bound_ctrl:1
	s_nop 0
	v_readlane_b32 s22, v12, 16
	v_readlane_b32 s23, v12, 48
	v_readlane_b32 s20, v12, 0
	v_readlane_b32 s21, v12, 32
	v_mov_b32_e32 v12, s22
	v_mov_b32_e32 v13, s23
	v_pk_add_f32 v[12:13], s[20:21], v[12:13]
	s_nop 0
	v_add_f32_e32 v36, v12, v13
	v_lshl_add_u64 v[12:13], s[10:11], 0, v[10:11]
	v_mov_b32_e32 v12, v55
	v_lshlrev_b32_e32 v37, 16, v12
	v_lshl_add_u64 v[12:13], s[12:13], 0, v[10:11]
	v_mov_b32_e32 v12, v63
	v_lshlrev_b32_e32 v12, 16, v12
	v_mul_f32_e32 v12, v37, v12
	v_mul_f32_e32 v13, v33, v12
	v_mov_b32_e32 v37, v1
	s_nop 1
	v_mov_b32_dpp v37, v13 quad_perm:[1,0,3,2] row_mask:0xf bank_mask:0xf
	v_fmac_f32_e32 v37, v33, v12
	s_nop 1
	v_add_f32_dpp v12, v37, v37 quad_perm:[2,3,0,1] row_mask:0xf bank_mask:0xf bound_ctrl:1
	s_nop 1
	v_add_f32_dpp v12, v12, v12 row_half_mirror row_mask:0xf bank_mask:0xf bound_ctrl:1
	s_nop 1
	v_add_f32_dpp v12, v12, v12 row_mirror row_mask:0xf bank_mask:0xf bound_ctrl:1
	s_nop 0
	v_readlane_b32 s21, v12, 16
	v_readlane_b32 s23, v12, 48
	v_readlane_b32 s20, v12, 0
	v_readlane_b32 s22, v12, 32
	v_mov_b32_e32 v12, s21
	v_mov_b32_e32 v13, s23
	v_add_f32_e32 v12, s20, v12
	v_add_f32_e32 v13, s22, v13
	v_add_f32_e32 v37, v12, v13
	v_fmamk_f32 v12, v36, 0x3c800000, v216
	v_cmp_gt_f32_e32 vcc, s27, v12
	v_mul_f32_e32 v13, 0x4b800000, v12
	s_nop 0
	v_cndmask_b32_e32 v12, v12, v13, vcc
	v_rsq_f32_e32 v12, v12
	s_nop 0
	v_mul_f32_e32 v13, 0x45800000, v12
	v_cndmask_b32_e32 v12, v12, v13, vcc
	v_mul_f32_e32 v3, v3, v12
	v_lshl_add_u64 v[12:13], s[14:15], 0, v[10:11]
	v_mov_b32_e32 v12, v71
	v_lshl_add_u64 v[10:11], s[16:17], 0, v[10:11]
	v_mov_b32_e32 v10, v79
	v_fma_f32 v3, v34, v3, v35
	v_cmp_lt_i32_e32 vcc, s33, v2
	s_or_b64 s[18:19], vcc, s[18:19]
	v_lshlrev_b32_e32 v12, 16, v12
	v_fmac_f32_e32 v3, v37, v12
	v_lshlrev_b32_e32 v10, 16, v10
	v_mul_f32_e32 v3, v3, v10
	v_cvt_pk_bf16_f32 v3, v3, s0
	global_store_short v[8:9], v3, off offset:896
	s_andn2_b64 exec, exec, s[18:19]
	s_cbranch_execnz .LBB0_507

.LBB0_1037:
	s_or_b64 exec, exec, s[10:11]
	s_movk_i32 s11, 0x410
	v_lshrrev_b32_e32 v130, 2, v140
	v_lshlrev_b32_e32 v131, 1, v140
	v_and_b32_e32 v0, 15, v140
	v_and_b32_e32 v130, 0xfffffcc, v130
	v_and_b32_e32 v131, 0x180, v131
	v_add_u32_e32 v131, 0, v131
	v_lshlrev_b32_e32 v0, 2, v0
	v_mul_lo_u32 v130, v130, s11
	v_add3_u32 v130, v131, v0, v130
	s_waitcnt vmcnt(0)
	s_barrier
	ds_write2_b32 v130, v114, v126 offset1:16
	v_add_u32_e32 v114, 0x400, v130
	ds_write2_b32 v114, v115, v127 offset0:4 offset1:20
	v_add_u32_e32 v115, 0x800, v130
	ds_write2_b32 v115, v116, v128 offset0:8 offset1:24
	v_add_u32_e32 v116, 0xc00, v130
	ds_write2_b32 v116, v117, v129 offset0:12 offset1:28
	v_add_u32_e32 v117, 0x4000, v130
	ds_write2_b32 v117, v82, v94 offset0:64 offset1:80
	v_add_u32_e32 v82, 0x4400, v130
	ds_write2_b32 v82, v83, v95 offset0:68 offset1:84
	v_add_u32_e32 v83, 0x4800, v130
	ds_write2_b32 v83, v84, v96 offset0:72 offset1:88
	v_add_u32_e32 v84, 0x4c00, v130
	ds_write2_b32 v84, v85, v97 offset0:76 offset1:92
	v_add_u32_e32 v85, 0x8000, v130
	ds_write2_b32 v85, v74, v78 offset0:128 offset1:144
	v_add_u32_e32 v74, 0x8400, v130
	ds_write2_b32 v74, v75, v79 offset0:132 offset1:148
	v_add_u32_e32 v75, 0x8800, v130
	ds_write2_b32 v75, v76, v80 offset0:136 offset1:152
	v_add_u32_e32 v76, 0x8c00, v130
	v_add_u32_e32 v80, 0xc000, v130
	ds_write2_b32 v76, v77, v81 offset0:140 offset1:156
	ds_write2_b32 v80, v66, v70 offset0:192 offset1:208
	v_add_u32_e32 v77, 0xc400, v130
	v_add_u32_e32 v78, 0xc800, v130
	v_add_u32_e32 v79, 0xcc00, v130
	v_add_u32_e32 v81, 0x9000, v130
	v_lshlrev_b32_e32 v66, 2, v140
	ds_write2_b32 v77, v67, v71 offset0:196 offset1:212
	ds_write2_b32 v78, v68, v72 offset0:200 offset1:216
	ds_write2_b32 v79, v69, v73 offset0:204 offset1:220
	ds_write2_b32 v130, v98, v118 offset0:128 offset1:144
	ds_write2_b32 v114, v99, v119 offset0:132 offset1:148
	ds_write2_b32 v115, v100, v120 offset0:136 offset1:152
	ds_write2_b32 v116, v101, v121 offset0:140 offset1:156
	ds_write2_b32 v117, v102, v122 offset0:192 offset1:208
	ds_write2_b32 v82, v103, v123 offset0:196 offset1:212
	ds_write2_b32 v83, v104, v124 offset0:200 offset1:216
	ds_write2_b32 v84, v105, v125 offset0:204 offset1:220
	ds_write2_b32 v74, v90, v110 offset1:16
	ds_write2_b32 v75, v91, v111 offset0:4 offset1:20
	ds_write2_b32 v76, v92, v112 offset0:8 offset1:24
	ds_write2_b32 v81, v93, v113 offset0:12 offset1:28
	ds_write2_b32 v77, v86, v106 offset0:64 offset1:80
	ds_write2_b32 v78, v87, v107 offset0:68 offset1:84
	ds_write2_b32 v79, v88, v108 offset0:72 offset1:88
	v_lshlrev_b32_e32 v0, 3, v140
	v_and_b32_e32 v66, 12, v66
	s_movk_i32 s10, 0xe0
	v_ashrrev_i32_e32 v87, 5, v140
	v_and_or_b32 v0, v0, s10, v66
	v_add_u32_e32 v68, s17, v87
	v_or_b32_e32 v66, s7, v0
	v_ashrrev_i32_e32 v69, 31, v68
	v_ashrrev_i32_e32 v67, 31, v66
	v_lshlrev_b64 v[70:71], 10, v[68:69]
	v_lshl_add_u64 v[98:99], v[70:71], 0, v[66:67]
	v_add_u32_e32 v86, 0xd000, v130
	v_lshl_add_u64 v[110:111], v[98:99], 2, s[18:19]
	ds_write2_b32 v86, v89, v109 offset0:76 offset1:92
	s_waitcnt lgkmcnt(0)
	s_barrier
	v_lshlrev_b32_e32 v141, 2, v98
	global_load_dwordx4 v[132:135], v141, s[18:19]
	global_load_dwordx4 v[136:139], v141, s[18:19] offset:64
	v_add_u32_e32 v141, 0x10000, v141
	global_load_dwordx4 v[142:145], v141, s[18:19]
	global_load_dwordx4 v[146:149], v141, s[18:19] offset:64
	v_add_u32_e32 v141, 0x10000, v141
	global_load_dwordx4 v[150:153], v141, s[18:19]
	global_load_dwordx4 v[154:157], v141, s[18:19] offset:64
	v_add_u32_e32 v141, 0x10000, v141
	global_load_dwordx4 v[158:161], v141, s[18:19]
	global_load_dwordx4 v[162:165], v141, s[18:19] offset:64
	v_add_u32_e32 v141, 0x10000, v141
	global_load_dwordx4 v[166:169], v141, s[18:19]
	global_load_dwordx4 v[170:173], v141, s[18:19] offset:64
	v_add_u32_e32 v141, 0x10000, v141
	global_load_dwordx4 v[174:177], v141, s[18:19]
	global_load_dwordx4 v[178:181], v141, s[18:19] offset:64
	v_add_u32_e32 v141, 0x10000, v141
	global_load_dwordx4 v[182:185], v141, s[18:19]
	global_load_dwordx4 v[186:189], v141, s[18:19] offset:64
	v_add_u32_e32 v141, 0x10000, v141
	global_load_dwordx4 v[190:193], v141, s[18:19]
	global_load_dwordx4 v[194:197], v141, s[18:19] offset:64
	v_lshl_add_u32 v101, v0, 2, 0
	v_mul_lo_u32 v72, v87, s11
	v_add_u32_e32 v88, v101, v72
	ds_read_b128 v[102:105], v88
	ds_read_b128 v[106:109], v88 offset:64
	v_and_b32_e32 v70, 64, v218
	v_xor_b32_e32 v0, 1, v218
	v_add_u32_e32 v100, 64, v70
	v_cmp_lt_i32_e32 vcc, v0, v100
	v_xor_b32_e32 v70, 2, v218
	v_xor_b32_e32 v71, 4, v218
	v_cndmask_b32_e32 v0, v218, v0, vcc
	v_lshlrev_b32_e32 v0, 2, v0
	v_cmp_lt_i32_e32 vcc, v70, v100
	v_xor_b32_e32 v112, 8, v218
	v_and_b32_e32 v89, 31, v140
	v_cndmask_b32_e32 v70, v218, v70, vcc
	v_lshlrev_b32_e32 v70, 2, v70
	v_cmp_lt_i32_e32 vcc, v71, v100
	s_ashr_i32 s7, s6, 31
	s_lshl_b64 s[10:11], s[6:7], 2
	v_cndmask_b32_e32 v71, v218, v71, vcc
	v_cmp_lt_i32_e32 vcc, v112, v100
	v_lshlrev_b32_e32 v71, 2, v71
	s_add_u32 s10, s40, s10
	s_movk_i32 s20, 0x410
	s_addc_u32 s11, s41, s11
	s_waitcnt lgkmcnt(1)
	s_waitcnt vmcnt(15)
	v_pk_fma_f32 v[90:91], v[102:103], 0.5, v[132:133] op_sel_hi:[1,0,1]
	s_waitcnt vmcnt(15)
	v_pk_fma_f32 v[92:93], v[104:105], 0.5, v[134:135] op_sel_hi:[1,0,1]
	v_pk_mul_f32 v[72:73], v[90:91], v[90:91]
	v_pk_mul_f32 v[102:103], v[92:93], v[92:93]
	v_add_f32_e32 v72, v72, v73
	s_waitcnt lgkmcnt(0)
	s_waitcnt vmcnt(14)
	v_pk_fma_f32 v[94:95], v[106:107], 0.5, v[136:137] op_sel_hi:[1,0,1]
	v_add_f32_e32 v72, v102, v72
	v_pk_mul_f32 v[104:105], v[94:95], v[94:95]
	v_add_f32_e32 v72, v103, v72
	s_waitcnt vmcnt(14)
	v_pk_fma_f32 v[96:97], v[108:109], 0.5, v[138:139] op_sel_hi:[1,0,1]
	v_add_f32_e32 v72, v104, v72
	v_pk_mul_f32 v[106:107], v[96:97], v[96:97]
	v_add_f32_e32 v72, v105, v72
	v_add_f32_e32 v72, v106, v72
	v_add_f32_e32 v72, v107, v72
	ds_bpermute_b32 v102, v0, v72
	v_xor_b32_e32 v103, 16, v218
	v_cndmask_b32_e32 v73, v218, v112, vcc
	v_cmp_lt_i32_e32 vcc, v103, v100
	v_lshlrev_b32_e32 v73, 2, v73
	s_waitcnt lgkmcnt(0)
	v_add_f32_e32 v102, v72, v102
	ds_bpermute_b32 v104, v70, v102
	v_cndmask_b32_e32 v72, v218, v103, vcc
	v_cmp_eq_u32_e32 vcc, 0, v89
	v_lshlrev_b32_e32 v72, 2, v72
	global_store_dwordx4 v[110:111], v[90:93], off
	s_waitcnt lgkmcnt(0)
	v_add_f32_e32 v89, v102, v104
	ds_bpermute_b32 v100, v71, v89
	v_cvt_pk_bf16_f32 v102, v90, v91
	global_store_dwordx4 v[110:111], v[94:97], off offset:64
	v_cvt_pk_bf16_f32 v103, v92, v93
	v_lshl_add_u64 v[92:93], v[98:99], 1, s[38:39]
	s_waitcnt lgkmcnt(0)
	v_add_f32_e32 v89, v89, v100
	ds_bpermute_b32 v100, v73, v89
	v_cvt_pk_bf16_f32 v94, v94, v95
	v_cvt_pk_bf16_f32 v95, v96, v97
	global_store_dwordx2 v[92:93], v[102:103], off
	global_store_dwordx2 v[92:93], v[94:95], off offset:32
	s_waitcnt lgkmcnt(0)
	v_add_f32_e32 v89, v89, v100
	ds_bpermute_b32 v90, v72, v89
	s_and_saveexec_b64 s[12:13], vcc
	s_mov_b32 s75, s46
	s_cbranch_execz .LBB0_1039
	s_waitcnt lgkmcnt(0)
	v_add_f32_e32 v89, v89, v90
	v_lshl_add_u64 v[68:69], v[68:69], 4, s[10:11]
	global_store_dword v[68:69], v89, off
.LBB0_1039:
	s_or_b64 exec, exec, s[12:13]
	v_add_u32_e32 v68, 0x200, v140
	s_waitcnt lgkmcnt(0)
	v_ashrrev_i32_e32 v90, 5, v68
	v_mul_lo_u32 v68, v90, s20
	v_add_u32_e32 v89, v101, v68
	v_add_u32_e32 v68, s17, v90
	v_ashrrev_i32_e32 v69, 31, v68
	v_lshlrev_b64 v[92:93], 10, v[68:69]
	v_lshl_add_u64 v[106:107], v[92:93], 0, v[66:67]
	v_lshl_add_u64 v[108:109], v[106:107], 2, s[18:19]
	ds_read_b128 v[92:95], v89
	s_waitcnt lgkmcnt(0)
	s_waitcnt vmcnt(18)
	v_pk_fma_f32 v[92:93], v[92:93], 0.5, v[142:143] op_sel_hi:[1,0,1]
	s_waitcnt vmcnt(18)
	v_pk_fma_f32 v[94:95], v[94:95], 0.5, v[144:145] op_sel_hi:[1,0,1]
	ds_read_b128 v[96:99], v89 offset:64
	global_store_dwordx4 v[108:109], v[92:95], off
	s_waitcnt lgkmcnt(0)
	s_waitcnt vmcnt(18)
	v_pk_fma_f32 v[96:97], v[96:97], 0.5, v[146:147] op_sel_hi:[1,0,1]
	v_cvt_pk_bf16_f32 v102, v92, v93
	v_pk_mul_f32 v[92:93], v[92:93], v[92:93]
	v_cvt_pk_bf16_f32 v103, v94, v95
	v_pk_mul_f32 v[94:95], v[94:95], v[94:95]
	v_add_f32_e32 v91, v92, v93
	s_waitcnt vmcnt(18)
	v_pk_fma_f32 v[98:99], v[98:99], 0.5, v[148:149] op_sel_hi:[1,0,1]
	v_lshl_add_u64 v[104:105], v[106:107], 1, s[38:39]
	v_add_f32_e32 v91, v94, v91
	global_store_dwordx4 v[108:109], v[96:99], off offset:64
	global_store_dwordx2 v[104:105], v[102:103], off
	v_cvt_pk_bf16_f32 v102, v96, v97
	v_pk_mul_f32 v[96:97], v[96:97], v[96:97]
	v_add_f32_e32 v91, v95, v91
	v_add_f32_e32 v91, v96, v91
	v_cvt_pk_bf16_f32 v103, v98, v99
	v_pk_mul_f32 v[98:99], v[98:99], v[98:99]
	v_add_f32_e32 v91, v97, v91
	v_add_f32_e32 v91, v98, v91
	v_add_f32_e32 v91, v99, v91
	ds_bpermute_b32 v92, v0, v91
	global_store_dwordx2 v[104:105], v[102:103], off offset:32
	s_waitcnt lgkmcnt(0)
	v_add_f32_e32 v91, v91, v92
	ds_bpermute_b32 v92, v70, v91
	s_waitcnt lgkmcnt(0)
	v_add_f32_e32 v91, v91, v92
	ds_bpermute_b32 v92, v71, v91
	s_waitcnt lgkmcnt(0)
	v_add_f32_e32 v91, v91, v92
	ds_bpermute_b32 v92, v73, v91
	s_waitcnt lgkmcnt(0)
	v_add_f32_e32 v91, v91, v92
	ds_bpermute_b32 v92, v72, v91
	s_and_saveexec_b64 s[12:13], vcc
	s_cbranch_execz .LBB0_1041
	s_waitcnt lgkmcnt(0)
	v_add_f32_e32 v91, v91, v92
	v_lshl_add_u64 v[68:69], v[68:69], 4, s[10:11]
	global_store_dword v[68:69], v91, off
.LBB0_1041:
	s_or_b64 exec, exec, s[12:13]
	v_add_u32_e32 v68, 0x400, v140
	s_waitcnt lgkmcnt(0)
	v_ashrrev_i32_e32 v92, 5, v68
	v_mul_lo_u32 v68, v92, s20
	v_add_u32_e32 v91, v101, v68
	v_add_u32_e32 v68, s17, v92
	v_ashrrev_i32_e32 v69, 31, v68
	v_lshlrev_b64 v[94:95], 10, v[68:69]
	v_lshl_add_u64 v[98:99], v[94:95], 0, v[66:67]
	v_lshl_add_u64 v[110:111], v[98:99], 2, s[18:19]
	ds_read_b128 v[94:97], v91
	v_lshl_add_u64 v[98:99], v[98:99], 1, s[38:39]
	s_waitcnt lgkmcnt(0)
	s_waitcnt vmcnt(21)
	v_pk_fma_f32 v[94:95], v[94:95], 0.5, v[150:151] op_sel_hi:[1,0,1]
	s_waitcnt vmcnt(21)
	v_pk_fma_f32 v[96:97], v[96:97], 0.5, v[152:153] op_sel_hi:[1,0,1]
	ds_read_b128 v[102:105], v91 offset:64
	global_store_dwordx4 v[110:111], v[94:97], off
	s_waitcnt lgkmcnt(0)
	s_waitcnt vmcnt(21)
	v_pk_fma_f32 v[102:103], v[102:103], 0.5, v[154:155] op_sel_hi:[1,0,1]
	v_cvt_pk_bf16_f32 v106, v94, v95
	v_pk_mul_f32 v[94:95], v[94:95], v[94:95]
	s_waitcnt vmcnt(21)
	v_pk_fma_f32 v[104:105], v[104:105], 0.5, v[156:157] op_sel_hi:[1,0,1]
	v_cvt_pk_bf16_f32 v107, v96, v97
	v_pk_mul_f32 v[96:97], v[96:97], v[96:97]
	v_add_f32_e32 v93, v94, v95
	global_store_dwordx4 v[110:111], v[102:105], off offset:64
	global_store_dwordx2 v[98:99], v[106:107], off
	v_cvt_pk_bf16_f32 v106, v102, v103
	v_cvt_pk_bf16_f32 v107, v104, v105
	v_add_f32_e32 v93, v96, v93
	global_store_dwordx2 v[98:99], v[106:107], off offset:32
	v_pk_mul_f32 v[98:99], v[102:103], v[102:103]
	v_add_f32_e32 v93, v97, v93
	v_add_f32_e32 v93, v98, v93
	v_pk_mul_f32 v[102:103], v[104:105], v[104:105]
	v_add_f32_e32 v93, v99, v93
	v_add_f32_e32 v93, v102, v93
	v_add_f32_e32 v93, v103, v93
	ds_bpermute_b32 v94, v0, v93
	s_waitcnt lgkmcnt(0)
	v_add_f32_e32 v93, v93, v94
	ds_bpermute_b32 v94, v70, v93
	s_waitcnt lgkmcnt(0)
	v_add_f32_e32 v93, v93, v94
	ds_bpermute_b32 v94, v71, v93
	s_waitcnt lgkmcnt(0)
	v_add_f32_e32 v93, v93, v94
	ds_bpermute_b32 v94, v73, v93
	s_waitcnt lgkmcnt(0)
	v_add_f32_e32 v93, v93, v94
	ds_bpermute_b32 v94, v72, v93
	s_and_saveexec_b64 s[12:13], vcc
	s_cbranch_execz .LBB0_1043
	s_waitcnt lgkmcnt(0)
	v_add_f32_e32 v93, v93, v94
	v_lshl_add_u64 v[68:69], v[68:69], 4, s[10:11]
	global_store_dword v[68:69], v93, off
.LBB0_1043:
	s_or_b64 exec, exec, s[12:13]
	v_add_u32_e32 v68, 0x600, v140
	s_waitcnt lgkmcnt(0)
	v_ashrrev_i32_e32 v94, 5, v68
	v_mul_lo_u32 v68, v94, s20
	v_add_u32_e32 v93, v101, v68
	v_add_u32_e32 v68, s17, v94
	v_ashrrev_i32_e32 v69, 31, v68
	v_lshlrev_b64 v[96:97], 10, v[68:69]
	v_lshl_add_u64 v[110:111], v[96:97], 0, v[66:67]
	v_lshl_add_u64 v[112:113], v[110:111], 2, s[18:19]
	ds_read_b128 v[96:99], v93
	s_waitcnt lgkmcnt(0)
	s_waitcnt vmcnt(24)
	v_pk_fma_f32 v[96:97], v[96:97], 0.5, v[158:159] op_sel_hi:[1,0,1]
	s_waitcnt vmcnt(24)
	v_pk_fma_f32 v[98:99], v[98:99], 0.5, v[160:161] op_sel_hi:[1,0,1]
	ds_read_b128 v[102:105], v93 offset:64
	global_store_dwordx4 v[112:113], v[96:99], off
	s_waitcnt lgkmcnt(0)
	s_waitcnt vmcnt(24)
	v_pk_fma_f32 v[102:103], v[102:103], 0.5, v[162:163] op_sel_hi:[1,0,1]
	v_cvt_pk_bf16_f32 v106, v96, v97
	v_pk_mul_f32 v[96:97], v[96:97], v[96:97]
	v_cvt_pk_bf16_f32 v107, v98, v99
	v_pk_mul_f32 v[98:99], v[98:99], v[98:99]
	v_add_f32_e32 v95, v96, v97
	s_waitcnt vmcnt(24)
	v_pk_fma_f32 v[104:105], v[104:105], 0.5, v[164:165] op_sel_hi:[1,0,1]
	v_lshl_add_u64 v[108:109], v[110:111], 1, s[38:39]
	v_add_f32_e32 v95, v98, v95
	global_store_dwordx4 v[112:113], v[102:105], off offset:64
	global_store_dwordx2 v[108:109], v[106:107], off
	v_cvt_pk_bf16_f32 v106, v102, v103
	v_pk_mul_f32 v[102:103], v[102:103], v[102:103]
	v_add_f32_e32 v95, v99, v95
	v_add_f32_e32 v95, v102, v95
	v_cvt_pk_bf16_f32 v107, v104, v105
	v_pk_mul_f32 v[104:105], v[104:105], v[104:105]
	v_add_f32_e32 v95, v103, v95
	v_add_f32_e32 v95, v104, v95
	v_add_f32_e32 v95, v105, v95
	ds_bpermute_b32 v96, v0, v95
	global_store_dwordx2 v[108:109], v[106:107], off offset:32
	s_waitcnt lgkmcnt(0)
	v_add_f32_e32 v95, v95, v96
	ds_bpermute_b32 v96, v70, v95
	s_waitcnt lgkmcnt(0)
	v_add_f32_e32 v95, v95, v96
	ds_bpermute_b32 v96, v71, v95
	s_waitcnt lgkmcnt(0)
	v_add_f32_e32 v95, v95, v96
	ds_bpermute_b32 v96, v73, v95
	s_waitcnt lgkmcnt(0)
	v_add_f32_e32 v95, v95, v96
	ds_bpermute_b32 v96, v72, v95
	s_and_saveexec_b64 s[12:13], vcc
	s_cbranch_execz .LBB0_1045
	s_waitcnt lgkmcnt(0)
	v_add_f32_e32 v95, v95, v96
	v_lshl_add_u64 v[68:69], v[68:69], 4, s[10:11]
	global_store_dword v[68:69], v95, off
.LBB0_1045:
	s_or_b64 exec, exec, s[12:13]
	v_add_u32_e32 v68, 0x800, v140
	s_waitcnt lgkmcnt(0)
	v_ashrrev_i32_e32 v96, 5, v68
	v_mul_lo_u32 v68, v96, s20
	v_add_u32_e32 v95, v101, v68
	v_add_u32_e32 v68, s17, v96
	v_ashrrev_i32_e32 v69, 31, v68
	v_lshlrev_b64 v[98:99], 10, v[68:69]
	v_lshl_add_u64 v[98:99], v[98:99], 0, v[66:67]
	v_lshl_add_u64 v[118:119], v[98:99], 2, s[18:19]
	ds_read_b128 v[102:105], v95
	v_lshl_add_u64 v[98:99], v[98:99], 1, s[38:39]
	s_waitcnt lgkmcnt(0)
	s_waitcnt vmcnt(27)
	v_pk_fma_f32 v[102:103], v[102:103], 0.5, v[166:167] op_sel_hi:[1,0,1]
	s_waitcnt vmcnt(27)
	v_pk_fma_f32 v[104:105], v[104:105], 0.5, v[168:169] op_sel_hi:[1,0,1]
	ds_read_b128 v[106:109], v95 offset:64
	global_store_dwordx4 v[118:119], v[102:105], off
	s_waitcnt lgkmcnt(0)
	s_waitcnt vmcnt(27)
	v_pk_fma_f32 v[106:107], v[106:107], 0.5, v[170:171] op_sel_hi:[1,0,1]
	s_waitcnt vmcnt(27)
	v_pk_fma_f32 v[108:109], v[108:109], 0.5, v[172:173] op_sel_hi:[1,0,1]
	v_cvt_pk_bf16_f32 v110, v102, v103
	v_cvt_pk_bf16_f32 v111, v104, v105
	global_store_dwordx4 v[118:119], v[106:109], off offset:64
	global_store_dwordx2 v[98:99], v[110:111], off
	v_cvt_pk_bf16_f32 v110, v106, v107
	v_cvt_pk_bf16_f32 v111, v108, v109
	global_store_dwordx2 v[98:99], v[110:111], off offset:32
	v_pk_mul_f32 v[98:99], v[102:103], v[102:103]
	v_pk_mul_f32 v[102:103], v[104:105], v[104:105]
	v_add_f32_e32 v97, v98, v99
	v_add_f32_e32 v97, v102, v97
	v_pk_mul_f32 v[104:105], v[106:107], v[106:107]
	v_add_f32_e32 v97, v103, v97
	v_add_f32_e32 v97, v104, v97
	v_pk_mul_f32 v[106:107], v[108:109], v[108:109]
	v_add_f32_e32 v97, v105, v97
	v_add_f32_e32 v97, v106, v97
	v_add_f32_e32 v97, v107, v97
	ds_bpermute_b32 v98, v0, v97
	s_waitcnt lgkmcnt(0)
	v_add_f32_e32 v97, v97, v98
	ds_bpermute_b32 v98, v70, v97
	s_waitcnt lgkmcnt(0)
	v_add_f32_e32 v97, v97, v98
	ds_bpermute_b32 v98, v71, v97
	s_waitcnt lgkmcnt(0)
	v_add_f32_e32 v97, v97, v98
	ds_bpermute_b32 v98, v73, v97
	s_waitcnt lgkmcnt(0)
	v_add_f32_e32 v97, v97, v98
	ds_bpermute_b32 v98, v72, v97
	s_and_saveexec_b64 s[12:13], vcc
	s_cbranch_execz .LBB0_1047
	s_waitcnt lgkmcnt(0)
	v_add_f32_e32 v97, v97, v98
	v_lshl_add_u64 v[68:69], v[68:69], 4, s[10:11]
	global_store_dword v[68:69], v97, off
.LBB0_1047:
	s_or_b64 exec, exec, s[12:13]
	v_add_u32_e32 v68, 0xa00, v140
	s_waitcnt lgkmcnt(0)
	v_ashrrev_i32_e32 v98, 5, v68
	v_mul_lo_u32 v68, v98, s20
	v_add_u32_e32 v97, v101, v68
	v_add_u32_e32 v68, s17, v98
	v_ashrrev_i32_e32 v69, 31, v68
	v_lshlrev_b64 v[102:103], 10, v[68:69]
	v_lshl_add_u64 v[118:119], v[102:103], 0, v[66:67]
	v_lshl_add_u64 v[120:121], v[118:119], 2, s[18:19]
	ds_read_b128 v[102:105], v97
	s_waitcnt lgkmcnt(0)
	s_waitcnt vmcnt(30)
	v_pk_fma_f32 v[102:103], v[102:103], 0.5, v[174:175] op_sel_hi:[1,0,1]
	s_waitcnt vmcnt(30)
	v_pk_fma_f32 v[104:105], v[104:105], 0.5, v[176:177] op_sel_hi:[1,0,1]
	ds_read_b128 v[106:109], v97 offset:64
	global_store_dwordx4 v[120:121], v[102:105], off
	s_waitcnt lgkmcnt(0)
	s_waitcnt vmcnt(30)
	v_pk_fma_f32 v[106:107], v[106:107], 0.5, v[178:179] op_sel_hi:[1,0,1]
	v_cvt_pk_bf16_f32 v110, v102, v103
	v_pk_mul_f32 v[102:103], v[102:103], v[102:103]
	v_cvt_pk_bf16_f32 v111, v104, v105
	v_pk_mul_f32 v[104:105], v[104:105], v[104:105]
	v_add_f32_e32 v99, v102, v103
	s_waitcnt vmcnt(30)
	v_pk_fma_f32 v[108:109], v[108:109], 0.5, v[180:181] op_sel_hi:[1,0,1]
	v_lshl_add_u64 v[112:113], v[118:119], 1, s[38:39]
	v_add_f32_e32 v99, v104, v99
	global_store_dwordx4 v[120:121], v[106:109], off offset:64
	global_store_dwordx2 v[112:113], v[110:111], off
	v_cvt_pk_bf16_f32 v110, v106, v107
	v_pk_mul_f32 v[106:107], v[106:107], v[106:107]
	v_add_f32_e32 v99, v105, v99
	v_add_f32_e32 v99, v106, v99
	v_cvt_pk_bf16_f32 v111, v108, v109
	v_pk_mul_f32 v[108:109], v[108:109], v[108:109]
	v_add_f32_e32 v99, v107, v99
	v_add_f32_e32 v99, v108, v99
	v_add_f32_e32 v99, v109, v99
	ds_bpermute_b32 v100, v0, v99
	global_store_dwordx2 v[112:113], v[110:111], off offset:32
	s_waitcnt lgkmcnt(0)
	v_add_f32_e32 v99, v99, v100
	ds_bpermute_b32 v100, v70, v99
	s_waitcnt lgkmcnt(0)
	v_add_f32_e32 v99, v99, v100
	ds_bpermute_b32 v100, v71, v99
	s_waitcnt lgkmcnt(0)
	v_add_f32_e32 v99, v99, v100
	ds_bpermute_b32 v100, v73, v99
	s_waitcnt lgkmcnt(0)
	v_add_f32_e32 v99, v99, v100
	ds_bpermute_b32 v100, v72, v99
	s_and_saveexec_b64 s[12:13], vcc
	s_cbranch_execz .LBB0_1049
	s_waitcnt lgkmcnt(0)
	v_add_f32_e32 v99, v99, v100
	v_lshl_add_u64 v[68:69], v[68:69], 4, s[10:11]
	global_store_dword v[68:69], v99, off
.LBB0_1049:
	s_or_b64 exec, exec, s[12:13]
	v_add_u32_e32 v68, 0xc00, v140
	s_waitcnt lgkmcnt(0)
	v_ashrrev_i32_e32 v100, 5, v68
	v_mul_lo_u32 v68, v100, s20
	v_add_u32_e32 v99, v101, v68
	v_add_u32_e32 v68, s17, v100
	v_ashrrev_i32_e32 v69, 31, v68
	v_lshlrev_b64 v[102:103], 10, v[68:69]
	v_lshl_add_u64 v[118:119], v[102:103], 0, v[66:67]
	v_lshl_add_u64 v[120:121], v[118:119], 2, s[18:19]
	ds_read_b128 v[102:105], v99
	s_waitcnt lgkmcnt(0)
	s_waitcnt vmcnt(33)
	v_pk_fma_f32 v[102:103], v[102:103], 0.5, v[182:183] op_sel_hi:[1,0,1]
	s_waitcnt vmcnt(33)
	v_pk_fma_f32 v[104:105], v[104:105], 0.5, v[184:185] op_sel_hi:[1,0,1]
	ds_read_b128 v[106:109], v99 offset:64
	global_store_dwordx4 v[120:121], v[102:105], off
	s_waitcnt lgkmcnt(0)
	s_waitcnt vmcnt(33)
	v_pk_fma_f32 v[106:107], v[106:107], 0.5, v[186:187] op_sel_hi:[1,0,1]
	v_cvt_pk_bf16_f32 v110, v102, v103
	v_pk_mul_f32 v[102:103], v[102:103], v[102:103]
	v_cvt_pk_bf16_f32 v111, v104, v105
	v_pk_mul_f32 v[104:105], v[104:105], v[104:105]
	v_add_f32_e32 v102, v102, v103
	s_waitcnt vmcnt(33)
	v_pk_fma_f32 v[108:109], v[108:109], 0.5, v[188:189] op_sel_hi:[1,0,1]
	v_lshl_add_u64 v[112:113], v[118:119], 1, s[38:39]
	v_add_f32_e32 v102, v104, v102
	global_store_dwordx4 v[120:121], v[106:109], off offset:64
	global_store_dwordx2 v[112:113], v[110:111], off
	v_cvt_pk_bf16_f32 v110, v106, v107
	v_pk_mul_f32 v[106:107], v[106:107], v[106:107]
	v_add_f32_e32 v102, v105, v102
	v_add_f32_e32 v102, v106, v102
	v_cvt_pk_bf16_f32 v111, v108, v109
	v_pk_mul_f32 v[108:109], v[108:109], v[108:109]
	v_add_f32_e32 v102, v107, v102
	v_add_f32_e32 v102, v108, v102
	v_add_f32_e32 v102, v109, v102
	ds_bpermute_b32 v103, v0, v102
	global_store_dwordx2 v[112:113], v[110:111], off offset:32
	s_waitcnt lgkmcnt(0)
	v_add_f32_e32 v102, v102, v103
	ds_bpermute_b32 v103, v70, v102
	s_waitcnt lgkmcnt(0)
	v_add_f32_e32 v102, v102, v103
	ds_bpermute_b32 v103, v71, v102
	s_waitcnt lgkmcnt(0)
	v_add_f32_e32 v102, v102, v103
	ds_bpermute_b32 v103, v73, v102
	s_waitcnt lgkmcnt(0)
	v_add_f32_e32 v102, v102, v103
	ds_bpermute_b32 v103, v72, v102
	s_and_saveexec_b64 s[12:13], vcc
	s_cbranch_execz .LBB0_1051
	s_waitcnt lgkmcnt(0)
	v_add_f32_e32 v102, v102, v103
	v_lshl_add_u64 v[68:69], v[68:69], 4, s[10:11]
	global_store_dword v[68:69], v102, off
.LBB0_1051:
	s_or_b64 exec, exec, s[12:13]
	v_add_u32_e32 v68, 0xe00, v140
	v_ashrrev_i32_e32 v102, 5, v68
	v_mul_lo_u32 v68, v102, s20
	v_add_u32_e32 v101, v101, v68
	v_add_u32_e32 v68, s17, v102
	v_ashrrev_i32_e32 v69, 31, v68
	v_lshlrev_b64 v[104:105], 10, v[68:69]
	v_lshl_add_u64 v[112:113], v[104:105], 0, v[66:67]
	v_lshl_add_u64 v[122:123], v[112:113], 2, s[18:19]
	ds_read_b128 v[104:107], v101
	v_lshl_add_u64 v[112:113], v[112:113], 1, s[38:39]
	s_waitcnt lgkmcnt(0)
	s_waitcnt vmcnt(36)
	v_pk_fma_f32 v[104:105], v[104:105], 0.5, v[190:191] op_sel_hi:[1,0,1]
	s_waitcnt vmcnt(36)
	v_pk_fma_f32 v[106:107], v[106:107], 0.5, v[192:193] op_sel_hi:[1,0,1]
	ds_read_b128 v[108:111], v101 offset:64
	global_store_dwordx4 v[122:123], v[104:107], off
	s_waitcnt lgkmcnt(0)
	s_waitcnt vmcnt(36)
	v_pk_fma_f32 v[108:109], v[108:109], 0.5, v[194:195] op_sel_hi:[1,0,1]
	v_cvt_pk_bf16_f32 v118, v104, v105
	v_pk_mul_f32 v[104:105], v[104:105], v[104:105]
	v_cvt_pk_bf16_f32 v119, v106, v107
	v_pk_mul_f32 v[106:107], v[106:107], v[106:107]
	v_add_f32_e32 v103, v104, v105
	s_waitcnt vmcnt(36)
	v_pk_fma_f32 v[110:111], v[110:111], 0.5, v[196:197] op_sel_hi:[1,0,1]
	v_add_f32_e32 v103, v106, v103
	global_store_dwordx4 v[122:123], v[108:111], off offset:64
	global_store_dwordx2 v[112:113], v[118:119], off
	v_cvt_pk_bf16_f32 v118, v108, v109
	v_pk_mul_f32 v[108:109], v[108:109], v[108:109]
	v_add_f32_e32 v103, v107, v103
	v_add_f32_e32 v103, v108, v103
	v_cvt_pk_bf16_f32 v119, v110, v111
	v_pk_mul_f32 v[110:111], v[110:111], v[110:111]
	v_add_f32_e32 v103, v109, v103
	v_add_f32_e32 v103, v110, v103
	v_add_f32_e32 v103, v111, v103
	ds_bpermute_b32 v104, v0, v103
	global_store_dwordx2 v[112:113], v[118:119], off offset:32
	s_waitcnt lgkmcnt(0)
	v_add_f32_e32 v103, v103, v104
	ds_bpermute_b32 v104, v70, v103
	s_waitcnt lgkmcnt(0)
	v_add_f32_e32 v103, v103, v104
	ds_bpermute_b32 v104, v71, v103
	s_waitcnt lgkmcnt(0)
	v_add_f32_e32 v103, v103, v104
	ds_bpermute_b32 v104, v73, v103
	s_waitcnt lgkmcnt(0)
	v_add_f32_e32 v103, v103, v104
	ds_bpermute_b32 v104, v72, v103
	s_and_saveexec_b64 s[12:13], vcc
	s_cbranch_execz .LBB0_1053
	s_waitcnt lgkmcnt(0)
	v_add_f32_e32 v103, v103, v104
	v_lshl_add_u64 v[68:69], v[68:69], 4, s[10:11]
	global_store_dword v[68:69], v103, off
.LBB0_1053:
	s_or_b64 exec, exec, s[12:13]
	s_waitcnt lgkmcnt(0)
	s_barrier
	ds_write2_b32 v130, v2, v18 offset1:16
	ds_write2_b32 v114, v3, v19 offset0:4 offset1:20
	ds_write2_b32 v115, v4, v20 offset0:8 offset1:24
	ds_write2_b32 v116, v5, v21 offset0:12 offset1:28
	ds_write2_b32 v117, v6, v22 offset0:64 offset1:80
	ds_write2_b32 v82, v7, v23 offset0:68 offset1:84
	ds_write2_b32 v83, v8, v24 offset0:72 offset1:88
	ds_write2_b32 v84, v9, v25 offset0:76 offset1:92
	ds_write2_b32 v85, v10, v26 offset0:128 offset1:144
	ds_write2_b32 v74, v11, v27 offset0:132 offset1:148
	ds_write2_b32 v75, v12, v28 offset0:136 offset1:152
	ds_write2_b32 v76, v13, v29 offset0:140 offset1:156
	ds_write2_b32 v80, v14, v30 offset0:192 offset1:208
	ds_write2_b32 v77, v15, v31 offset0:196 offset1:212
	ds_write2_b32 v78, v16, v32 offset0:200 offset1:216
	ds_write2_b32 v79, v17, v33 offset0:204 offset1:220
	ds_write2_b32 v130, v34, v50 offset0:128 offset1:144
	ds_write2_b32 v114, v35, v51 offset0:132 offset1:148
	ds_write2_b32 v115, v36, v52 offset0:136 offset1:152
	ds_write2_b32 v116, v37, v53 offset0:140 offset1:156
	ds_write2_b32 v117, v38, v54 offset0:192 offset1:208
	ds_write2_b32 v82, v39, v55 offset0:196 offset1:212
	ds_write2_b32 v83, v40, v56 offset0:200 offset1:216
	ds_write2_b32 v84, v41, v57 offset0:204 offset1:220
	ds_write2_b32 v74, v42, v58 offset1:16
	ds_write2_b32 v75, v43, v59 offset0:4 offset1:20
	ds_write2_b32 v76, v44, v60 offset0:8 offset1:24
	ds_write2_b32 v81, v45, v61 offset0:12 offset1:28
	ds_write2_b32 v77, v46, v62 offset0:64 offset1:80
	ds_write2_b32 v78, v47, v63 offset0:68 offset1:84
	ds_write2_b32 v79, v48, v64 offset0:72 offset1:88
	ds_write2_b32 v86, v49, v65 offset0:76 offset1:92
	v_add_u32_e32 v2, s16, v87
	v_ashrrev_i32_e32 v3, 31, v2
	v_lshlrev_b64 v[4:5], 10, v[2:3]
	v_lshl_add_u64 v[20:21], v[4:5], 0, v[66:67]
	v_lshl_add_u64 v[22:23], v[20:21], 2, s[18:19]
	s_waitcnt lgkmcnt(0)
	s_barrier
	v_lshlrev_b32_e32 v141, 2, v20
	global_load_dwordx4 v[132:135], v141, s[18:19]
	global_load_dwordx4 v[136:139], v141, s[18:19] offset:64
	v_add_u32_e32 v141, 0x10000, v141
	global_load_dwordx4 v[142:145], v141, s[18:19]
	global_load_dwordx4 v[146:149], v141, s[18:19] offset:64
	v_add_u32_e32 v141, 0x10000, v141
	global_load_dwordx4 v[150:153], v141, s[18:19]
	global_load_dwordx4 v[154:157], v141, s[18:19] offset:64
	v_add_u32_e32 v141, 0x10000, v141
	global_load_dwordx4 v[158:161], v141, s[18:19]
	global_load_dwordx4 v[162:165], v141, s[18:19] offset:64
	v_add_u32_e32 v141, 0x10000, v141
	global_load_dwordx4 v[166:169], v141, s[18:19]
	global_load_dwordx4 v[170:173], v141, s[18:19] offset:64
	v_add_u32_e32 v141, 0x10000, v141
	global_load_dwordx4 v[174:177], v141, s[18:19]
	global_load_dwordx4 v[178:181], v141, s[18:19] offset:64
	v_add_u32_e32 v141, 0x10000, v141
	global_load_dwordx4 v[182:185], v141, s[18:19]
	global_load_dwordx4 v[186:189], v141, s[18:19] offset:64
	v_add_u32_e32 v141, 0x10000, v141
	global_load_dwordx4 v[190:193], v141, s[18:19]
	global_load_dwordx4 v[194:197], v141, s[18:19] offset:64
	ds_read_b128 v[12:15], v88
	ds_read_b128 v[16:19], v88 offset:64
	s_waitcnt lgkmcnt(1)
	s_waitcnt vmcnt(15)
	v_pk_fma_f32 v[4:5], v[12:13], 0.5, v[132:133] op_sel_hi:[1,0,1]
	s_waitcnt vmcnt(15)
	v_pk_fma_f32 v[6:7], v[14:15], 0.5, v[134:135] op_sel_hi:[1,0,1]
	v_pk_mul_f32 v[12:13], v[4:5], v[4:5]
	v_pk_mul_f32 v[14:15], v[6:7], v[6:7]
	v_add_f32_e32 v12, v12, v13
	s_waitcnt lgkmcnt(0)
	s_waitcnt vmcnt(14)
	v_pk_fma_f32 v[8:9], v[16:17], 0.5, v[136:137] op_sel_hi:[1,0,1]
	v_add_f32_e32 v12, v14, v12
	v_pk_mul_f32 v[16:17], v[8:9], v[8:9]
	v_add_f32_e32 v12, v15, v12
	s_waitcnt vmcnt(14)
	v_pk_fma_f32 v[10:11], v[18:19], 0.5, v[138:139] op_sel_hi:[1,0,1]
	v_add_f32_e32 v12, v16, v12
	v_pk_mul_f32 v[18:19], v[10:11], v[10:11]
	v_add_f32_e32 v12, v17, v12
	v_add_f32_e32 v12, v18, v12
	v_add_f32_e32 v12, v19, v12
	ds_bpermute_b32 v13, v0, v12
	global_store_dwordx4 v[22:23], v[4:7], off
	global_store_dwordx4 v[22:23], v[8:11], off offset:64
	s_waitcnt lgkmcnt(0)
	v_add_f32_e32 v12, v12, v13
	ds_bpermute_b32 v13, v70, v12
	v_cvt_pk_bf16_f32 v8, v8, v9
	v_cvt_pk_bf16_f32 v9, v10, v11
	s_waitcnt lgkmcnt(0)
	v_add_f32_e32 v12, v12, v13
	ds_bpermute_b32 v13, v71, v12
	s_waitcnt lgkmcnt(0)
	v_add_f32_e32 v14, v12, v13
	ds_bpermute_b32 v15, v73, v14
	v_cvt_pk_bf16_f32 v12, v4, v5
	v_cvt_pk_bf16_f32 v13, v6, v7
	v_lshl_add_u64 v[6:7], v[20:21], 1, s[38:39]
	global_store_dwordx2 v[6:7], v[12:13], off
	s_waitcnt lgkmcnt(0)
	v_add_f32_e32 v4, v14, v15
	ds_bpermute_b32 v5, v72, v4
	global_store_dwordx2 v[6:7], v[8:9], off offset:32
	s_and_saveexec_b64 s[12:13], vcc
	s_cbranch_execz .LBB0_1055
	s_waitcnt lgkmcnt(0)
	v_add_f32_e32 v4, v4, v5
	v_lshl_add_u64 v[2:3], v[2:3], 4, s[10:11]
	global_store_dword v[2:3], v4, off
.LBB0_1055:
	s_or_b64 exec, exec, s[12:13]
	v_add_u32_e32 v2, s16, v90
	v_ashrrev_i32_e32 v3, 31, v2
	s_waitcnt lgkmcnt(0)
	v_lshlrev_b64 v[4:5], 10, v[2:3]
	v_lshl_add_u64 v[16:17], v[4:5], 0, v[66:67]
	v_lshl_add_u64 v[18:19], v[16:17], 2, s[18:19]
	ds_read_b128 v[4:7], v89
	s_waitcnt lgkmcnt(0)
	s_waitcnt vmcnt(18)
	v_pk_fma_f32 v[4:5], v[4:5], 0.5, v[142:143] op_sel_hi:[1,0,1]
	s_waitcnt vmcnt(18)
	v_pk_fma_f32 v[6:7], v[6:7], 0.5, v[144:145] op_sel_hi:[1,0,1]
	ds_read_b128 v[8:11], v89 offset:64
	global_store_dwordx4 v[18:19], v[4:7], off
	s_waitcnt lgkmcnt(0)
	s_waitcnt vmcnt(18)
	v_pk_fma_f32 v[8:9], v[8:9], 0.5, v[146:147] op_sel_hi:[1,0,1]
	v_cvt_pk_bf16_f32 v12, v4, v5
	v_pk_mul_f32 v[4:5], v[4:5], v[4:5]
	v_cvt_pk_bf16_f32 v13, v6, v7
	v_pk_mul_f32 v[6:7], v[6:7], v[6:7]
	v_add_f32_e32 v4, v4, v5
	s_waitcnt vmcnt(18)
	v_pk_fma_f32 v[10:11], v[10:11], 0.5, v[148:149] op_sel_hi:[1,0,1]
	v_lshl_add_u64 v[14:15], v[16:17], 1, s[38:39]
	v_add_f32_e32 v4, v6, v4
	global_store_dwordx4 v[18:19], v[8:11], off offset:64
	global_store_dwordx2 v[14:15], v[12:13], off
	v_cvt_pk_bf16_f32 v12, v8, v9
	v_pk_mul_f32 v[8:9], v[8:9], v[8:9]
	v_add_f32_e32 v4, v7, v4
	v_add_f32_e32 v4, v8, v4
	v_cvt_pk_bf16_f32 v13, v10, v11
	v_pk_mul_f32 v[10:11], v[10:11], v[10:11]
	v_add_f32_e32 v4, v9, v4
	v_add_f32_e32 v4, v10, v4
	v_add_f32_e32 v4, v11, v4
	ds_bpermute_b32 v5, v0, v4
	global_store_dwordx2 v[14:15], v[12:13], off offset:32
	s_waitcnt lgkmcnt(0)
	v_add_f32_e32 v4, v4, v5
	ds_bpermute_b32 v5, v70, v4
	s_waitcnt lgkmcnt(0)
	v_add_f32_e32 v4, v4, v5
	ds_bpermute_b32 v5, v71, v4
	s_waitcnt lgkmcnt(0)
	v_add_f32_e32 v4, v4, v5
	ds_bpermute_b32 v5, v73, v4
	s_waitcnt lgkmcnt(0)
	v_add_f32_e32 v4, v4, v5
	ds_bpermute_b32 v5, v72, v4
	s_and_saveexec_b64 s[12:13], vcc
	s_cbranch_execz .LBB0_1057
	s_waitcnt lgkmcnt(0)
	v_add_f32_e32 v4, v4, v5
	v_lshl_add_u64 v[2:3], v[2:3], 4, s[10:11]
	global_store_dword v[2:3], v4, off
.LBB0_1057:
	s_or_b64 exec, exec, s[12:13]
	v_add_u32_e32 v2, s16, v92
	v_ashrrev_i32_e32 v3, 31, v2
	s_waitcnt lgkmcnt(0)
	v_lshlrev_b64 v[4:5], 10, v[2:3]
	v_lshl_add_u64 v[16:17], v[4:5], 0, v[66:67]
	v_lshl_add_u64 v[18:19], v[16:17], 2, s[18:19]
	ds_read_b128 v[4:7], v91
	s_waitcnt lgkmcnt(0)
	s_waitcnt vmcnt(21)
	v_pk_fma_f32 v[4:5], v[4:5], 0.5, v[150:151] op_sel_hi:[1,0,1]
	s_waitcnt vmcnt(21)
	v_pk_fma_f32 v[6:7], v[6:7], 0.5, v[152:153] op_sel_hi:[1,0,1]
	ds_read_b128 v[8:11], v91 offset:64
	global_store_dwordx4 v[18:19], v[4:7], off
	s_waitcnt lgkmcnt(0)
	s_waitcnt vmcnt(21)
	v_pk_fma_f32 v[8:9], v[8:9], 0.5, v[154:155] op_sel_hi:[1,0,1]
	v_cvt_pk_bf16_f32 v12, v4, v5
	v_pk_mul_f32 v[4:5], v[4:5], v[4:5]
	v_cvt_pk_bf16_f32 v13, v6, v7
	v_pk_mul_f32 v[6:7], v[6:7], v[6:7]
	v_add_f32_e32 v4, v4, v5
	s_waitcnt vmcnt(21)
	v_pk_fma_f32 v[10:11], v[10:11], 0.5, v[156:157] op_sel_hi:[1,0,1]
	v_lshl_add_u64 v[14:15], v[16:17], 1, s[38:39]
	v_add_f32_e32 v4, v6, v4
	global_store_dwordx4 v[18:19], v[8:11], off offset:64
	global_store_dwordx2 v[14:15], v[12:13], off
	v_cvt_pk_bf16_f32 v12, v8, v9
	v_pk_mul_f32 v[8:9], v[8:9], v[8:9]
	v_add_f32_e32 v4, v7, v4
	v_add_f32_e32 v4, v8, v4
	v_cvt_pk_bf16_f32 v13, v10, v11
	v_pk_mul_f32 v[10:11], v[10:11], v[10:11]
	v_add_f32_e32 v4, v9, v4
	v_add_f32_e32 v4, v10, v4
	v_add_f32_e32 v4, v11, v4
	ds_bpermute_b32 v5, v0, v4
	global_store_dwordx2 v[14:15], v[12:13], off offset:32
	s_waitcnt lgkmcnt(0)
	v_add_f32_e32 v4, v4, v5
	ds_bpermute_b32 v5, v70, v4
	s_waitcnt lgkmcnt(0)
	v_add_f32_e32 v4, v4, v5
	ds_bpermute_b32 v5, v71, v4
	s_waitcnt lgkmcnt(0)
	v_add_f32_e32 v4, v4, v5
	ds_bpermute_b32 v5, v73, v4
	s_waitcnt lgkmcnt(0)
	v_add_f32_e32 v4, v4, v5
	ds_bpermute_b32 v5, v72, v4
	s_and_saveexec_b64 s[12:13], vcc
	s_cbranch_execz .LBB0_1059
	s_waitcnt lgkmcnt(0)
	v_add_f32_e32 v4, v4, v5
	v_lshl_add_u64 v[2:3], v[2:3], 4, s[10:11]
	global_store_dword v[2:3], v4, off
.LBB0_1059:
	s_or_b64 exec, exec, s[12:13]
	v_add_u32_e32 v2, s16, v94
	v_ashrrev_i32_e32 v3, 31, v2
	s_waitcnt lgkmcnt(0)
	v_lshlrev_b64 v[4:5], 10, v[2:3]
	v_lshl_add_u64 v[16:17], v[4:5], 0, v[66:67]
	v_lshl_add_u64 v[18:19], v[16:17], 2, s[18:19]
	ds_read_b128 v[4:7], v93
	s_waitcnt lgkmcnt(0)
	s_waitcnt vmcnt(24)
	v_pk_fma_f32 v[4:5], v[4:5], 0.5, v[158:159] op_sel_hi:[1,0,1]
	s_waitcnt vmcnt(24)
	v_pk_fma_f32 v[6:7], v[6:7], 0.5, v[160:161] op_sel_hi:[1,0,1]
	ds_read_b128 v[8:11], v93 offset:64
	global_store_dwordx4 v[18:19], v[4:7], off
	s_waitcnt lgkmcnt(0)
	s_waitcnt vmcnt(24)
	v_pk_fma_f32 v[8:9], v[8:9], 0.5, v[162:163] op_sel_hi:[1,0,1]
	v_cvt_pk_bf16_f32 v12, v4, v5
	v_pk_mul_f32 v[4:5], v[4:5], v[4:5]
	v_cvt_pk_bf16_f32 v13, v6, v7
	v_pk_mul_f32 v[6:7], v[6:7], v[6:7]
	v_add_f32_e32 v4, v4, v5
	s_waitcnt vmcnt(24)
	v_pk_fma_f32 v[10:11], v[10:11], 0.5, v[164:165] op_sel_hi:[1,0,1]
	v_lshl_add_u64 v[14:15], v[16:17], 1, s[38:39]
	v_add_f32_e32 v4, v6, v4
	global_store_dwordx4 v[18:19], v[8:11], off offset:64
	global_store_dwordx2 v[14:15], v[12:13], off
	v_cvt_pk_bf16_f32 v12, v8, v9
	v_pk_mul_f32 v[8:9], v[8:9], v[8:9]
	v_add_f32_e32 v4, v7, v4
	v_add_f32_e32 v4, v8, v4
	v_cvt_pk_bf16_f32 v13, v10, v11
	v_pk_mul_f32 v[10:11], v[10:11], v[10:11]
	v_add_f32_e32 v4, v9, v4
	v_add_f32_e32 v4, v10, v4
	v_add_f32_e32 v4, v11, v4
	ds_bpermute_b32 v5, v0, v4
	global_store_dwordx2 v[14:15], v[12:13], off offset:32
	s_waitcnt lgkmcnt(0)
	v_add_f32_e32 v4, v4, v5
	ds_bpermute_b32 v5, v70, v4
	s_waitcnt lgkmcnt(0)
	v_add_f32_e32 v4, v4, v5
	ds_bpermute_b32 v5, v71, v4
	s_waitcnt lgkmcnt(0)
	v_add_f32_e32 v4, v4, v5
	ds_bpermute_b32 v5, v73, v4
	s_waitcnt lgkmcnt(0)
	v_add_f32_e32 v4, v4, v5
	ds_bpermute_b32 v5, v72, v4
	s_and_saveexec_b64 s[12:13], vcc
	s_cbranch_execz .LBB0_1061
	s_waitcnt lgkmcnt(0)
	v_add_f32_e32 v4, v4, v5
	v_lshl_add_u64 v[2:3], v[2:3], 4, s[10:11]
	global_store_dword v[2:3], v4, off
.LBB0_1061:
	s_or_b64 exec, exec, s[12:13]
	v_add_u32_e32 v2, s16, v96
	v_ashrrev_i32_e32 v3, 31, v2
	s_waitcnt lgkmcnt(0)
	v_lshlrev_b64 v[4:5], 10, v[2:3]
	v_lshl_add_u64 v[16:17], v[4:5], 0, v[66:67]
	v_lshl_add_u64 v[18:19], v[16:17], 2, s[18:19]
	ds_read_b128 v[4:7], v95
	s_waitcnt lgkmcnt(0)
	s_waitcnt vmcnt(27)
	v_pk_fma_f32 v[4:5], v[4:5], 0.5, v[166:167] op_sel_hi:[1,0,1]
	s_waitcnt vmcnt(27)
	v_pk_fma_f32 v[6:7], v[6:7], 0.5, v[168:169] op_sel_hi:[1,0,1]
	ds_read_b128 v[8:11], v95 offset:64
	global_store_dwordx4 v[18:19], v[4:7], off
	s_waitcnt lgkmcnt(0)
	s_waitcnt vmcnt(27)
	v_pk_fma_f32 v[8:9], v[8:9], 0.5, v[170:171] op_sel_hi:[1,0,1]
	v_cvt_pk_bf16_f32 v12, v4, v5
	v_pk_mul_f32 v[4:5], v[4:5], v[4:5]
	v_cvt_pk_bf16_f32 v13, v6, v7
	v_pk_mul_f32 v[6:7], v[6:7], v[6:7]
	v_add_f32_e32 v4, v4, v5
	s_waitcnt vmcnt(27)
	v_pk_fma_f32 v[10:11], v[10:11], 0.5, v[172:173] op_sel_hi:[1,0,1]
	v_lshl_add_u64 v[14:15], v[16:17], 1, s[38:39]
	v_add_f32_e32 v4, v6, v4
	global_store_dwordx4 v[18:19], v[8:11], off offset:64
	global_store_dwordx2 v[14:15], v[12:13], off
	v_cvt_pk_bf16_f32 v12, v8, v9
	v_pk_mul_f32 v[8:9], v[8:9], v[8:9]
	v_add_f32_e32 v4, v7, v4
	v_add_f32_e32 v4, v8, v4
	v_cvt_pk_bf16_f32 v13, v10, v11
	v_pk_mul_f32 v[10:11], v[10:11], v[10:11]
	v_add_f32_e32 v4, v9, v4
	v_add_f32_e32 v4, v10, v4
	v_add_f32_e32 v4, v11, v4
	ds_bpermute_b32 v5, v0, v4
	global_store_dwordx2 v[14:15], v[12:13], off offset:32
	s_waitcnt lgkmcnt(0)
	v_add_f32_e32 v4, v4, v5
	ds_bpermute_b32 v5, v70, v4
	s_waitcnt lgkmcnt(0)
	v_add_f32_e32 v4, v4, v5
	ds_bpermute_b32 v5, v71, v4
	s_waitcnt lgkmcnt(0)
	v_add_f32_e32 v4, v4, v5
	ds_bpermute_b32 v5, v73, v4
	s_waitcnt lgkmcnt(0)
	v_add_f32_e32 v4, v4, v5
	ds_bpermute_b32 v5, v72, v4
	s_and_saveexec_b64 s[12:13], vcc
	s_cbranch_execz .LBB0_1063
	s_waitcnt lgkmcnt(0)
	v_add_f32_e32 v4, v4, v5
	v_lshl_add_u64 v[2:3], v[2:3], 4, s[10:11]
	global_store_dword v[2:3], v4, off
.LBB0_1063:
	s_or_b64 exec, exec, s[12:13]
	v_add_u32_e32 v2, s16, v98
	v_ashrrev_i32_e32 v3, 31, v2
	s_waitcnt lgkmcnt(0)
	v_lshlrev_b64 v[4:5], 10, v[2:3]
	v_lshl_add_u64 v[16:17], v[4:5], 0, v[66:67]
	v_lshl_add_u64 v[18:19], v[16:17], 2, s[18:19]
	ds_read_b128 v[4:7], v97
	s_waitcnt lgkmcnt(0)
	s_waitcnt vmcnt(30)
	v_pk_fma_f32 v[4:5], v[4:5], 0.5, v[174:175] op_sel_hi:[1,0,1]
	s_waitcnt vmcnt(30)
	v_pk_fma_f32 v[6:7], v[6:7], 0.5, v[176:177] op_sel_hi:[1,0,1]
	ds_read_b128 v[8:11], v97 offset:64
	global_store_dwordx4 v[18:19], v[4:7], off
	s_waitcnt lgkmcnt(0)
	s_waitcnt vmcnt(30)
	v_pk_fma_f32 v[8:9], v[8:9], 0.5, v[178:179] op_sel_hi:[1,0,1]
	v_cvt_pk_bf16_f32 v12, v4, v5
	v_pk_mul_f32 v[4:5], v[4:5], v[4:5]
	v_cvt_pk_bf16_f32 v13, v6, v7
	v_pk_mul_f32 v[6:7], v[6:7], v[6:7]
	v_add_f32_e32 v4, v4, v5
	s_waitcnt vmcnt(30)
	v_pk_fma_f32 v[10:11], v[10:11], 0.5, v[180:181] op_sel_hi:[1,0,1]
	v_lshl_add_u64 v[14:15], v[16:17], 1, s[38:39]
	v_add_f32_e32 v4, v6, v4
	global_store_dwordx4 v[18:19], v[8:11], off offset:64
	global_store_dwordx2 v[14:15], v[12:13], off
	v_cvt_pk_bf16_f32 v12, v8, v9
	v_pk_mul_f32 v[8:9], v[8:9], v[8:9]
	v_add_f32_e32 v4, v7, v4
	v_add_f32_e32 v4, v8, v4
	v_cvt_pk_bf16_f32 v13, v10, v11
	v_pk_mul_f32 v[10:11], v[10:11], v[10:11]
	v_add_f32_e32 v4, v9, v4
	v_add_f32_e32 v4, v10, v4
	v_add_f32_e32 v4, v11, v4
	ds_bpermute_b32 v5, v0, v4
	global_store_dwordx2 v[14:15], v[12:13], off offset:32
	s_waitcnt lgkmcnt(0)
	v_add_f32_e32 v4, v4, v5
	ds_bpermute_b32 v5, v70, v4
	s_waitcnt lgkmcnt(0)
	v_add_f32_e32 v4, v4, v5
	ds_bpermute_b32 v5, v71, v4
	s_waitcnt lgkmcnt(0)
	v_add_f32_e32 v4, v4, v5
	ds_bpermute_b32 v5, v73, v4
	s_waitcnt lgkmcnt(0)
	v_add_f32_e32 v4, v4, v5
	ds_bpermute_b32 v5, v72, v4
	s_and_saveexec_b64 s[12:13], vcc
	s_cbranch_execz .LBB0_1065
	s_waitcnt lgkmcnt(0)
	v_add_f32_e32 v4, v4, v5
	v_lshl_add_u64 v[2:3], v[2:3], 4, s[10:11]
	global_store_dword v[2:3], v4, off
.LBB0_1065:
	s_or_b64 exec, exec, s[12:13]
	v_add_u32_e32 v2, s16, v100
	v_ashrrev_i32_e32 v3, 31, v2
	s_waitcnt lgkmcnt(0)
	v_lshlrev_b64 v[4:5], 10, v[2:3]
	v_lshl_add_u64 v[16:17], v[4:5], 0, v[66:67]
	v_lshl_add_u64 v[18:19], v[16:17], 2, s[18:19]
	ds_read_b128 v[4:7], v99
	s_waitcnt lgkmcnt(0)
	s_waitcnt vmcnt(33)
	v_pk_fma_f32 v[4:5], v[4:5], 0.5, v[182:183] op_sel_hi:[1,0,1]
	s_waitcnt vmcnt(33)
	v_pk_fma_f32 v[6:7], v[6:7], 0.5, v[184:185] op_sel_hi:[1,0,1]
	ds_read_b128 v[8:11], v99 offset:64
	global_store_dwordx4 v[18:19], v[4:7], off
	s_waitcnt lgkmcnt(0)
	s_waitcnt vmcnt(33)
	v_pk_fma_f32 v[8:9], v[8:9], 0.5, v[186:187] op_sel_hi:[1,0,1]
	v_cvt_pk_bf16_f32 v12, v4, v5
	v_pk_mul_f32 v[4:5], v[4:5], v[4:5]
	v_cvt_pk_bf16_f32 v13, v6, v7
	v_pk_mul_f32 v[6:7], v[6:7], v[6:7]
	v_add_f32_e32 v4, v4, v5
	s_waitcnt vmcnt(33)
	v_pk_fma_f32 v[10:11], v[10:11], 0.5, v[188:189] op_sel_hi:[1,0,1]
	v_lshl_add_u64 v[14:15], v[16:17], 1, s[38:39]
	v_add_f32_e32 v4, v6, v4
	global_store_dwordx4 v[18:19], v[8:11], off offset:64
	global_store_dwordx2 v[14:15], v[12:13], off
	v_cvt_pk_bf16_f32 v12, v8, v9
	v_pk_mul_f32 v[8:9], v[8:9], v[8:9]
	v_add_f32_e32 v4, v7, v4
	v_add_f32_e32 v4, v8, v4
	v_cvt_pk_bf16_f32 v13, v10, v11
	v_pk_mul_f32 v[10:11], v[10:11], v[10:11]
	v_add_f32_e32 v4, v9, v4
	v_add_f32_e32 v4, v10, v4
	v_add_f32_e32 v4, v11, v4
	ds_bpermute_b32 v5, v0, v4
	global_store_dwordx2 v[14:15], v[12:13], off offset:32
	s_waitcnt lgkmcnt(0)
	v_add_f32_e32 v4, v4, v5
	ds_bpermute_b32 v5, v70, v4
	s_waitcnt lgkmcnt(0)
	v_add_f32_e32 v4, v4, v5
	ds_bpermute_b32 v5, v71, v4
	s_waitcnt lgkmcnt(0)
	v_add_f32_e32 v4, v4, v5
	ds_bpermute_b32 v5, v73, v4
	s_waitcnt lgkmcnt(0)
	v_add_f32_e32 v4, v4, v5
	ds_bpermute_b32 v5, v72, v4
	s_and_saveexec_b64 s[12:13], vcc
	s_cbranch_execz .LBB0_1067
	s_waitcnt lgkmcnt(0)
	v_add_f32_e32 v4, v4, v5
	v_lshl_add_u64 v[2:3], v[2:3], 4, s[10:11]
	global_store_dword v[2:3], v4, off
.LBB0_1067:
	s_or_b64 exec, exec, s[12:13]
	v_add_u32_e32 v2, s16, v102
	v_ashrrev_i32_e32 v3, 31, v2
	s_waitcnt lgkmcnt(0)
	v_lshlrev_b64 v[4:5], 10, v[2:3]
	v_lshl_add_u64 v[16:17], v[4:5], 0, v[66:67]
	v_lshl_add_u64 v[18:19], v[16:17], 2, s[18:19]
	ds_read_b128 v[4:7], v101
	s_waitcnt lgkmcnt(0)
	s_waitcnt vmcnt(36)
	v_pk_fma_f32 v[4:5], v[4:5], 0.5, v[190:191] op_sel_hi:[1,0,1]
	s_waitcnt vmcnt(36)
	v_pk_fma_f32 v[6:7], v[6:7], 0.5, v[192:193] op_sel_hi:[1,0,1]
	ds_read_b128 v[8:11], v101 offset:64
	global_store_dwordx4 v[18:19], v[4:7], off
	s_waitcnt lgkmcnt(0)
	s_waitcnt vmcnt(36)
	v_pk_fma_f32 v[8:9], v[8:9], 0.5, v[194:195] op_sel_hi:[1,0,1]
	v_cvt_pk_bf16_f32 v12, v4, v5
	v_pk_mul_f32 v[4:5], v[4:5], v[4:5]
	v_cvt_pk_bf16_f32 v13, v6, v7
	v_pk_mul_f32 v[6:7], v[6:7], v[6:7]
	v_add_f32_e32 v4, v4, v5
	s_waitcnt vmcnt(36)
	v_pk_fma_f32 v[10:11], v[10:11], 0.5, v[196:197] op_sel_hi:[1,0,1]
	v_lshl_add_u64 v[14:15], v[16:17], 1, s[38:39]
	v_add_f32_e32 v4, v6, v4
	global_store_dwordx4 v[18:19], v[8:11], off offset:64
	global_store_dwordx2 v[14:15], v[12:13], off
	v_cvt_pk_bf16_f32 v12, v8, v9
	v_pk_mul_f32 v[8:9], v[8:9], v[8:9]
	v_add_f32_e32 v4, v7, v4
	v_add_f32_e32 v4, v8, v4
	v_cvt_pk_bf16_f32 v13, v10, v11
	v_pk_mul_f32 v[10:11], v[10:11], v[10:11]
	v_add_f32_e32 v4, v9, v4
	v_add_f32_e32 v4, v10, v4
	v_add_f32_e32 v4, v11, v4
	ds_bpermute_b32 v0, v0, v4
	global_store_dwordx2 v[14:15], v[12:13], off offset:32
	s_waitcnt lgkmcnt(0)
	v_add_f32_e32 v0, v4, v0
	ds_bpermute_b32 v4, v70, v0
	s_waitcnt lgkmcnt(0)
	v_add_f32_e32 v0, v0, v4
	ds_bpermute_b32 v4, v71, v0
	s_waitcnt lgkmcnt(0)
	v_add_f32_e32 v0, v0, v4
	ds_bpermute_b32 v4, v73, v0
	s_waitcnt lgkmcnt(0)
	v_add_f32_e32 v0, v0, v4
	ds_bpermute_b32 v4, v72, v0
	s_and_saveexec_b64 s[12:13], vcc
	s_cbranch_execz .LBB0_1069
	s_waitcnt lgkmcnt(0)
	v_add_f32_e32 v0, v0, v4
	v_lshl_add_u64 v[2:3], v[2:3], 4, s[10:11]
	global_store_dword v[2:3], v0, off

.LBB0_1094:
	s_or_b64 exec, exec, s[10:11]
	s_movk_i32 s11, 0x410
	v_lshrrev_b32_e32 v130, 2, v140
	v_lshlrev_b32_e32 v131, 1, v140
	v_and_b32_e32 v0, 15, v140
	v_and_b32_e32 v130, 0xfffffcc, v130
	v_and_b32_e32 v131, 0x180, v131
	v_add_u32_e32 v131, 0, v131
	v_lshlrev_b32_e32 v0, 2, v0
	v_mul_lo_u32 v130, v130, s11
	v_add3_u32 v130, v131, v0, v130
	s_waitcnt vmcnt(0)
	s_barrier
	ds_write2_b32 v130, v114, v126 offset1:16
	v_add_u32_e32 v114, 0x400, v130
	ds_write2_b32 v114, v115, v127 offset0:4 offset1:20
	v_add_u32_e32 v115, 0x800, v130
	ds_write2_b32 v115, v116, v128 offset0:8 offset1:24
	v_add_u32_e32 v116, 0xc00, v130
	ds_write2_b32 v116, v117, v129 offset0:12 offset1:28
	v_add_u32_e32 v117, 0x4000, v130
	ds_write2_b32 v117, v82, v94 offset0:64 offset1:80
	v_add_u32_e32 v82, 0x4400, v130
	ds_write2_b32 v82, v83, v95 offset0:68 offset1:84
	v_add_u32_e32 v83, 0x4800, v130
	ds_write2_b32 v83, v84, v96 offset0:72 offset1:88
	v_add_u32_e32 v84, 0x4c00, v130
	ds_write2_b32 v84, v85, v97 offset0:76 offset1:92
	v_add_u32_e32 v85, 0x8000, v130
	ds_write2_b32 v85, v74, v78 offset0:128 offset1:144
	v_add_u32_e32 v74, 0x8400, v130
	ds_write2_b32 v74, v75, v79 offset0:132 offset1:148
	v_add_u32_e32 v75, 0x8800, v130
	ds_write2_b32 v75, v76, v80 offset0:136 offset1:152
	v_add_u32_e32 v76, 0x8c00, v130
	v_add_u32_e32 v80, 0xc000, v130
	ds_write2_b32 v76, v77, v81 offset0:140 offset1:156
	ds_write2_b32 v80, v66, v70 offset0:192 offset1:208
	v_add_u32_e32 v77, 0xc400, v130
	v_add_u32_e32 v78, 0xc800, v130
	v_add_u32_e32 v79, 0xcc00, v130
	v_add_u32_e32 v81, 0x9000, v130
	v_lshlrev_b32_e32 v66, 2, v140
	ds_write2_b32 v77, v67, v71 offset0:196 offset1:212
	ds_write2_b32 v78, v68, v72 offset0:200 offset1:216
	ds_write2_b32 v79, v69, v73 offset0:204 offset1:220
	ds_write2_b32 v130, v98, v118 offset0:128 offset1:144
	ds_write2_b32 v114, v99, v119 offset0:132 offset1:148
	ds_write2_b32 v115, v100, v120 offset0:136 offset1:152
	ds_write2_b32 v116, v101, v121 offset0:140 offset1:156
	ds_write2_b32 v117, v102, v122 offset0:192 offset1:208
	ds_write2_b32 v82, v103, v123 offset0:196 offset1:212
	ds_write2_b32 v83, v104, v124 offset0:200 offset1:216
	ds_write2_b32 v84, v105, v125 offset0:204 offset1:220
	ds_write2_b32 v74, v90, v110 offset1:16
	ds_write2_b32 v75, v91, v111 offset0:4 offset1:20
	ds_write2_b32 v76, v92, v112 offset0:8 offset1:24
	ds_write2_b32 v81, v93, v113 offset0:12 offset1:28
	ds_write2_b32 v77, v86, v106 offset0:64 offset1:80
	ds_write2_b32 v78, v87, v107 offset0:68 offset1:84
	ds_write2_b32 v79, v88, v108 offset0:72 offset1:88
	v_lshlrev_b32_e32 v0, 3, v140
	v_and_b32_e32 v66, 12, v66
	s_movk_i32 s10, 0xe0
	v_ashrrev_i32_e32 v87, 5, v140
	v_and_or_b32 v0, v0, s10, v66
	v_add_u32_e32 v68, s17, v87
	v_or_b32_e32 v66, s7, v0
	v_ashrrev_i32_e32 v69, 31, v68
	v_ashrrev_i32_e32 v67, 31, v66
	v_lshlrev_b64 v[70:71], 10, v[68:69]
	v_lshl_add_u64 v[98:99], v[70:71], 0, v[66:67]
	v_add_u32_e32 v86, 0xd000, v130
	v_lshl_add_u64 v[110:111], v[98:99], 2, s[18:19]
	ds_write2_b32 v86, v89, v109 offset0:76 offset1:92
	s_waitcnt lgkmcnt(0)
	s_barrier
	v_lshlrev_b32_e32 v141, 2, v98
	global_load_dwordx4 v[132:135], v141, s[18:19]
	global_load_dwordx4 v[136:139], v141, s[18:19] offset:64
	v_add_u32_e32 v141, 0x10000, v141
	global_load_dwordx4 v[142:145], v141, s[18:19]
	global_load_dwordx4 v[146:149], v141, s[18:19] offset:64
	v_add_u32_e32 v141, 0x10000, v141
	global_load_dwordx4 v[150:153], v141, s[18:19]
	global_load_dwordx4 v[154:157], v141, s[18:19] offset:64
	v_add_u32_e32 v141, 0x10000, v141
	global_load_dwordx4 v[158:161], v141, s[18:19]
	global_load_dwordx4 v[162:165], v141, s[18:19] offset:64
	v_add_u32_e32 v141, 0x10000, v141
	global_load_dwordx4 v[166:169], v141, s[18:19]
	global_load_dwordx4 v[170:173], v141, s[18:19] offset:64
	v_add_u32_e32 v141, 0x10000, v141
	global_load_dwordx4 v[174:177], v141, s[18:19]
	global_load_dwordx4 v[178:181], v141, s[18:19] offset:64
	v_add_u32_e32 v141, 0x10000, v141
	global_load_dwordx4 v[182:185], v141, s[18:19]
	global_load_dwordx4 v[186:189], v141, s[18:19] offset:64
	v_add_u32_e32 v141, 0x10000, v141
	global_load_dwordx4 v[190:193], v141, s[18:19]
	global_load_dwordx4 v[194:197], v141, s[18:19] offset:64
	v_lshl_add_u32 v101, v0, 2, 0
	v_mul_lo_u32 v72, v87, s11
	v_add_u32_e32 v88, v101, v72
	ds_read_b128 v[102:105], v88
	ds_read_b128 v[106:109], v88 offset:64
	v_and_b32_e32 v70, 64, v218
	v_xor_b32_e32 v0, 1, v218
	v_add_u32_e32 v100, 64, v70
	v_cmp_lt_i32_e32 vcc, v0, v100
	v_xor_b32_e32 v70, 2, v218
	v_xor_b32_e32 v71, 4, v218
	v_cndmask_b32_e32 v0, v218, v0, vcc
	v_lshlrev_b32_e32 v0, 2, v0
	v_cmp_lt_i32_e32 vcc, v70, v100
	v_xor_b32_e32 v112, 8, v218
	v_and_b32_e32 v89, 31, v140
	v_cndmask_b32_e32 v70, v218, v70, vcc
	v_lshlrev_b32_e32 v70, 2, v70
	v_cmp_lt_i32_e32 vcc, v71, v100
	s_ashr_i32 s7, s6, 31
	s_lshl_b64 s[10:11], s[6:7], 2
	v_cndmask_b32_e32 v71, v218, v71, vcc
	v_cmp_lt_i32_e32 vcc, v112, v100
	v_lshlrev_b32_e32 v71, 2, v71
	s_add_u32 s10, s40, s10
	s_movk_i32 s20, 0x410
	s_addc_u32 s11, s41, s11
	s_waitcnt lgkmcnt(1)
	s_waitcnt vmcnt(15)
	v_pk_fma_f32 v[90:91], v[102:103], 0.5, v[132:133] op_sel_hi:[1,0,1]
	s_waitcnt vmcnt(15)
	v_pk_fma_f32 v[92:93], v[104:105], 0.5, v[134:135] op_sel_hi:[1,0,1]
	v_pk_mul_f32 v[72:73], v[90:91], v[90:91]
	v_pk_mul_f32 v[102:103], v[92:93], v[92:93]
	v_add_f32_e32 v72, v72, v73
	s_waitcnt lgkmcnt(0)
	s_waitcnt vmcnt(14)
	v_pk_fma_f32 v[94:95], v[106:107], 0.5, v[136:137] op_sel_hi:[1,0,1]
	v_add_f32_e32 v72, v102, v72
	v_pk_mul_f32 v[104:105], v[94:95], v[94:95]
	v_add_f32_e32 v72, v103, v72
	s_waitcnt vmcnt(14)
	v_pk_fma_f32 v[96:97], v[108:109], 0.5, v[138:139] op_sel_hi:[1,0,1]
	v_add_f32_e32 v72, v104, v72
	v_pk_mul_f32 v[106:107], v[96:97], v[96:97]
	v_add_f32_e32 v72, v105, v72
	v_add_f32_e32 v72, v106, v72
	v_add_f32_e32 v72, v107, v72
	ds_bpermute_b32 v102, v0, v72
	v_xor_b32_e32 v103, 16, v218
	v_cndmask_b32_e32 v73, v218, v112, vcc
	v_cmp_lt_i32_e32 vcc, v103, v100
	v_lshlrev_b32_e32 v73, 2, v73
	s_waitcnt lgkmcnt(0)
	v_add_f32_e32 v102, v72, v102
	ds_bpermute_b32 v104, v70, v102
	v_cndmask_b32_e32 v72, v218, v103, vcc
	v_cmp_eq_u32_e32 vcc, 0, v89
	v_lshlrev_b32_e32 v72, 2, v72
	global_store_dwordx4 v[110:111], v[90:93], off
	s_waitcnt lgkmcnt(0)
	v_add_f32_e32 v89, v102, v104
	ds_bpermute_b32 v100, v71, v89
	v_cvt_pk_bf16_f32 v102, v90, v91
	global_store_dwordx4 v[110:111], v[94:97], off offset:64
	v_cvt_pk_bf16_f32 v103, v92, v93
	v_lshl_add_u64 v[92:93], v[98:99], 1, s[38:39]
	s_waitcnt lgkmcnt(0)
	v_add_f32_e32 v89, v89, v100
	ds_bpermute_b32 v100, v73, v89
	v_cvt_pk_bf16_f32 v94, v94, v95
	v_cvt_pk_bf16_f32 v95, v96, v97
	global_store_dwordx2 v[92:93], v[102:103], off
	global_store_dwordx2 v[92:93], v[94:95], off offset:32
	s_waitcnt lgkmcnt(0)
	v_add_f32_e32 v89, v89, v100
	ds_bpermute_b32 v90, v72, v89
	s_and_saveexec_b64 s[12:13], vcc
	s_cbranch_execz .LBB0_1096
	s_waitcnt lgkmcnt(0)
	v_add_f32_e32 v89, v89, v90
	v_lshl_add_u64 v[68:69], v[68:69], 4, s[10:11]
	global_store_dword v[68:69], v89, off

.LBB0_1152:
	s_or_b64 exec, exec, s[14:15]
	s_movk_i32 s11, 0x410
	v_lshrrev_b32_e32 v130, 2, v142
	v_lshlrev_b32_e32 v131, 1, v142
	v_and_b32_e32 v0, 15, v142
	v_and_b32_e32 v130, 0xfffffcc, v130
	v_and_b32_e32 v131, 0x180, v131
	v_add_u32_e32 v131, 0, v131
	v_lshlrev_b32_e32 v0, 2, v0
	v_mul_lo_u32 v130, v130, s11
	v_add3_u32 v130, v131, v0, v130
	s_waitcnt vmcnt(0)
	s_barrier
	ds_write2_b32 v130, v114, v126 offset1:16
	v_add_u32_e32 v114, 0x400, v130
	ds_write2_b32 v114, v115, v127 offset0:4 offset1:20
	v_add_u32_e32 v115, 0x800, v130
	ds_write2_b32 v115, v116, v128 offset0:8 offset1:24
	v_add_u32_e32 v116, 0xc00, v130
	ds_write2_b32 v116, v117, v129 offset0:12 offset1:28
	v_add_u32_e32 v117, 0x4000, v130
	ds_write2_b32 v117, v82, v94 offset0:64 offset1:80
	v_add_u32_e32 v82, 0x4400, v130
	ds_write2_b32 v82, v83, v95 offset0:68 offset1:84
	v_add_u32_e32 v83, 0x4800, v130
	ds_write2_b32 v83, v84, v96 offset0:72 offset1:88
	v_add_u32_e32 v84, 0x4c00, v130
	ds_write2_b32 v84, v85, v97 offset0:76 offset1:92
	v_add_u32_e32 v85, 0x8000, v130
	ds_write2_b32 v85, v74, v78 offset0:128 offset1:144
	v_add_u32_e32 v74, 0x8400, v130
	ds_write2_b32 v74, v75, v79 offset0:132 offset1:148
	v_add_u32_e32 v75, 0x8800, v130
	ds_write2_b32 v75, v76, v80 offset0:136 offset1:152
	v_add_u32_e32 v76, 0x8c00, v130
	v_add_u32_e32 v80, 0xc000, v130
	ds_write2_b32 v76, v77, v81 offset0:140 offset1:156
	ds_write2_b32 v80, v66, v70 offset0:192 offset1:208
	v_add_u32_e32 v77, 0xc400, v130
	v_add_u32_e32 v78, 0xc800, v130
	v_add_u32_e32 v79, 0xcc00, v130
	v_add_u32_e32 v81, 0x9000, v130
	v_lshlrev_b32_e32 v66, 2, v142
	ds_write2_b32 v77, v67, v71 offset0:196 offset1:212
	ds_write2_b32 v78, v68, v72 offset0:200 offset1:216
	ds_write2_b32 v79, v69, v73 offset0:204 offset1:220
	ds_write2_b32 v130, v98, v118 offset0:128 offset1:144
	ds_write2_b32 v114, v99, v119 offset0:132 offset1:148
	ds_write2_b32 v115, v100, v120 offset0:136 offset1:152
	ds_write2_b32 v116, v101, v121 offset0:140 offset1:156
	ds_write2_b32 v117, v102, v122 offset0:192 offset1:208
	ds_write2_b32 v82, v103, v123 offset0:196 offset1:212
	ds_write2_b32 v83, v104, v124 offset0:200 offset1:216
	ds_write2_b32 v84, v105, v125 offset0:204 offset1:220
	ds_write2_b32 v74, v90, v110 offset1:16
	ds_write2_b32 v75, v91, v111 offset0:4 offset1:20
	ds_write2_b32 v76, v92, v112 offset0:8 offset1:24
	ds_write2_b32 v81, v93, v113 offset0:12 offset1:28
	ds_write2_b32 v77, v86, v106 offset0:64 offset1:80
	ds_write2_b32 v78, v87, v107 offset0:68 offset1:84
	ds_write2_b32 v79, v88, v108 offset0:72 offset1:88
	v_lshlrev_b32_e32 v0, 3, v142
	v_and_b32_e32 v66, 12, v66
	s_movk_i32 s7, 0xe0
	v_ashrrev_i32_e32 v87, 5, v142
	v_and_or_b32 v0, v0, s7, v66
	v_add_u32_e32 v68, s10, v87
	v_or_b32_e32 v66, s12, v0
	v_ashrrev_i32_e32 v69, 31, v68
	v_ashrrev_i32_e32 v67, 31, v66
	v_lshlrev_b64 v[70:71], 10, v[68:69]
	v_lshl_add_u64 v[98:99], v[70:71], 0, v[66:67]
	v_add_u32_e32 v86, 0xd000, v130
	v_lshl_add_u64 v[110:111], v[98:99], 2, s[18:19]
	ds_write2_b32 v86, v89, v109 offset0:76 offset1:92
	s_waitcnt lgkmcnt(0)
	s_barrier
	v_lshlrev_b32_e32 v140, 2, v98
	global_load_dwordx4 v[132:135], v140, s[18:19]
	global_load_dwordx4 v[136:139], v140, s[18:19] offset:64
	v_add_u32_e32 v140, 0x10000, v140
	global_load_dwordx4 v[144:147], v140, s[18:19]
	global_load_dwordx4 v[148:151], v140, s[18:19] offset:64
	v_add_u32_e32 v140, 0x10000, v140
	global_load_dwordx4 v[152:155], v140, s[18:19]
	global_load_dwordx4 v[156:159], v140, s[18:19] offset:64
	v_add_u32_e32 v140, 0x10000, v140
	global_load_dwordx4 v[160:163], v140, s[18:19]
	global_load_dwordx4 v[164:167], v140, s[18:19] offset:64
	v_add_u32_e32 v140, 0x10000, v140
	global_load_dwordx4 v[168:171], v140, s[18:19]
	global_load_dwordx4 v[172:175], v140, s[18:19] offset:64
	v_add_u32_e32 v140, 0x10000, v140
	global_load_dwordx4 v[176:179], v140, s[18:19]
	global_load_dwordx4 v[180:183], v140, s[18:19] offset:64
	v_add_u32_e32 v140, 0x10000, v140
	global_load_dwordx4 v[184:187], v140, s[18:19]
	global_load_dwordx4 v[188:191], v140, s[18:19] offset:64
	v_add_u32_e32 v140, 0x10000, v140
	global_load_dwordx4 v[192:195], v140, s[18:19]
	global_load_dwordx4 v[196:199], v140, s[18:19] offset:64
	v_lshl_add_u32 v101, v0, 2, 0
	v_mul_lo_u32 v72, v87, s11
	v_add_u32_e32 v88, v101, v72
	ds_read_b128 v[102:105], v88
	ds_read_b128 v[106:109], v88 offset:64
	v_and_b32_e32 v70, 64, v218
	v_xor_b32_e32 v0, 1, v218
	v_add_u32_e32 v100, 64, v70
	v_cmp_lt_i32_e32 vcc, v0, v100
	v_xor_b32_e32 v70, 2, v218
	v_xor_b32_e32 v71, 4, v218
	v_cndmask_b32_e32 v0, v218, v0, vcc
	v_lshlrev_b32_e32 v0, 2, v0
	v_cmp_lt_i32_e32 vcc, v70, v100
	v_xor_b32_e32 v112, 8, v218
	v_and_b32_e32 v89, 31, v142
	v_cndmask_b32_e32 v70, v218, v70, vcc
	v_lshlrev_b32_e32 v70, 2, v70
	v_cmp_lt_i32_e32 vcc, v71, v100
	s_ashr_i32 s7, s6, 31
	s_lshl_b64 s[12:13], s[6:7], 2
	v_cndmask_b32_e32 v71, v218, v71, vcc
	v_cmp_lt_i32_e32 vcc, v112, v100
	v_lshlrev_b32_e32 v71, 2, v71
	s_add_u32 s12, s40, s12
	s_movk_i32 s9, 0x410
	s_addc_u32 s13, s41, s13
	s_waitcnt lgkmcnt(1)
	s_waitcnt vmcnt(15)
	v_pk_add_f32 v[90:91], v[102:103], v[132:133]
	s_waitcnt vmcnt(15)
	v_pk_add_f32 v[92:93], v[104:105], v[134:135]
	v_pk_mul_f32 v[72:73], v[90:91], v[90:91]
	v_pk_mul_f32 v[102:103], v[92:93], v[92:93]
	v_add_f32_e32 v72, v72, v73
	s_waitcnt lgkmcnt(0)
	s_waitcnt vmcnt(14)
	v_pk_add_f32 v[94:95], v[106:107], v[136:137]
	v_add_f32_e32 v72, v102, v72
	v_pk_mul_f32 v[104:105], v[94:95], v[94:95]
	v_add_f32_e32 v72, v103, v72
	s_waitcnt vmcnt(14)
	v_pk_add_f32 v[96:97], v[108:109], v[138:139]
	v_add_f32_e32 v72, v104, v72
	v_pk_mul_f32 v[106:107], v[96:97], v[96:97]
	v_add_f32_e32 v72, v105, v72
	v_add_f32_e32 v72, v106, v72
	v_add_f32_e32 v72, v107, v72
	ds_bpermute_b32 v102, v0, v72
	v_xor_b32_e32 v103, 16, v218
	v_cndmask_b32_e32 v73, v218, v112, vcc
	v_cmp_lt_i32_e32 vcc, v103, v100
	v_lshlrev_b32_e32 v73, 2, v73
	s_waitcnt lgkmcnt(0)
	v_add_f32_e32 v102, v72, v102
	ds_bpermute_b32 v104, v70, v102
	v_cndmask_b32_e32 v72, v218, v103, vcc
	v_cmp_eq_u32_e32 vcc, 0, v89
	v_lshlrev_b32_e32 v72, 2, v72
	global_store_dwordx4 v[110:111], v[90:93], off
	s_waitcnt lgkmcnt(0)
	v_add_f32_e32 v89, v102, v104
	ds_bpermute_b32 v100, v71, v89
	v_cvt_pk_bf16_f32 v102, v90, v91
	global_store_dwordx4 v[110:111], v[94:97], off offset:64
	v_cvt_pk_bf16_f32 v103, v92, v93
	v_lshl_add_u64 v[92:93], v[98:99], 1, s[38:39]
	s_waitcnt lgkmcnt(0)
	v_add_f32_e32 v89, v89, v100
	ds_bpermute_b32 v100, v73, v89
	v_cvt_pk_bf16_f32 v94, v94, v95
	v_cvt_pk_bf16_f32 v95, v96, v97
	global_store_dwordx2 v[92:93], v[102:103], off
	global_store_dwordx2 v[92:93], v[94:95], off offset:32
	s_waitcnt lgkmcnt(0)
	v_add_f32_e32 v89, v89, v100
	ds_bpermute_b32 v90, v72, v89
	s_and_saveexec_b64 s[14:15], vcc
	s_cbranch_execz .LBB0_1154
	s_waitcnt lgkmcnt(0)
	v_add_f32_e32 v89, v89, v90
	v_lshl_add_u64 v[68:69], v[68:69], 4, s[12:13]
	global_store_dword v[68:69], v89, off
.LBB0_1154:
	s_or_b64 exec, exec, s[14:15]
	v_add_u32_e32 v68, 0x200, v142
	s_waitcnt lgkmcnt(0)
	v_ashrrev_i32_e32 v90, 5, v68
	v_mul_lo_u32 v68, v90, s9
	v_add_u32_e32 v89, v101, v68
	v_add_u32_e32 v68, s10, v90
	v_ashrrev_i32_e32 v69, 31, v68
	v_lshlrev_b64 v[92:93], 10, v[68:69]
	v_lshl_add_u64 v[106:107], v[92:93], 0, v[66:67]
	v_lshl_add_u64 v[108:109], v[106:107], 2, s[18:19]
	ds_read_b128 v[92:95], v89
	s_waitcnt lgkmcnt(0)
	s_waitcnt vmcnt(18)
	v_pk_add_f32 v[92:93], v[92:93], v[144:145]
	s_waitcnt vmcnt(18)
	v_pk_add_f32 v[94:95], v[94:95], v[146:147]
	ds_read_b128 v[96:99], v89 offset:64
	global_store_dwordx4 v[108:109], v[92:95], off
	s_waitcnt lgkmcnt(0)
	s_waitcnt vmcnt(18)
	v_pk_add_f32 v[96:97], v[96:97], v[148:149]
	v_cvt_pk_bf16_f32 v102, v92, v93
	v_pk_mul_f32 v[92:93], v[92:93], v[92:93]
	v_cvt_pk_bf16_f32 v103, v94, v95
	v_pk_mul_f32 v[94:95], v[94:95], v[94:95]
	v_add_f32_e32 v91, v92, v93
	s_waitcnt vmcnt(18)
	v_pk_add_f32 v[98:99], v[98:99], v[150:151]
	v_lshl_add_u64 v[104:105], v[106:107], 1, s[38:39]
	v_add_f32_e32 v91, v94, v91
	global_store_dwordx4 v[108:109], v[96:99], off offset:64
	global_store_dwordx2 v[104:105], v[102:103], off
	v_cvt_pk_bf16_f32 v102, v96, v97
	v_pk_mul_f32 v[96:97], v[96:97], v[96:97]
	v_add_f32_e32 v91, v95, v91
	v_add_f32_e32 v91, v96, v91
	v_cvt_pk_bf16_f32 v103, v98, v99
	v_pk_mul_f32 v[98:99], v[98:99], v[98:99]
	v_add_f32_e32 v91, v97, v91
	v_add_f32_e32 v91, v98, v91
	v_add_f32_e32 v91, v99, v91
	ds_bpermute_b32 v92, v0, v91
	global_store_dwordx2 v[104:105], v[102:103], off offset:32
	s_waitcnt lgkmcnt(0)
	v_add_f32_e32 v91, v91, v92
	ds_bpermute_b32 v92, v70, v91
	s_waitcnt lgkmcnt(0)
	v_add_f32_e32 v91, v91, v92
	ds_bpermute_b32 v92, v71, v91
	s_waitcnt lgkmcnt(0)
	v_add_f32_e32 v91, v91, v92
	ds_bpermute_b32 v92, v73, v91
	s_waitcnt lgkmcnt(0)
	v_add_f32_e32 v91, v91, v92
	ds_bpermute_b32 v92, v72, v91
	s_and_saveexec_b64 s[14:15], vcc
	s_cbranch_execz .LBB0_1156
	s_waitcnt lgkmcnt(0)
	v_add_f32_e32 v91, v91, v92
	v_lshl_add_u64 v[68:69], v[68:69], 4, s[12:13]
	global_store_dword v[68:69], v91, off
.LBB0_1156:
	s_or_b64 exec, exec, s[14:15]
	v_add_u32_e32 v68, 0x400, v142
	s_waitcnt lgkmcnt(0)
	v_ashrrev_i32_e32 v92, 5, v68
	v_mul_lo_u32 v68, v92, s9
	v_add_u32_e32 v91, v101, v68
	v_add_u32_e32 v68, s10, v92
	v_ashrrev_i32_e32 v69, 31, v68
	v_lshlrev_b64 v[94:95], 10, v[68:69]
	v_lshl_add_u64 v[98:99], v[94:95], 0, v[66:67]
	v_lshl_add_u64 v[110:111], v[98:99], 2, s[18:19]
	ds_read_b128 v[94:97], v91
	v_lshl_add_u64 v[98:99], v[98:99], 1, s[38:39]
	s_waitcnt lgkmcnt(0)
	s_waitcnt vmcnt(21)
	v_pk_add_f32 v[94:95], v[94:95], v[152:153]
	s_waitcnt vmcnt(21)
	v_pk_add_f32 v[96:97], v[96:97], v[154:155]
	ds_read_b128 v[102:105], v91 offset:64
	global_store_dwordx4 v[110:111], v[94:97], off
	s_waitcnt lgkmcnt(0)
	s_waitcnt vmcnt(21)
	v_pk_add_f32 v[102:103], v[102:103], v[156:157]
	v_cvt_pk_bf16_f32 v106, v94, v95
	v_pk_mul_f32 v[94:95], v[94:95], v[94:95]
	s_waitcnt vmcnt(21)
	v_pk_add_f32 v[104:105], v[104:105], v[158:159]
	v_cvt_pk_bf16_f32 v107, v96, v97
	v_pk_mul_f32 v[96:97], v[96:97], v[96:97]
	v_add_f32_e32 v93, v94, v95
	global_store_dwordx4 v[110:111], v[102:105], off offset:64
	global_store_dwordx2 v[98:99], v[106:107], off
	v_cvt_pk_bf16_f32 v106, v102, v103
	v_cvt_pk_bf16_f32 v107, v104, v105
	v_add_f32_e32 v93, v96, v93
	global_store_dwordx2 v[98:99], v[106:107], off offset:32
	v_pk_mul_f32 v[98:99], v[102:103], v[102:103]
	v_add_f32_e32 v93, v97, v93
	v_add_f32_e32 v93, v98, v93
	v_pk_mul_f32 v[102:103], v[104:105], v[104:105]
	v_add_f32_e32 v93, v99, v93
	v_add_f32_e32 v93, v102, v93
	v_add_f32_e32 v93, v103, v93
	ds_bpermute_b32 v94, v0, v93
	s_waitcnt lgkmcnt(0)
	v_add_f32_e32 v93, v93, v94
	ds_bpermute_b32 v94, v70, v93
	s_waitcnt lgkmcnt(0)
	v_add_f32_e32 v93, v93, v94
	ds_bpermute_b32 v94, v71, v93
	s_waitcnt lgkmcnt(0)
	v_add_f32_e32 v93, v93, v94
	ds_bpermute_b32 v94, v73, v93
	s_waitcnt lgkmcnt(0)
	v_add_f32_e32 v93, v93, v94
	ds_bpermute_b32 v94, v72, v93
	s_and_saveexec_b64 s[14:15], vcc
	s_cbranch_execz .LBB0_1158
	s_waitcnt lgkmcnt(0)
	v_add_f32_e32 v93, v93, v94
	v_lshl_add_u64 v[68:69], v[68:69], 4, s[12:13]
	global_store_dword v[68:69], v93, off
.LBB0_1158:
	s_or_b64 exec, exec, s[14:15]
	v_add_u32_e32 v68, 0x600, v142
	s_waitcnt lgkmcnt(0)
	v_ashrrev_i32_e32 v94, 5, v68
	v_mul_lo_u32 v68, v94, s9
	v_add_u32_e32 v93, v101, v68
	v_add_u32_e32 v68, s10, v94
	v_ashrrev_i32_e32 v69, 31, v68
	v_lshlrev_b64 v[96:97], 10, v[68:69]
	v_lshl_add_u64 v[110:111], v[96:97], 0, v[66:67]
	v_lshl_add_u64 v[112:113], v[110:111], 2, s[18:19]
	ds_read_b128 v[96:99], v93
	s_waitcnt lgkmcnt(0)
	s_waitcnt vmcnt(24)
	v_pk_add_f32 v[96:97], v[96:97], v[160:161]
	s_waitcnt vmcnt(24)
	v_pk_add_f32 v[98:99], v[98:99], v[162:163]
	ds_read_b128 v[102:105], v93 offset:64
	global_store_dwordx4 v[112:113], v[96:99], off
	s_waitcnt lgkmcnt(0)
	s_waitcnt vmcnt(24)
	v_pk_add_f32 v[102:103], v[102:103], v[164:165]
	v_cvt_pk_bf16_f32 v106, v96, v97
	v_pk_mul_f32 v[96:97], v[96:97], v[96:97]
	v_cvt_pk_bf16_f32 v107, v98, v99
	v_pk_mul_f32 v[98:99], v[98:99], v[98:99]
	v_add_f32_e32 v95, v96, v97
	s_waitcnt vmcnt(24)
	v_pk_add_f32 v[104:105], v[104:105], v[166:167]
	v_lshl_add_u64 v[108:109], v[110:111], 1, s[38:39]
	v_add_f32_e32 v95, v98, v95
	global_store_dwordx4 v[112:113], v[102:105], off offset:64
	global_store_dwordx2 v[108:109], v[106:107], off
	v_cvt_pk_bf16_f32 v106, v102, v103
	v_pk_mul_f32 v[102:103], v[102:103], v[102:103]
	v_add_f32_e32 v95, v99, v95
	v_add_f32_e32 v95, v102, v95
	v_cvt_pk_bf16_f32 v107, v104, v105
	v_pk_mul_f32 v[104:105], v[104:105], v[104:105]
	v_add_f32_e32 v95, v103, v95
	v_add_f32_e32 v95, v104, v95
	v_add_f32_e32 v95, v105, v95
	ds_bpermute_b32 v96, v0, v95
	global_store_dwordx2 v[108:109], v[106:107], off offset:32
	s_waitcnt lgkmcnt(0)
	v_add_f32_e32 v95, v95, v96
	ds_bpermute_b32 v96, v70, v95
	s_waitcnt lgkmcnt(0)
	v_add_f32_e32 v95, v95, v96
	ds_bpermute_b32 v96, v71, v95
	s_waitcnt lgkmcnt(0)
	v_add_f32_e32 v95, v95, v96
	ds_bpermute_b32 v96, v73, v95
	s_waitcnt lgkmcnt(0)
	v_add_f32_e32 v95, v95, v96
	ds_bpermute_b32 v96, v72, v95
	s_and_saveexec_b64 s[14:15], vcc
	s_cbranch_execz .LBB0_1160
	s_waitcnt lgkmcnt(0)
	v_add_f32_e32 v95, v95, v96
	v_lshl_add_u64 v[68:69], v[68:69], 4, s[12:13]
	global_store_dword v[68:69], v95, off
.LBB0_1160:
	s_or_b64 exec, exec, s[14:15]
	v_add_u32_e32 v68, 0x800, v142
	s_waitcnt lgkmcnt(0)
	v_ashrrev_i32_e32 v96, 5, v68
	v_mul_lo_u32 v68, v96, s9
	v_add_u32_e32 v95, v101, v68
	v_add_u32_e32 v68, s10, v96
	v_ashrrev_i32_e32 v69, 31, v68
	v_lshlrev_b64 v[98:99], 10, v[68:69]
	v_lshl_add_u64 v[98:99], v[98:99], 0, v[66:67]
	v_lshl_add_u64 v[118:119], v[98:99], 2, s[18:19]
	ds_read_b128 v[102:105], v95
	v_lshl_add_u64 v[98:99], v[98:99], 1, s[38:39]
	s_waitcnt lgkmcnt(0)
	s_waitcnt vmcnt(27)
	v_pk_add_f32 v[102:103], v[102:103], v[168:169]
	s_waitcnt vmcnt(27)
	v_pk_add_f32 v[104:105], v[104:105], v[170:171]
	ds_read_b128 v[106:109], v95 offset:64
	global_store_dwordx4 v[118:119], v[102:105], off
	s_waitcnt lgkmcnt(0)
	s_waitcnt vmcnt(27)
	v_pk_add_f32 v[106:107], v[106:107], v[172:173]
	s_waitcnt vmcnt(27)
	v_pk_add_f32 v[108:109], v[108:109], v[174:175]
	v_cvt_pk_bf16_f32 v110, v102, v103
	v_cvt_pk_bf16_f32 v111, v104, v105
	global_store_dwordx4 v[118:119], v[106:109], off offset:64
	global_store_dwordx2 v[98:99], v[110:111], off
	v_cvt_pk_bf16_f32 v110, v106, v107
	v_cvt_pk_bf16_f32 v111, v108, v109
	global_store_dwordx2 v[98:99], v[110:111], off offset:32
	v_pk_mul_f32 v[98:99], v[102:103], v[102:103]
	v_pk_mul_f32 v[102:103], v[104:105], v[104:105]
	v_add_f32_e32 v97, v98, v99
	v_add_f32_e32 v97, v102, v97
	v_pk_mul_f32 v[104:105], v[106:107], v[106:107]
	v_add_f32_e32 v97, v103, v97
	v_add_f32_e32 v97, v104, v97
	v_pk_mul_f32 v[106:107], v[108:109], v[108:109]
	v_add_f32_e32 v97, v105, v97
	v_add_f32_e32 v97, v106, v97
	v_add_f32_e32 v97, v107, v97
	ds_bpermute_b32 v98, v0, v97
	s_waitcnt lgkmcnt(0)
	v_add_f32_e32 v97, v97, v98
	ds_bpermute_b32 v98, v70, v97
	s_waitcnt lgkmcnt(0)
	v_add_f32_e32 v97, v97, v98
	ds_bpermute_b32 v98, v71, v97
	s_waitcnt lgkmcnt(0)
	v_add_f32_e32 v97, v97, v98
	ds_bpermute_b32 v98, v73, v97
	s_waitcnt lgkmcnt(0)
	v_add_f32_e32 v97, v97, v98
	ds_bpermute_b32 v98, v72, v97
	s_and_saveexec_b64 s[14:15], vcc
	s_cbranch_execz .LBB0_1162
	s_waitcnt lgkmcnt(0)
	v_add_f32_e32 v97, v97, v98
	v_lshl_add_u64 v[68:69], v[68:69], 4, s[12:13]
	global_store_dword v[68:69], v97, off
.LBB0_1162:
	s_or_b64 exec, exec, s[14:15]
	v_add_u32_e32 v68, 0xa00, v142
	s_waitcnt lgkmcnt(0)
	v_ashrrev_i32_e32 v98, 5, v68
	v_mul_lo_u32 v68, v98, s9
	v_add_u32_e32 v97, v101, v68
	v_add_u32_e32 v68, s10, v98
	v_ashrrev_i32_e32 v69, 31, v68
	v_lshlrev_b64 v[102:103], 10, v[68:69]
	v_lshl_add_u64 v[118:119], v[102:103], 0, v[66:67]
	v_lshl_add_u64 v[120:121], v[118:119], 2, s[18:19]
	ds_read_b128 v[102:105], v97
	s_waitcnt lgkmcnt(0)
	s_waitcnt vmcnt(30)
	v_pk_add_f32 v[102:103], v[102:103], v[176:177]
	s_waitcnt vmcnt(30)
	v_pk_add_f32 v[104:105], v[104:105], v[178:179]
	ds_read_b128 v[106:109], v97 offset:64
	global_store_dwordx4 v[120:121], v[102:105], off
	s_waitcnt lgkmcnt(0)
	s_waitcnt vmcnt(30)
	v_pk_add_f32 v[106:107], v[106:107], v[180:181]
	v_cvt_pk_bf16_f32 v110, v102, v103
	v_pk_mul_f32 v[102:103], v[102:103], v[102:103]
	v_cvt_pk_bf16_f32 v111, v104, v105
	v_pk_mul_f32 v[104:105], v[104:105], v[104:105]
	v_add_f32_e32 v99, v102, v103
	s_waitcnt vmcnt(30)
	v_pk_add_f32 v[108:109], v[108:109], v[182:183]
	v_lshl_add_u64 v[112:113], v[118:119], 1, s[38:39]
	v_add_f32_e32 v99, v104, v99
	global_store_dwordx4 v[120:121], v[106:109], off offset:64
	global_store_dwordx2 v[112:113], v[110:111], off
	v_cvt_pk_bf16_f32 v110, v106, v107
	v_pk_mul_f32 v[106:107], v[106:107], v[106:107]
	v_add_f32_e32 v99, v105, v99
	v_add_f32_e32 v99, v106, v99
	v_cvt_pk_bf16_f32 v111, v108, v109
	v_pk_mul_f32 v[108:109], v[108:109], v[108:109]
	v_add_f32_e32 v99, v107, v99
	v_add_f32_e32 v99, v108, v99
	v_add_f32_e32 v99, v109, v99
	ds_bpermute_b32 v100, v0, v99
	global_store_dwordx2 v[112:113], v[110:111], off offset:32
	s_waitcnt lgkmcnt(0)
	v_add_f32_e32 v99, v99, v100
	ds_bpermute_b32 v100, v70, v99
	s_waitcnt lgkmcnt(0)
	v_add_f32_e32 v99, v99, v100
	ds_bpermute_b32 v100, v71, v99
	s_waitcnt lgkmcnt(0)
	v_add_f32_e32 v99, v99, v100
	ds_bpermute_b32 v100, v73, v99
	s_waitcnt lgkmcnt(0)
	v_add_f32_e32 v99, v99, v100
	ds_bpermute_b32 v100, v72, v99
	s_and_saveexec_b64 s[14:15], vcc
	s_cbranch_execz .LBB0_1164
	s_waitcnt lgkmcnt(0)
	v_add_f32_e32 v99, v99, v100
	v_lshl_add_u64 v[68:69], v[68:69], 4, s[12:13]
	global_store_dword v[68:69], v99, off
.LBB0_1164:
	s_or_b64 exec, exec, s[14:15]
	v_add_u32_e32 v68, 0xc00, v142
	s_waitcnt lgkmcnt(0)
	v_ashrrev_i32_e32 v100, 5, v68
	v_mul_lo_u32 v68, v100, s9
	v_add_u32_e32 v99, v101, v68
	v_add_u32_e32 v68, s10, v100
	v_ashrrev_i32_e32 v69, 31, v68
	v_lshlrev_b64 v[102:103], 10, v[68:69]
	v_lshl_add_u64 v[118:119], v[102:103], 0, v[66:67]
	v_lshl_add_u64 v[120:121], v[118:119], 2, s[18:19]
	ds_read_b128 v[102:105], v99
	s_waitcnt lgkmcnt(0)
	s_waitcnt vmcnt(33)
	v_pk_add_f32 v[102:103], v[102:103], v[184:185]
	s_waitcnt vmcnt(33)
	v_pk_add_f32 v[104:105], v[104:105], v[186:187]
	ds_read_b128 v[106:109], v99 offset:64
	global_store_dwordx4 v[120:121], v[102:105], off
	s_waitcnt lgkmcnt(0)
	s_waitcnt vmcnt(33)
	v_pk_add_f32 v[106:107], v[106:107], v[188:189]
	v_cvt_pk_bf16_f32 v110, v102, v103
	v_pk_mul_f32 v[102:103], v[102:103], v[102:103]
	v_cvt_pk_bf16_f32 v111, v104, v105
	v_pk_mul_f32 v[104:105], v[104:105], v[104:105]
	v_add_f32_e32 v102, v102, v103
	s_waitcnt vmcnt(33)
	v_pk_add_f32 v[108:109], v[108:109], v[190:191]
	v_lshl_add_u64 v[112:113], v[118:119], 1, s[38:39]
	v_add_f32_e32 v102, v104, v102
	global_store_dwordx4 v[120:121], v[106:109], off offset:64
	global_store_dwordx2 v[112:113], v[110:111], off
	v_cvt_pk_bf16_f32 v110, v106, v107
	v_pk_mul_f32 v[106:107], v[106:107], v[106:107]
	v_add_f32_e32 v102, v105, v102
	v_add_f32_e32 v102, v106, v102
	v_cvt_pk_bf16_f32 v111, v108, v109
	v_pk_mul_f32 v[108:109], v[108:109], v[108:109]
	v_add_f32_e32 v102, v107, v102
	v_add_f32_e32 v102, v108, v102
	v_add_f32_e32 v102, v109, v102
	ds_bpermute_b32 v103, v0, v102
	global_store_dwordx2 v[112:113], v[110:111], off offset:32
	s_waitcnt lgkmcnt(0)
	v_add_f32_e32 v102, v102, v103
	ds_bpermute_b32 v103, v70, v102
	s_waitcnt lgkmcnt(0)
	v_add_f32_e32 v102, v102, v103
	ds_bpermute_b32 v103, v71, v102
	s_waitcnt lgkmcnt(0)
	v_add_f32_e32 v102, v102, v103
	ds_bpermute_b32 v103, v73, v102
	s_waitcnt lgkmcnt(0)
	v_add_f32_e32 v102, v102, v103
	ds_bpermute_b32 v103, v72, v102
	s_and_saveexec_b64 s[14:15], vcc
	s_cbranch_execz .LBB0_1166
	s_waitcnt lgkmcnt(0)
	v_add_f32_e32 v102, v102, v103
	v_lshl_add_u64 v[68:69], v[68:69], 4, s[12:13]
	global_store_dword v[68:69], v102, off
.LBB0_1166:
	s_or_b64 exec, exec, s[14:15]
	v_add_u32_e32 v68, 0xe00, v142
	v_ashrrev_i32_e32 v102, 5, v68
	v_mul_lo_u32 v68, v102, s9
	v_add_u32_e32 v101, v101, v68
	v_add_u32_e32 v68, s10, v102
	v_ashrrev_i32_e32 v69, 31, v68
	v_lshlrev_b64 v[104:105], 10, v[68:69]
	v_lshl_add_u64 v[112:113], v[104:105], 0, v[66:67]
	v_lshl_add_u64 v[122:123], v[112:113], 2, s[18:19]
	ds_read_b128 v[104:107], v101
	v_lshl_add_u64 v[112:113], v[112:113], 1, s[38:39]
	s_waitcnt lgkmcnt(0)
	s_waitcnt vmcnt(36)
	v_pk_add_f32 v[104:105], v[104:105], v[192:193]
	s_waitcnt vmcnt(36)
	v_pk_add_f32 v[106:107], v[106:107], v[194:195]
	ds_read_b128 v[108:111], v101 offset:64
	global_store_dwordx4 v[122:123], v[104:107], off
	s_waitcnt lgkmcnt(0)
	s_waitcnt vmcnt(36)
	v_pk_add_f32 v[108:109], v[108:109], v[196:197]
	v_cvt_pk_bf16_f32 v118, v104, v105
	v_pk_mul_f32 v[104:105], v[104:105], v[104:105]
	v_cvt_pk_bf16_f32 v119, v106, v107
	v_pk_mul_f32 v[106:107], v[106:107], v[106:107]
	v_add_f32_e32 v103, v104, v105
	s_waitcnt vmcnt(36)
	v_pk_add_f32 v[110:111], v[110:111], v[198:199]
	v_add_f32_e32 v103, v106, v103
	global_store_dwordx4 v[122:123], v[108:111], off offset:64
	global_store_dwordx2 v[112:113], v[118:119], off
	v_cvt_pk_bf16_f32 v118, v108, v109
	v_pk_mul_f32 v[108:109], v[108:109], v[108:109]
	v_add_f32_e32 v103, v107, v103
	v_add_f32_e32 v103, v108, v103
	v_cvt_pk_bf16_f32 v119, v110, v111
	v_pk_mul_f32 v[110:111], v[110:111], v[110:111]
	v_add_f32_e32 v103, v109, v103
	v_add_f32_e32 v103, v110, v103
	v_add_f32_e32 v103, v111, v103
	ds_bpermute_b32 v104, v0, v103
	global_store_dwordx2 v[112:113], v[118:119], off offset:32
	s_waitcnt lgkmcnt(0)
	v_add_f32_e32 v103, v103, v104
	ds_bpermute_b32 v104, v70, v103
	s_waitcnt lgkmcnt(0)
	v_add_f32_e32 v103, v103, v104
	ds_bpermute_b32 v104, v71, v103
	s_waitcnt lgkmcnt(0)
	v_add_f32_e32 v103, v103, v104
	ds_bpermute_b32 v104, v73, v103
	s_waitcnt lgkmcnt(0)
	v_add_f32_e32 v103, v103, v104
	ds_bpermute_b32 v104, v72, v103
	s_and_saveexec_b64 s[10:11], vcc
	s_cbranch_execz .LBB0_1168
	s_waitcnt lgkmcnt(0)
	v_add_f32_e32 v103, v103, v104
	v_lshl_add_u64 v[68:69], v[68:69], 4, s[12:13]
	global_store_dword v[68:69], v103, off
.LBB0_1168:
	s_or_b64 exec, exec, s[10:11]
	s_waitcnt lgkmcnt(0)
	s_barrier
	ds_write2_b32 v130, v2, v18 offset1:16
	ds_write2_b32 v114, v3, v19 offset0:4 offset1:20
	ds_write2_b32 v115, v4, v20 offset0:8 offset1:24
	ds_write2_b32 v116, v5, v21 offset0:12 offset1:28
	ds_write2_b32 v117, v6, v22 offset0:64 offset1:80
	ds_write2_b32 v82, v7, v23 offset0:68 offset1:84
	ds_write2_b32 v83, v8, v24 offset0:72 offset1:88
	ds_write2_b32 v84, v9, v25 offset0:76 offset1:92
	ds_write2_b32 v85, v10, v26 offset0:128 offset1:144
	ds_write2_b32 v74, v11, v27 offset0:132 offset1:148
	ds_write2_b32 v75, v12, v28 offset0:136 offset1:152
	ds_write2_b32 v76, v13, v29 offset0:140 offset1:156
	ds_write2_b32 v80, v14, v30 offset0:192 offset1:208
	ds_write2_b32 v77, v15, v31 offset0:196 offset1:212
	ds_write2_b32 v78, v16, v32 offset0:200 offset1:216
	ds_write2_b32 v79, v17, v33 offset0:204 offset1:220
	ds_write2_b32 v130, v34, v50 offset0:128 offset1:144
	ds_write2_b32 v114, v35, v51 offset0:132 offset1:148
	ds_write2_b32 v115, v36, v52 offset0:136 offset1:152
	ds_write2_b32 v116, v37, v53 offset0:140 offset1:156
	ds_write2_b32 v117, v38, v54 offset0:192 offset1:208
	ds_write2_b32 v82, v39, v55 offset0:196 offset1:212
	ds_write2_b32 v83, v40, v56 offset0:200 offset1:216
	ds_write2_b32 v84, v41, v57 offset0:204 offset1:220
	ds_write2_b32 v74, v42, v58 offset1:16
	ds_write2_b32 v75, v43, v59 offset0:4 offset1:20
	ds_write2_b32 v76, v44, v60 offset0:8 offset1:24
	ds_write2_b32 v81, v45, v61 offset0:12 offset1:28
	ds_write2_b32 v77, v46, v62 offset0:64 offset1:80
	ds_write2_b32 v78, v47, v63 offset0:68 offset1:84
	ds_write2_b32 v79, v48, v64 offset0:72 offset1:88
	ds_write2_b32 v86, v49, v65 offset0:76 offset1:92
	v_add_u32_e32 v2, s8, v87
	v_ashrrev_i32_e32 v3, 31, v2
	v_lshlrev_b64 v[4:5], 10, v[2:3]
	v_lshl_add_u64 v[20:21], v[4:5], 0, v[66:67]
	v_lshl_add_u64 v[22:23], v[20:21], 2, s[18:19]
	s_waitcnt lgkmcnt(0)
	s_barrier
	v_lshlrev_b32_e32 v140, 2, v20
	global_load_dwordx4 v[132:135], v140, s[18:19]
	global_load_dwordx4 v[136:139], v140, s[18:19] offset:64
	v_add_u32_e32 v140, 0x10000, v140
	global_load_dwordx4 v[144:147], v140, s[18:19]
	global_load_dwordx4 v[148:151], v140, s[18:19] offset:64
	v_add_u32_e32 v140, 0x10000, v140
	global_load_dwordx4 v[152:155], v140, s[18:19]
	global_load_dwordx4 v[156:159], v140, s[18:19] offset:64
	v_add_u32_e32 v140, 0x10000, v140
	global_load_dwordx4 v[160:163], v140, s[18:19]
	global_load_dwordx4 v[164:167], v140, s[18:19] offset:64
	v_add_u32_e32 v140, 0x10000, v140
	global_load_dwordx4 v[168:171], v140, s[18:19]
	global_load_dwordx4 v[172:175], v140, s[18:19] offset:64
	v_add_u32_e32 v140, 0x10000, v140
	global_load_dwordx4 v[176:179], v140, s[18:19]
	global_load_dwordx4 v[180:183], v140, s[18:19] offset:64
	v_add_u32_e32 v140, 0x10000, v140
	global_load_dwordx4 v[184:187], v140, s[18:19]
	global_load_dwordx4 v[188:191], v140, s[18:19] offset:64
	v_add_u32_e32 v140, 0x10000, v140
	global_load_dwordx4 v[192:195], v140, s[18:19]
	global_load_dwordx4 v[196:199], v140, s[18:19] offset:64
	ds_read_b128 v[12:15], v88
	ds_read_b128 v[16:19], v88 offset:64
	s_waitcnt lgkmcnt(1)
	s_waitcnt vmcnt(15)
	v_pk_add_f32 v[4:5], v[12:13], v[132:133]
	s_waitcnt vmcnt(15)
	v_pk_add_f32 v[6:7], v[14:15], v[134:135]
	v_pk_mul_f32 v[12:13], v[4:5], v[4:5]
	v_pk_mul_f32 v[14:15], v[6:7], v[6:7]
	v_add_f32_e32 v12, v12, v13
	s_waitcnt lgkmcnt(0)
	s_waitcnt vmcnt(14)
	v_pk_add_f32 v[8:9], v[16:17], v[136:137]
	v_add_f32_e32 v12, v14, v12
	v_pk_mul_f32 v[16:17], v[8:9], v[8:9]
	v_add_f32_e32 v12, v15, v12
	s_waitcnt vmcnt(14)
	v_pk_add_f32 v[10:11], v[18:19], v[138:139]
	v_add_f32_e32 v12, v16, v12
	v_pk_mul_f32 v[18:19], v[10:11], v[10:11]
	v_add_f32_e32 v12, v17, v12
	v_add_f32_e32 v12, v18, v12
	v_add_f32_e32 v12, v19, v12
	ds_bpermute_b32 v13, v0, v12
	global_store_dwordx4 v[22:23], v[4:7], off
	global_store_dwordx4 v[22:23], v[8:11], off offset:64
	s_waitcnt lgkmcnt(0)
	v_add_f32_e32 v12, v12, v13
	ds_bpermute_b32 v13, v70, v12
	v_cvt_pk_bf16_f32 v8, v8, v9
	v_cvt_pk_bf16_f32 v9, v10, v11
	s_waitcnt lgkmcnt(0)
	v_add_f32_e32 v12, v12, v13
	ds_bpermute_b32 v13, v71, v12
	s_waitcnt lgkmcnt(0)
	v_add_f32_e32 v14, v12, v13
	ds_bpermute_b32 v15, v73, v14
	v_cvt_pk_bf16_f32 v12, v4, v5
	v_cvt_pk_bf16_f32 v13, v6, v7
	v_lshl_add_u64 v[6:7], v[20:21], 1, s[38:39]
	global_store_dwordx2 v[6:7], v[12:13], off
	s_waitcnt lgkmcnt(0)
	v_add_f32_e32 v4, v14, v15
	ds_bpermute_b32 v5, v72, v4
	global_store_dwordx2 v[6:7], v[8:9], off offset:32
	s_and_saveexec_b64 s[10:11], vcc
	s_cbranch_execz .LBB0_1170
	s_waitcnt lgkmcnt(0)
	v_add_f32_e32 v4, v4, v5
	v_lshl_add_u64 v[2:3], v[2:3], 4, s[12:13]
	global_store_dword v[2:3], v4, off
.LBB0_1170:
	s_or_b64 exec, exec, s[10:11]
	v_add_u32_e32 v2, s8, v90
	v_ashrrev_i32_e32 v3, 31, v2
	s_waitcnt lgkmcnt(0)
	v_lshlrev_b64 v[4:5], 10, v[2:3]
	v_lshl_add_u64 v[16:17], v[4:5], 0, v[66:67]
	v_lshl_add_u64 v[18:19], v[16:17], 2, s[18:19]
	ds_read_b128 v[4:7], v89
	s_waitcnt lgkmcnt(0)
	s_waitcnt vmcnt(18)
	v_pk_add_f32 v[4:5], v[4:5], v[144:145]
	s_waitcnt vmcnt(18)
	v_pk_add_f32 v[6:7], v[6:7], v[146:147]
	ds_read_b128 v[8:11], v89 offset:64
	global_store_dwordx4 v[18:19], v[4:7], off
	s_waitcnt lgkmcnt(0)
	s_waitcnt vmcnt(18)
	v_pk_add_f32 v[8:9], v[8:9], v[148:149]
	v_cvt_pk_bf16_f32 v12, v4, v5
	v_pk_mul_f32 v[4:5], v[4:5], v[4:5]
	v_cvt_pk_bf16_f32 v13, v6, v7
	v_pk_mul_f32 v[6:7], v[6:7], v[6:7]
	v_add_f32_e32 v4, v4, v5
	s_waitcnt vmcnt(18)
	v_pk_add_f32 v[10:11], v[10:11], v[150:151]
	v_lshl_add_u64 v[14:15], v[16:17], 1, s[38:39]
	v_add_f32_e32 v4, v6, v4
	global_store_dwordx4 v[18:19], v[8:11], off offset:64
	global_store_dwordx2 v[14:15], v[12:13], off
	v_cvt_pk_bf16_f32 v12, v8, v9
	v_pk_mul_f32 v[8:9], v[8:9], v[8:9]
	v_add_f32_e32 v4, v7, v4
	v_add_f32_e32 v4, v8, v4
	v_cvt_pk_bf16_f32 v13, v10, v11
	v_pk_mul_f32 v[10:11], v[10:11], v[10:11]
	v_add_f32_e32 v4, v9, v4
	v_add_f32_e32 v4, v10, v4
	v_add_f32_e32 v4, v11, v4
	ds_bpermute_b32 v5, v0, v4
	global_store_dwordx2 v[14:15], v[12:13], off offset:32
	s_waitcnt lgkmcnt(0)
	v_add_f32_e32 v4, v4, v5
	ds_bpermute_b32 v5, v70, v4
	s_waitcnt lgkmcnt(0)
	v_add_f32_e32 v4, v4, v5
	ds_bpermute_b32 v5, v71, v4
	s_waitcnt lgkmcnt(0)
	v_add_f32_e32 v4, v4, v5
	ds_bpermute_b32 v5, v73, v4
	s_waitcnt lgkmcnt(0)
	v_add_f32_e32 v4, v4, v5
	ds_bpermute_b32 v5, v72, v4
	s_and_saveexec_b64 s[10:11], vcc
	s_cbranch_execz .LBB0_1172
	s_waitcnt lgkmcnt(0)
	v_add_f32_e32 v4, v4, v5
	v_lshl_add_u64 v[2:3], v[2:3], 4, s[12:13]
	global_store_dword v[2:3], v4, off
.LBB0_1172:
	s_or_b64 exec, exec, s[10:11]
	v_add_u32_e32 v2, s8, v92
	v_ashrrev_i32_e32 v3, 31, v2
	s_waitcnt lgkmcnt(0)
	v_lshlrev_b64 v[4:5], 10, v[2:3]
	v_lshl_add_u64 v[16:17], v[4:5], 0, v[66:67]
	v_lshl_add_u64 v[18:19], v[16:17], 2, s[18:19]
	ds_read_b128 v[4:7], v91
	s_waitcnt lgkmcnt(0)
	s_waitcnt vmcnt(21)
	v_pk_add_f32 v[4:5], v[4:5], v[152:153]
	s_waitcnt vmcnt(21)
	v_pk_add_f32 v[6:7], v[6:7], v[154:155]
	ds_read_b128 v[8:11], v91 offset:64
	global_store_dwordx4 v[18:19], v[4:7], off
	s_waitcnt lgkmcnt(0)
	s_waitcnt vmcnt(21)
	v_pk_add_f32 v[8:9], v[8:9], v[156:157]
	v_cvt_pk_bf16_f32 v12, v4, v5
	v_pk_mul_f32 v[4:5], v[4:5], v[4:5]
	v_cvt_pk_bf16_f32 v13, v6, v7
	v_pk_mul_f32 v[6:7], v[6:7], v[6:7]
	v_add_f32_e32 v4, v4, v5
	s_waitcnt vmcnt(21)
	v_pk_add_f32 v[10:11], v[10:11], v[158:159]
	v_lshl_add_u64 v[14:15], v[16:17], 1, s[38:39]
	v_add_f32_e32 v4, v6, v4
	global_store_dwordx4 v[18:19], v[8:11], off offset:64
	global_store_dwordx2 v[14:15], v[12:13], off
	v_cvt_pk_bf16_f32 v12, v8, v9
	v_pk_mul_f32 v[8:9], v[8:9], v[8:9]
	v_add_f32_e32 v4, v7, v4
	v_add_f32_e32 v4, v8, v4
	v_cvt_pk_bf16_f32 v13, v10, v11
	v_pk_mul_f32 v[10:11], v[10:11], v[10:11]
	v_add_f32_e32 v4, v9, v4
	v_add_f32_e32 v4, v10, v4
	v_add_f32_e32 v4, v11, v4
	ds_bpermute_b32 v5, v0, v4
	global_store_dwordx2 v[14:15], v[12:13], off offset:32
	s_waitcnt lgkmcnt(0)
	v_add_f32_e32 v4, v4, v5
	ds_bpermute_b32 v5, v70, v4
	s_waitcnt lgkmcnt(0)
	v_add_f32_e32 v4, v4, v5
	ds_bpermute_b32 v5, v71, v4
	s_waitcnt lgkmcnt(0)
	v_add_f32_e32 v4, v4, v5
	ds_bpermute_b32 v5, v73, v4
	s_waitcnt lgkmcnt(0)
	v_add_f32_e32 v4, v4, v5
	ds_bpermute_b32 v5, v72, v4
	s_and_saveexec_b64 s[10:11], vcc
	s_cbranch_execz .LBB0_1174
	s_waitcnt lgkmcnt(0)
	v_add_f32_e32 v4, v4, v5
	v_lshl_add_u64 v[2:3], v[2:3], 4, s[12:13]
	global_store_dword v[2:3], v4, off
.LBB0_1174:
	s_or_b64 exec, exec, s[10:11]
	v_add_u32_e32 v2, s8, v94
	v_ashrrev_i32_e32 v3, 31, v2
	s_waitcnt lgkmcnt(0)
	v_lshlrev_b64 v[4:5], 10, v[2:3]
	v_lshl_add_u64 v[16:17], v[4:5], 0, v[66:67]
	v_lshl_add_u64 v[18:19], v[16:17], 2, s[18:19]
	ds_read_b128 v[4:7], v93
	s_waitcnt lgkmcnt(0)
	s_waitcnt vmcnt(24)
	v_pk_add_f32 v[4:5], v[4:5], v[160:161]
	s_waitcnt vmcnt(24)
	v_pk_add_f32 v[6:7], v[6:7], v[162:163]
	ds_read_b128 v[8:11], v93 offset:64
	global_store_dwordx4 v[18:19], v[4:7], off
	s_waitcnt lgkmcnt(0)
	s_waitcnt vmcnt(24)
	v_pk_add_f32 v[8:9], v[8:9], v[164:165]
	v_cvt_pk_bf16_f32 v12, v4, v5
	v_pk_mul_f32 v[4:5], v[4:5], v[4:5]
	v_cvt_pk_bf16_f32 v13, v6, v7
	v_pk_mul_f32 v[6:7], v[6:7], v[6:7]
	v_add_f32_e32 v4, v4, v5
	s_waitcnt vmcnt(24)
	v_pk_add_f32 v[10:11], v[10:11], v[166:167]
	v_lshl_add_u64 v[14:15], v[16:17], 1, s[38:39]
	v_add_f32_e32 v4, v6, v4
	global_store_dwordx4 v[18:19], v[8:11], off offset:64
	global_store_dwordx2 v[14:15], v[12:13], off
	v_cvt_pk_bf16_f32 v12, v8, v9
	v_pk_mul_f32 v[8:9], v[8:9], v[8:9]
	v_add_f32_e32 v4, v7, v4
	v_add_f32_e32 v4, v8, v4
	v_cvt_pk_bf16_f32 v13, v10, v11
	v_pk_mul_f32 v[10:11], v[10:11], v[10:11]
	v_add_f32_e32 v4, v9, v4
	v_add_f32_e32 v4, v10, v4
	v_add_f32_e32 v4, v11, v4
	ds_bpermute_b32 v5, v0, v4
	global_store_dwordx2 v[14:15], v[12:13], off offset:32
	s_waitcnt lgkmcnt(0)
	v_add_f32_e32 v4, v4, v5
	ds_bpermute_b32 v5, v70, v4
	s_waitcnt lgkmcnt(0)
	v_add_f32_e32 v4, v4, v5
	ds_bpermute_b32 v5, v71, v4
	s_waitcnt lgkmcnt(0)
	v_add_f32_e32 v4, v4, v5
	ds_bpermute_b32 v5, v73, v4
	s_waitcnt lgkmcnt(0)
	v_add_f32_e32 v4, v4, v5
	ds_bpermute_b32 v5, v72, v4
	s_and_saveexec_b64 s[10:11], vcc
	s_cbranch_execz .LBB0_1176
	s_waitcnt lgkmcnt(0)
	v_add_f32_e32 v4, v4, v5
	v_lshl_add_u64 v[2:3], v[2:3], 4, s[12:13]
	global_store_dword v[2:3], v4, off
.LBB0_1176:
	s_or_b64 exec, exec, s[10:11]
	v_add_u32_e32 v2, s8, v96
	v_ashrrev_i32_e32 v3, 31, v2
	s_waitcnt lgkmcnt(0)
	v_lshlrev_b64 v[4:5], 10, v[2:3]
	v_lshl_add_u64 v[16:17], v[4:5], 0, v[66:67]
	v_lshl_add_u64 v[18:19], v[16:17], 2, s[18:19]
	ds_read_b128 v[4:7], v95
	s_waitcnt lgkmcnt(0)
	s_waitcnt vmcnt(27)
	v_pk_add_f32 v[4:5], v[4:5], v[168:169]
	s_waitcnt vmcnt(27)
	v_pk_add_f32 v[6:7], v[6:7], v[170:171]
	ds_read_b128 v[8:11], v95 offset:64
	global_store_dwordx4 v[18:19], v[4:7], off
	s_waitcnt lgkmcnt(0)
	s_waitcnt vmcnt(27)
	v_pk_add_f32 v[8:9], v[8:9], v[172:173]
	v_cvt_pk_bf16_f32 v12, v4, v5
	v_pk_mul_f32 v[4:5], v[4:5], v[4:5]
	v_cvt_pk_bf16_f32 v13, v6, v7
	v_pk_mul_f32 v[6:7], v[6:7], v[6:7]
	v_add_f32_e32 v4, v4, v5
	s_waitcnt vmcnt(27)
	v_pk_add_f32 v[10:11], v[10:11], v[174:175]
	v_lshl_add_u64 v[14:15], v[16:17], 1, s[38:39]
	v_add_f32_e32 v4, v6, v4
	global_store_dwordx4 v[18:19], v[8:11], off offset:64
	global_store_dwordx2 v[14:15], v[12:13], off
	v_cvt_pk_bf16_f32 v12, v8, v9
	v_pk_mul_f32 v[8:9], v[8:9], v[8:9]
	v_add_f32_e32 v4, v7, v4
	v_add_f32_e32 v4, v8, v4
	v_cvt_pk_bf16_f32 v13, v10, v11
	v_pk_mul_f32 v[10:11], v[10:11], v[10:11]
	v_add_f32_e32 v4, v9, v4
	v_add_f32_e32 v4, v10, v4
	v_add_f32_e32 v4, v11, v4
	ds_bpermute_b32 v5, v0, v4
	global_store_dwordx2 v[14:15], v[12:13], off offset:32
	s_waitcnt lgkmcnt(0)
	v_add_f32_e32 v4, v4, v5
	ds_bpermute_b32 v5, v70, v4
	s_waitcnt lgkmcnt(0)
	v_add_f32_e32 v4, v4, v5
	ds_bpermute_b32 v5, v71, v4
	s_waitcnt lgkmcnt(0)
	v_add_f32_e32 v4, v4, v5
	ds_bpermute_b32 v5, v73, v4
	s_waitcnt lgkmcnt(0)
	v_add_f32_e32 v4, v4, v5
	ds_bpermute_b32 v5, v72, v4
	s_and_saveexec_b64 s[10:11], vcc
	s_cbranch_execz .LBB0_1178
	s_waitcnt lgkmcnt(0)
	v_add_f32_e32 v4, v4, v5
	v_lshl_add_u64 v[2:3], v[2:3], 4, s[12:13]
	global_store_dword v[2:3], v4, off
.LBB0_1178:
	s_or_b64 exec, exec, s[10:11]
	v_add_u32_e32 v2, s8, v98
	v_ashrrev_i32_e32 v3, 31, v2
	s_waitcnt lgkmcnt(0)
	v_lshlrev_b64 v[4:5], 10, v[2:3]
	v_lshl_add_u64 v[16:17], v[4:5], 0, v[66:67]
	v_lshl_add_u64 v[18:19], v[16:17], 2, s[18:19]
	ds_read_b128 v[4:7], v97
	s_waitcnt lgkmcnt(0)
	s_waitcnt vmcnt(30)
	v_pk_add_f32 v[4:5], v[4:5], v[176:177]
	s_waitcnt vmcnt(30)
	v_pk_add_f32 v[6:7], v[6:7], v[178:179]
	ds_read_b128 v[8:11], v97 offset:64
	global_store_dwordx4 v[18:19], v[4:7], off
	s_waitcnt lgkmcnt(0)
	s_waitcnt vmcnt(30)
	v_pk_add_f32 v[8:9], v[8:9], v[180:181]
	v_cvt_pk_bf16_f32 v12, v4, v5
	v_pk_mul_f32 v[4:5], v[4:5], v[4:5]
	v_cvt_pk_bf16_f32 v13, v6, v7
	v_pk_mul_f32 v[6:7], v[6:7], v[6:7]
	v_add_f32_e32 v4, v4, v5
	s_waitcnt vmcnt(30)
	v_pk_add_f32 v[10:11], v[10:11], v[182:183]
	v_lshl_add_u64 v[14:15], v[16:17], 1, s[38:39]
	v_add_f32_e32 v4, v6, v4
	global_store_dwordx4 v[18:19], v[8:11], off offset:64
	global_store_dwordx2 v[14:15], v[12:13], off
	v_cvt_pk_bf16_f32 v12, v8, v9
	v_pk_mul_f32 v[8:9], v[8:9], v[8:9]
	v_add_f32_e32 v4, v7, v4
	v_add_f32_e32 v4, v8, v4
	v_cvt_pk_bf16_f32 v13, v10, v11
	v_pk_mul_f32 v[10:11], v[10:11], v[10:11]
	v_add_f32_e32 v4, v9, v4
	v_add_f32_e32 v4, v10, v4
	v_add_f32_e32 v4, v11, v4
	ds_bpermute_b32 v5, v0, v4
	global_store_dwordx2 v[14:15], v[12:13], off offset:32
	s_waitcnt lgkmcnt(0)
	v_add_f32_e32 v4, v4, v5
	ds_bpermute_b32 v5, v70, v4
	s_waitcnt lgkmcnt(0)
	v_add_f32_e32 v4, v4, v5
	ds_bpermute_b32 v5, v71, v4
	s_waitcnt lgkmcnt(0)
	v_add_f32_e32 v4, v4, v5
	ds_bpermute_b32 v5, v73, v4
	s_waitcnt lgkmcnt(0)
	v_add_f32_e32 v4, v4, v5
	ds_bpermute_b32 v5, v72, v4
	s_and_saveexec_b64 s[10:11], vcc
	s_cbranch_execz .LBB0_1180
	s_waitcnt lgkmcnt(0)
	v_add_f32_e32 v4, v4, v5
	v_lshl_add_u64 v[2:3], v[2:3], 4, s[12:13]
	global_store_dword v[2:3], v4, off
.LBB0_1180:
	s_or_b64 exec, exec, s[10:11]
	v_add_u32_e32 v2, s8, v100
	v_ashrrev_i32_e32 v3, 31, v2
	s_waitcnt lgkmcnt(0)
	v_lshlrev_b64 v[4:5], 10, v[2:3]
	v_lshl_add_u64 v[16:17], v[4:5], 0, v[66:67]
	v_lshl_add_u64 v[18:19], v[16:17], 2, s[18:19]
	ds_read_b128 v[4:7], v99
	s_waitcnt lgkmcnt(0)
	s_waitcnt vmcnt(33)
	v_pk_add_f32 v[4:5], v[4:5], v[184:185]
	s_waitcnt vmcnt(33)
	v_pk_add_f32 v[6:7], v[6:7], v[186:187]
	ds_read_b128 v[8:11], v99 offset:64
	global_store_dwordx4 v[18:19], v[4:7], off
	s_waitcnt lgkmcnt(0)
	s_waitcnt vmcnt(33)
	v_pk_add_f32 v[8:9], v[8:9], v[188:189]
	v_cvt_pk_bf16_f32 v12, v4, v5
	v_pk_mul_f32 v[4:5], v[4:5], v[4:5]
	v_cvt_pk_bf16_f32 v13, v6, v7
	v_pk_mul_f32 v[6:7], v[6:7], v[6:7]
	v_add_f32_e32 v4, v4, v5
	s_waitcnt vmcnt(33)
	v_pk_add_f32 v[10:11], v[10:11], v[190:191]
	v_lshl_add_u64 v[14:15], v[16:17], 1, s[38:39]
	v_add_f32_e32 v4, v6, v4
	global_store_dwordx4 v[18:19], v[8:11], off offset:64
	global_store_dwordx2 v[14:15], v[12:13], off
	v_cvt_pk_bf16_f32 v12, v8, v9
	v_pk_mul_f32 v[8:9], v[8:9], v[8:9]
	v_add_f32_e32 v4, v7, v4
	v_add_f32_e32 v4, v8, v4
	v_cvt_pk_bf16_f32 v13, v10, v11
	v_pk_mul_f32 v[10:11], v[10:11], v[10:11]
	v_add_f32_e32 v4, v9, v4
	v_add_f32_e32 v4, v10, v4
	v_add_f32_e32 v4, v11, v4
	ds_bpermute_b32 v5, v0, v4
	global_store_dwordx2 v[14:15], v[12:13], off offset:32
	s_waitcnt lgkmcnt(0)
	v_add_f32_e32 v4, v4, v5
	ds_bpermute_b32 v5, v70, v4
	s_waitcnt lgkmcnt(0)
	v_add_f32_e32 v4, v4, v5
	ds_bpermute_b32 v5, v71, v4
	s_waitcnt lgkmcnt(0)
	v_add_f32_e32 v4, v4, v5
	ds_bpermute_b32 v5, v73, v4
	s_waitcnt lgkmcnt(0)
	v_add_f32_e32 v4, v4, v5
	ds_bpermute_b32 v5, v72, v4
	s_and_saveexec_b64 s[10:11], vcc
	s_cbranch_execz .LBB0_1182
	s_waitcnt lgkmcnt(0)
	v_add_f32_e32 v4, v4, v5
	v_lshl_add_u64 v[2:3], v[2:3], 4, s[12:13]
	global_store_dword v[2:3], v4, off
.LBB0_1182:
	s_or_b64 exec, exec, s[10:11]
	v_add_u32_e32 v2, s8, v102
	v_ashrrev_i32_e32 v3, 31, v2
	s_waitcnt lgkmcnt(0)
	v_lshlrev_b64 v[4:5], 10, v[2:3]
	v_lshl_add_u64 v[16:17], v[4:5], 0, v[66:67]
	v_lshl_add_u64 v[18:19], v[16:17], 2, s[18:19]
	ds_read_b128 v[4:7], v101
	s_waitcnt lgkmcnt(0)
	s_waitcnt vmcnt(36)
	v_pk_add_f32 v[4:5], v[4:5], v[192:193]
	s_waitcnt vmcnt(36)
	v_pk_add_f32 v[6:7], v[6:7], v[194:195]
	ds_read_b128 v[8:11], v101 offset:64
	global_store_dwordx4 v[18:19], v[4:7], off
	s_waitcnt lgkmcnt(0)
	s_waitcnt vmcnt(36)
	v_pk_add_f32 v[8:9], v[8:9], v[196:197]
	v_cvt_pk_bf16_f32 v12, v4, v5
	v_pk_mul_f32 v[4:5], v[4:5], v[4:5]
	v_cvt_pk_bf16_f32 v13, v6, v7
	v_pk_mul_f32 v[6:7], v[6:7], v[6:7]
	v_add_f32_e32 v4, v4, v5
	s_waitcnt vmcnt(36)
	v_pk_add_f32 v[10:11], v[10:11], v[198:199]
	v_lshl_add_u64 v[14:15], v[16:17], 1, s[38:39]
	v_add_f32_e32 v4, v6, v4
	global_store_dwordx4 v[18:19], v[8:11], off offset:64
	global_store_dwordx2 v[14:15], v[12:13], off
	v_cvt_pk_bf16_f32 v12, v8, v9
	v_pk_mul_f32 v[8:9], v[8:9], v[8:9]
	v_add_f32_e32 v4, v7, v4
	v_add_f32_e32 v4, v8, v4
	v_cvt_pk_bf16_f32 v13, v10, v11
	v_pk_mul_f32 v[10:11], v[10:11], v[10:11]
	v_add_f32_e32 v4, v9, v4
	v_add_f32_e32 v4, v10, v4
	v_add_f32_e32 v4, v11, v4
	ds_bpermute_b32 v0, v0, v4
	global_store_dwordx2 v[14:15], v[12:13], off offset:32
	s_waitcnt lgkmcnt(0)
	v_add_f32_e32 v0, v4, v0
	ds_bpermute_b32 v4, v70, v0
	s_waitcnt lgkmcnt(0)
	v_add_f32_e32 v0, v0, v4
	ds_bpermute_b32 v4, v71, v0
	s_waitcnt lgkmcnt(0)
	v_add_f32_e32 v0, v0, v4
	ds_bpermute_b32 v4, v73, v0
	s_waitcnt lgkmcnt(0)
	v_add_f32_e32 v0, v0, v4
	ds_bpermute_b32 v4, v72, v0
	s_and_saveexec_b64 s[8:9], vcc
	s_cbranch_execz .LBB0_1184
	s_waitcnt lgkmcnt(0)
	v_add_f32_e32 v0, v0, v4
	v_lshl_add_u64 v[2:3], v[2:3], 4, s[12:13]
	global_store_dword v[2:3], v0, off

.LBB0_1309:
	s_or_b64 exec, exec, s[8:9]
	s_movk_i32 s9, 0x410
	v_lshrrev_b32_e32 v130, 2, v142
	v_lshlrev_b32_e32 v131, 1, v142
	v_and_b32_e32 v0, 15, v142
	v_and_b32_e32 v130, 0xfffffcc, v130
	v_and_b32_e32 v131, 0x180, v131
	v_add_u32_e32 v131, 0, v131
	v_lshlrev_b32_e32 v0, 2, v0
	v_mul_lo_u32 v130, v130, s9
	v_add3_u32 v130, v131, v0, v130
	s_waitcnt vmcnt(0)
	s_barrier
	ds_write2_b32 v130, v114, v126 offset1:16
	v_add_u32_e32 v114, 0x400, v130
	ds_write2_b32 v114, v115, v127 offset0:4 offset1:20
	v_add_u32_e32 v115, 0x800, v130
	ds_write2_b32 v115, v116, v128 offset0:8 offset1:24
	v_add_u32_e32 v116, 0xc00, v130
	ds_write2_b32 v116, v117, v129 offset0:12 offset1:28
	v_add_u32_e32 v117, 0x4000, v130
	ds_write2_b32 v117, v82, v94 offset0:64 offset1:80
	v_add_u32_e32 v82, 0x4400, v130
	ds_write2_b32 v82, v83, v95 offset0:68 offset1:84
	v_add_u32_e32 v83, 0x4800, v130
	ds_write2_b32 v83, v84, v96 offset0:72 offset1:88
	v_add_u32_e32 v84, 0x4c00, v130
	ds_write2_b32 v84, v85, v97 offset0:76 offset1:92
	v_add_u32_e32 v85, 0x8000, v130
	ds_write2_b32 v85, v74, v78 offset0:128 offset1:144
	v_add_u32_e32 v74, 0x8400, v130
	ds_write2_b32 v74, v75, v79 offset0:132 offset1:148
	v_add_u32_e32 v75, 0x8800, v130
	ds_write2_b32 v75, v76, v80 offset0:136 offset1:152
	v_add_u32_e32 v76, 0x8c00, v130
	v_add_u32_e32 v80, 0xc000, v130
	ds_write2_b32 v76, v77, v81 offset0:140 offset1:156
	ds_write2_b32 v80, v66, v70 offset0:192 offset1:208
	v_add_u32_e32 v77, 0xc400, v130
	v_add_u32_e32 v78, 0xc800, v130
	v_add_u32_e32 v79, 0xcc00, v130
	v_add_u32_e32 v81, 0x9000, v130
	v_lshlrev_b32_e32 v66, 2, v142
	ds_write2_b32 v77, v67, v71 offset0:196 offset1:212
	ds_write2_b32 v78, v68, v72 offset0:200 offset1:216
	ds_write2_b32 v79, v69, v73 offset0:204 offset1:220
	ds_write2_b32 v130, v98, v118 offset0:128 offset1:144
	ds_write2_b32 v114, v99, v119 offset0:132 offset1:148
	ds_write2_b32 v115, v100, v120 offset0:136 offset1:152
	ds_write2_b32 v116, v101, v121 offset0:140 offset1:156
	ds_write2_b32 v117, v102, v122 offset0:192 offset1:208
	ds_write2_b32 v82, v103, v123 offset0:196 offset1:212
	ds_write2_b32 v83, v104, v124 offset0:200 offset1:216
	ds_write2_b32 v84, v105, v125 offset0:204 offset1:220
	ds_write2_b32 v74, v90, v110 offset1:16
	ds_write2_b32 v75, v91, v111 offset0:4 offset1:20
	ds_write2_b32 v76, v92, v112 offset0:8 offset1:24
	ds_write2_b32 v81, v93, v113 offset0:12 offset1:28
	ds_write2_b32 v77, v86, v106 offset0:64 offset1:80
	ds_write2_b32 v78, v87, v107 offset0:68 offset1:84
	ds_write2_b32 v79, v88, v108 offset0:72 offset1:88
	v_lshlrev_b32_e32 v0, 3, v142
	v_and_b32_e32 v66, 12, v66
	s_movk_i32 s8, 0xe0
	v_ashrrev_i32_e32 v87, 5, v142
	v_and_or_b32 v0, v0, s8, v66
	v_add_u32_e32 v68, s15, v87
	v_or_b32_e32 v66, s7, v0
	v_ashrrev_i32_e32 v69, 31, v68
	v_ashrrev_i32_e32 v67, 31, v66
	v_lshlrev_b64 v[70:71], 10, v[68:69]
	v_lshl_add_u64 v[98:99], v[70:71], 0, v[66:67]
	v_add_u32_e32 v86, 0xd000, v130
	v_lshl_add_u64 v[110:111], v[98:99], 2, s[18:19]
	ds_write2_b32 v86, v89, v109 offset0:76 offset1:92
	s_waitcnt lgkmcnt(0)
	s_barrier
	v_lshlrev_b32_e32 v140, 2, v98
	global_load_dwordx4 v[132:135], v140, s[18:19]
	global_load_dwordx4 v[136:139], v140, s[18:19] offset:64
	v_add_u32_e32 v140, 0x10000, v140
	global_load_dwordx4 v[144:147], v140, s[18:19]
	global_load_dwordx4 v[148:151], v140, s[18:19] offset:64
	v_add_u32_e32 v140, 0x10000, v140
	global_load_dwordx4 v[152:155], v140, s[18:19]
	global_load_dwordx4 v[156:159], v140, s[18:19] offset:64
	v_add_u32_e32 v140, 0x10000, v140
	global_load_dwordx4 v[160:163], v140, s[18:19]
	global_load_dwordx4 v[164:167], v140, s[18:19] offset:64
	v_add_u32_e32 v140, 0x10000, v140
	global_load_dwordx4 v[168:171], v140, s[18:19]
	global_load_dwordx4 v[172:175], v140, s[18:19] offset:64
	v_add_u32_e32 v140, 0x10000, v140
	global_load_dwordx4 v[176:179], v140, s[18:19]
	global_load_dwordx4 v[180:183], v140, s[18:19] offset:64
	v_add_u32_e32 v140, 0x10000, v140
	global_load_dwordx4 v[184:187], v140, s[18:19]
	global_load_dwordx4 v[188:191], v140, s[18:19] offset:64
	v_add_u32_e32 v140, 0x10000, v140
	global_load_dwordx4 v[192:195], v140, s[18:19]
	global_load_dwordx4 v[196:199], v140, s[18:19] offset:64
	v_lshl_add_u32 v101, v0, 2, 0
	v_mul_lo_u32 v72, v87, s9
	v_add_u32_e32 v88, v101, v72
	ds_read_b128 v[102:105], v88
	ds_read_b128 v[106:109], v88 offset:64
	v_and_b32_e32 v70, 64, v218
	v_xor_b32_e32 v0, 1, v218
	v_add_u32_e32 v100, 64, v70
	v_cmp_lt_i32_e32 vcc, v0, v100
	v_xor_b32_e32 v70, 2, v218
	v_xor_b32_e32 v71, 4, v218
	v_cndmask_b32_e32 v0, v218, v0, vcc
	v_lshlrev_b32_e32 v0, 2, v0
	v_cmp_lt_i32_e32 vcc, v70, v100
	v_xor_b32_e32 v112, 8, v218
	v_and_b32_e32 v89, 31, v142
	v_cndmask_b32_e32 v70, v218, v70, vcc
	v_lshlrev_b32_e32 v70, 2, v70
	v_cmp_lt_i32_e32 vcc, v71, v100
	s_ashr_i32 s7, s6, 31
	s_lshl_b64 s[6:7], s[6:7], 2
	v_cndmask_b32_e32 v71, v218, v71, vcc
	v_cmp_lt_i32_e32 vcc, v112, v100
	v_lshlrev_b32_e32 v71, 2, v71
	s_add_u32 s6, s40, s6
	s_movk_i32 s12, 0x410
	s_addc_u32 s7, s41, s7
	s_waitcnt lgkmcnt(1)
	s_waitcnt vmcnt(15)
	v_pk_add_f32 v[90:91], v[102:103], v[132:133]
	s_waitcnt vmcnt(15)
	v_pk_add_f32 v[92:93], v[104:105], v[134:135]
	v_pk_mul_f32 v[72:73], v[90:91], v[90:91]
	v_pk_mul_f32 v[102:103], v[92:93], v[92:93]
	v_add_f32_e32 v72, v72, v73
	s_waitcnt lgkmcnt(0)
	s_waitcnt vmcnt(14)
	v_pk_add_f32 v[94:95], v[106:107], v[136:137]
	v_add_f32_e32 v72, v102, v72
	v_pk_mul_f32 v[104:105], v[94:95], v[94:95]
	v_add_f32_e32 v72, v103, v72
	s_waitcnt vmcnt(14)
	v_pk_add_f32 v[96:97], v[108:109], v[138:139]
	v_add_f32_e32 v72, v104, v72
	v_pk_mul_f32 v[106:107], v[96:97], v[96:97]
	v_add_f32_e32 v72, v105, v72
	v_add_f32_e32 v72, v106, v72
	v_add_f32_e32 v72, v107, v72
	ds_bpermute_b32 v102, v0, v72
	v_xor_b32_e32 v103, 16, v218
	v_cndmask_b32_e32 v73, v218, v112, vcc
	v_cmp_lt_i32_e32 vcc, v103, v100
	v_lshlrev_b32_e32 v73, 2, v73
	s_waitcnt lgkmcnt(0)
	v_add_f32_e32 v102, v72, v102
	ds_bpermute_b32 v104, v70, v102
	v_cndmask_b32_e32 v72, v218, v103, vcc
	v_cmp_eq_u32_e32 vcc, 0, v89
	v_lshlrev_b32_e32 v72, 2, v72
	global_store_dwordx4 v[110:111], v[90:93], off
	s_waitcnt lgkmcnt(0)
	v_add_f32_e32 v89, v102, v104
	ds_bpermute_b32 v100, v71, v89
	v_cvt_pk_bf16_f32 v102, v90, v91
	global_store_dwordx4 v[110:111], v[94:97], off offset:64
	v_cvt_pk_bf16_f32 v103, v92, v93
	v_lshl_add_u64 v[92:93], v[98:99], 1, s[38:39]
	s_waitcnt lgkmcnt(0)
	v_add_f32_e32 v89, v89, v100
	ds_bpermute_b32 v100, v73, v89
	v_cvt_pk_bf16_f32 v94, v94, v95
	v_cvt_pk_bf16_f32 v95, v96, v97
	global_store_dwordx2 v[92:93], v[102:103], off
	global_store_dwordx2 v[92:93], v[94:95], off offset:32
	s_waitcnt lgkmcnt(0)
	v_add_f32_e32 v89, v89, v100
	ds_bpermute_b32 v90, v72, v89
	s_and_saveexec_b64 s[8:9], vcc
	s_cbranch_execz .LBB0_1311
	s_waitcnt lgkmcnt(0)
	v_add_f32_e32 v89, v89, v90
	v_lshl_add_u64 v[68:69], v[68:69], 4, s[6:7]
	global_store_dword v[68:69], v89, off
.LBB0_1311:
	s_or_b64 exec, exec, s[8:9]
	v_add_u32_e32 v68, 0x200, v142
	s_waitcnt lgkmcnt(0)
	v_ashrrev_i32_e32 v90, 5, v68
	v_mul_lo_u32 v68, v90, s12
	v_add_u32_e32 v89, v101, v68
	v_add_u32_e32 v68, s15, v90
	v_ashrrev_i32_e32 v69, 31, v68
	v_lshlrev_b64 v[92:93], 10, v[68:69]
	v_lshl_add_u64 v[106:107], v[92:93], 0, v[66:67]
	v_lshl_add_u64 v[108:109], v[106:107], 2, s[18:19]
	ds_read_b128 v[92:95], v89
	s_waitcnt lgkmcnt(0)
	s_waitcnt vmcnt(18)
	v_pk_add_f32 v[92:93], v[92:93], v[144:145]
	s_waitcnt vmcnt(18)
	v_pk_add_f32 v[94:95], v[94:95], v[146:147]
	ds_read_b128 v[96:99], v89 offset:64
	global_store_dwordx4 v[108:109], v[92:95], off
	s_waitcnt lgkmcnt(0)
	s_waitcnt vmcnt(18)
	v_pk_add_f32 v[96:97], v[96:97], v[148:149]
	v_cvt_pk_bf16_f32 v102, v92, v93
	v_pk_mul_f32 v[92:93], v[92:93], v[92:93]
	v_cvt_pk_bf16_f32 v103, v94, v95
	v_pk_mul_f32 v[94:95], v[94:95], v[94:95]
	v_add_f32_e32 v91, v92, v93
	s_waitcnt vmcnt(18)
	v_pk_add_f32 v[98:99], v[98:99], v[150:151]
	v_lshl_add_u64 v[104:105], v[106:107], 1, s[38:39]
	v_add_f32_e32 v91, v94, v91
	global_store_dwordx4 v[108:109], v[96:99], off offset:64
	global_store_dwordx2 v[104:105], v[102:103], off
	v_cvt_pk_bf16_f32 v102, v96, v97
	v_pk_mul_f32 v[96:97], v[96:97], v[96:97]
	v_add_f32_e32 v91, v95, v91
	v_add_f32_e32 v91, v96, v91
	v_cvt_pk_bf16_f32 v103, v98, v99
	v_pk_mul_f32 v[98:99], v[98:99], v[98:99]
	v_add_f32_e32 v91, v97, v91
	v_add_f32_e32 v91, v98, v91
	v_add_f32_e32 v91, v99, v91
	ds_bpermute_b32 v92, v0, v91
	global_store_dwordx2 v[104:105], v[102:103], off offset:32
	s_waitcnt lgkmcnt(0)
	v_add_f32_e32 v91, v91, v92
	ds_bpermute_b32 v92, v70, v91
	s_waitcnt lgkmcnt(0)
	v_add_f32_e32 v91, v91, v92
	ds_bpermute_b32 v92, v71, v91
	s_waitcnt lgkmcnt(0)
	v_add_f32_e32 v91, v91, v92
	ds_bpermute_b32 v92, v73, v91
	s_waitcnt lgkmcnt(0)
	v_add_f32_e32 v91, v91, v92
	ds_bpermute_b32 v92, v72, v91
	s_and_saveexec_b64 s[8:9], vcc
	s_cbranch_execz .LBB0_1313
	s_waitcnt lgkmcnt(0)
	v_add_f32_e32 v91, v91, v92
	v_lshl_add_u64 v[68:69], v[68:69], 4, s[6:7]
	global_store_dword v[68:69], v91, off
.LBB0_1313:
	s_or_b64 exec, exec, s[8:9]
	v_add_u32_e32 v68, 0x400, v142
	s_waitcnt lgkmcnt(0)
	v_ashrrev_i32_e32 v92, 5, v68
	v_mul_lo_u32 v68, v92, s12
	v_add_u32_e32 v91, v101, v68
	v_add_u32_e32 v68, s15, v92
	v_ashrrev_i32_e32 v69, 31, v68
	v_lshlrev_b64 v[94:95], 10, v[68:69]
	v_lshl_add_u64 v[98:99], v[94:95], 0, v[66:67]
	v_lshl_add_u64 v[110:111], v[98:99], 2, s[18:19]
	ds_read_b128 v[94:97], v91
	v_lshl_add_u64 v[98:99], v[98:99], 1, s[38:39]
	s_waitcnt lgkmcnt(0)
	s_waitcnt vmcnt(21)
	v_pk_add_f32 v[94:95], v[94:95], v[152:153]
	s_waitcnt vmcnt(21)
	v_pk_add_f32 v[96:97], v[96:97], v[154:155]
	ds_read_b128 v[102:105], v91 offset:64
	global_store_dwordx4 v[110:111], v[94:97], off
	s_waitcnt lgkmcnt(0)
	s_waitcnt vmcnt(21)
	v_pk_add_f32 v[102:103], v[102:103], v[156:157]
	v_cvt_pk_bf16_f32 v106, v94, v95
	v_pk_mul_f32 v[94:95], v[94:95], v[94:95]
	s_waitcnt vmcnt(21)
	v_pk_add_f32 v[104:105], v[104:105], v[158:159]
	v_cvt_pk_bf16_f32 v107, v96, v97
	v_pk_mul_f32 v[96:97], v[96:97], v[96:97]
	v_add_f32_e32 v93, v94, v95
	global_store_dwordx4 v[110:111], v[102:105], off offset:64
	global_store_dwordx2 v[98:99], v[106:107], off
	v_cvt_pk_bf16_f32 v106, v102, v103
	v_cvt_pk_bf16_f32 v107, v104, v105
	v_add_f32_e32 v93, v96, v93
	global_store_dwordx2 v[98:99], v[106:107], off offset:32
	v_pk_mul_f32 v[98:99], v[102:103], v[102:103]
	v_add_f32_e32 v93, v97, v93
	v_add_f32_e32 v93, v98, v93
	v_pk_mul_f32 v[102:103], v[104:105], v[104:105]
	v_add_f32_e32 v93, v99, v93
	v_add_f32_e32 v93, v102, v93
	v_add_f32_e32 v93, v103, v93
	ds_bpermute_b32 v94, v0, v93
	s_waitcnt lgkmcnt(0)
	v_add_f32_e32 v93, v93, v94
	ds_bpermute_b32 v94, v70, v93
	s_waitcnt lgkmcnt(0)
	v_add_f32_e32 v93, v93, v94
	ds_bpermute_b32 v94, v71, v93
	s_waitcnt lgkmcnt(0)
	v_add_f32_e32 v93, v93, v94
	ds_bpermute_b32 v94, v73, v93
	s_waitcnt lgkmcnt(0)
	v_add_f32_e32 v93, v93, v94
	ds_bpermute_b32 v94, v72, v93
	s_and_saveexec_b64 s[8:9], vcc
	s_cbranch_execz .LBB0_1315
	s_waitcnt lgkmcnt(0)
	v_add_f32_e32 v93, v93, v94
	v_lshl_add_u64 v[68:69], v[68:69], 4, s[6:7]
	global_store_dword v[68:69], v93, off
.LBB0_1315:
	s_or_b64 exec, exec, s[8:9]
	v_add_u32_e32 v68, 0x600, v142
	s_waitcnt lgkmcnt(0)
	v_ashrrev_i32_e32 v94, 5, v68
	v_mul_lo_u32 v68, v94, s12
	v_add_u32_e32 v93, v101, v68
	v_add_u32_e32 v68, s15, v94
	v_ashrrev_i32_e32 v69, 31, v68
	v_lshlrev_b64 v[96:97], 10, v[68:69]
	v_lshl_add_u64 v[110:111], v[96:97], 0, v[66:67]
	v_lshl_add_u64 v[112:113], v[110:111], 2, s[18:19]
	ds_read_b128 v[96:99], v93
	s_waitcnt lgkmcnt(0)
	s_waitcnt vmcnt(24)
	v_pk_add_f32 v[96:97], v[96:97], v[160:161]
	s_waitcnt vmcnt(24)
	v_pk_add_f32 v[98:99], v[98:99], v[162:163]
	ds_read_b128 v[102:105], v93 offset:64
	global_store_dwordx4 v[112:113], v[96:99], off
	s_waitcnt lgkmcnt(0)
	s_waitcnt vmcnt(24)
	v_pk_add_f32 v[102:103], v[102:103], v[164:165]
	v_cvt_pk_bf16_f32 v106, v96, v97
	v_pk_mul_f32 v[96:97], v[96:97], v[96:97]
	v_cvt_pk_bf16_f32 v107, v98, v99
	v_pk_mul_f32 v[98:99], v[98:99], v[98:99]
	v_add_f32_e32 v95, v96, v97
	s_waitcnt vmcnt(24)
	v_pk_add_f32 v[104:105], v[104:105], v[166:167]
	v_lshl_add_u64 v[108:109], v[110:111], 1, s[38:39]
	v_add_f32_e32 v95, v98, v95
	global_store_dwordx4 v[112:113], v[102:105], off offset:64
	global_store_dwordx2 v[108:109], v[106:107], off
	v_cvt_pk_bf16_f32 v106, v102, v103
	v_pk_mul_f32 v[102:103], v[102:103], v[102:103]
	v_add_f32_e32 v95, v99, v95
	v_add_f32_e32 v95, v102, v95
	v_cvt_pk_bf16_f32 v107, v104, v105
	v_pk_mul_f32 v[104:105], v[104:105], v[104:105]
	v_add_f32_e32 v95, v103, v95
	v_add_f32_e32 v95, v104, v95
	v_add_f32_e32 v95, v105, v95
	ds_bpermute_b32 v96, v0, v95
	global_store_dwordx2 v[108:109], v[106:107], off offset:32
	s_waitcnt lgkmcnt(0)
	v_add_f32_e32 v95, v95, v96
	ds_bpermute_b32 v96, v70, v95
	s_waitcnt lgkmcnt(0)
	v_add_f32_e32 v95, v95, v96
	ds_bpermute_b32 v96, v71, v95
	s_waitcnt lgkmcnt(0)
	v_add_f32_e32 v95, v95, v96
	ds_bpermute_b32 v96, v73, v95
	s_waitcnt lgkmcnt(0)
	v_add_f32_e32 v95, v95, v96
	ds_bpermute_b32 v96, v72, v95
	s_and_saveexec_b64 s[8:9], vcc
	s_cbranch_execz .LBB0_1317
	s_waitcnt lgkmcnt(0)
	v_add_f32_e32 v95, v95, v96
	v_lshl_add_u64 v[68:69], v[68:69], 4, s[6:7]
	global_store_dword v[68:69], v95, off
.LBB0_1317:
	s_or_b64 exec, exec, s[8:9]
	v_add_u32_e32 v68, 0x800, v142
	s_waitcnt lgkmcnt(0)
	v_ashrrev_i32_e32 v96, 5, v68
	v_mul_lo_u32 v68, v96, s12
	v_add_u32_e32 v95, v101, v68
	v_add_u32_e32 v68, s15, v96
	v_ashrrev_i32_e32 v69, 31, v68
	v_lshlrev_b64 v[98:99], 10, v[68:69]
	v_lshl_add_u64 v[98:99], v[98:99], 0, v[66:67]
	v_lshl_add_u64 v[118:119], v[98:99], 2, s[18:19]
	ds_read_b128 v[102:105], v95
	v_lshl_add_u64 v[98:99], v[98:99], 1, s[38:39]
	s_waitcnt lgkmcnt(0)
	s_waitcnt vmcnt(27)
	v_pk_add_f32 v[102:103], v[102:103], v[168:169]
	s_waitcnt vmcnt(27)
	v_pk_add_f32 v[104:105], v[104:105], v[170:171]
	ds_read_b128 v[106:109], v95 offset:64
	global_store_dwordx4 v[118:119], v[102:105], off
	s_waitcnt lgkmcnt(0)
	s_waitcnt vmcnt(27)
	v_pk_add_f32 v[106:107], v[106:107], v[172:173]
	s_waitcnt vmcnt(27)
	v_pk_add_f32 v[108:109], v[108:109], v[174:175]
	v_cvt_pk_bf16_f32 v110, v102, v103
	v_cvt_pk_bf16_f32 v111, v104, v105
	global_store_dwordx4 v[118:119], v[106:109], off offset:64
	global_store_dwordx2 v[98:99], v[110:111], off
	v_cvt_pk_bf16_f32 v110, v106, v107
	v_cvt_pk_bf16_f32 v111, v108, v109
	global_store_dwordx2 v[98:99], v[110:111], off offset:32
	v_pk_mul_f32 v[98:99], v[102:103], v[102:103]
	v_pk_mul_f32 v[102:103], v[104:105], v[104:105]
	v_add_f32_e32 v97, v98, v99
	v_add_f32_e32 v97, v102, v97
	v_pk_mul_f32 v[104:105], v[106:107], v[106:107]
	v_add_f32_e32 v97, v103, v97
	v_add_f32_e32 v97, v104, v97
	v_pk_mul_f32 v[106:107], v[108:109], v[108:109]
	v_add_f32_e32 v97, v105, v97
	v_add_f32_e32 v97, v106, v97
	v_add_f32_e32 v97, v107, v97
	ds_bpermute_b32 v98, v0, v97
	s_waitcnt lgkmcnt(0)
	v_add_f32_e32 v97, v97, v98
	ds_bpermute_b32 v98, v70, v97
	s_waitcnt lgkmcnt(0)
	v_add_f32_e32 v97, v97, v98
	ds_bpermute_b32 v98, v71, v97
	s_waitcnt lgkmcnt(0)
	v_add_f32_e32 v97, v97, v98
	ds_bpermute_b32 v98, v73, v97
	s_waitcnt lgkmcnt(0)
	v_add_f32_e32 v97, v97, v98
	ds_bpermute_b32 v98, v72, v97
	s_and_saveexec_b64 s[8:9], vcc
	s_cbranch_execz .LBB0_1319
	s_waitcnt lgkmcnt(0)
	v_add_f32_e32 v97, v97, v98
	v_lshl_add_u64 v[68:69], v[68:69], 4, s[6:7]
	global_store_dword v[68:69], v97, off
.LBB0_1319:
	s_or_b64 exec, exec, s[8:9]
	v_add_u32_e32 v68, 0xa00, v142
	s_waitcnt lgkmcnt(0)
	v_ashrrev_i32_e32 v98, 5, v68
	v_mul_lo_u32 v68, v98, s12
	v_add_u32_e32 v97, v101, v68
	v_add_u32_e32 v68, s15, v98
	v_ashrrev_i32_e32 v69, 31, v68
	v_lshlrev_b64 v[102:103], 10, v[68:69]
	v_lshl_add_u64 v[118:119], v[102:103], 0, v[66:67]
	v_lshl_add_u64 v[120:121], v[118:119], 2, s[18:19]
	ds_read_b128 v[102:105], v97
	s_waitcnt lgkmcnt(0)
	s_waitcnt vmcnt(30)
	v_pk_add_f32 v[102:103], v[102:103], v[176:177]
	s_waitcnt vmcnt(30)
	v_pk_add_f32 v[104:105], v[104:105], v[178:179]
	ds_read_b128 v[106:109], v97 offset:64
	global_store_dwordx4 v[120:121], v[102:105], off
	s_waitcnt lgkmcnt(0)
	s_waitcnt vmcnt(30)
	v_pk_add_f32 v[106:107], v[106:107], v[180:181]
	v_cvt_pk_bf16_f32 v110, v102, v103
	v_pk_mul_f32 v[102:103], v[102:103], v[102:103]
	v_cvt_pk_bf16_f32 v111, v104, v105
	v_pk_mul_f32 v[104:105], v[104:105], v[104:105]
	v_add_f32_e32 v99, v102, v103
	s_waitcnt vmcnt(30)
	v_pk_add_f32 v[108:109], v[108:109], v[182:183]
	v_lshl_add_u64 v[112:113], v[118:119], 1, s[38:39]
	v_add_f32_e32 v99, v104, v99
	global_store_dwordx4 v[120:121], v[106:109], off offset:64
	global_store_dwordx2 v[112:113], v[110:111], off
	v_cvt_pk_bf16_f32 v110, v106, v107
	v_pk_mul_f32 v[106:107], v[106:107], v[106:107]
	v_add_f32_e32 v99, v105, v99
	v_add_f32_e32 v99, v106, v99
	v_cvt_pk_bf16_f32 v111, v108, v109
	v_pk_mul_f32 v[108:109], v[108:109], v[108:109]
	v_add_f32_e32 v99, v107, v99
	v_add_f32_e32 v99, v108, v99
	v_add_f32_e32 v99, v109, v99
	ds_bpermute_b32 v100, v0, v99
	global_store_dwordx2 v[112:113], v[110:111], off offset:32
	s_waitcnt lgkmcnt(0)
	v_add_f32_e32 v99, v99, v100
	ds_bpermute_b32 v100, v70, v99
	s_waitcnt lgkmcnt(0)
	v_add_f32_e32 v99, v99, v100
	ds_bpermute_b32 v100, v71, v99
	s_waitcnt lgkmcnt(0)
	v_add_f32_e32 v99, v99, v100
	ds_bpermute_b32 v100, v73, v99
	s_waitcnt lgkmcnt(0)
	v_add_f32_e32 v99, v99, v100
	ds_bpermute_b32 v100, v72, v99
	s_and_saveexec_b64 s[8:9], vcc
	s_cbranch_execz .LBB0_1321
	s_waitcnt lgkmcnt(0)
	v_add_f32_e32 v99, v99, v100
	v_lshl_add_u64 v[68:69], v[68:69], 4, s[6:7]
	global_store_dword v[68:69], v99, off
.LBB0_1321:
	s_or_b64 exec, exec, s[8:9]
	v_add_u32_e32 v68, 0xc00, v142
	s_waitcnt lgkmcnt(0)
	v_ashrrev_i32_e32 v100, 5, v68
	v_mul_lo_u32 v68, v100, s12
	v_add_u32_e32 v99, v101, v68
	v_add_u32_e32 v68, s15, v100
	v_ashrrev_i32_e32 v69, 31, v68
	v_lshlrev_b64 v[102:103], 10, v[68:69]
	v_lshl_add_u64 v[118:119], v[102:103], 0, v[66:67]
	v_lshl_add_u64 v[120:121], v[118:119], 2, s[18:19]
	ds_read_b128 v[102:105], v99
	s_waitcnt lgkmcnt(0)
	s_waitcnt vmcnt(33)
	v_pk_add_f32 v[102:103], v[102:103], v[184:185]
	s_waitcnt vmcnt(33)
	v_pk_add_f32 v[104:105], v[104:105], v[186:187]
	ds_read_b128 v[106:109], v99 offset:64
	global_store_dwordx4 v[120:121], v[102:105], off
	s_waitcnt lgkmcnt(0)
	s_waitcnt vmcnt(33)
	v_pk_add_f32 v[106:107], v[106:107], v[188:189]
	v_cvt_pk_bf16_f32 v110, v102, v103
	v_pk_mul_f32 v[102:103], v[102:103], v[102:103]
	v_cvt_pk_bf16_f32 v111, v104, v105
	v_pk_mul_f32 v[104:105], v[104:105], v[104:105]
	v_add_f32_e32 v102, v102, v103
	s_waitcnt vmcnt(33)
	v_pk_add_f32 v[108:109], v[108:109], v[190:191]
	v_lshl_add_u64 v[112:113], v[118:119], 1, s[38:39]
	v_add_f32_e32 v102, v104, v102
	global_store_dwordx4 v[120:121], v[106:109], off offset:64
	global_store_dwordx2 v[112:113], v[110:111], off
	v_cvt_pk_bf16_f32 v110, v106, v107
	v_pk_mul_f32 v[106:107], v[106:107], v[106:107]
	v_add_f32_e32 v102, v105, v102
	v_add_f32_e32 v102, v106, v102
	v_cvt_pk_bf16_f32 v111, v108, v109
	v_pk_mul_f32 v[108:109], v[108:109], v[108:109]
	v_add_f32_e32 v102, v107, v102
	v_add_f32_e32 v102, v108, v102
	v_add_f32_e32 v102, v109, v102
	ds_bpermute_b32 v103, v0, v102
	global_store_dwordx2 v[112:113], v[110:111], off offset:32
	s_waitcnt lgkmcnt(0)
	v_add_f32_e32 v102, v102, v103
	ds_bpermute_b32 v103, v70, v102
	s_waitcnt lgkmcnt(0)
	v_add_f32_e32 v102, v102, v103
	ds_bpermute_b32 v103, v71, v102
	s_waitcnt lgkmcnt(0)
	v_add_f32_e32 v102, v102, v103
	ds_bpermute_b32 v103, v73, v102
	s_waitcnt lgkmcnt(0)
	v_add_f32_e32 v102, v102, v103
	ds_bpermute_b32 v103, v72, v102
	s_and_saveexec_b64 s[8:9], vcc
	s_cbranch_execz .LBB0_1323
	s_waitcnt lgkmcnt(0)
	v_add_f32_e32 v102, v102, v103
	v_lshl_add_u64 v[68:69], v[68:69], 4, s[6:7]
	global_store_dword v[68:69], v102, off
.LBB0_1323:
	s_or_b64 exec, exec, s[8:9]
	v_add_u32_e32 v68, 0xe00, v142
	v_ashrrev_i32_e32 v102, 5, v68
	v_mul_lo_u32 v68, v102, s12
	v_add_u32_e32 v101, v101, v68
	v_add_u32_e32 v68, s15, v102
	v_ashrrev_i32_e32 v69, 31, v68
	v_lshlrev_b64 v[104:105], 10, v[68:69]
	v_lshl_add_u64 v[112:113], v[104:105], 0, v[66:67]
	v_lshl_add_u64 v[122:123], v[112:113], 2, s[18:19]
	ds_read_b128 v[104:107], v101
	v_lshl_add_u64 v[112:113], v[112:113], 1, s[38:39]
	s_waitcnt lgkmcnt(0)
	s_waitcnt vmcnt(36)
	v_pk_add_f32 v[104:105], v[104:105], v[192:193]
	s_waitcnt vmcnt(36)
	v_pk_add_f32 v[106:107], v[106:107], v[194:195]
	ds_read_b128 v[108:111], v101 offset:64
	global_store_dwordx4 v[122:123], v[104:107], off
	s_waitcnt lgkmcnt(0)
	s_waitcnt vmcnt(36)
	v_pk_add_f32 v[108:109], v[108:109], v[196:197]
	v_cvt_pk_bf16_f32 v118, v104, v105
	v_pk_mul_f32 v[104:105], v[104:105], v[104:105]
	v_cvt_pk_bf16_f32 v119, v106, v107
	v_pk_mul_f32 v[106:107], v[106:107], v[106:107]
	v_add_f32_e32 v103, v104, v105
	s_waitcnt vmcnt(36)
	v_pk_add_f32 v[110:111], v[110:111], v[198:199]
	v_add_f32_e32 v103, v106, v103
	global_store_dwordx4 v[122:123], v[108:111], off offset:64
	global_store_dwordx2 v[112:113], v[118:119], off
	v_cvt_pk_bf16_f32 v118, v108, v109
	v_pk_mul_f32 v[108:109], v[108:109], v[108:109]
	v_add_f32_e32 v103, v107, v103
	v_add_f32_e32 v103, v108, v103
	v_cvt_pk_bf16_f32 v119, v110, v111
	v_pk_mul_f32 v[110:111], v[110:111], v[110:111]
	v_add_f32_e32 v103, v109, v103
	v_add_f32_e32 v103, v110, v103
	v_add_f32_e32 v103, v111, v103
	ds_bpermute_b32 v104, v0, v103
	global_store_dwordx2 v[112:113], v[118:119], off offset:32
	s_waitcnt lgkmcnt(0)
	v_add_f32_e32 v103, v103, v104
	ds_bpermute_b32 v104, v70, v103
	s_waitcnt lgkmcnt(0)
	v_add_f32_e32 v103, v103, v104
	ds_bpermute_b32 v104, v71, v103
	s_waitcnt lgkmcnt(0)
	v_add_f32_e32 v103, v103, v104
	ds_bpermute_b32 v104, v73, v103
	s_waitcnt lgkmcnt(0)
	v_add_f32_e32 v103, v103, v104
	ds_bpermute_b32 v104, v72, v103
	s_and_saveexec_b64 s[8:9], vcc
	s_cbranch_execz .LBB0_1325
	s_waitcnt lgkmcnt(0)
	v_add_f32_e32 v103, v103, v104
	v_lshl_add_u64 v[68:69], v[68:69], 4, s[6:7]
	global_store_dword v[68:69], v103, off
.LBB0_1325:
	s_or_b64 exec, exec, s[8:9]
	s_waitcnt lgkmcnt(0)
	s_barrier
	ds_write2_b32 v130, v2, v18 offset1:16
	ds_write2_b32 v114, v3, v19 offset0:4 offset1:20
	ds_write2_b32 v115, v4, v20 offset0:8 offset1:24
	ds_write2_b32 v116, v5, v21 offset0:12 offset1:28
	ds_write2_b32 v117, v6, v22 offset0:64 offset1:80
	ds_write2_b32 v82, v7, v23 offset0:68 offset1:84
	ds_write2_b32 v83, v8, v24 offset0:72 offset1:88
	ds_write2_b32 v84, v9, v25 offset0:76 offset1:92
	ds_write2_b32 v85, v10, v26 offset0:128 offset1:144
	ds_write2_b32 v74, v11, v27 offset0:132 offset1:148
	ds_write2_b32 v75, v12, v28 offset0:136 offset1:152
	ds_write2_b32 v76, v13, v29 offset0:140 offset1:156
	ds_write2_b32 v80, v14, v30 offset0:192 offset1:208
	ds_write2_b32 v77, v15, v31 offset0:196 offset1:212
	ds_write2_b32 v78, v16, v32 offset0:200 offset1:216
	ds_write2_b32 v79, v17, v33 offset0:204 offset1:220
	ds_write2_b32 v130, v34, v50 offset0:128 offset1:144
	ds_write2_b32 v114, v35, v51 offset0:132 offset1:148
	ds_write2_b32 v115, v36, v52 offset0:136 offset1:152
	ds_write2_b32 v116, v37, v53 offset0:140 offset1:156
	ds_write2_b32 v117, v38, v54 offset0:192 offset1:208
	ds_write2_b32 v82, v39, v55 offset0:196 offset1:212
	ds_write2_b32 v83, v40, v56 offset0:200 offset1:216
	ds_write2_b32 v84, v41, v57 offset0:204 offset1:220
	ds_write2_b32 v74, v42, v58 offset1:16
	ds_write2_b32 v75, v43, v59 offset0:4 offset1:20
	ds_write2_b32 v76, v44, v60 offset0:8 offset1:24
	ds_write2_b32 v81, v45, v61 offset0:12 offset1:28
	ds_write2_b32 v77, v46, v62 offset0:64 offset1:80
	ds_write2_b32 v78, v47, v63 offset0:68 offset1:84
	ds_write2_b32 v79, v48, v64 offset0:72 offset1:88
	ds_write2_b32 v86, v49, v65 offset0:76 offset1:92
	v_add_u32_e32 v2, s14, v87
	v_ashrrev_i32_e32 v3, 31, v2
	v_lshlrev_b64 v[4:5], 10, v[2:3]
	v_lshl_add_u64 v[20:21], v[4:5], 0, v[66:67]
	v_lshl_add_u64 v[22:23], v[20:21], 2, s[18:19]
	s_waitcnt lgkmcnt(0)
	s_barrier
	v_lshlrev_b32_e32 v140, 2, v20
	global_load_dwordx4 v[132:135], v140, s[18:19]
	global_load_dwordx4 v[136:139], v140, s[18:19] offset:64
	v_add_u32_e32 v140, 0x10000, v140
	global_load_dwordx4 v[144:147], v140, s[18:19]
	global_load_dwordx4 v[148:151], v140, s[18:19] offset:64
	v_add_u32_e32 v140, 0x10000, v140
	global_load_dwordx4 v[152:155], v140, s[18:19]
	global_load_dwordx4 v[156:159], v140, s[18:19] offset:64
	v_add_u32_e32 v140, 0x10000, v140
	global_load_dwordx4 v[160:163], v140, s[18:19]
	global_load_dwordx4 v[164:167], v140, s[18:19] offset:64
	v_add_u32_e32 v140, 0x10000, v140
	global_load_dwordx4 v[168:171], v140, s[18:19]
	global_load_dwordx4 v[172:175], v140, s[18:19] offset:64
	v_add_u32_e32 v140, 0x10000, v140
	global_load_dwordx4 v[176:179], v140, s[18:19]
	global_load_dwordx4 v[180:183], v140, s[18:19] offset:64
	v_add_u32_e32 v140, 0x10000, v140
	global_load_dwordx4 v[184:187], v140, s[18:19]
	global_load_dwordx4 v[188:191], v140, s[18:19] offset:64
	v_add_u32_e32 v140, 0x10000, v140
	global_load_dwordx4 v[192:195], v140, s[18:19]
	global_load_dwordx4 v[196:199], v140, s[18:19] offset:64
	ds_read_b128 v[12:15], v88
	ds_read_b128 v[16:19], v88 offset:64
	s_waitcnt lgkmcnt(1)
	s_waitcnt vmcnt(15)
	v_pk_add_f32 v[4:5], v[12:13], v[132:133]
	s_waitcnt vmcnt(15)
	v_pk_add_f32 v[6:7], v[14:15], v[134:135]
	v_pk_mul_f32 v[12:13], v[4:5], v[4:5]
	v_pk_mul_f32 v[14:15], v[6:7], v[6:7]
	v_add_f32_e32 v12, v12, v13
	s_waitcnt lgkmcnt(0)
	s_waitcnt vmcnt(14)
	v_pk_add_f32 v[8:9], v[16:17], v[136:137]
	v_add_f32_e32 v12, v14, v12
	v_pk_mul_f32 v[16:17], v[8:9], v[8:9]
	v_add_f32_e32 v12, v15, v12
	s_waitcnt vmcnt(14)
	v_pk_add_f32 v[10:11], v[18:19], v[138:139]
	v_add_f32_e32 v12, v16, v12
	v_pk_mul_f32 v[18:19], v[10:11], v[10:11]
	v_add_f32_e32 v12, v17, v12
	v_add_f32_e32 v12, v18, v12
	v_add_f32_e32 v12, v19, v12
	ds_bpermute_b32 v13, v0, v12
	global_store_dwordx4 v[22:23], v[4:7], off
	global_store_dwordx4 v[22:23], v[8:11], off offset:64
	s_waitcnt lgkmcnt(0)
	v_add_f32_e32 v12, v12, v13
	ds_bpermute_b32 v13, v70, v12
	v_cvt_pk_bf16_f32 v8, v8, v9
	v_cvt_pk_bf16_f32 v9, v10, v11
	s_waitcnt lgkmcnt(0)
	v_add_f32_e32 v12, v12, v13
	ds_bpermute_b32 v13, v71, v12
	s_waitcnt lgkmcnt(0)
	v_add_f32_e32 v14, v12, v13
	ds_bpermute_b32 v15, v73, v14
	v_cvt_pk_bf16_f32 v12, v4, v5
	v_cvt_pk_bf16_f32 v13, v6, v7
	v_lshl_add_u64 v[6:7], v[20:21], 1, s[38:39]
	global_store_dwordx2 v[6:7], v[12:13], off
	s_waitcnt lgkmcnt(0)
	v_add_f32_e32 v4, v14, v15
	ds_bpermute_b32 v5, v72, v4
	global_store_dwordx2 v[6:7], v[8:9], off offset:32
	s_and_saveexec_b64 s[8:9], vcc
	s_cbranch_execz .LBB0_1327
	s_waitcnt lgkmcnt(0)
	v_add_f32_e32 v4, v4, v5
	v_lshl_add_u64 v[2:3], v[2:3], 4, s[6:7]
	global_store_dword v[2:3], v4, off
.LBB0_1327:
	s_or_b64 exec, exec, s[8:9]
	v_add_u32_e32 v2, s14, v90
	v_ashrrev_i32_e32 v3, 31, v2
	s_waitcnt lgkmcnt(0)
	v_lshlrev_b64 v[4:5], 10, v[2:3]
	v_lshl_add_u64 v[16:17], v[4:5], 0, v[66:67]
	v_lshl_add_u64 v[18:19], v[16:17], 2, s[18:19]
	ds_read_b128 v[4:7], v89
	s_waitcnt lgkmcnt(0)
	s_waitcnt vmcnt(18)
	v_pk_add_f32 v[4:5], v[4:5], v[144:145]
	s_waitcnt vmcnt(18)
	v_pk_add_f32 v[6:7], v[6:7], v[146:147]
	ds_read_b128 v[8:11], v89 offset:64
	global_store_dwordx4 v[18:19], v[4:7], off
	s_waitcnt lgkmcnt(0)
	s_waitcnt vmcnt(18)
	v_pk_add_f32 v[8:9], v[8:9], v[148:149]
	v_cvt_pk_bf16_f32 v12, v4, v5
	v_pk_mul_f32 v[4:5], v[4:5], v[4:5]
	v_cvt_pk_bf16_f32 v13, v6, v7
	v_pk_mul_f32 v[6:7], v[6:7], v[6:7]
	v_add_f32_e32 v4, v4, v5
	s_waitcnt vmcnt(18)
	v_pk_add_f32 v[10:11], v[10:11], v[150:151]
	v_lshl_add_u64 v[14:15], v[16:17], 1, s[38:39]
	v_add_f32_e32 v4, v6, v4
	global_store_dwordx4 v[18:19], v[8:11], off offset:64
	global_store_dwordx2 v[14:15], v[12:13], off
	v_cvt_pk_bf16_f32 v12, v8, v9
	v_pk_mul_f32 v[8:9], v[8:9], v[8:9]
	v_add_f32_e32 v4, v7, v4
	v_add_f32_e32 v4, v8, v4
	v_cvt_pk_bf16_f32 v13, v10, v11
	v_pk_mul_f32 v[10:11], v[10:11], v[10:11]
	v_add_f32_e32 v4, v9, v4
	v_add_f32_e32 v4, v10, v4
	v_add_f32_e32 v4, v11, v4
	ds_bpermute_b32 v5, v0, v4
	global_store_dwordx2 v[14:15], v[12:13], off offset:32
	s_waitcnt lgkmcnt(0)
	v_add_f32_e32 v4, v4, v5
	ds_bpermute_b32 v5, v70, v4
	s_waitcnt lgkmcnt(0)
	v_add_f32_e32 v4, v4, v5
	ds_bpermute_b32 v5, v71, v4
	s_waitcnt lgkmcnt(0)
	v_add_f32_e32 v4, v4, v5
	ds_bpermute_b32 v5, v73, v4
	s_waitcnt lgkmcnt(0)
	v_add_f32_e32 v4, v4, v5
	ds_bpermute_b32 v5, v72, v4
	s_and_saveexec_b64 s[8:9], vcc
	s_cbranch_execz .LBB0_1329
	s_waitcnt lgkmcnt(0)
	v_add_f32_e32 v4, v4, v5
	v_lshl_add_u64 v[2:3], v[2:3], 4, s[6:7]
	global_store_dword v[2:3], v4, off
.LBB0_1329:
	s_or_b64 exec, exec, s[8:9]
	v_add_u32_e32 v2, s14, v92
	v_ashrrev_i32_e32 v3, 31, v2
	s_waitcnt lgkmcnt(0)
	v_lshlrev_b64 v[4:5], 10, v[2:3]
	v_lshl_add_u64 v[16:17], v[4:5], 0, v[66:67]
	v_lshl_add_u64 v[18:19], v[16:17], 2, s[18:19]
	ds_read_b128 v[4:7], v91
	s_waitcnt lgkmcnt(0)
	s_waitcnt vmcnt(21)
	v_pk_add_f32 v[4:5], v[4:5], v[152:153]
	s_waitcnt vmcnt(21)
	v_pk_add_f32 v[6:7], v[6:7], v[154:155]
	ds_read_b128 v[8:11], v91 offset:64
	global_store_dwordx4 v[18:19], v[4:7], off
	s_waitcnt lgkmcnt(0)
	s_waitcnt vmcnt(21)
	v_pk_add_f32 v[8:9], v[8:9], v[156:157]
	v_cvt_pk_bf16_f32 v12, v4, v5
	v_pk_mul_f32 v[4:5], v[4:5], v[4:5]
	v_cvt_pk_bf16_f32 v13, v6, v7
	v_pk_mul_f32 v[6:7], v[6:7], v[6:7]
	v_add_f32_e32 v4, v4, v5
	s_waitcnt vmcnt(21)
	v_pk_add_f32 v[10:11], v[10:11], v[158:159]
	v_lshl_add_u64 v[14:15], v[16:17], 1, s[38:39]
	v_add_f32_e32 v4, v6, v4
	global_store_dwordx4 v[18:19], v[8:11], off offset:64
	global_store_dwordx2 v[14:15], v[12:13], off
	v_cvt_pk_bf16_f32 v12, v8, v9
	v_pk_mul_f32 v[8:9], v[8:9], v[8:9]
	v_add_f32_e32 v4, v7, v4
	v_add_f32_e32 v4, v8, v4
	v_cvt_pk_bf16_f32 v13, v10, v11
	v_pk_mul_f32 v[10:11], v[10:11], v[10:11]
	v_add_f32_e32 v4, v9, v4
	v_add_f32_e32 v4, v10, v4
	v_add_f32_e32 v4, v11, v4
	ds_bpermute_b32 v5, v0, v4
	global_store_dwordx2 v[14:15], v[12:13], off offset:32
	s_waitcnt lgkmcnt(0)
	v_add_f32_e32 v4, v4, v5
	ds_bpermute_b32 v5, v70, v4
	s_waitcnt lgkmcnt(0)
	v_add_f32_e32 v4, v4, v5
	ds_bpermute_b32 v5, v71, v4
	s_waitcnt lgkmcnt(0)
	v_add_f32_e32 v4, v4, v5
	ds_bpermute_b32 v5, v73, v4
	s_waitcnt lgkmcnt(0)
	v_add_f32_e32 v4, v4, v5
	ds_bpermute_b32 v5, v72, v4
	s_and_saveexec_b64 s[8:9], vcc
	s_cbranch_execz .LBB0_1331
	s_waitcnt lgkmcnt(0)
	v_add_f32_e32 v4, v4, v5
	v_lshl_add_u64 v[2:3], v[2:3], 4, s[6:7]
	global_store_dword v[2:3], v4, off
.LBB0_1331:
	s_or_b64 exec, exec, s[8:9]
	v_add_u32_e32 v2, s14, v94
	v_ashrrev_i32_e32 v3, 31, v2
	s_waitcnt lgkmcnt(0)
	v_lshlrev_b64 v[4:5], 10, v[2:3]
	v_lshl_add_u64 v[16:17], v[4:5], 0, v[66:67]
	v_lshl_add_u64 v[18:19], v[16:17], 2, s[18:19]
	ds_read_b128 v[4:7], v93
	s_waitcnt lgkmcnt(0)
	s_waitcnt vmcnt(24)
	v_pk_add_f32 v[4:5], v[4:5], v[160:161]
	s_waitcnt vmcnt(24)
	v_pk_add_f32 v[6:7], v[6:7], v[162:163]
	ds_read_b128 v[8:11], v93 offset:64
	global_store_dwordx4 v[18:19], v[4:7], off
	s_waitcnt lgkmcnt(0)
	s_waitcnt vmcnt(24)
	v_pk_add_f32 v[8:9], v[8:9], v[164:165]
	v_cvt_pk_bf16_f32 v12, v4, v5
	v_pk_mul_f32 v[4:5], v[4:5], v[4:5]
	v_cvt_pk_bf16_f32 v13, v6, v7
	v_pk_mul_f32 v[6:7], v[6:7], v[6:7]
	v_add_f32_e32 v4, v4, v5
	s_waitcnt vmcnt(24)
	v_pk_add_f32 v[10:11], v[10:11], v[166:167]
	v_lshl_add_u64 v[14:15], v[16:17], 1, s[38:39]
	v_add_f32_e32 v4, v6, v4
	global_store_dwordx4 v[18:19], v[8:11], off offset:64
	global_store_dwordx2 v[14:15], v[12:13], off
	v_cvt_pk_bf16_f32 v12, v8, v9
	v_pk_mul_f32 v[8:9], v[8:9], v[8:9]
	v_add_f32_e32 v4, v7, v4
	v_add_f32_e32 v4, v8, v4
	v_cvt_pk_bf16_f32 v13, v10, v11
	v_pk_mul_f32 v[10:11], v[10:11], v[10:11]
	v_add_f32_e32 v4, v9, v4
	v_add_f32_e32 v4, v10, v4
	v_add_f32_e32 v4, v11, v4
	ds_bpermute_b32 v5, v0, v4
	global_store_dwordx2 v[14:15], v[12:13], off offset:32
	s_waitcnt lgkmcnt(0)
	v_add_f32_e32 v4, v4, v5
	ds_bpermute_b32 v5, v70, v4
	s_waitcnt lgkmcnt(0)
	v_add_f32_e32 v4, v4, v5
	ds_bpermute_b32 v5, v71, v4
	s_waitcnt lgkmcnt(0)
	v_add_f32_e32 v4, v4, v5
	ds_bpermute_b32 v5, v73, v4
	s_waitcnt lgkmcnt(0)
	v_add_f32_e32 v4, v4, v5
	ds_bpermute_b32 v5, v72, v4
	s_and_saveexec_b64 s[8:9], vcc
	s_cbranch_execz .LBB0_1333
	s_waitcnt lgkmcnt(0)
	v_add_f32_e32 v4, v4, v5
	v_lshl_add_u64 v[2:3], v[2:3], 4, s[6:7]
	global_store_dword v[2:3], v4, off
.LBB0_1333:
	s_or_b64 exec, exec, s[8:9]
	v_add_u32_e32 v2, s14, v96
	v_ashrrev_i32_e32 v3, 31, v2
	s_waitcnt lgkmcnt(0)
	v_lshlrev_b64 v[4:5], 10, v[2:3]
	v_lshl_add_u64 v[16:17], v[4:5], 0, v[66:67]
	v_lshl_add_u64 v[18:19], v[16:17], 2, s[18:19]
	ds_read_b128 v[4:7], v95
	s_waitcnt lgkmcnt(0)
	s_waitcnt vmcnt(27)
	v_pk_add_f32 v[4:5], v[4:5], v[168:169]
	s_waitcnt vmcnt(27)
	v_pk_add_f32 v[6:7], v[6:7], v[170:171]
	ds_read_b128 v[8:11], v95 offset:64
	global_store_dwordx4 v[18:19], v[4:7], off
	s_waitcnt lgkmcnt(0)
	s_waitcnt vmcnt(27)
	v_pk_add_f32 v[8:9], v[8:9], v[172:173]
	v_cvt_pk_bf16_f32 v12, v4, v5
	v_pk_mul_f32 v[4:5], v[4:5], v[4:5]
	v_cvt_pk_bf16_f32 v13, v6, v7
	v_pk_mul_f32 v[6:7], v[6:7], v[6:7]
	v_add_f32_e32 v4, v4, v5
	s_waitcnt vmcnt(27)
	v_pk_add_f32 v[10:11], v[10:11], v[174:175]
	v_lshl_add_u64 v[14:15], v[16:17], 1, s[38:39]
	v_add_f32_e32 v4, v6, v4
	global_store_dwordx4 v[18:19], v[8:11], off offset:64
	global_store_dwordx2 v[14:15], v[12:13], off
	v_cvt_pk_bf16_f32 v12, v8, v9
	v_pk_mul_f32 v[8:9], v[8:9], v[8:9]
	v_add_f32_e32 v4, v7, v4
	v_add_f32_e32 v4, v8, v4
	v_cvt_pk_bf16_f32 v13, v10, v11
	v_pk_mul_f32 v[10:11], v[10:11], v[10:11]
	v_add_f32_e32 v4, v9, v4
	v_add_f32_e32 v4, v10, v4
	v_add_f32_e32 v4, v11, v4
	ds_bpermute_b32 v5, v0, v4
	global_store_dwordx2 v[14:15], v[12:13], off offset:32
	s_waitcnt lgkmcnt(0)
	v_add_f32_e32 v4, v4, v5
	ds_bpermute_b32 v5, v70, v4
	s_waitcnt lgkmcnt(0)
	v_add_f32_e32 v4, v4, v5
	ds_bpermute_b32 v5, v71, v4
	s_waitcnt lgkmcnt(0)
	v_add_f32_e32 v4, v4, v5
	ds_bpermute_b32 v5, v73, v4
	s_waitcnt lgkmcnt(0)
	v_add_f32_e32 v4, v4, v5
	ds_bpermute_b32 v5, v72, v4
	s_and_saveexec_b64 s[8:9], vcc
	s_cbranch_execz .LBB0_1335
	s_waitcnt lgkmcnt(0)
	v_add_f32_e32 v4, v4, v5
	v_lshl_add_u64 v[2:3], v[2:3], 4, s[6:7]
	global_store_dword v[2:3], v4, off
.LBB0_1335:
	s_or_b64 exec, exec, s[8:9]
	v_add_u32_e32 v2, s14, v98
	v_ashrrev_i32_e32 v3, 31, v2
	s_waitcnt lgkmcnt(0)
	v_lshlrev_b64 v[4:5], 10, v[2:3]
	v_lshl_add_u64 v[16:17], v[4:5], 0, v[66:67]
	v_lshl_add_u64 v[18:19], v[16:17], 2, s[18:19]
	ds_read_b128 v[4:7], v97
	s_waitcnt lgkmcnt(0)
	s_waitcnt vmcnt(30)
	v_pk_add_f32 v[4:5], v[4:5], v[176:177]
	s_waitcnt vmcnt(30)
	v_pk_add_f32 v[6:7], v[6:7], v[178:179]
	ds_read_b128 v[8:11], v97 offset:64
	global_store_dwordx4 v[18:19], v[4:7], off
	s_waitcnt lgkmcnt(0)
	s_waitcnt vmcnt(30)
	v_pk_add_f32 v[8:9], v[8:9], v[180:181]
	v_cvt_pk_bf16_f32 v12, v4, v5
	v_pk_mul_f32 v[4:5], v[4:5], v[4:5]
	v_cvt_pk_bf16_f32 v13, v6, v7
	v_pk_mul_f32 v[6:7], v[6:7], v[6:7]
	v_add_f32_e32 v4, v4, v5
	s_waitcnt vmcnt(30)
	v_pk_add_f32 v[10:11], v[10:11], v[182:183]
	v_lshl_add_u64 v[14:15], v[16:17], 1, s[38:39]
	v_add_f32_e32 v4, v6, v4
	global_store_dwordx4 v[18:19], v[8:11], off offset:64
	global_store_dwordx2 v[14:15], v[12:13], off
	v_cvt_pk_bf16_f32 v12, v8, v9
	v_pk_mul_f32 v[8:9], v[8:9], v[8:9]
	v_add_f32_e32 v4, v7, v4
	v_add_f32_e32 v4, v8, v4
	v_cvt_pk_bf16_f32 v13, v10, v11
	v_pk_mul_f32 v[10:11], v[10:11], v[10:11]
	v_add_f32_e32 v4, v9, v4
	v_add_f32_e32 v4, v10, v4
	v_add_f32_e32 v4, v11, v4
	ds_bpermute_b32 v5, v0, v4
	global_store_dwordx2 v[14:15], v[12:13], off offset:32
	s_waitcnt lgkmcnt(0)
	v_add_f32_e32 v4, v4, v5
	ds_bpermute_b32 v5, v70, v4
	s_waitcnt lgkmcnt(0)
	v_add_f32_e32 v4, v4, v5
	ds_bpermute_b32 v5, v71, v4
	s_waitcnt lgkmcnt(0)
	v_add_f32_e32 v4, v4, v5
	ds_bpermute_b32 v5, v73, v4
	s_waitcnt lgkmcnt(0)
	v_add_f32_e32 v4, v4, v5
	ds_bpermute_b32 v5, v72, v4
	s_and_saveexec_b64 s[8:9], vcc
	s_cbranch_execz .LBB0_1337
	s_waitcnt lgkmcnt(0)
	v_add_f32_e32 v4, v4, v5
	v_lshl_add_u64 v[2:3], v[2:3], 4, s[6:7]
	global_store_dword v[2:3], v4, off
.LBB0_1337:
	s_or_b64 exec, exec, s[8:9]
	v_add_u32_e32 v2, s14, v100
	v_ashrrev_i32_e32 v3, 31, v2
	s_waitcnt lgkmcnt(0)
	v_lshlrev_b64 v[4:5], 10, v[2:3]
	v_lshl_add_u64 v[16:17], v[4:5], 0, v[66:67]
	v_lshl_add_u64 v[18:19], v[16:17], 2, s[18:19]
	ds_read_b128 v[4:7], v99
	s_waitcnt lgkmcnt(0)
	s_waitcnt vmcnt(33)
	v_pk_add_f32 v[4:5], v[4:5], v[184:185]
	s_waitcnt vmcnt(33)
	v_pk_add_f32 v[6:7], v[6:7], v[186:187]
	ds_read_b128 v[8:11], v99 offset:64
	global_store_dwordx4 v[18:19], v[4:7], off
	s_waitcnt lgkmcnt(0)
	s_waitcnt vmcnt(33)
	v_pk_add_f32 v[8:9], v[8:9], v[188:189]
	v_cvt_pk_bf16_f32 v12, v4, v5
	v_pk_mul_f32 v[4:5], v[4:5], v[4:5]
	v_cvt_pk_bf16_f32 v13, v6, v7
	v_pk_mul_f32 v[6:7], v[6:7], v[6:7]
	v_add_f32_e32 v4, v4, v5
	s_waitcnt vmcnt(33)
	v_pk_add_f32 v[10:11], v[10:11], v[190:191]
	v_lshl_add_u64 v[14:15], v[16:17], 1, s[38:39]
	v_add_f32_e32 v4, v6, v4
	global_store_dwordx4 v[18:19], v[8:11], off offset:64
	global_store_dwordx2 v[14:15], v[12:13], off
	v_cvt_pk_bf16_f32 v12, v8, v9
	v_pk_mul_f32 v[8:9], v[8:9], v[8:9]
	v_add_f32_e32 v4, v7, v4
	v_add_f32_e32 v4, v8, v4
	v_cvt_pk_bf16_f32 v13, v10, v11
	v_pk_mul_f32 v[10:11], v[10:11], v[10:11]
	v_add_f32_e32 v4, v9, v4
	v_add_f32_e32 v4, v10, v4
	v_add_f32_e32 v4, v11, v4
	ds_bpermute_b32 v5, v0, v4
	global_store_dwordx2 v[14:15], v[12:13], off offset:32
	s_waitcnt lgkmcnt(0)
	v_add_f32_e32 v4, v4, v5
	ds_bpermute_b32 v5, v70, v4
	s_waitcnt lgkmcnt(0)
	v_add_f32_e32 v4, v4, v5
	ds_bpermute_b32 v5, v71, v4
	s_waitcnt lgkmcnt(0)
	v_add_f32_e32 v4, v4, v5
	ds_bpermute_b32 v5, v73, v4
	s_waitcnt lgkmcnt(0)
	v_add_f32_e32 v4, v4, v5
	ds_bpermute_b32 v5, v72, v4
	s_and_saveexec_b64 s[8:9], vcc
	s_cbranch_execz .LBB0_1339
	s_waitcnt lgkmcnt(0)
	v_add_f32_e32 v4, v4, v5
	v_lshl_add_u64 v[2:3], v[2:3], 4, s[6:7]
	global_store_dword v[2:3], v4, off
.LBB0_1339:
	s_or_b64 exec, exec, s[8:9]
	v_add_u32_e32 v2, s14, v102
	v_ashrrev_i32_e32 v3, 31, v2
	s_waitcnt lgkmcnt(0)
	v_lshlrev_b64 v[4:5], 10, v[2:3]
	v_lshl_add_u64 v[16:17], v[4:5], 0, v[66:67]
	v_lshl_add_u64 v[18:19], v[16:17], 2, s[18:19]
	ds_read_b128 v[4:7], v101
	s_waitcnt lgkmcnt(0)
	s_waitcnt vmcnt(36)
	v_pk_add_f32 v[4:5], v[4:5], v[192:193]
	s_waitcnt vmcnt(36)
	v_pk_add_f32 v[6:7], v[6:7], v[194:195]
	ds_read_b128 v[8:11], v101 offset:64
	global_store_dwordx4 v[18:19], v[4:7], off
	s_waitcnt lgkmcnt(0)
	s_waitcnt vmcnt(36)
	v_pk_add_f32 v[8:9], v[8:9], v[196:197]
	v_cvt_pk_bf16_f32 v12, v4, v5
	v_pk_mul_f32 v[4:5], v[4:5], v[4:5]
	v_cvt_pk_bf16_f32 v13, v6, v7
	v_pk_mul_f32 v[6:7], v[6:7], v[6:7]
	v_add_f32_e32 v4, v4, v5
	s_waitcnt vmcnt(36)
	v_pk_add_f32 v[10:11], v[10:11], v[198:199]
	v_lshl_add_u64 v[14:15], v[16:17], 1, s[38:39]
	v_add_f32_e32 v4, v6, v4
	global_store_dwordx4 v[18:19], v[8:11], off offset:64
	global_store_dwordx2 v[14:15], v[12:13], off
	v_cvt_pk_bf16_f32 v12, v8, v9
	v_pk_mul_f32 v[8:9], v[8:9], v[8:9]
	v_add_f32_e32 v4, v7, v4
	v_add_f32_e32 v4, v8, v4
	v_cvt_pk_bf16_f32 v13, v10, v11
	v_pk_mul_f32 v[10:11], v[10:11], v[10:11]
	v_add_f32_e32 v4, v9, v4
	v_add_f32_e32 v4, v10, v4
	v_add_f32_e32 v4, v11, v4
	ds_bpermute_b32 v0, v0, v4
	global_store_dwordx2 v[14:15], v[12:13], off offset:32
	s_waitcnt lgkmcnt(0)
	v_add_f32_e32 v0, v4, v0
	ds_bpermute_b32 v4, v70, v0
	s_waitcnt lgkmcnt(0)
	v_add_f32_e32 v0, v0, v4
	ds_bpermute_b32 v4, v71, v0
	s_waitcnt lgkmcnt(0)
	v_add_f32_e32 v0, v0, v4
	ds_bpermute_b32 v4, v73, v0
	s_waitcnt lgkmcnt(0)
	v_add_f32_e32 v0, v0, v4
	ds_bpermute_b32 v4, v72, v0
	s_and_saveexec_b64 s[8:9], vcc
	s_cbranch_execz .LBB0_1341
	s_waitcnt lgkmcnt(0)
	v_add_f32_e32 v0, v0, v4
	v_lshl_add_u64 v[2:3], v[2:3], 4, s[6:7]
	global_store_dword v[2:3], v0, off
